# v26 + wave priority lowered after MFMA 23 of each k-step instead of after the last one
# speedup vs baseline: 1.0051x; 1.0009x over previous
;     ...
;   __syncthreads();
;   G2_STAGE(0); G2_STAGE(1);
;   const int fsw = (0x78 >> (((r16 >> 2) & 3) * 2)) & 3;
;   const int aoff = (wm * 128 + r16) * 64 + ((quad ^ fsw) << 4);
;   const int boff = 16384 + (wn * 64 + r16) * 64 + ((quad ^ fsw) << 4);
;   for (int kt = 0; kt < nk; kt++) {
;     if (kt + 1 < nk) asm volatile("s_waitcnt vmcnt(6)" ::: "memory");
;     else asm volatile("s_waitcnt vmcnt(0)" ::: "memory");
;     __builtin_amdgcn_s_barrier();
;     asm volatile("" ::: "memory");
;     if (kt + 2 < nk) G2_STAGE(kt + 2);
;     const char* cS = smem + (kt % 3) * 24576;
;     bf16x8 xa[8], wb[4];
; #pragma unroll
;     for (int f = 0; f < 8; f++) xa[f] = *(const bf16x8*)(cS + aoff + f * 1024);
; #pragma unroll
;     for (int f = 0; f < 4; f++) wb[f] = *(const bf16x8*)(cS + boff + f * 1024);
; #pragma unroll
;     for (int nf = 0; nf < 4; nf++)
; #pragma unroll
;       for (int mf = 0; mf < 8; mf++)
;         acc[nf][mf] = __builtin_amdgcn_mfma_f32_16x16x32_bf16(wb[nf], xa[mf], acc[nf][mf], 0, 0, 0);
.Lta11_loop:
	.p2align 3
	s_waitcnt vmcnt(6) lgkmcnt(0)
	s_barrier
	s_setprio 1
	v_add_u32_e32 v144, s40, v136
	v_mfma_f32_16x16x32_bf16 v[126:129], v[184:187], v[146:149], v[126:129]
	ds_read_b128 v[200:203], v144 offset:0
	v_mfma_f32_16x16x32_bf16 v[122:125], v[184:187], v[152:155], v[122:125]
	ds_read_b128 v[204:207], v144 offset:1024
	v_mfma_f32_16x16x32_bf16 v[118:121], v[184:187], v[156:159], v[118:121]
	ds_read_b128 v[208:211], v144 offset:2048
	v_mfma_f32_16x16x32_bf16 v[114:117], v[184:187], v[162:165], v[114:117]
	ds_read_b128 v[212:215], v144 offset:3072
	v_mfma_f32_16x16x32_bf16 v[110:113], v[184:187], v[166:169], v[110:113]
	ds_read_b128 v[216:219], v144 offset:4096
	v_mfma_f32_16x16x32_bf16 v[106:109], v[184:187], v[170:173], v[106:109]
	ds_read_b128 v[220:223], v144 offset:5120
	v_mfma_f32_16x16x32_bf16 v[102:105], v[184:187], v[176:179], v[102:105]
	ds_read_b128 v[224:227], v144 offset:6144
	v_mfma_f32_16x16x32_bf16 v[98:101], v[184:187], v[180:183], v[98:101]
	ds_read_b128 v[228:231], v144 offset:7168
	v_mfma_f32_16x16x32_bf16 v[94:97], v[188:191], v[146:149], v[94:97]
	v_add_u32_e64 v144, s40, v137
	v_mfma_f32_16x16x32_bf16 v[90:93], v[188:191], v[152:155], v[90:93]
	v_mfma_f32_16x16x32_bf16 v[86:89], v[188:191], v[156:159], v[86:89]
	ds_read_b128 v[232:235], v144 offset:16384
	v_mfma_f32_16x16x32_bf16 v[82:85], v[188:191], v[162:165], v[82:85]
	ds_read_b128 v[236:239], v144 offset:17408
	v_mfma_f32_16x16x32_bf16 v[78:81], v[188:191], v[166:169], v[78:81]
	ds_read_b128 v[240:243], v144 offset:18432
	v_mfma_f32_16x16x32_bf16 v[74:77], v[188:191], v[170:173], v[74:77]
	ds_read_b128 v[244:247], v144 offset:19456
	v_mfma_f32_16x16x32_bf16 v[70:73], v[188:191], v[176:179], v[70:73]
	s_add_i32 s42, s46, s41
	s_mov_b32 m0, s42
	v_lshl_add_u64 v[142:143], v[132:133], 0, s[2:3]
	v_mfma_f32_16x16x32_bf16 v[66:69], v[188:191], v[180:183], v[66:69]
	global_load_lds_dwordx4 v[132:133], off
	s_add_i32 m0, m0, 0x1000
	v_mfma_f32_16x16x32_bf16 v[62:65], v[192:195], v[146:149], v[62:65]
	v_mfma_f32_16x16x32_bf16 v[58:61], v[192:195], v[152:155], v[58:61]
	v_mfma_f32_16x16x32_bf16 v[54:57], v[192:195], v[156:159], v[54:57]
	global_load_lds_dwordx4 v[142:143], off
	v_lshl_add_u64 v[142:143], v[142:143], 0, s[2:3]
	s_add_i32 m0, m0, 0x1000
	v_mfma_f32_16x16x32_bf16 v[50:53], v[192:195], v[162:165], v[50:53]
	v_mfma_f32_16x16x32_bf16 v[46:49], v[192:195], v[166:169], v[46:49]
	v_mfma_f32_16x16x32_bf16 v[42:45], v[192:195], v[170:173], v[42:45]
	global_load_lds_dwordx4 v[142:143], off
	v_lshl_add_u64 v[142:143], v[142:143], 0, s[2:3]
	s_add_i32 m0, m0, 0x1000
	v_mfma_f32_16x16x32_bf16 v[38:41], v[192:195], v[176:179], v[38:41]
	v_mfma_f32_16x16x32_bf16 v[34:37], v[192:195], v[180:183], v[34:37]
	s_setprio 0
	s_nop 0
	v_mfma_f32_16x16x32_bf16 v[30:33], v[196:199], v[146:149], v[30:33]
	global_load_lds_dwordx4 v[142:143], off
	s_add_i32 m0, m0, 0x1000
	v_lshl_add_u64 v[142:143], v[134:135], 0, s[2:3]
	v_mfma_f32_16x16x32_bf16 v[26:29], v[196:199], v[152:155], v[26:29]
	v_mfma_f32_16x16x32_bf16 v[22:25], v[196:199], v[156:159], v[22:25]
	v_mfma_f32_16x16x32_bf16 v[18:21], v[196:199], v[162:165], v[18:21]
	global_load_lds_dwordx4 v[134:135], off
	s_add_i32 m0, m0, 0x1000
	v_lshl_add_u64 v[132:133], v[132:133], 0, s[12:13]
	v_mfma_f32_16x16x32_bf16 v[14:17], v[196:199], v[166:169], v[14:17]
	v_mfma_f32_16x16x32_bf16 v[10:13], v[196:199], v[170:173], v[10:13]
	v_mfma_f32_16x16x32_bf16 v[6:9], v[196:199], v[176:179], v[6:9]
	global_load_lds_dwordx4 v[142:143], off
	v_lshl_add_u64 v[134:135], v[134:135], 0, s[4:5]
	v_mfma_f32_16x16x32_bf16 v[2:5], v[196:199], v[180:183], v[2:5]
	s_mov_b32 s41, s40
	s_nop 0
	s_add_i32 s40, s40, 0x6000
	s_cmp_eq_u32 s40, 0x12000
	s_cselect_b32 s40, 0, s40
	s_nop 0
	.p2align 3
	s_waitcnt vmcnt(6) lgkmcnt(0)
	s_barrier
	s_setprio 1
	v_add_u32_e32 v144, s40, v136
	v_mfma_f32_16x16x32_bf16 v[126:129], v[232:235], v[200:203], v[126:129]
	ds_read_b128 v[146:149], v144 offset:0
	v_mfma_f32_16x16x32_bf16 v[122:125], v[232:235], v[204:207], v[122:125]
	ds_read_b128 v[152:155], v144 offset:1024
	v_mfma_f32_16x16x32_bf16 v[118:121], v[232:235], v[208:211], v[118:121]
	ds_read_b128 v[156:159], v144 offset:2048
	v_mfma_f32_16x16x32_bf16 v[114:117], v[232:235], v[212:215], v[114:117]
	ds_read_b128 v[162:165], v144 offset:3072
	v_mfma_f32_16x16x32_bf16 v[110:113], v[232:235], v[216:219], v[110:113]
	ds_read_b128 v[166:169], v144 offset:4096
	v_mfma_f32_16x16x32_bf16 v[106:109], v[232:235], v[220:223], v[106:109]
	ds_read_b128 v[170:173], v144 offset:5120
	v_mfma_f32_16x16x32_bf16 v[102:105], v[232:235], v[224:227], v[102:105]
	ds_read_b128 v[176:179], v144 offset:6144
	v_mfma_f32_16x16x32_bf16 v[98:101], v[232:235], v[228:231], v[98:101]
	ds_read_b128 v[180:183], v144 offset:7168
	v_mfma_f32_16x16x32_bf16 v[94:97], v[236:239], v[200:203], v[94:97]
	v_add_u32_e64 v144, s40, v137
	v_mfma_f32_16x16x32_bf16 v[90:93], v[236:239], v[204:207], v[90:93]
	v_mfma_f32_16x16x32_bf16 v[86:89], v[236:239], v[208:211], v[86:89]
	ds_read_b128 v[184:187], v144 offset:16384
	v_mfma_f32_16x16x32_bf16 v[82:85], v[236:239], v[212:215], v[82:85]
	ds_read_b128 v[188:191], v144 offset:17408
	v_mfma_f32_16x16x32_bf16 v[78:81], v[236:239], v[216:219], v[78:81]
	ds_read_b128 v[192:195], v144 offset:18432
	v_mfma_f32_16x16x32_bf16 v[74:77], v[236:239], v[220:223], v[74:77]
	ds_read_b128 v[196:199], v144 offset:19456
	v_mfma_f32_16x16x32_bf16 v[70:73], v[236:239], v[224:227], v[70:73]
	s_add_i32 s42, s46, s41
	s_mov_b32 m0, s42
	v_lshl_add_u64 v[142:143], v[132:133], 0, s[2:3]
	v_mfma_f32_16x16x32_bf16 v[66:69], v[236:239], v[228:231], v[66:69]
;     ...
;   __syncthreads();
;   G2_STAGE(0); G2_STAGE(1);
;   const int fsw = (0x78 >> (((r16 >> 2) & 3) * 2)) & 3;
;   const int aoff = (wm * 128 + r16) * 64 + ((quad ^ fsw) << 4);
;   const int boff = 16384 + (wn * 64 + r16) * 64 + ((quad ^ fsw) << 4);
;   for (int kt = 0; kt < nk; kt++) {
;     if (kt + 1 < nk) asm volatile("s_waitcnt vmcnt(6)" ::: "memory");
;     else asm volatile("s_waitcnt vmcnt(0)" ::: "memory");
;     __builtin_amdgcn_s_barrier();
;     asm volatile("" ::: "memory");
;     if (kt + 2 < nk) G2_STAGE(kt + 2);
;     const char* cS = smem + (kt % 3) * 24576;
;     bf16x8 xa[8], wb[4];
; #pragma unroll
;     for (int f = 0; f < 8; f++) xa[f] = *(const bf16x8*)(cS + aoff + f * 1024);
; #pragma unroll
;     for (int f = 0; f < 4; f++) wb[f] = *(const bf16x8*)(cS + boff + f * 1024);
; #pragma unroll
;     for (int nf = 0; nf < 4; nf++)
; #pragma unroll
;       for (int mf = 0; mf < 8; mf++)
;         acc[nf][mf] = __builtin_amdgcn_mfma_f32_16x16x32_bf16(wb[nf], xa[mf], acc[nf][mf], 0, 0, 0);
	global_load_lds_dwordx4 v[132:133], off
	s_add_i32 m0, m0, 0x1000
	v_mfma_f32_16x16x32_bf16 v[62:65], v[240:243], v[200:203], v[62:65]
	v_mfma_f32_16x16x32_bf16 v[58:61], v[240:243], v[204:207], v[58:61]
	v_mfma_f32_16x16x32_bf16 v[54:57], v[240:243], v[208:211], v[54:57]
	global_load_lds_dwordx4 v[142:143], off
	v_lshl_add_u64 v[142:143], v[142:143], 0, s[2:3]
	s_add_i32 m0, m0, 0x1000
	v_mfma_f32_16x16x32_bf16 v[50:53], v[240:243], v[212:215], v[50:53]
	v_mfma_f32_16x16x32_bf16 v[46:49], v[240:243], v[216:219], v[46:49]
	v_mfma_f32_16x16x32_bf16 v[42:45], v[240:243], v[220:223], v[42:45]
	global_load_lds_dwordx4 v[142:143], off
	v_lshl_add_u64 v[142:143], v[142:143], 0, s[2:3]
	s_add_i32 m0, m0, 0x1000
	v_mfma_f32_16x16x32_bf16 v[38:41], v[240:243], v[224:227], v[38:41]
	v_mfma_f32_16x16x32_bf16 v[34:37], v[240:243], v[228:231], v[34:37]
	s_setprio 0
	s_nop 0
	v_mfma_f32_16x16x32_bf16 v[30:33], v[244:247], v[200:203], v[30:33]
	global_load_lds_dwordx4 v[142:143], off
	s_add_i32 m0, m0, 0x1000
	v_lshl_add_u64 v[142:143], v[134:135], 0, s[2:3]
	v_mfma_f32_16x16x32_bf16 v[26:29], v[244:247], v[204:207], v[26:29]
	v_mfma_f32_16x16x32_bf16 v[22:25], v[244:247], v[208:211], v[22:25]
	v_mfma_f32_16x16x32_bf16 v[18:21], v[244:247], v[212:215], v[18:21]
	global_load_lds_dwordx4 v[134:135], off
	s_add_i32 m0, m0, 0x1000
	v_lshl_add_u64 v[132:133], v[132:133], 0, s[12:13]
	v_mfma_f32_16x16x32_bf16 v[14:17], v[244:247], v[216:219], v[14:17]
	v_mfma_f32_16x16x32_bf16 v[10:13], v[244:247], v[220:223], v[10:13]
	v_mfma_f32_16x16x32_bf16 v[6:9], v[244:247], v[224:227], v[6:9]
	global_load_lds_dwordx4 v[142:143], off
	v_lshl_add_u64 v[134:135], v[134:135], 0, s[4:5]
	v_mfma_f32_16x16x32_bf16 v[2:5], v[244:247], v[228:231], v[2:5]
	s_mov_b32 s41, s40
	s_nop 0
	s_add_i32 s40, s40, 0x6000
	s_cmp_eq_u32 s40, 0x12000
	s_cselect_b32 s40, 0, s40
	s_nop 0
	s_sub_i32 s39, s39, 1
	s_cmp_lg_u32 s39, 0
	s_cbranch_scc1 .Lta11_loop
	.p2align 3
	s_waitcnt vmcnt(6) lgkmcnt(0)
	s_barrier
	s_setprio 1
	v_add_u32_e32 v144, s40, v136
	v_mfma_f32_16x16x32_bf16 v[126:129], v[184:187], v[146:149], v[126:129]
	ds_read_b128 v[200:203], v144 offset:0
	v_mfma_f32_16x16x32_bf16 v[122:125], v[184:187], v[152:155], v[122:125]
	ds_read_b128 v[204:207], v144 offset:1024
	v_mfma_f32_16x16x32_bf16 v[118:121], v[184:187], v[156:159], v[118:121]
	ds_read_b128 v[208:211], v144 offset:2048
	v_mfma_f32_16x16x32_bf16 v[114:117], v[184:187], v[162:165], v[114:117]
	ds_read_b128 v[212:215], v144 offset:3072
	v_mfma_f32_16x16x32_bf16 v[110:113], v[184:187], v[166:169], v[110:113]
	ds_read_b128 v[216:219], v144 offset:4096
	v_mfma_f32_16x16x32_bf16 v[106:109], v[184:187], v[170:173], v[106:109]
	ds_read_b128 v[220:223], v144 offset:5120
	v_mfma_f32_16x16x32_bf16 v[102:105], v[184:187], v[176:179], v[102:105]
	ds_read_b128 v[224:227], v144 offset:6144
	v_mfma_f32_16x16x32_bf16 v[98:101], v[184:187], v[180:183], v[98:101]
	ds_read_b128 v[228:231], v144 offset:7168
	v_mfma_f32_16x16x32_bf16 v[94:97], v[188:191], v[146:149], v[94:97]
	v_add_u32_e64 v144, s40, v137
	v_mfma_f32_16x16x32_bf16 v[90:93], v[188:191], v[152:155], v[90:93]
	v_mfma_f32_16x16x32_bf16 v[86:89], v[188:191], v[156:159], v[86:89]
	ds_read_b128 v[232:235], v144 offset:16384
	v_mfma_f32_16x16x32_bf16 v[82:85], v[188:191], v[162:165], v[82:85]
	ds_read_b128 v[236:239], v144 offset:17408
	v_mfma_f32_16x16x32_bf16 v[78:81], v[188:191], v[166:169], v[78:81]
	ds_read_b128 v[240:243], v144 offset:18432
	v_mfma_f32_16x16x32_bf16 v[74:77], v[188:191], v[170:173], v[74:77]
	ds_read_b128 v[244:247], v144 offset:19456
	v_mfma_f32_16x16x32_bf16 v[70:73], v[188:191], v[176:179], v[70:73]
	s_add_i32 s42, s46, s41
	s_mov_b32 m0, s42
	v_lshl_add_u64 v[142:143], v[132:133], 0, s[2:3]
	v_mfma_f32_16x16x32_bf16 v[66:69], v[188:191], v[180:183], v[66:69]
	global_load_lds_dwordx4 v[132:133], off
	s_add_i32 m0, m0, 0x1000
	v_mfma_f32_16x16x32_bf16 v[62:65], v[192:195], v[146:149], v[62:65]
	v_mfma_f32_16x16x32_bf16 v[58:61], v[192:195], v[152:155], v[58:61]
	v_mfma_f32_16x16x32_bf16 v[54:57], v[192:195], v[156:159], v[54:57]
	global_load_lds_dwordx4 v[142:143], off
	v_lshl_add_u64 v[142:143], v[142:143], 0, s[2:3]
	s_add_i32 m0, m0, 0x1000
	v_mfma_f32_16x16x32_bf16 v[50:53], v[192:195], v[162:165], v[50:53]
	v_mfma_f32_16x16x32_bf16 v[46:49], v[192:195], v[166:169], v[46:49]
	v_mfma_f32_16x16x32_bf16 v[42:45], v[192:195], v[170:173], v[42:45]
	global_load_lds_dwordx4 v[142:143], off
	v_lshl_add_u64 v[142:143], v[142:143], 0, s[2:3]
	s_add_i32 m0, m0, 0x1000
	v_mfma_f32_16x16x32_bf16 v[38:41], v[192:195], v[176:179], v[38:41]
	v_mfma_f32_16x16x32_bf16 v[34:37], v[192:195], v[180:183], v[34:37]
	s_setprio 0
	s_nop 0
	v_mfma_f32_16x16x32_bf16 v[30:33], v[196:199], v[146:149], v[30:33]
	global_load_lds_dwordx4 v[142:143], off
	s_add_i32 m0, m0, 0x1000
	v_lshl_add_u64 v[142:143], v[134:135], 0, s[2:3]
	v_mfma_f32_16x16x32_bf16 v[26:29], v[196:199], v[152:155], v[26:29]
	v_mfma_f32_16x16x32_bf16 v[22:25], v[196:199], v[156:159], v[22:25]
	v_mfma_f32_16x16x32_bf16 v[18:21], v[196:199], v[162:165], v[18:21]
	global_load_lds_dwordx4 v[134:135], off
	s_add_i32 m0, m0, 0x1000
	v_lshl_add_u64 v[132:133], v[132:133], 0, s[12:13]
	v_mfma_f32_16x16x32_bf16 v[14:17], v[196:199], v[166:169], v[14:17]
	v_mfma_f32_16x16x32_bf16 v[10:13], v[196:199], v[170:173], v[10:13]
	v_mfma_f32_16x16x32_bf16 v[6:9], v[196:199], v[176:179], v[6:9]
	global_load_lds_dwordx4 v[142:143], off
	v_lshl_add_u64 v[134:135], v[134:135], 0, s[4:5]
	v_mfma_f32_16x16x32_bf16 v[2:5], v[196:199], v[180:183], v[2:5]
	s_mov_b32 s41, s40
	s_nop 0
	s_add_i32 s40, s40, 0x6000
	s_cmp_eq_u32 s40, 0x12000
	s_cselect_b32 s40, 0, s40
	s_nop 0
	.p2align 3
	s_waitcnt vmcnt(6) lgkmcnt(0)
	s_barrier
;     ...
;   for (int kt = 0; kt < nk; kt++) {
;     if (kt + 1 < nk) asm volatile("s_waitcnt vmcnt(6)" ::: "memory");
;     else asm volatile("s_waitcnt vmcnt(0)" ::: "memory");
;     __builtin_amdgcn_s_barrier();
;     asm volatile("" ::: "memory");
;     if (kt + 2 < nk) G2_STAGE(kt + 2);
;     const char* cS = smem + (kt % 3) * 24576;
;     bf16x8 xa[8], wb[4];
; #pragma unroll
;     for (int f = 0; f < 8; f++) xa[f] = *(const bf16x8*)(cS + aoff + f * 1024);
; #pragma unroll
;     for (int f = 0; f < 4; f++) wb[f] = *(const bf16x8*)(cS + boff + f * 1024);
; #pragma unroll
;     for (int nf = 0; nf < 4; nf++)
; #pragma unroll
;       for (int mf = 0; mf < 8; mf++)
;         acc[nf][mf] = __builtin_amdgcn_mfma_f32_16x16x32_bf16(wb[nf], xa[mf], acc[nf][mf], 0, 0, 0);
	s_setprio 1
	v_add_u32_e32 v144, s40, v136
	v_mfma_f32_16x16x32_bf16 v[126:129], v[232:235], v[200:203], v[126:129]
	ds_read_b128 v[146:149], v144 offset:0
	v_mfma_f32_16x16x32_bf16 v[122:125], v[232:235], v[204:207], v[122:125]
	ds_read_b128 v[152:155], v144 offset:1024
	v_mfma_f32_16x16x32_bf16 v[118:121], v[232:235], v[208:211], v[118:121]
	ds_read_b128 v[156:159], v144 offset:2048
	v_mfma_f32_16x16x32_bf16 v[114:117], v[232:235], v[212:215], v[114:117]
	ds_read_b128 v[162:165], v144 offset:3072
	v_mfma_f32_16x16x32_bf16 v[110:113], v[232:235], v[216:219], v[110:113]
	ds_read_b128 v[166:169], v144 offset:4096
	v_mfma_f32_16x16x32_bf16 v[106:109], v[232:235], v[220:223], v[106:109]
	ds_read_b128 v[170:173], v144 offset:5120
	v_mfma_f32_16x16x32_bf16 v[102:105], v[232:235], v[224:227], v[102:105]
	ds_read_b128 v[176:179], v144 offset:6144
	v_mfma_f32_16x16x32_bf16 v[98:101], v[232:235], v[228:231], v[98:101]
	ds_read_b128 v[180:183], v144 offset:7168
	v_mfma_f32_16x16x32_bf16 v[94:97], v[236:239], v[200:203], v[94:97]
	v_add_u32_e64 v144, s40, v137
	v_mfma_f32_16x16x32_bf16 v[90:93], v[236:239], v[204:207], v[90:93]
	v_mfma_f32_16x16x32_bf16 v[86:89], v[236:239], v[208:211], v[86:89]
	ds_read_b128 v[184:187], v144 offset:16384
	v_mfma_f32_16x16x32_bf16 v[82:85], v[236:239], v[212:215], v[82:85]
	ds_read_b128 v[188:191], v144 offset:17408
	v_mfma_f32_16x16x32_bf16 v[78:81], v[236:239], v[216:219], v[78:81]
	ds_read_b128 v[192:195], v144 offset:18432
	v_mfma_f32_16x16x32_bf16 v[74:77], v[236:239], v[220:223], v[74:77]
	ds_read_b128 v[196:199], v144 offset:19456
	v_mfma_f32_16x16x32_bf16 v[70:73], v[236:239], v[224:227], v[70:73]
	v_mfma_f32_16x16x32_bf16 v[66:69], v[236:239], v[228:231], v[66:69]
	v_mfma_f32_16x16x32_bf16 v[62:65], v[240:243], v[200:203], v[62:65]
	v_mfma_f32_16x16x32_bf16 v[58:61], v[240:243], v[204:207], v[58:61]
	v_mfma_f32_16x16x32_bf16 v[54:57], v[240:243], v[208:211], v[54:57]
	v_mfma_f32_16x16x32_bf16 v[50:53], v[240:243], v[212:215], v[50:53]
	v_mfma_f32_16x16x32_bf16 v[46:49], v[240:243], v[216:219], v[46:49]
	v_mfma_f32_16x16x32_bf16 v[42:45], v[240:243], v[220:223], v[42:45]
	v_mfma_f32_16x16x32_bf16 v[38:41], v[240:243], v[224:227], v[38:41]
	v_mfma_f32_16x16x32_bf16 v[34:37], v[240:243], v[228:231], v[34:37]
	s_setprio 0
	s_nop 0
	v_mfma_f32_16x16x32_bf16 v[30:33], v[244:247], v[200:203], v[30:33]
	v_mfma_f32_16x16x32_bf16 v[26:29], v[244:247], v[204:207], v[26:29]
	v_mfma_f32_16x16x32_bf16 v[22:25], v[244:247], v[208:211], v[22:25]
	v_mfma_f32_16x16x32_bf16 v[18:21], v[244:247], v[212:215], v[18:21]
	v_mfma_f32_16x16x32_bf16 v[14:17], v[244:247], v[216:219], v[14:17]
	v_mfma_f32_16x16x32_bf16 v[10:13], v[244:247], v[220:223], v[10:13]
	v_mfma_f32_16x16x32_bf16 v[6:9], v[244:247], v[224:227], v[6:9]
	v_mfma_f32_16x16x32_bf16 v[2:5], v[244:247], v[228:231], v[2:5]
	s_mov_b32 s41, s40
	s_nop 0
	s_add_i32 s40, s40, 0x6000
	s_cmp_eq_u32 s40, 0x12000
	s_cselect_b32 s40, 0, s40
	s_nop 0
	.p2align 3
	s_waitcnt vmcnt(0) lgkmcnt(0)
	s_barrier
	s_setprio 1
	v_add_u32_e32 v144, s40, v136
	v_mfma_f32_16x16x32_bf16 v[126:129], v[184:187], v[146:149], v[126:129]
	ds_read_b128 v[200:203], v144 offset:0
	v_mfma_f32_16x16x32_bf16 v[122:125], v[184:187], v[152:155], v[122:125]
	ds_read_b128 v[204:207], v144 offset:1024
	v_mfma_f32_16x16x32_bf16 v[118:121], v[184:187], v[156:159], v[118:121]
	ds_read_b128 v[208:211], v144 offset:2048
	v_mfma_f32_16x16x32_bf16 v[114:117], v[184:187], v[162:165], v[114:117]
	ds_read_b128 v[212:215], v144 offset:3072
	v_mfma_f32_16x16x32_bf16 v[110:113], v[184:187], v[166:169], v[110:113]
	ds_read_b128 v[216:219], v144 offset:4096
	v_mfma_f32_16x16x32_bf16 v[106:109], v[184:187], v[170:173], v[106:109]
	ds_read_b128 v[220:223], v144 offset:5120
	v_mfma_f32_16x16x32_bf16 v[102:105], v[184:187], v[176:179], v[102:105]
	ds_read_b128 v[224:227], v144 offset:6144
	v_mfma_f32_16x16x32_bf16 v[98:101], v[184:187], v[180:183], v[98:101]
	ds_read_b128 v[228:231], v144 offset:7168
	v_mfma_f32_16x16x32_bf16 v[94:97], v[188:191], v[146:149], v[94:97]
	v_add_u32_e64 v144, s40, v137
	v_mfma_f32_16x16x32_bf16 v[90:93], v[188:191], v[152:155], v[90:93]
	v_mfma_f32_16x16x32_bf16 v[86:89], v[188:191], v[156:159], v[86:89]
	ds_read_b128 v[232:235], v144 offset:16384
	v_mfma_f32_16x16x32_bf16 v[82:85], v[188:191], v[162:165], v[82:85]
	ds_read_b128 v[236:239], v144 offset:17408
	v_mfma_f32_16x16x32_bf16 v[78:81], v[188:191], v[166:169], v[78:81]
	ds_read_b128 v[240:243], v144 offset:18432
	v_mfma_f32_16x16x32_bf16 v[74:77], v[188:191], v[170:173], v[74:77]
	ds_read_b128 v[244:247], v144 offset:19456
	v_mfma_f32_16x16x32_bf16 v[70:73], v[188:191], v[176:179], v[70:73]
	v_mfma_f32_16x16x32_bf16 v[66:69], v[188:191], v[180:183], v[66:69]
	v_mfma_f32_16x16x32_bf16 v[62:65], v[192:195], v[146:149], v[62:65]
	v_mfma_f32_16x16x32_bf16 v[58:61], v[192:195], v[152:155], v[58:61]
	v_mfma_f32_16x16x32_bf16 v[54:57], v[192:195], v[156:159], v[54:57]
	v_mfma_f32_16x16x32_bf16 v[50:53], v[192:195], v[162:165], v[50:53]
	v_mfma_f32_16x16x32_bf16 v[46:49], v[192:195], v[166:169], v[46:49]
	v_mfma_f32_16x16x32_bf16 v[42:45], v[192:195], v[170:173], v[42:45]
	v_mfma_f32_16x16x32_bf16 v[38:41], v[192:195], v[176:179], v[38:41]
	v_mfma_f32_16x16x32_bf16 v[34:37], v[192:195], v[180:183], v[34:37]
	s_setprio 0
	s_nop 0
	v_mfma_f32_16x16x32_bf16 v[30:33], v[196:199], v[146:149], v[30:33]
	v_mfma_f32_16x16x32_bf16 v[26:29], v[196:199], v[152:155], v[26:29]
	v_mfma_f32_16x16x32_bf16 v[22:25], v[196:199], v[156:159], v[22:25]
	v_mfma_f32_16x16x32_bf16 v[18:21], v[196:199], v[162:165], v[18:21]
	v_mfma_f32_16x16x32_bf16 v[14:17], v[196:199], v[166:169], v[14:17]
	v_mfma_f32_16x16x32_bf16 v[10:13], v[196:199], v[170:173], v[10:13]
	v_mfma_f32_16x16x32_bf16 v[6:9], v[196:199], v[176:179], v[6:9]
	v_mfma_f32_16x16x32_bf16 v[2:5], v[196:199], v[180:183], v[2:5]
	s_mov_b32 s41, s40
	s_nop 0
	s_add_i32 s40, s40, 0x6000
	s_cmp_eq_u32 s40, 0x12000
	s_cselect_b32 s40, 0, s40
	s_nop 0
	s_mov_b32 s4, 0x8000
	s_mov_b32 s5, 0
	s_mov_b32 s10, 0x10000
	s_mov_b32 s11, 0
	s_mov_b32 s44, 0x3fd744fd
	.p2align 3
	s_waitcnt lgkmcnt(0)
; DEVI unsigned pack2(float a, float b) { return __builtin_bit_cast(unsigned, __builtin_convertvector((f32x2_t){a, b}, bf16x2_t)); }
; DEVI float blo(unsigned u) { return __uint_as_float(u << 16); }
; DEVI float bhi(unsigned u) { return __uint_as_float(u & 0xffff0000u); }
; DEVI float siluf_(float x) { return x * __builtin_amdgcn_rcpf(1.f + __expf(-x)); }
;     ...
;     for (int nf = 0; nf < 4; nf++)
; #pragma unroll
;       for (int mf = 0; mf < 8; mf++)
;         acc[nf][mf] = __builtin_amdgcn_mfma_f32_16x16x32_bf16(wb[nf], xa[mf], acc[nf][mf], 0, 0, 0);
;   }
;     ...
; #pragma unroll
;   for (int mf = 0; mf < 8; mf++) {
;     const int row = m0 + wm * 128 + mf * 16 + r16;
;     if (EPI == EPI_SWIGLU) {
; #pragma unroll
;       for (int nf = 0; nf < 2; nf++) {
;         const int hcol = (n0 >> 1) + wn * 32 + nf * 16 + quad * 4;
;         f32x4 g = acc[nf][mf], u = acc[nf + 2][mf];
;         u32x2 pk;
;         pk[0] = pack2(siluf_(g[0]) * u[0], siluf_(g[1]) * u[1]);
;         pk[1] = pack2(siluf_(g[2]) * u[2], siluf_(g[3]) * u[3]);
;         *(u32x2*)(outb + (size_t)row * DFF + hcol) = pk;
;       }
;     } else {
; #pragma unroll
;       for (int nf = 0; nf < 4; nf++) {
;         const int col = n0 + wn * 64 + nf * 16 + quad * 4;
;         f32x4 a = acc[nf][mf];
;         if (EPI == EPI_RESID || EPI == EPI_RESID_ATOMIC) {
;           f32x4 x = a;
;           if (EPI == EPI_RESID || kpart == 0) {
;             const u32x2 xr = *(const u32x2*)((const u16*)(p.ws + WS_XB) + (size_t)row * 1024 + col);
;             x[0] += ALPHA * blo(xr[0]); x[1] += ALPHA * bhi(xr[0]); x[2] += ALPHA * blo(xr[1]); x[3] += ALPHA * bhi(xr[1]);
;           }
;           if (EPI == EPI_RESID) *(f32x4*)((float*)(p.ws + WS_XF) + (size_t)row * 1024 + col) = x;
;           else *(f32x4*)((float*)(p.ws + WS_SLAB) + ((size_t)kpart * 512 + (row - T_P)) * 1024 + col) = x;
	s_nop 0
	v_mfma_f32_16x16x32_bf16 v[126:129], v[232:235], v[200:203], v[126:129]
	v_mfma_f32_16x16x32_bf16 v[122:125], v[232:235], v[204:207], v[122:125]
	v_mfma_f32_16x16x32_bf16 v[118:121], v[232:235], v[208:211], v[118:121]
	v_mfma_f32_16x16x32_bf16 v[114:117], v[232:235], v[212:215], v[114:117]
	v_mfma_f32_16x16x32_bf16 v[110:113], v[232:235], v[216:219], v[110:113]
	v_mfma_f32_16x16x32_bf16 v[106:109], v[232:235], v[220:223], v[106:109]
	v_mfma_f32_16x16x32_bf16 v[102:105], v[232:235], v[224:227], v[102:105]
	v_mfma_f32_16x16x32_bf16 v[98:101], v[232:235], v[228:231], v[98:101]
	v_mfma_f32_16x16x32_bf16 v[94:97], v[236:239], v[200:203], v[94:97]
	v_mfma_f32_16x16x32_bf16 v[90:93], v[236:239], v[204:207], v[90:93]
	v_mfma_f32_16x16x32_bf16 v[86:89], v[236:239], v[208:211], v[86:89]
	v_mfma_f32_16x16x32_bf16 v[82:85], v[236:239], v[212:215], v[82:85]
	v_mfma_f32_16x16x32_bf16 v[78:81], v[236:239], v[216:219], v[78:81]
	v_mfma_f32_16x16x32_bf16 v[74:77], v[236:239], v[220:223], v[74:77]
	v_mfma_f32_16x16x32_bf16 v[70:73], v[236:239], v[224:227], v[70:73]
	v_mfma_f32_16x16x32_bf16 v[66:69], v[236:239], v[228:231], v[66:69]
	v_mfma_f32_16x16x32_bf16 v[62:65], v[240:243], v[200:203], v[62:65]
	v_mfma_f32_16x16x32_bf16 v[58:61], v[240:243], v[204:207], v[58:61]
	v_mfma_f32_16x16x32_bf16 v[54:57], v[240:243], v[208:211], v[54:57]
	v_mfma_f32_16x16x32_bf16 v[50:53], v[240:243], v[212:215], v[50:53]
	v_mfma_f32_16x16x32_bf16 v[46:49], v[240:243], v[216:219], v[46:49]
	v_mfma_f32_16x16x32_bf16 v[42:45], v[240:243], v[220:223], v[42:45]
	v_mfma_f32_16x16x32_bf16 v[38:41], v[240:243], v[224:227], v[38:41]
	v_mfma_f32_16x16x32_bf16 v[34:37], v[240:243], v[228:231], v[34:37]
	v_mfma_f32_16x16x32_bf16 v[30:33], v[244:247], v[200:203], v[30:33]
	v_mfma_f32_16x16x32_bf16 v[26:29], v[244:247], v[204:207], v[26:29]
	v_mfma_f32_16x16x32_bf16 v[22:25], v[244:247], v[208:211], v[22:25]
	v_mfma_f32_16x16x32_bf16 v[18:21], v[244:247], v[212:215], v[18:21]
	v_mfma_f32_16x16x32_bf16 v[14:17], v[244:247], v[216:219], v[14:17]
	v_mfma_f32_16x16x32_bf16 v[10:13], v[244:247], v[220:223], v[10:13]
	v_mfma_f32_16x16x32_bf16 v[6:9], v[244:247], v[224:227], v[6:9]
	v_mfma_f32_16x16x32_bf16 v[2:5], v[244:247], v[228:231], v[2:5]
	s_mov_b32 m0, s43
	s_cmp_eq_u32 s47, 0
	s_cbranch_scc1 .Lta11_first
	s_nop 7
	global_store_dwordx4 v[140:141], v[126:129], off offset:0
	global_store_dwordx4 v[140:141], v[94:97], off offset:64
	global_store_dwordx4 v[140:141], v[62:65], off offset:128
	global_store_dwordx4 v[140:141], v[30:33], off offset:192
	v_lshl_add_u64 v[140:141], v[140:141], 0, s[10:11]
	global_store_dwordx4 v[140:141], v[122:125], off offset:0
	global_store_dwordx4 v[140:141], v[90:93], off offset:64
	global_store_dwordx4 v[140:141], v[58:61], off offset:128
	global_store_dwordx4 v[140:141], v[26:29], off offset:192
	v_lshl_add_u64 v[140:141], v[140:141], 0, s[10:11]
	global_store_dwordx4 v[140:141], v[118:121], off offset:0
	global_store_dwordx4 v[140:141], v[86:89], off offset:64
	global_store_dwordx4 v[140:141], v[54:57], off offset:128
	global_store_dwordx4 v[140:141], v[22:25], off offset:192
	v_lshl_add_u64 v[140:141], v[140:141], 0, s[10:11]
	global_store_dwordx4 v[140:141], v[114:117], off offset:0
	global_store_dwordx4 v[140:141], v[82:85], off offset:64
	global_store_dwordx4 v[140:141], v[50:53], off offset:128
	global_store_dwordx4 v[140:141], v[18:21], off offset:192
	v_lshl_add_u64 v[140:141], v[140:141], 0, s[10:11]
	global_store_dwordx4 v[140:141], v[110:113], off offset:0
	global_store_dwordx4 v[140:141], v[78:81], off offset:64
	global_store_dwordx4 v[140:141], v[46:49], off offset:128
	global_store_dwordx4 v[140:141], v[14:17], off offset:192
	v_lshl_add_u64 v[140:141], v[140:141], 0, s[10:11]
	global_store_dwordx4 v[140:141], v[106:109], off offset:0
	global_store_dwordx4 v[140:141], v[74:77], off offset:64
	global_store_dwordx4 v[140:141], v[42:45], off offset:128
	global_store_dwordx4 v[140:141], v[10:13], off offset:192
	v_lshl_add_u64 v[140:141], v[140:141], 0, s[10:11]
	global_store_dwordx4 v[140:141], v[102:105], off offset:0
	global_store_dwordx4 v[140:141], v[70:73], off offset:64
	global_store_dwordx4 v[140:141], v[38:41], off offset:128
	global_store_dwordx4 v[140:141], v[6:9], off offset:192
	v_lshl_add_u64 v[140:141], v[140:141], 0, s[10:11]
	global_store_dwordx4 v[140:141], v[98:101], off offset:0
	global_store_dwordx4 v[140:141], v[66:69], off offset:64
	global_store_dwordx4 v[140:141], v[34:37], off offset:128
	global_store_dwordx4 v[140:141], v[2:5], off offset:192
	v_readlane_b32 s39, v250, 7
	s_cmpk_lg_u32 s39, 0x200
	s_cbranch_scc1 .Lta11_ar1
	s_mov_b32 s39, 1
	v_writelane_b32 v255, s39, 41
	v_readlane_b32 s40, v250, 0
	s_lshr_b32 s41, s40, 3
	s_and_b32 s40, s40, 7
	s_lshl_b32 s40, s40, 6
	s_add_i32 s40, s40, s41
	s_sub_i32 s38, s40, 0x200

;     ...
;   __syncthreads();
;   G2_STAGE(0); G2_STAGE(1);
;   const int fsw = (0x78 >> (((r16 >> 2) & 3) * 2)) & 3;
;   const int aoff = (wm * 128 + r16) * 64 + ((quad ^ fsw) << 4);
;   const int boff = 16384 + (wn * 64 + r16) * 64 + ((quad ^ fsw) << 4);
;   for (int kt = 0; kt < nk; kt++) {
;     if (kt + 1 < nk) asm volatile("s_waitcnt vmcnt(6)" ::: "memory");
;     else asm volatile("s_waitcnt vmcnt(0)" ::: "memory");
;     __builtin_amdgcn_s_barrier();
;     asm volatile("" ::: "memory");
;     if (kt + 2 < nk) G2_STAGE(kt + 2);
;     const char* cS = smem + (kt % 3) * 24576;
;     bf16x8 xa[8], wb[4];
; #pragma unroll
;     for (int f = 0; f < 8; f++) xa[f] = *(const bf16x8*)(cS + aoff + f * 1024);
; #pragma unroll
;     for (int f = 0; f < 4; f++) wb[f] = *(const bf16x8*)(cS + boff + f * 1024);
; #pragma unroll
;     for (int nf = 0; nf < 4; nf++)
; #pragma unroll
;       for (int mf = 0; mf < 8; mf++)
;         acc[nf][mf] = __builtin_amdgcn_mfma_f32_16x16x32_bf16(wb[nf], xa[mf], acc[nf][mf], 0, 0, 0);
.Lt11_loop:
	.p2align 3
	s_waitcnt vmcnt(6) lgkmcnt(0)
	s_barrier
	s_setprio 1
	v_add_u32_e32 v144, s40, v136
	v_mfma_f32_16x16x32_bf16 v[126:129], v[184:187], v[146:149], v[126:129]
	ds_read_b128 v[200:203], v144 offset:0
	v_mfma_f32_16x16x32_bf16 v[122:125], v[184:187], v[152:155], v[122:125]
	ds_read_b128 v[204:207], v144 offset:1024
	v_mfma_f32_16x16x32_bf16 v[118:121], v[184:187], v[156:159], v[118:121]
	ds_read_b128 v[208:211], v144 offset:2048
	v_mfma_f32_16x16x32_bf16 v[114:117], v[184:187], v[162:165], v[114:117]
	ds_read_b128 v[212:215], v144 offset:3072
	v_mfma_f32_16x16x32_bf16 v[110:113], v[184:187], v[166:169], v[110:113]
	ds_read_b128 v[216:219], v144 offset:4096
	v_mfma_f32_16x16x32_bf16 v[106:109], v[184:187], v[170:173], v[106:109]
	ds_read_b128 v[220:223], v144 offset:5120
	v_mfma_f32_16x16x32_bf16 v[102:105], v[184:187], v[176:179], v[102:105]
	ds_read_b128 v[224:227], v144 offset:6144
	v_mfma_f32_16x16x32_bf16 v[98:101], v[184:187], v[180:183], v[98:101]
	ds_read_b128 v[228:231], v144 offset:7168
	v_mfma_f32_16x16x32_bf16 v[94:97], v[188:191], v[146:149], v[94:97]
	v_add_u32_e64 v144, s40, v137
	v_mfma_f32_16x16x32_bf16 v[90:93], v[188:191], v[152:155], v[90:93]
	v_mfma_f32_16x16x32_bf16 v[86:89], v[188:191], v[156:159], v[86:89]
	ds_read_b128 v[232:235], v144 offset:16384
	v_mfma_f32_16x16x32_bf16 v[82:85], v[188:191], v[162:165], v[82:85]
	ds_read_b128 v[236:239], v144 offset:17408
	v_mfma_f32_16x16x32_bf16 v[78:81], v[188:191], v[166:169], v[78:81]
	ds_read_b128 v[240:243], v144 offset:18432
	v_mfma_f32_16x16x32_bf16 v[74:77], v[188:191], v[170:173], v[74:77]
	ds_read_b128 v[244:247], v144 offset:19456
	v_mfma_f32_16x16x32_bf16 v[70:73], v[188:191], v[176:179], v[70:73]
	s_add_i32 s42, s46, s41
	s_mov_b32 m0, s42
	v_lshl_add_u64 v[142:143], v[132:133], 0, s[2:3]
	v_mfma_f32_16x16x32_bf16 v[66:69], v[188:191], v[180:183], v[66:69]
	global_load_lds_dwordx4 v[132:133], off
	s_add_i32 m0, m0, 0x1000
	v_mfma_f32_16x16x32_bf16 v[62:65], v[192:195], v[146:149], v[62:65]
	v_mfma_f32_16x16x32_bf16 v[58:61], v[192:195], v[152:155], v[58:61]
	v_mfma_f32_16x16x32_bf16 v[54:57], v[192:195], v[156:159], v[54:57]
	global_load_lds_dwordx4 v[142:143], off
	v_lshl_add_u64 v[142:143], v[142:143], 0, s[2:3]
	s_add_i32 m0, m0, 0x1000
	v_mfma_f32_16x16x32_bf16 v[50:53], v[192:195], v[162:165], v[50:53]
	v_mfma_f32_16x16x32_bf16 v[46:49], v[192:195], v[166:169], v[46:49]
	v_mfma_f32_16x16x32_bf16 v[42:45], v[192:195], v[170:173], v[42:45]
	global_load_lds_dwordx4 v[142:143], off
	v_lshl_add_u64 v[142:143], v[142:143], 0, s[2:3]
	s_add_i32 m0, m0, 0x1000
	v_mfma_f32_16x16x32_bf16 v[38:41], v[192:195], v[176:179], v[38:41]
	v_mfma_f32_16x16x32_bf16 v[34:37], v[192:195], v[180:183], v[34:37]
	s_setprio 0
	s_nop 0
	v_mfma_f32_16x16x32_bf16 v[30:33], v[196:199], v[146:149], v[30:33]
	global_load_lds_dwordx4 v[142:143], off
	s_add_i32 m0, m0, 0x1000
	v_lshl_add_u64 v[142:143], v[134:135], 0, s[2:3]
	v_mfma_f32_16x16x32_bf16 v[26:29], v[196:199], v[152:155], v[26:29]
	v_mfma_f32_16x16x32_bf16 v[22:25], v[196:199], v[156:159], v[22:25]
	v_mfma_f32_16x16x32_bf16 v[18:21], v[196:199], v[162:165], v[18:21]
	global_load_lds_dwordx4 v[134:135], off
	s_add_i32 m0, m0, 0x1000
	v_lshl_add_u64 v[132:133], v[132:133], 0, s[12:13]
	v_mfma_f32_16x16x32_bf16 v[14:17], v[196:199], v[166:169], v[14:17]
	v_mfma_f32_16x16x32_bf16 v[10:13], v[196:199], v[170:173], v[10:13]
	v_mfma_f32_16x16x32_bf16 v[6:9], v[196:199], v[176:179], v[6:9]
	global_load_lds_dwordx4 v[142:143], off
	v_lshl_add_u64 v[134:135], v[134:135], 0, s[4:5]
	v_mfma_f32_16x16x32_bf16 v[2:5], v[196:199], v[180:183], v[2:5]
	s_mov_b32 s41, s40
	s_nop 0
	s_add_i32 s40, s40, 0x6000
	s_cmp_eq_u32 s40, 0x12000
	s_cselect_b32 s40, 0, s40
	s_nop 0
	.p2align 3
	s_waitcnt vmcnt(6) lgkmcnt(0)
	s_barrier
	s_setprio 1
	v_add_u32_e32 v144, s40, v136
	v_mfma_f32_16x16x32_bf16 v[126:129], v[232:235], v[200:203], v[126:129]
	ds_read_b128 v[146:149], v144 offset:0
	v_mfma_f32_16x16x32_bf16 v[122:125], v[232:235], v[204:207], v[122:125]
	ds_read_b128 v[152:155], v144 offset:1024
	v_mfma_f32_16x16x32_bf16 v[118:121], v[232:235], v[208:211], v[118:121]
	ds_read_b128 v[156:159], v144 offset:2048
	v_mfma_f32_16x16x32_bf16 v[114:117], v[232:235], v[212:215], v[114:117]
	ds_read_b128 v[162:165], v144 offset:3072
	v_mfma_f32_16x16x32_bf16 v[110:113], v[232:235], v[216:219], v[110:113]
	ds_read_b128 v[166:169], v144 offset:4096
	v_mfma_f32_16x16x32_bf16 v[106:109], v[232:235], v[220:223], v[106:109]
	ds_read_b128 v[170:173], v144 offset:5120
	v_mfma_f32_16x16x32_bf16 v[102:105], v[232:235], v[224:227], v[102:105]
	ds_read_b128 v[176:179], v144 offset:6144
	v_mfma_f32_16x16x32_bf16 v[98:101], v[232:235], v[228:231], v[98:101]
	ds_read_b128 v[180:183], v144 offset:7168
	v_mfma_f32_16x16x32_bf16 v[94:97], v[236:239], v[200:203], v[94:97]
	v_add_u32_e64 v144, s40, v137
	v_mfma_f32_16x16x32_bf16 v[90:93], v[236:239], v[204:207], v[90:93]
	v_mfma_f32_16x16x32_bf16 v[86:89], v[236:239], v[208:211], v[86:89]
	ds_read_b128 v[184:187], v144 offset:16384
	v_mfma_f32_16x16x32_bf16 v[82:85], v[236:239], v[212:215], v[82:85]
	ds_read_b128 v[188:191], v144 offset:17408
	v_mfma_f32_16x16x32_bf16 v[78:81], v[236:239], v[216:219], v[78:81]
	ds_read_b128 v[192:195], v144 offset:18432
	v_mfma_f32_16x16x32_bf16 v[74:77], v[236:239], v[220:223], v[74:77]
	ds_read_b128 v[196:199], v144 offset:19456
	v_mfma_f32_16x16x32_bf16 v[70:73], v[236:239], v[224:227], v[70:73]
	s_add_i32 s42, s46, s41
	s_mov_b32 m0, s42
	v_lshl_add_u64 v[142:143], v[132:133], 0, s[2:3]
	v_mfma_f32_16x16x32_bf16 v[66:69], v[236:239], v[228:231], v[66:69]
;     ...
;   for (int kt = 0; kt < nk; kt++) {
;     if (kt + 1 < nk) asm volatile("s_waitcnt vmcnt(6)" ::: "memory");
;     else asm volatile("s_waitcnt vmcnt(0)" ::: "memory");
;     __builtin_amdgcn_s_barrier();
;     asm volatile("" ::: "memory");
;     if (kt + 2 < nk) G2_STAGE(kt + 2);
;     const char* cS = smem + (kt % 3) * 24576;
;     bf16x8 xa[8], wb[4];
; #pragma unroll
;     for (int f = 0; f < 8; f++) xa[f] = *(const bf16x8*)(cS + aoff + f * 1024);
; #pragma unroll
;     for (int f = 0; f < 4; f++) wb[f] = *(const bf16x8*)(cS + boff + f * 1024);
; #pragma unroll
;     for (int nf = 0; nf < 4; nf++)
; #pragma unroll
;       for (int mf = 0; mf < 8; mf++)
;         acc[nf][mf] = __builtin_amdgcn_mfma_f32_16x16x32_bf16(wb[nf], xa[mf], acc[nf][mf], 0, 0, 0);
;   }
	global_load_lds_dwordx4 v[132:133], off
	s_add_i32 m0, m0, 0x1000
	v_mfma_f32_16x16x32_bf16 v[62:65], v[240:243], v[200:203], v[62:65]
	v_mfma_f32_16x16x32_bf16 v[58:61], v[240:243], v[204:207], v[58:61]
	v_mfma_f32_16x16x32_bf16 v[54:57], v[240:243], v[208:211], v[54:57]
	global_load_lds_dwordx4 v[142:143], off
	v_lshl_add_u64 v[142:143], v[142:143], 0, s[2:3]
	s_add_i32 m0, m0, 0x1000
	v_mfma_f32_16x16x32_bf16 v[50:53], v[240:243], v[212:215], v[50:53]
	v_mfma_f32_16x16x32_bf16 v[46:49], v[240:243], v[216:219], v[46:49]
	v_mfma_f32_16x16x32_bf16 v[42:45], v[240:243], v[220:223], v[42:45]
	global_load_lds_dwordx4 v[142:143], off
	v_lshl_add_u64 v[142:143], v[142:143], 0, s[2:3]
	s_add_i32 m0, m0, 0x1000
	v_mfma_f32_16x16x32_bf16 v[38:41], v[240:243], v[224:227], v[38:41]
	v_mfma_f32_16x16x32_bf16 v[34:37], v[240:243], v[228:231], v[34:37]
	s_setprio 0
	s_nop 0
	v_mfma_f32_16x16x32_bf16 v[30:33], v[244:247], v[200:203], v[30:33]
	global_load_lds_dwordx4 v[142:143], off
	s_add_i32 m0, m0, 0x1000
	v_lshl_add_u64 v[142:143], v[134:135], 0, s[2:3]
	v_mfma_f32_16x16x32_bf16 v[26:29], v[244:247], v[204:207], v[26:29]
	v_mfma_f32_16x16x32_bf16 v[22:25], v[244:247], v[208:211], v[22:25]
	v_mfma_f32_16x16x32_bf16 v[18:21], v[244:247], v[212:215], v[18:21]
	global_load_lds_dwordx4 v[134:135], off
	s_add_i32 m0, m0, 0x1000
	v_lshl_add_u64 v[132:133], v[132:133], 0, s[12:13]
	v_mfma_f32_16x16x32_bf16 v[14:17], v[244:247], v[216:219], v[14:17]
	v_mfma_f32_16x16x32_bf16 v[10:13], v[244:247], v[220:223], v[10:13]
	v_mfma_f32_16x16x32_bf16 v[6:9], v[244:247], v[224:227], v[6:9]
	global_load_lds_dwordx4 v[142:143], off
	v_lshl_add_u64 v[134:135], v[134:135], 0, s[4:5]
	v_mfma_f32_16x16x32_bf16 v[2:5], v[244:247], v[228:231], v[2:5]
	s_mov_b32 s41, s40
	s_nop 0
	s_add_i32 s40, s40, 0x6000
	s_cmp_eq_u32 s40, 0x12000
	s_cselect_b32 s40, 0, s40
	s_nop 0
	s_sub_i32 s39, s39, 1
	s_cmp_lg_u32 s39, 0
	s_cbranch_scc1 .Lt11_loop
	.p2align 3
	s_waitcnt vmcnt(6) lgkmcnt(0)
	s_barrier
	s_setprio 1
	v_add_u32_e32 v144, s40, v136
	v_mfma_f32_16x16x32_bf16 v[126:129], v[184:187], v[146:149], v[126:129]
	ds_read_b128 v[200:203], v144 offset:0
	v_mfma_f32_16x16x32_bf16 v[122:125], v[184:187], v[152:155], v[122:125]
	ds_read_b128 v[204:207], v144 offset:1024
	v_mfma_f32_16x16x32_bf16 v[118:121], v[184:187], v[156:159], v[118:121]
	ds_read_b128 v[208:211], v144 offset:2048
	v_mfma_f32_16x16x32_bf16 v[114:117], v[184:187], v[162:165], v[114:117]
	ds_read_b128 v[212:215], v144 offset:3072
	v_mfma_f32_16x16x32_bf16 v[110:113], v[184:187], v[166:169], v[110:113]
	ds_read_b128 v[216:219], v144 offset:4096
	v_mfma_f32_16x16x32_bf16 v[106:109], v[184:187], v[170:173], v[106:109]
	ds_read_b128 v[220:223], v144 offset:5120
	v_mfma_f32_16x16x32_bf16 v[102:105], v[184:187], v[176:179], v[102:105]
	ds_read_b128 v[224:227], v144 offset:6144
	v_mfma_f32_16x16x32_bf16 v[98:101], v[184:187], v[180:183], v[98:101]
	ds_read_b128 v[228:231], v144 offset:7168
	v_mfma_f32_16x16x32_bf16 v[94:97], v[188:191], v[146:149], v[94:97]
	v_add_u32_e64 v144, s40, v137
	v_mfma_f32_16x16x32_bf16 v[90:93], v[188:191], v[152:155], v[90:93]
	v_mfma_f32_16x16x32_bf16 v[86:89], v[188:191], v[156:159], v[86:89]
	ds_read_b128 v[232:235], v144 offset:16384
	v_mfma_f32_16x16x32_bf16 v[82:85], v[188:191], v[162:165], v[82:85]
	ds_read_b128 v[236:239], v144 offset:17408
	v_mfma_f32_16x16x32_bf16 v[78:81], v[188:191], v[166:169], v[78:81]
	ds_read_b128 v[240:243], v144 offset:18432
	v_mfma_f32_16x16x32_bf16 v[74:77], v[188:191], v[170:173], v[74:77]
	ds_read_b128 v[244:247], v144 offset:19456
	v_mfma_f32_16x16x32_bf16 v[70:73], v[188:191], v[176:179], v[70:73]
	s_add_i32 s42, s46, s41
	s_mov_b32 m0, s42
	v_lshl_add_u64 v[142:143], v[132:133], 0, s[2:3]
	v_mfma_f32_16x16x32_bf16 v[66:69], v[188:191], v[180:183], v[66:69]
	global_load_lds_dwordx4 v[132:133], off
	s_add_i32 m0, m0, 0x1000
	v_mfma_f32_16x16x32_bf16 v[62:65], v[192:195], v[146:149], v[62:65]
	v_mfma_f32_16x16x32_bf16 v[58:61], v[192:195], v[152:155], v[58:61]
	v_mfma_f32_16x16x32_bf16 v[54:57], v[192:195], v[156:159], v[54:57]
	global_load_lds_dwordx4 v[142:143], off
	v_lshl_add_u64 v[142:143], v[142:143], 0, s[2:3]
	s_add_i32 m0, m0, 0x1000
	v_mfma_f32_16x16x32_bf16 v[50:53], v[192:195], v[162:165], v[50:53]
	v_mfma_f32_16x16x32_bf16 v[46:49], v[192:195], v[166:169], v[46:49]
	v_mfma_f32_16x16x32_bf16 v[42:45], v[192:195], v[170:173], v[42:45]
	global_load_lds_dwordx4 v[142:143], off
	v_lshl_add_u64 v[142:143], v[142:143], 0, s[2:3]
	s_add_i32 m0, m0, 0x1000
	v_mfma_f32_16x16x32_bf16 v[38:41], v[192:195], v[176:179], v[38:41]
	v_mfma_f32_16x16x32_bf16 v[34:37], v[192:195], v[180:183], v[34:37]
	s_setprio 0
	s_nop 0
	v_mfma_f32_16x16x32_bf16 v[30:33], v[196:199], v[146:149], v[30:33]
	global_load_lds_dwordx4 v[142:143], off
	s_add_i32 m0, m0, 0x1000
	v_lshl_add_u64 v[142:143], v[134:135], 0, s[2:3]
	v_mfma_f32_16x16x32_bf16 v[26:29], v[196:199], v[152:155], v[26:29]
	v_mfma_f32_16x16x32_bf16 v[22:25], v[196:199], v[156:159], v[22:25]
	v_mfma_f32_16x16x32_bf16 v[18:21], v[196:199], v[162:165], v[18:21]
	global_load_lds_dwordx4 v[134:135], off
	s_add_i32 m0, m0, 0x1000
	v_lshl_add_u64 v[132:133], v[132:133], 0, s[12:13]
	v_mfma_f32_16x16x32_bf16 v[14:17], v[196:199], v[166:169], v[14:17]
	v_mfma_f32_16x16x32_bf16 v[10:13], v[196:199], v[170:173], v[10:13]
	v_mfma_f32_16x16x32_bf16 v[6:9], v[196:199], v[176:179], v[6:9]
	global_load_lds_dwordx4 v[142:143], off
	v_lshl_add_u64 v[134:135], v[134:135], 0, s[4:5]
	v_mfma_f32_16x16x32_bf16 v[2:5], v[196:199], v[180:183], v[2:5]
	s_mov_b32 s41, s40
	s_nop 0
	s_add_i32 s40, s40, 0x6000
	s_cmp_eq_u32 s40, 0x12000
	s_cselect_b32 s40, 0, s40
	s_nop 0
	.p2align 3
	s_waitcnt vmcnt(6) lgkmcnt(0)
	s_barrier
;     ...
;   for (int kt = 0; kt < nk; kt++) {
;     if (kt + 1 < nk) asm volatile("s_waitcnt vmcnt(6)" ::: "memory");
;     else asm volatile("s_waitcnt vmcnt(0)" ::: "memory");
;     __builtin_amdgcn_s_barrier();
;     asm volatile("" ::: "memory");
;     if (kt + 2 < nk) G2_STAGE(kt + 2);
;     const char* cS = smem + (kt % 3) * 24576;
;     bf16x8 xa[8], wb[4];
; #pragma unroll
;     for (int f = 0; f < 8; f++) xa[f] = *(const bf16x8*)(cS + aoff + f * 1024);
; #pragma unroll
;     for (int f = 0; f < 4; f++) wb[f] = *(const bf16x8*)(cS + boff + f * 1024);
; #pragma unroll
;     for (int nf = 0; nf < 4; nf++)
; #pragma unroll
;       for (int mf = 0; mf < 8; mf++)
;         acc[nf][mf] = __builtin_amdgcn_mfma_f32_16x16x32_bf16(wb[nf], xa[mf], acc[nf][mf], 0, 0, 0);
;   }
	s_setprio 1
	v_add_u32_e32 v144, s40, v136
	v_mfma_f32_16x16x32_bf16 v[126:129], v[232:235], v[200:203], v[126:129]
	ds_read_b128 v[146:149], v144 offset:0
	v_mfma_f32_16x16x32_bf16 v[122:125], v[232:235], v[204:207], v[122:125]
	ds_read_b128 v[152:155], v144 offset:1024
	v_mfma_f32_16x16x32_bf16 v[118:121], v[232:235], v[208:211], v[118:121]
	ds_read_b128 v[156:159], v144 offset:2048
	v_mfma_f32_16x16x32_bf16 v[114:117], v[232:235], v[212:215], v[114:117]
	ds_read_b128 v[162:165], v144 offset:3072
	v_mfma_f32_16x16x32_bf16 v[110:113], v[232:235], v[216:219], v[110:113]
	ds_read_b128 v[166:169], v144 offset:4096
	v_mfma_f32_16x16x32_bf16 v[106:109], v[232:235], v[220:223], v[106:109]
	ds_read_b128 v[170:173], v144 offset:5120
	v_mfma_f32_16x16x32_bf16 v[102:105], v[232:235], v[224:227], v[102:105]
	ds_read_b128 v[176:179], v144 offset:6144
	v_mfma_f32_16x16x32_bf16 v[98:101], v[232:235], v[228:231], v[98:101]
	ds_read_b128 v[180:183], v144 offset:7168
	v_mfma_f32_16x16x32_bf16 v[94:97], v[236:239], v[200:203], v[94:97]
	v_add_u32_e64 v144, s40, v137
	v_mfma_f32_16x16x32_bf16 v[90:93], v[236:239], v[204:207], v[90:93]
	v_mfma_f32_16x16x32_bf16 v[86:89], v[236:239], v[208:211], v[86:89]
	ds_read_b128 v[184:187], v144 offset:16384
	v_mfma_f32_16x16x32_bf16 v[82:85], v[236:239], v[212:215], v[82:85]
	ds_read_b128 v[188:191], v144 offset:17408
	v_mfma_f32_16x16x32_bf16 v[78:81], v[236:239], v[216:219], v[78:81]
	ds_read_b128 v[192:195], v144 offset:18432
	v_mfma_f32_16x16x32_bf16 v[74:77], v[236:239], v[220:223], v[74:77]
	ds_read_b128 v[196:199], v144 offset:19456
	v_mfma_f32_16x16x32_bf16 v[70:73], v[236:239], v[224:227], v[70:73]
	v_mfma_f32_16x16x32_bf16 v[66:69], v[236:239], v[228:231], v[66:69]
	v_mfma_f32_16x16x32_bf16 v[62:65], v[240:243], v[200:203], v[62:65]
	v_mfma_f32_16x16x32_bf16 v[58:61], v[240:243], v[204:207], v[58:61]
	v_mfma_f32_16x16x32_bf16 v[54:57], v[240:243], v[208:211], v[54:57]
	v_mfma_f32_16x16x32_bf16 v[50:53], v[240:243], v[212:215], v[50:53]
	v_mfma_f32_16x16x32_bf16 v[46:49], v[240:243], v[216:219], v[46:49]
	v_mfma_f32_16x16x32_bf16 v[42:45], v[240:243], v[220:223], v[42:45]
	v_mfma_f32_16x16x32_bf16 v[38:41], v[240:243], v[224:227], v[38:41]
	v_mfma_f32_16x16x32_bf16 v[34:37], v[240:243], v[228:231], v[34:37]
	s_setprio 0
	s_nop 0
	v_mfma_f32_16x16x32_bf16 v[30:33], v[244:247], v[200:203], v[30:33]
	v_mfma_f32_16x16x32_bf16 v[26:29], v[244:247], v[204:207], v[26:29]
	v_mfma_f32_16x16x32_bf16 v[22:25], v[244:247], v[208:211], v[22:25]
	v_mfma_f32_16x16x32_bf16 v[18:21], v[244:247], v[212:215], v[18:21]
	v_mfma_f32_16x16x32_bf16 v[14:17], v[244:247], v[216:219], v[14:17]
	v_mfma_f32_16x16x32_bf16 v[10:13], v[244:247], v[220:223], v[10:13]
	v_mfma_f32_16x16x32_bf16 v[6:9], v[244:247], v[224:227], v[6:9]
	v_mfma_f32_16x16x32_bf16 v[2:5], v[244:247], v[228:231], v[2:5]
	s_mov_b32 s41, s40
	s_nop 0
	s_add_i32 s40, s40, 0x6000
	s_cmp_eq_u32 s40, 0x12000
	s_cselect_b32 s40, 0, s40
	s_nop 0
	.p2align 3
	s_waitcnt vmcnt(0) lgkmcnt(0)
	s_barrier
	s_setprio 1
	v_add_u32_e32 v144, s40, v136
	v_mfma_f32_16x16x32_bf16 v[126:129], v[184:187], v[146:149], v[126:129]
	ds_read_b128 v[200:203], v144 offset:0
	v_mfma_f32_16x16x32_bf16 v[122:125], v[184:187], v[152:155], v[122:125]
	ds_read_b128 v[204:207], v144 offset:1024
	v_mfma_f32_16x16x32_bf16 v[118:121], v[184:187], v[156:159], v[118:121]
	ds_read_b128 v[208:211], v144 offset:2048
	v_mfma_f32_16x16x32_bf16 v[114:117], v[184:187], v[162:165], v[114:117]
	ds_read_b128 v[212:215], v144 offset:3072
	v_mfma_f32_16x16x32_bf16 v[110:113], v[184:187], v[166:169], v[110:113]
	ds_read_b128 v[216:219], v144 offset:4096
	v_mfma_f32_16x16x32_bf16 v[106:109], v[184:187], v[170:173], v[106:109]
	ds_read_b128 v[220:223], v144 offset:5120
	v_mfma_f32_16x16x32_bf16 v[102:105], v[184:187], v[176:179], v[102:105]
	ds_read_b128 v[224:227], v144 offset:6144
	v_mfma_f32_16x16x32_bf16 v[98:101], v[184:187], v[180:183], v[98:101]
	ds_read_b128 v[228:231], v144 offset:7168
	v_mfma_f32_16x16x32_bf16 v[94:97], v[188:191], v[146:149], v[94:97]
	v_add_u32_e64 v144, s40, v137
	v_mfma_f32_16x16x32_bf16 v[90:93], v[188:191], v[152:155], v[90:93]
	v_mfma_f32_16x16x32_bf16 v[86:89], v[188:191], v[156:159], v[86:89]
	ds_read_b128 v[232:235], v144 offset:16384
	v_mfma_f32_16x16x32_bf16 v[82:85], v[188:191], v[162:165], v[82:85]
	ds_read_b128 v[236:239], v144 offset:17408
	v_mfma_f32_16x16x32_bf16 v[78:81], v[188:191], v[166:169], v[78:81]
	ds_read_b128 v[240:243], v144 offset:18432
	v_mfma_f32_16x16x32_bf16 v[74:77], v[188:191], v[170:173], v[74:77]
	ds_read_b128 v[244:247], v144 offset:19456
	v_mfma_f32_16x16x32_bf16 v[70:73], v[188:191], v[176:179], v[70:73]
	v_mfma_f32_16x16x32_bf16 v[66:69], v[188:191], v[180:183], v[66:69]
	v_mfma_f32_16x16x32_bf16 v[62:65], v[192:195], v[146:149], v[62:65]
	v_mfma_f32_16x16x32_bf16 v[58:61], v[192:195], v[152:155], v[58:61]
	v_mfma_f32_16x16x32_bf16 v[54:57], v[192:195], v[156:159], v[54:57]
	v_mfma_f32_16x16x32_bf16 v[50:53], v[192:195], v[162:165], v[50:53]
	v_mfma_f32_16x16x32_bf16 v[46:49], v[192:195], v[166:169], v[46:49]
	v_mfma_f32_16x16x32_bf16 v[42:45], v[192:195], v[170:173], v[42:45]
	v_mfma_f32_16x16x32_bf16 v[38:41], v[192:195], v[176:179], v[38:41]
	v_mfma_f32_16x16x32_bf16 v[34:37], v[192:195], v[180:183], v[34:37]
	s_setprio 0
	s_nop 0
	v_mfma_f32_16x16x32_bf16 v[30:33], v[196:199], v[146:149], v[30:33]
	v_mfma_f32_16x16x32_bf16 v[26:29], v[196:199], v[152:155], v[26:29]
	v_mfma_f32_16x16x32_bf16 v[22:25], v[196:199], v[156:159], v[22:25]
	v_mfma_f32_16x16x32_bf16 v[18:21], v[196:199], v[162:165], v[18:21]
	v_mfma_f32_16x16x32_bf16 v[14:17], v[196:199], v[166:169], v[14:17]
	v_mfma_f32_16x16x32_bf16 v[10:13], v[196:199], v[170:173], v[10:13]
	v_mfma_f32_16x16x32_bf16 v[6:9], v[196:199], v[176:179], v[6:9]
	v_mfma_f32_16x16x32_bf16 v[2:5], v[196:199], v[180:183], v[2:5]
	s_mov_b32 s41, s40
	s_nop 0
	s_add_i32 s40, s40, 0x6000
	s_cmp_eq_u32 s40, 0x12000
	s_cselect_b32 s40, 0, s40
	s_nop 0
	s_mov_b32 s4, 0x8000
	s_mov_b32 s5, 0
	s_mov_b32 s10, 0x10000
	s_mov_b32 s11, 0
	s_mov_b32 s44, 0x3fd744fd
	.p2align 3
	s_waitcnt lgkmcnt(0)
; DEVI float blo(unsigned u) { return __uint_as_float(u << 16); }
; DEVI float bhi(unsigned u) { return __uint_as_float(u & 0xffff0000u); }
;     ...
;     for (int nf = 0; nf < 4; nf++)
; #pragma unroll
;       for (int mf = 0; mf < 8; mf++)
;         acc[nf][mf] = __builtin_amdgcn_mfma_f32_16x16x32_bf16(wb[nf], xa[mf], acc[nf][mf], 0, 0, 0);
;     ...
; #pragma unroll
;       for (int nf = 0; nf < 4; nf++) {
;         const int col = n0 + wn * 64 + nf * 16 + quad * 4;
;         f32x4 a = acc[nf][mf];
;         if (EPI == EPI_RESID || EPI == EPI_RESID_ATOMIC) {
;           f32x4 x = a;
;           if (EPI == EPI_RESID || kpart == 0) {
;             const u32x2 xr = *(const u32x2*)((const u16*)(p.ws + WS_XB) + (size_t)row * 1024 + col);
;             x[0] += ALPHA * blo(xr[0]); x[1] += ALPHA * bhi(xr[0]); x[2] += ALPHA * blo(xr[1]); x[3] += ALPHA * bhi(xr[1]);
;           }
;           if (EPI == EPI_RESID) *(f32x4*)((float*)(p.ws + WS_XF) + (size_t)row * 1024 + col) = x;
;           else *(f32x4*)((float*)(p.ws + WS_SLAB) + ((size_t)kpart * 512 + (row - T_P)) * 1024 + col) = x;
	s_nop 0
	v_mfma_f32_16x16x32_bf16 v[126:129], v[232:235], v[200:203], v[126:129]
	v_mfma_f32_16x16x32_bf16 v[122:125], v[232:235], v[204:207], v[122:125]
	v_mfma_f32_16x16x32_bf16 v[118:121], v[232:235], v[208:211], v[118:121]
	v_mfma_f32_16x16x32_bf16 v[114:117], v[232:235], v[212:215], v[114:117]
	v_mfma_f32_16x16x32_bf16 v[110:113], v[232:235], v[216:219], v[110:113]
	global_load_dwordx4 v[146:149], v[138:139], off offset:0
	v_mfma_f32_16x16x32_bf16 v[106:109], v[232:235], v[220:223], v[106:109]
	v_mfma_f32_16x16x32_bf16 v[102:105], v[232:235], v[224:227], v[102:105]
	global_load_dwordx4 v[152:155], v[138:139], off offset:128
	v_mfma_f32_16x16x32_bf16 v[98:101], v[232:235], v[228:231], v[98:101]
	v_lshl_add_u64 v[138:139], v[138:139], 0, s[4:5]
	v_mfma_f32_16x16x32_bf16 v[94:97], v[236:239], v[200:203], v[94:97]
	global_load_dwordx4 v[156:159], v[138:139], off offset:0
	v_mfma_f32_16x16x32_bf16 v[90:93], v[236:239], v[204:207], v[90:93]
	v_mfma_f32_16x16x32_bf16 v[86:89], v[236:239], v[208:211], v[86:89]
	global_load_dwordx4 v[162:165], v[138:139], off offset:128
	v_mfma_f32_16x16x32_bf16 v[82:85], v[236:239], v[212:215], v[82:85]
	v_lshl_add_u64 v[138:139], v[138:139], 0, s[4:5]
	v_mfma_f32_16x16x32_bf16 v[78:81], v[236:239], v[216:219], v[78:81]
	global_load_dwordx4 v[166:169], v[138:139], off offset:0
	v_mfma_f32_16x16x32_bf16 v[74:77], v[236:239], v[220:223], v[74:77]
	v_mfma_f32_16x16x32_bf16 v[70:73], v[236:239], v[224:227], v[70:73]
	global_load_dwordx4 v[170:173], v[138:139], off offset:128
	v_mfma_f32_16x16x32_bf16 v[66:69], v[236:239], v[228:231], v[66:69]
	v_lshl_add_u64 v[138:139], v[138:139], 0, s[4:5]
	v_mfma_f32_16x16x32_bf16 v[62:65], v[240:243], v[200:203], v[62:65]
	global_load_dwordx4 v[176:179], v[138:139], off offset:0
	v_mfma_f32_16x16x32_bf16 v[58:61], v[240:243], v[204:207], v[58:61]
	v_mfma_f32_16x16x32_bf16 v[54:57], v[240:243], v[208:211], v[54:57]
	global_load_dwordx4 v[180:183], v[138:139], off offset:128
	v_mfma_f32_16x16x32_bf16 v[50:53], v[240:243], v[212:215], v[50:53]
	v_lshl_add_u64 v[138:139], v[138:139], 0, s[4:5]
	v_mfma_f32_16x16x32_bf16 v[46:49], v[240:243], v[216:219], v[46:49]
	global_load_dwordx4 v[184:187], v[138:139], off offset:0
	v_mfma_f32_16x16x32_bf16 v[42:45], v[240:243], v[220:223], v[42:45]
	v_mfma_f32_16x16x32_bf16 v[38:41], v[240:243], v[224:227], v[38:41]
	global_load_dwordx4 v[188:191], v[138:139], off offset:128
	v_mfma_f32_16x16x32_bf16 v[34:37], v[240:243], v[228:231], v[34:37]
	v_lshl_add_u64 v[138:139], v[138:139], 0, s[4:5]
	v_mfma_f32_16x16x32_bf16 v[30:33], v[244:247], v[200:203], v[30:33]
	global_load_dwordx4 v[192:195], v[138:139], off offset:0
	v_mfma_f32_16x16x32_bf16 v[26:29], v[244:247], v[204:207], v[26:29]
	v_mfma_f32_16x16x32_bf16 v[22:25], v[244:247], v[208:211], v[22:25]
	global_load_dwordx4 v[196:199], v[138:139], off offset:128
	v_mfma_f32_16x16x32_bf16 v[18:21], v[244:247], v[212:215], v[18:21]
	v_lshl_add_u64 v[138:139], v[138:139], 0, s[4:5]
	v_mfma_f32_16x16x32_bf16 v[14:17], v[244:247], v[216:219], v[14:17]
	v_mfma_f32_16x16x32_bf16 v[10:13], v[244:247], v[220:223], v[10:13]
	v_mfma_f32_16x16x32_bf16 v[6:9], v[244:247], v[224:227], v[6:9]
	v_mfma_f32_16x16x32_bf16 v[2:5], v[244:247], v[228:231], v[2:5]
	s_mov_b32 m0, s43
	global_load_dwordx4 v[200:203], v[138:139], off offset:0
	global_load_dwordx4 v[204:207], v[138:139], off offset:128
	v_lshl_add_u64 v[138:139], v[138:139], 0, s[4:5]
	global_load_dwordx4 v[208:211], v[138:139], off offset:0
	global_load_dwordx4 v[212:215], v[138:139], off offset:128
	v_lshl_add_u64 v[138:139], v[138:139], 0, s[4:5]
	s_nop 7
	v_and_b32_e32 v228, 1, v145
	v_cmp_ne_u32_e32 vcc, 0, v228
	v_mov_b32_e32 v229, 0xfffff040
	v_cndmask_b32_e32 v230, 0, v229, vcc
	v_ashrrev_i32_e32 v231, 31, v230
	v_lshl_add_u64 v[140:141], v[140:141], 0, v[230:231]
	v_add_co_u32_e32 v142, vcc, 0x1000, v140
	s_nop 0
	v_addc_co_u32_e32 v143, vcc, 0, v141, vcc
	v_cmp_ne_u32_e32 vcc, 0, v228
	s_waitcnt vmcnt(15)
	v_permlane16_swap_b32_e32 v146, v148
	v_permlane16_swap_b32_e32 v147, v149
	v_lshlrev_b32_e32 v216, 16, v146
	v_and_b32_e32 v146, 0xffff0000, v146
	v_lshlrev_b32_e32 v217, 16, v147
	v_and_b32_e32 v147, 0xffff0000, v147
	v_fmac_f32_e32 v126, s44, v216
	v_fmac_f32_e32 v127, s44, v146
	v_fmac_f32_e32 v128, s44, v217
	v_fmac_f32_e32 v129, s44, v147
	v_lshlrev_b32_e32 v216, 16, v148
	v_and_b32_e32 v148, 0xffff0000, v148
	v_lshlrev_b32_e32 v217, 16, v149
	v_and_b32_e32 v149, 0xffff0000, v149
	v_fmac_f32_e32 v94, s44, v216
	v_fmac_f32_e32 v95, s44, v148
	v_fmac_f32_e32 v96, s44, v217
	v_fmac_f32_e32 v97, s44, v149
	v_mov_b32_dpp v220, v94 quad_perm:[1,0,3,2] row_mask:0xf bank_mask:0xf
	v_mov_b32_dpp v221, v95 quad_perm:[1,0,3,2] row_mask:0xf bank_mask:0xf
	v_mov_b32_dpp v222, v96 quad_perm:[1,0,3,2] row_mask:0xf bank_mask:0xf
	v_mov_b32_dpp v223, v97 quad_perm:[1,0,3,2] row_mask:0xf bank_mask:0xf
	v_mov_b32_dpp v224, v126 quad_perm:[1,0,3,2] row_mask:0xf bank_mask:0xf
	v_mov_b32_dpp v225, v127 quad_perm:[1,0,3,2] row_mask:0xf bank_mask:0xf
	v_mov_b32_dpp v226, v128 quad_perm:[1,0,3,2] row_mask:0xf bank_mask:0xf
	v_mov_b32_dpp v227, v129 quad_perm:[1,0,3,2] row_mask:0xf bank_mask:0xf
	v_cndmask_b32_e32 v94, v224, v94, vcc
	v_cndmask_b32_e32 v95, v225, v95, vcc
	v_cndmask_b32_e32 v96, v226, v96, vcc
	v_cndmask_b32_e32 v97, v227, v97, vcc
	v_cndmask_b32_e32 v126, v126, v220, vcc
	v_cndmask_b32_e32 v127, v127, v221, vcc
	v_cndmask_b32_e32 v128, v128, v222, vcc
	v_cndmask_b32_e32 v129, v129, v223, vcc
	global_store_dwordx4 v[140:141], v[126:129], off
	global_store_dwordx4 v[142:143], v[94:97], off
	s_waitcnt vmcnt(16)
; DEVI float blo(unsigned u) { return __uint_as_float(u << 16); }
; DEVI float bhi(unsigned u) { return __uint_as_float(u & 0xffff0000u); }
;     ...
; #pragma unroll
;       for (int nf = 0; nf < 4; nf++) {
;         const int col = n0 + wn * 64 + nf * 16 + quad * 4;
;         f32x4 a = acc[nf][mf];
;         if (EPI == EPI_RESID || EPI == EPI_RESID_ATOMIC) {
;           f32x4 x = a;
;           if (EPI == EPI_RESID || kpart == 0) {
;             const u32x2 xr = *(const u32x2*)((const u16*)(p.ws + WS_XB) + (size_t)row * 1024 + col);
;             x[0] += ALPHA * blo(xr[0]); x[1] += ALPHA * bhi(xr[0]); x[2] += ALPHA * blo(xr[1]); x[3] += ALPHA * bhi(xr[1]);
;           }
;           if (EPI == EPI_RESID) *(f32x4*)((float*)(p.ws + WS_XF) + (size_t)row * 1024 + col) = x;
;           else *(f32x4*)((float*)(p.ws + WS_SLAB) + ((size_t)kpart * 512 + (row - T_P)) * 1024 + col) = x;
	v_permlane16_swap_b32_e32 v152, v154
	v_permlane16_swap_b32_e32 v153, v155
	v_lshlrev_b32_e32 v216, 16, v152
	v_and_b32_e32 v152, 0xffff0000, v152
	v_lshlrev_b32_e32 v217, 16, v153
	v_and_b32_e32 v153, 0xffff0000, v153
	v_fmac_f32_e32 v62, s44, v216
	v_fmac_f32_e32 v63, s44, v152
	v_fmac_f32_e32 v64, s44, v217
	v_fmac_f32_e32 v65, s44, v153
	v_lshlrev_b32_e32 v216, 16, v154
	v_and_b32_e32 v154, 0xffff0000, v154
	v_lshlrev_b32_e32 v217, 16, v155
	v_and_b32_e32 v155, 0xffff0000, v155
	v_fmac_f32_e32 v30, s44, v216
	v_fmac_f32_e32 v31, s44, v154
	v_fmac_f32_e32 v32, s44, v217
	v_fmac_f32_e32 v33, s44, v155
	v_mov_b32_dpp v220, v30 quad_perm:[1,0,3,2] row_mask:0xf bank_mask:0xf
	v_mov_b32_dpp v221, v31 quad_perm:[1,0,3,2] row_mask:0xf bank_mask:0xf
	v_mov_b32_dpp v222, v32 quad_perm:[1,0,3,2] row_mask:0xf bank_mask:0xf
	v_mov_b32_dpp v223, v33 quad_perm:[1,0,3,2] row_mask:0xf bank_mask:0xf
	v_mov_b32_dpp v224, v62 quad_perm:[1,0,3,2] row_mask:0xf bank_mask:0xf
	v_mov_b32_dpp v225, v63 quad_perm:[1,0,3,2] row_mask:0xf bank_mask:0xf
	v_mov_b32_dpp v226, v64 quad_perm:[1,0,3,2] row_mask:0xf bank_mask:0xf
	v_mov_b32_dpp v227, v65 quad_perm:[1,0,3,2] row_mask:0xf bank_mask:0xf
	v_cndmask_b32_e32 v30, v224, v30, vcc
	v_cndmask_b32_e32 v31, v225, v31, vcc
	v_cndmask_b32_e32 v32, v226, v32, vcc
	v_cndmask_b32_e32 v33, v227, v33, vcc
	v_cndmask_b32_e32 v62, v62, v220, vcc
	v_cndmask_b32_e32 v63, v63, v221, vcc
	v_cndmask_b32_e32 v64, v64, v222, vcc
	v_cndmask_b32_e32 v65, v65, v223, vcc
	global_store_dwordx4 v[140:141], v[62:65], off offset:128
	global_store_dwordx4 v[142:143], v[30:33], off offset:128
	v_lshl_add_u64 v[140:141], v[140:141], 0, s[10:11]
	v_lshl_add_u64 v[142:143], v[142:143], 0, s[10:11]
	s_waitcnt vmcnt(17)
	v_permlane16_swap_b32_e32 v156, v158
	v_permlane16_swap_b32_e32 v157, v159
	v_lshlrev_b32_e32 v216, 16, v156
	v_and_b32_e32 v156, 0xffff0000, v156
	v_lshlrev_b32_e32 v217, 16, v157
	v_and_b32_e32 v157, 0xffff0000, v157
	v_fmac_f32_e32 v122, s44, v216
	v_fmac_f32_e32 v123, s44, v156
	v_fmac_f32_e32 v124, s44, v217
	v_fmac_f32_e32 v125, s44, v157
	v_lshlrev_b32_e32 v216, 16, v158
	v_and_b32_e32 v158, 0xffff0000, v158
	v_lshlrev_b32_e32 v217, 16, v159
	v_and_b32_e32 v159, 0xffff0000, v159
	v_fmac_f32_e32 v90, s44, v216
	v_fmac_f32_e32 v91, s44, v158
	v_fmac_f32_e32 v92, s44, v217
	v_fmac_f32_e32 v93, s44, v159
	v_mov_b32_dpp v220, v90 quad_perm:[1,0,3,2] row_mask:0xf bank_mask:0xf
	v_mov_b32_dpp v221, v91 quad_perm:[1,0,3,2] row_mask:0xf bank_mask:0xf
	v_mov_b32_dpp v222, v92 quad_perm:[1,0,3,2] row_mask:0xf bank_mask:0xf
	v_mov_b32_dpp v223, v93 quad_perm:[1,0,3,2] row_mask:0xf bank_mask:0xf
	v_mov_b32_dpp v224, v122 quad_perm:[1,0,3,2] row_mask:0xf bank_mask:0xf
	v_mov_b32_dpp v225, v123 quad_perm:[1,0,3,2] row_mask:0xf bank_mask:0xf
	v_mov_b32_dpp v226, v124 quad_perm:[1,0,3,2] row_mask:0xf bank_mask:0xf
	v_mov_b32_dpp v227, v125 quad_perm:[1,0,3,2] row_mask:0xf bank_mask:0xf
	v_cndmask_b32_e32 v90, v224, v90, vcc
	v_cndmask_b32_e32 v91, v225, v91, vcc
	v_cndmask_b32_e32 v92, v226, v92, vcc
	v_cndmask_b32_e32 v93, v227, v93, vcc
	v_cndmask_b32_e32 v122, v122, v220, vcc
	v_cndmask_b32_e32 v123, v123, v221, vcc
	v_cndmask_b32_e32 v124, v124, v222, vcc
	v_cndmask_b32_e32 v125, v125, v223, vcc
	global_store_dwordx4 v[140:141], v[122:125], off
	global_store_dwordx4 v[142:143], v[90:93], off
	s_waitcnt vmcnt(18)
	v_permlane16_swap_b32_e32 v162, v164
	v_permlane16_swap_b32_e32 v163, v165
	v_lshlrev_b32_e32 v216, 16, v162
	v_and_b32_e32 v162, 0xffff0000, v162
	v_lshlrev_b32_e32 v217, 16, v163
	v_and_b32_e32 v163, 0xffff0000, v163
	v_fmac_f32_e32 v58, s44, v216
	v_fmac_f32_e32 v59, s44, v162
	v_fmac_f32_e32 v60, s44, v217
	v_fmac_f32_e32 v61, s44, v163
	v_lshlrev_b32_e32 v216, 16, v164
	v_and_b32_e32 v164, 0xffff0000, v164
	v_lshlrev_b32_e32 v217, 16, v165
	v_and_b32_e32 v165, 0xffff0000, v165
	v_fmac_f32_e32 v26, s44, v216
	v_fmac_f32_e32 v27, s44, v164
	v_fmac_f32_e32 v28, s44, v217
	v_fmac_f32_e32 v29, s44, v165
	v_mov_b32_dpp v220, v26 quad_perm:[1,0,3,2] row_mask:0xf bank_mask:0xf
	v_mov_b32_dpp v221, v27 quad_perm:[1,0,3,2] row_mask:0xf bank_mask:0xf
	v_mov_b32_dpp v222, v28 quad_perm:[1,0,3,2] row_mask:0xf bank_mask:0xf
	v_mov_b32_dpp v223, v29 quad_perm:[1,0,3,2] row_mask:0xf bank_mask:0xf
	v_mov_b32_dpp v224, v58 quad_perm:[1,0,3,2] row_mask:0xf bank_mask:0xf
	v_mov_b32_dpp v225, v59 quad_perm:[1,0,3,2] row_mask:0xf bank_mask:0xf
	v_mov_b32_dpp v226, v60 quad_perm:[1,0,3,2] row_mask:0xf bank_mask:0xf
	v_mov_b32_dpp v227, v61 quad_perm:[1,0,3,2] row_mask:0xf bank_mask:0xf
	v_cndmask_b32_e32 v26, v224, v26, vcc
	v_cndmask_b32_e32 v27, v225, v27, vcc
	v_cndmask_b32_e32 v28, v226, v28, vcc
	v_cndmask_b32_e32 v29, v227, v29, vcc
	v_cndmask_b32_e32 v58, v58, v220, vcc
	v_cndmask_b32_e32 v59, v59, v221, vcc
	v_cndmask_b32_e32 v60, v60, v222, vcc
	v_cndmask_b32_e32 v61, v61, v223, vcc
	global_store_dwordx4 v[140:141], v[58:61], off offset:128
	global_store_dwordx4 v[142:143], v[26:29], off offset:128
	v_lshl_add_u64 v[140:141], v[140:141], 0, s[10:11]
	v_lshl_add_u64 v[142:143], v[142:143], 0, s[10:11]
	s_waitcnt vmcnt(19)
; DEVI float blo(unsigned u) { return __uint_as_float(u << 16); }
; DEVI float bhi(unsigned u) { return __uint_as_float(u & 0xffff0000u); }
;     ...
; #pragma unroll
;       for (int nf = 0; nf < 4; nf++) {
;         const int col = n0 + wn * 64 + nf * 16 + quad * 4;
;         f32x4 a = acc[nf][mf];
;         if (EPI == EPI_RESID || EPI == EPI_RESID_ATOMIC) {
;           f32x4 x = a;
;           if (EPI == EPI_RESID || kpart == 0) {
;             const u32x2 xr = *(const u32x2*)((const u16*)(p.ws + WS_XB) + (size_t)row * 1024 + col);
;             x[0] += ALPHA * blo(xr[0]); x[1] += ALPHA * bhi(xr[0]); x[2] += ALPHA * blo(xr[1]); x[3] += ALPHA * bhi(xr[1]);
;           }
;           if (EPI == EPI_RESID) *(f32x4*)((float*)(p.ws + WS_XF) + (size_t)row * 1024 + col) = x;
;           else *(f32x4*)((float*)(p.ws + WS_SLAB) + ((size_t)kpart * 512 + (row - T_P)) * 1024 + col) = x;
	v_permlane16_swap_b32_e32 v166, v168
	v_permlane16_swap_b32_e32 v167, v169
	v_lshlrev_b32_e32 v216, 16, v166
	v_and_b32_e32 v166, 0xffff0000, v166
	v_lshlrev_b32_e32 v217, 16, v167
	v_and_b32_e32 v167, 0xffff0000, v167
	v_fmac_f32_e32 v118, s44, v216
	v_fmac_f32_e32 v119, s44, v166
	v_fmac_f32_e32 v120, s44, v217
	v_fmac_f32_e32 v121, s44, v167
	v_lshlrev_b32_e32 v216, 16, v168
	v_and_b32_e32 v168, 0xffff0000, v168
	v_lshlrev_b32_e32 v217, 16, v169
	v_and_b32_e32 v169, 0xffff0000, v169
	v_fmac_f32_e32 v86, s44, v216
	v_fmac_f32_e32 v87, s44, v168
	v_fmac_f32_e32 v88, s44, v217
	v_fmac_f32_e32 v89, s44, v169
	v_mov_b32_dpp v220, v86 quad_perm:[1,0,3,2] row_mask:0xf bank_mask:0xf
	v_mov_b32_dpp v221, v87 quad_perm:[1,0,3,2] row_mask:0xf bank_mask:0xf
	v_mov_b32_dpp v222, v88 quad_perm:[1,0,3,2] row_mask:0xf bank_mask:0xf
	v_mov_b32_dpp v223, v89 quad_perm:[1,0,3,2] row_mask:0xf bank_mask:0xf
	v_mov_b32_dpp v224, v118 quad_perm:[1,0,3,2] row_mask:0xf bank_mask:0xf
	v_mov_b32_dpp v225, v119 quad_perm:[1,0,3,2] row_mask:0xf bank_mask:0xf
	v_mov_b32_dpp v226, v120 quad_perm:[1,0,3,2] row_mask:0xf bank_mask:0xf
	v_mov_b32_dpp v227, v121 quad_perm:[1,0,3,2] row_mask:0xf bank_mask:0xf
	v_cndmask_b32_e32 v86, v224, v86, vcc
	v_cndmask_b32_e32 v87, v225, v87, vcc
	v_cndmask_b32_e32 v88, v226, v88, vcc
	v_cndmask_b32_e32 v89, v227, v89, vcc
	v_cndmask_b32_e32 v118, v118, v220, vcc
	v_cndmask_b32_e32 v119, v119, v221, vcc
	v_cndmask_b32_e32 v120, v120, v222, vcc
	v_cndmask_b32_e32 v121, v121, v223, vcc
	global_store_dwordx4 v[140:141], v[118:121], off
	global_store_dwordx4 v[142:143], v[86:89], off
	s_waitcnt vmcnt(20)
	v_permlane16_swap_b32_e32 v170, v172
	v_permlane16_swap_b32_e32 v171, v173
	v_lshlrev_b32_e32 v216, 16, v170
	v_and_b32_e32 v170, 0xffff0000, v170
	v_lshlrev_b32_e32 v217, 16, v171
	v_and_b32_e32 v171, 0xffff0000, v171
	v_fmac_f32_e32 v54, s44, v216
	v_fmac_f32_e32 v55, s44, v170
	v_fmac_f32_e32 v56, s44, v217
	v_fmac_f32_e32 v57, s44, v171
	v_lshlrev_b32_e32 v216, 16, v172
	v_and_b32_e32 v172, 0xffff0000, v172
	v_lshlrev_b32_e32 v217, 16, v173
	v_and_b32_e32 v173, 0xffff0000, v173
	v_fmac_f32_e32 v22, s44, v216
	v_fmac_f32_e32 v23, s44, v172
	v_fmac_f32_e32 v24, s44, v217
	v_fmac_f32_e32 v25, s44, v173
	v_mov_b32_dpp v220, v22 quad_perm:[1,0,3,2] row_mask:0xf bank_mask:0xf
	v_mov_b32_dpp v221, v23 quad_perm:[1,0,3,2] row_mask:0xf bank_mask:0xf
	v_mov_b32_dpp v222, v24 quad_perm:[1,0,3,2] row_mask:0xf bank_mask:0xf
	v_mov_b32_dpp v223, v25 quad_perm:[1,0,3,2] row_mask:0xf bank_mask:0xf
	v_mov_b32_dpp v224, v54 quad_perm:[1,0,3,2] row_mask:0xf bank_mask:0xf
	v_mov_b32_dpp v225, v55 quad_perm:[1,0,3,2] row_mask:0xf bank_mask:0xf
	v_mov_b32_dpp v226, v56 quad_perm:[1,0,3,2] row_mask:0xf bank_mask:0xf
	v_mov_b32_dpp v227, v57 quad_perm:[1,0,3,2] row_mask:0xf bank_mask:0xf
	v_cndmask_b32_e32 v22, v224, v22, vcc
	v_cndmask_b32_e32 v23, v225, v23, vcc
	v_cndmask_b32_e32 v24, v226, v24, vcc
	v_cndmask_b32_e32 v25, v227, v25, vcc
	v_cndmask_b32_e32 v54, v54, v220, vcc
	v_cndmask_b32_e32 v55, v55, v221, vcc
	v_cndmask_b32_e32 v56, v56, v222, vcc
	v_cndmask_b32_e32 v57, v57, v223, vcc
	global_store_dwordx4 v[140:141], v[54:57], off offset:128
	global_store_dwordx4 v[142:143], v[22:25], off offset:128
	v_lshl_add_u64 v[140:141], v[140:141], 0, s[10:11]
	v_lshl_add_u64 v[142:143], v[142:143], 0, s[10:11]
	s_waitcnt vmcnt(21)
	v_permlane16_swap_b32_e32 v176, v178
	v_permlane16_swap_b32_e32 v177, v179
	v_lshlrev_b32_e32 v216, 16, v176
	v_and_b32_e32 v176, 0xffff0000, v176
	v_lshlrev_b32_e32 v217, 16, v177
	v_and_b32_e32 v177, 0xffff0000, v177
	v_fmac_f32_e32 v114, s44, v216
	v_fmac_f32_e32 v115, s44, v176
	v_fmac_f32_e32 v116, s44, v217
	v_fmac_f32_e32 v117, s44, v177
	v_lshlrev_b32_e32 v216, 16, v178
	v_and_b32_e32 v178, 0xffff0000, v178
	v_lshlrev_b32_e32 v217, 16, v179
	v_and_b32_e32 v179, 0xffff0000, v179
	v_fmac_f32_e32 v82, s44, v216
	v_fmac_f32_e32 v83, s44, v178
	v_fmac_f32_e32 v84, s44, v217
	v_fmac_f32_e32 v85, s44, v179
	v_mov_b32_dpp v220, v82 quad_perm:[1,0,3,2] row_mask:0xf bank_mask:0xf
	v_mov_b32_dpp v221, v83 quad_perm:[1,0,3,2] row_mask:0xf bank_mask:0xf
	v_mov_b32_dpp v222, v84 quad_perm:[1,0,3,2] row_mask:0xf bank_mask:0xf
	v_mov_b32_dpp v223, v85 quad_perm:[1,0,3,2] row_mask:0xf bank_mask:0xf
	v_mov_b32_dpp v224, v114 quad_perm:[1,0,3,2] row_mask:0xf bank_mask:0xf
	v_mov_b32_dpp v225, v115 quad_perm:[1,0,3,2] row_mask:0xf bank_mask:0xf
	v_mov_b32_dpp v226, v116 quad_perm:[1,0,3,2] row_mask:0xf bank_mask:0xf
	v_mov_b32_dpp v227, v117 quad_perm:[1,0,3,2] row_mask:0xf bank_mask:0xf
	v_cndmask_b32_e32 v82, v224, v82, vcc
	v_cndmask_b32_e32 v83, v225, v83, vcc
	v_cndmask_b32_e32 v84, v226, v84, vcc
	v_cndmask_b32_e32 v85, v227, v85, vcc
	v_cndmask_b32_e32 v114, v114, v220, vcc
	v_cndmask_b32_e32 v115, v115, v221, vcc
	v_cndmask_b32_e32 v116, v116, v222, vcc
	v_cndmask_b32_e32 v117, v117, v223, vcc
	global_store_dwordx4 v[140:141], v[114:117], off
	global_store_dwordx4 v[142:143], v[82:85], off
	s_waitcnt vmcnt(22)
; DEVI float blo(unsigned u) { return __uint_as_float(u << 16); }
; DEVI float bhi(unsigned u) { return __uint_as_float(u & 0xffff0000u); }
;     ...
; #pragma unroll
;       for (int nf = 0; nf < 4; nf++) {
;         const int col = n0 + wn * 64 + nf * 16 + quad * 4;
;         f32x4 a = acc[nf][mf];
;         if (EPI == EPI_RESID || EPI == EPI_RESID_ATOMIC) {
;           f32x4 x = a;
;           if (EPI == EPI_RESID || kpart == 0) {
;             const u32x2 xr = *(const u32x2*)((const u16*)(p.ws + WS_XB) + (size_t)row * 1024 + col);
;             x[0] += ALPHA * blo(xr[0]); x[1] += ALPHA * bhi(xr[0]); x[2] += ALPHA * blo(xr[1]); x[3] += ALPHA * bhi(xr[1]);
;           }
;           if (EPI == EPI_RESID) *(f32x4*)((float*)(p.ws + WS_XF) + (size_t)row * 1024 + col) = x;
;           else *(f32x4*)((float*)(p.ws + WS_SLAB) + ((size_t)kpart * 512 + (row - T_P)) * 1024 + col) = x;
	v_permlane16_swap_b32_e32 v180, v182
	v_permlane16_swap_b32_e32 v181, v183
	v_lshlrev_b32_e32 v216, 16, v180
	v_and_b32_e32 v180, 0xffff0000, v180
	v_lshlrev_b32_e32 v217, 16, v181
	v_and_b32_e32 v181, 0xffff0000, v181
	v_fmac_f32_e32 v50, s44, v216
	v_fmac_f32_e32 v51, s44, v180
	v_fmac_f32_e32 v52, s44, v217
	v_fmac_f32_e32 v53, s44, v181
	v_lshlrev_b32_e32 v216, 16, v182
	v_and_b32_e32 v182, 0xffff0000, v182
	v_lshlrev_b32_e32 v217, 16, v183
	v_and_b32_e32 v183, 0xffff0000, v183
	v_fmac_f32_e32 v18, s44, v216
	v_fmac_f32_e32 v19, s44, v182
	v_fmac_f32_e32 v20, s44, v217
	v_fmac_f32_e32 v21, s44, v183
	v_mov_b32_dpp v220, v18 quad_perm:[1,0,3,2] row_mask:0xf bank_mask:0xf
	v_mov_b32_dpp v221, v19 quad_perm:[1,0,3,2] row_mask:0xf bank_mask:0xf
	v_mov_b32_dpp v222, v20 quad_perm:[1,0,3,2] row_mask:0xf bank_mask:0xf
	v_mov_b32_dpp v223, v21 quad_perm:[1,0,3,2] row_mask:0xf bank_mask:0xf
	v_mov_b32_dpp v224, v50 quad_perm:[1,0,3,2] row_mask:0xf bank_mask:0xf
	v_mov_b32_dpp v225, v51 quad_perm:[1,0,3,2] row_mask:0xf bank_mask:0xf
	v_mov_b32_dpp v226, v52 quad_perm:[1,0,3,2] row_mask:0xf bank_mask:0xf
	v_mov_b32_dpp v227, v53 quad_perm:[1,0,3,2] row_mask:0xf bank_mask:0xf
	v_cndmask_b32_e32 v18, v224, v18, vcc
	v_cndmask_b32_e32 v19, v225, v19, vcc
	v_cndmask_b32_e32 v20, v226, v20, vcc
	v_cndmask_b32_e32 v21, v227, v21, vcc
	v_cndmask_b32_e32 v50, v50, v220, vcc
	v_cndmask_b32_e32 v51, v51, v221, vcc
	v_cndmask_b32_e32 v52, v52, v222, vcc
	v_cndmask_b32_e32 v53, v53, v223, vcc
	global_store_dwordx4 v[140:141], v[50:53], off offset:128
	global_store_dwordx4 v[142:143], v[18:21], off offset:128
	v_lshl_add_u64 v[140:141], v[140:141], 0, s[10:11]
	v_lshl_add_u64 v[142:143], v[142:143], 0, s[10:11]
	s_waitcnt vmcnt(23)
	v_permlane16_swap_b32_e32 v184, v186
	v_permlane16_swap_b32_e32 v185, v187
	v_lshlrev_b32_e32 v216, 16, v184
	v_and_b32_e32 v184, 0xffff0000, v184
	v_lshlrev_b32_e32 v217, 16, v185
	v_and_b32_e32 v185, 0xffff0000, v185
	v_fmac_f32_e32 v110, s44, v216
	v_fmac_f32_e32 v111, s44, v184
	v_fmac_f32_e32 v112, s44, v217
	v_fmac_f32_e32 v113, s44, v185
	v_lshlrev_b32_e32 v216, 16, v186
	v_and_b32_e32 v186, 0xffff0000, v186
	v_lshlrev_b32_e32 v217, 16, v187
	v_and_b32_e32 v187, 0xffff0000, v187
	v_fmac_f32_e32 v78, s44, v216
	v_fmac_f32_e32 v79, s44, v186
	v_fmac_f32_e32 v80, s44, v217
	v_fmac_f32_e32 v81, s44, v187
	v_mov_b32_dpp v220, v78 quad_perm:[1,0,3,2] row_mask:0xf bank_mask:0xf
	v_mov_b32_dpp v221, v79 quad_perm:[1,0,3,2] row_mask:0xf bank_mask:0xf
	v_mov_b32_dpp v222, v80 quad_perm:[1,0,3,2] row_mask:0xf bank_mask:0xf
	v_mov_b32_dpp v223, v81 quad_perm:[1,0,3,2] row_mask:0xf bank_mask:0xf
	v_mov_b32_dpp v224, v110 quad_perm:[1,0,3,2] row_mask:0xf bank_mask:0xf
	v_mov_b32_dpp v225, v111 quad_perm:[1,0,3,2] row_mask:0xf bank_mask:0xf
	v_mov_b32_dpp v226, v112 quad_perm:[1,0,3,2] row_mask:0xf bank_mask:0xf
	v_mov_b32_dpp v227, v113 quad_perm:[1,0,3,2] row_mask:0xf bank_mask:0xf
	v_cndmask_b32_e32 v78, v224, v78, vcc
	v_cndmask_b32_e32 v79, v225, v79, vcc
	v_cndmask_b32_e32 v80, v226, v80, vcc
	v_cndmask_b32_e32 v81, v227, v81, vcc
	v_cndmask_b32_e32 v110, v110, v220, vcc
	v_cndmask_b32_e32 v111, v111, v221, vcc
	v_cndmask_b32_e32 v112, v112, v222, vcc
	v_cndmask_b32_e32 v113, v113, v223, vcc
	global_store_dwordx4 v[140:141], v[110:113], off
	global_store_dwordx4 v[142:143], v[78:81], off
	s_waitcnt vmcnt(24)
	v_permlane16_swap_b32_e32 v188, v190
	v_permlane16_swap_b32_e32 v189, v191
	v_lshlrev_b32_e32 v216, 16, v188
	v_and_b32_e32 v188, 0xffff0000, v188
	v_lshlrev_b32_e32 v217, 16, v189
	v_and_b32_e32 v189, 0xffff0000, v189
	v_fmac_f32_e32 v46, s44, v216
	v_fmac_f32_e32 v47, s44, v188
	v_fmac_f32_e32 v48, s44, v217
	v_fmac_f32_e32 v49, s44, v189
	v_lshlrev_b32_e32 v216, 16, v190
	v_and_b32_e32 v190, 0xffff0000, v190
	v_lshlrev_b32_e32 v217, 16, v191
	v_and_b32_e32 v191, 0xffff0000, v191
	v_fmac_f32_e32 v14, s44, v216
	v_fmac_f32_e32 v15, s44, v190
	v_fmac_f32_e32 v16, s44, v217
	v_fmac_f32_e32 v17, s44, v191
	v_mov_b32_dpp v220, v14 quad_perm:[1,0,3,2] row_mask:0xf bank_mask:0xf
	v_mov_b32_dpp v221, v15 quad_perm:[1,0,3,2] row_mask:0xf bank_mask:0xf
	v_mov_b32_dpp v222, v16 quad_perm:[1,0,3,2] row_mask:0xf bank_mask:0xf
	v_mov_b32_dpp v223, v17 quad_perm:[1,0,3,2] row_mask:0xf bank_mask:0xf
	v_mov_b32_dpp v224, v46 quad_perm:[1,0,3,2] row_mask:0xf bank_mask:0xf
	v_mov_b32_dpp v225, v47 quad_perm:[1,0,3,2] row_mask:0xf bank_mask:0xf
	v_mov_b32_dpp v226, v48 quad_perm:[1,0,3,2] row_mask:0xf bank_mask:0xf
	v_mov_b32_dpp v227, v49 quad_perm:[1,0,3,2] row_mask:0xf bank_mask:0xf
	v_cndmask_b32_e32 v14, v224, v14, vcc
	v_cndmask_b32_e32 v15, v225, v15, vcc
	v_cndmask_b32_e32 v16, v226, v16, vcc
	v_cndmask_b32_e32 v17, v227, v17, vcc
	v_cndmask_b32_e32 v46, v46, v220, vcc
	v_cndmask_b32_e32 v47, v47, v221, vcc
	v_cndmask_b32_e32 v48, v48, v222, vcc
	v_cndmask_b32_e32 v49, v49, v223, vcc
	global_store_dwordx4 v[140:141], v[46:49], off offset:128
	global_store_dwordx4 v[142:143], v[14:17], off offset:128
	v_lshl_add_u64 v[140:141], v[140:141], 0, s[10:11]
	v_lshl_add_u64 v[142:143], v[142:143], 0, s[10:11]
	s_waitcnt vmcnt(25)
; DEVI float blo(unsigned u) { return __uint_as_float(u << 16); }
; DEVI float bhi(unsigned u) { return __uint_as_float(u & 0xffff0000u); }
;     ...
; #pragma unroll
;       for (int nf = 0; nf < 4; nf++) {
;         const int col = n0 + wn * 64 + nf * 16 + quad * 4;
;         f32x4 a = acc[nf][mf];
;         if (EPI == EPI_RESID || EPI == EPI_RESID_ATOMIC) {
;           f32x4 x = a;
;           if (EPI == EPI_RESID || kpart == 0) {
;             const u32x2 xr = *(const u32x2*)((const u16*)(p.ws + WS_XB) + (size_t)row * 1024 + col);
;             x[0] += ALPHA * blo(xr[0]); x[1] += ALPHA * bhi(xr[0]); x[2] += ALPHA * blo(xr[1]); x[3] += ALPHA * bhi(xr[1]);
;           }
;           if (EPI == EPI_RESID) *(f32x4*)((float*)(p.ws + WS_XF) + (size_t)row * 1024 + col) = x;
;           else *(f32x4*)((float*)(p.ws + WS_SLAB) + ((size_t)kpart * 512 + (row - T_P)) * 1024 + col) = x;
	v_permlane16_swap_b32_e32 v192, v194
	v_permlane16_swap_b32_e32 v193, v195
	v_lshlrev_b32_e32 v216, 16, v192
	v_and_b32_e32 v192, 0xffff0000, v192
	v_lshlrev_b32_e32 v217, 16, v193
	v_and_b32_e32 v193, 0xffff0000, v193
	v_fmac_f32_e32 v106, s44, v216
	v_fmac_f32_e32 v107, s44, v192
	v_fmac_f32_e32 v108, s44, v217
	v_fmac_f32_e32 v109, s44, v193
	v_lshlrev_b32_e32 v216, 16, v194
	v_and_b32_e32 v194, 0xffff0000, v194
	v_lshlrev_b32_e32 v217, 16, v195
	v_and_b32_e32 v195, 0xffff0000, v195
	v_fmac_f32_e32 v74, s44, v216
	v_fmac_f32_e32 v75, s44, v194
	v_fmac_f32_e32 v76, s44, v217
	v_fmac_f32_e32 v77, s44, v195
	v_mov_b32_dpp v220, v74 quad_perm:[1,0,3,2] row_mask:0xf bank_mask:0xf
	v_mov_b32_dpp v221, v75 quad_perm:[1,0,3,2] row_mask:0xf bank_mask:0xf
	v_mov_b32_dpp v222, v76 quad_perm:[1,0,3,2] row_mask:0xf bank_mask:0xf
	v_mov_b32_dpp v223, v77 quad_perm:[1,0,3,2] row_mask:0xf bank_mask:0xf
	v_mov_b32_dpp v224, v106 quad_perm:[1,0,3,2] row_mask:0xf bank_mask:0xf
	v_mov_b32_dpp v225, v107 quad_perm:[1,0,3,2] row_mask:0xf bank_mask:0xf
	v_mov_b32_dpp v226, v108 quad_perm:[1,0,3,2] row_mask:0xf bank_mask:0xf
	v_mov_b32_dpp v227, v109 quad_perm:[1,0,3,2] row_mask:0xf bank_mask:0xf
	v_cndmask_b32_e32 v74, v224, v74, vcc
	v_cndmask_b32_e32 v75, v225, v75, vcc
	v_cndmask_b32_e32 v76, v226, v76, vcc
	v_cndmask_b32_e32 v77, v227, v77, vcc
	v_cndmask_b32_e32 v106, v106, v220, vcc
	v_cndmask_b32_e32 v107, v107, v221, vcc
	v_cndmask_b32_e32 v108, v108, v222, vcc
	v_cndmask_b32_e32 v109, v109, v223, vcc
	global_store_dwordx4 v[140:141], v[106:109], off
	global_store_dwordx4 v[142:143], v[74:77], off
	s_waitcnt vmcnt(26)
	v_permlane16_swap_b32_e32 v196, v198
	v_permlane16_swap_b32_e32 v197, v199
	v_lshlrev_b32_e32 v216, 16, v196
	v_and_b32_e32 v196, 0xffff0000, v196
	v_lshlrev_b32_e32 v217, 16, v197
	v_and_b32_e32 v197, 0xffff0000, v197
	v_fmac_f32_e32 v42, s44, v216
	v_fmac_f32_e32 v43, s44, v196
	v_fmac_f32_e32 v44, s44, v217
	v_fmac_f32_e32 v45, s44, v197
	v_lshlrev_b32_e32 v216, 16, v198
	v_and_b32_e32 v198, 0xffff0000, v198
	v_lshlrev_b32_e32 v217, 16, v199
	v_and_b32_e32 v199, 0xffff0000, v199
	v_fmac_f32_e32 v10, s44, v216
	v_fmac_f32_e32 v11, s44, v198
	v_fmac_f32_e32 v12, s44, v217
	v_fmac_f32_e32 v13, s44, v199
	v_mov_b32_dpp v220, v10 quad_perm:[1,0,3,2] row_mask:0xf bank_mask:0xf
	v_mov_b32_dpp v221, v11 quad_perm:[1,0,3,2] row_mask:0xf bank_mask:0xf
	v_mov_b32_dpp v222, v12 quad_perm:[1,0,3,2] row_mask:0xf bank_mask:0xf
	v_mov_b32_dpp v223, v13 quad_perm:[1,0,3,2] row_mask:0xf bank_mask:0xf
	v_mov_b32_dpp v224, v42 quad_perm:[1,0,3,2] row_mask:0xf bank_mask:0xf
	v_mov_b32_dpp v225, v43 quad_perm:[1,0,3,2] row_mask:0xf bank_mask:0xf
	v_mov_b32_dpp v226, v44 quad_perm:[1,0,3,2] row_mask:0xf bank_mask:0xf
	v_mov_b32_dpp v227, v45 quad_perm:[1,0,3,2] row_mask:0xf bank_mask:0xf
	v_cndmask_b32_e32 v10, v224, v10, vcc
	v_cndmask_b32_e32 v11, v225, v11, vcc
	v_cndmask_b32_e32 v12, v226, v12, vcc
	v_cndmask_b32_e32 v13, v227, v13, vcc
	v_cndmask_b32_e32 v42, v42, v220, vcc
	v_cndmask_b32_e32 v43, v43, v221, vcc
	v_cndmask_b32_e32 v44, v44, v222, vcc
	v_cndmask_b32_e32 v45, v45, v223, vcc
	global_store_dwordx4 v[140:141], v[42:45], off offset:128
	global_store_dwordx4 v[142:143], v[10:13], off offset:128
	v_lshl_add_u64 v[140:141], v[140:141], 0, s[10:11]
	v_lshl_add_u64 v[142:143], v[142:143], 0, s[10:11]
	s_waitcnt vmcnt(27)
	v_permlane16_swap_b32_e32 v200, v202
	v_permlane16_swap_b32_e32 v201, v203
	v_lshlrev_b32_e32 v216, 16, v200
	v_and_b32_e32 v200, 0xffff0000, v200
	v_lshlrev_b32_e32 v217, 16, v201
	v_and_b32_e32 v201, 0xffff0000, v201
	v_fmac_f32_e32 v102, s44, v216
	v_fmac_f32_e32 v103, s44, v200
	v_fmac_f32_e32 v104, s44, v217
	v_fmac_f32_e32 v105, s44, v201
	v_lshlrev_b32_e32 v216, 16, v202
	v_and_b32_e32 v202, 0xffff0000, v202
	v_lshlrev_b32_e32 v217, 16, v203
	v_and_b32_e32 v203, 0xffff0000, v203
	v_fmac_f32_e32 v70, s44, v216
	v_fmac_f32_e32 v71, s44, v202
	v_fmac_f32_e32 v72, s44, v217
	v_fmac_f32_e32 v73, s44, v203
	v_mov_b32_dpp v220, v70 quad_perm:[1,0,3,2] row_mask:0xf bank_mask:0xf
	v_mov_b32_dpp v221, v71 quad_perm:[1,0,3,2] row_mask:0xf bank_mask:0xf
	v_mov_b32_dpp v222, v72 quad_perm:[1,0,3,2] row_mask:0xf bank_mask:0xf
	v_mov_b32_dpp v223, v73 quad_perm:[1,0,3,2] row_mask:0xf bank_mask:0xf
	v_mov_b32_dpp v224, v102 quad_perm:[1,0,3,2] row_mask:0xf bank_mask:0xf
	v_mov_b32_dpp v225, v103 quad_perm:[1,0,3,2] row_mask:0xf bank_mask:0xf
	v_mov_b32_dpp v226, v104 quad_perm:[1,0,3,2] row_mask:0xf bank_mask:0xf
	v_mov_b32_dpp v227, v105 quad_perm:[1,0,3,2] row_mask:0xf bank_mask:0xf
	v_cndmask_b32_e32 v70, v224, v70, vcc
	v_cndmask_b32_e32 v71, v225, v71, vcc
	v_cndmask_b32_e32 v72, v226, v72, vcc
	v_cndmask_b32_e32 v73, v227, v73, vcc
	v_cndmask_b32_e32 v102, v102, v220, vcc
	v_cndmask_b32_e32 v103, v103, v221, vcc
	v_cndmask_b32_e32 v104, v104, v222, vcc
	v_cndmask_b32_e32 v105, v105, v223, vcc
	global_store_dwordx4 v[140:141], v[102:105], off
	global_store_dwordx4 v[142:143], v[70:73], off
	s_waitcnt vmcnt(28)
; DEVI float blo(unsigned u) { return __uint_as_float(u << 16); }
; DEVI float bhi(unsigned u) { return __uint_as_float(u & 0xffff0000u); }
; DEVI int xcd_first_tile() { return (blockIdx.x & 7) * (gridDim.x >> 3) + (blockIdx.x >> 3); }
;     ...
; #pragma unroll
;       for (int nf = 0; nf < 4; nf++) {
;         const int col = n0 + wn * 64 + nf * 16 + quad * 4;
;         f32x4 a = acc[nf][mf];
;         if (EPI == EPI_RESID || EPI == EPI_RESID_ATOMIC) {
;           f32x4 x = a;
;           if (EPI == EPI_RESID || kpart == 0) {
;             const u32x2 xr = *(const u32x2*)((const u16*)(p.ws + WS_XB) + (size_t)row * 1024 + col);
;             x[0] += ALPHA * blo(xr[0]); x[1] += ALPHA * bhi(xr[0]); x[2] += ALPHA * blo(xr[1]); x[3] += ALPHA * bhi(xr[1]);
;           }
;           if (EPI == EPI_RESID) *(f32x4*)((float*)(p.ws + WS_XF) + (size_t)row * 1024 + col) = x;
;           else *(f32x4*)((float*)(p.ws + WS_SLAB) + ((size_t)kpart * 512 + (row - T_P)) * 1024 + col) = x;
; DEVI void run_phase(const Params& p, int ph, char* smem) {
;     ...
;       for (int t = xcd_first_tile(); t < 512 + 16 * 11; t += xcd_tile_step()) {
;         if (t < 512) {
;           int mt_, nt_; tile_coords(t, 64, 8, mt_, nt_);
;           gemm_tile256<EPI_RESID>(p, hb, DFF, Bt, DFF, mt_ * 256, nt_ * 128, nullptr, 0, smem);
	v_permlane16_swap_b32_e32 v204, v206
	v_permlane16_swap_b32_e32 v205, v207
	v_lshlrev_b32_e32 v216, 16, v204
	v_and_b32_e32 v204, 0xffff0000, v204
	v_lshlrev_b32_e32 v217, 16, v205
	v_and_b32_e32 v205, 0xffff0000, v205
	v_fmac_f32_e32 v38, s44, v216
	v_fmac_f32_e32 v39, s44, v204
	v_fmac_f32_e32 v40, s44, v217
	v_fmac_f32_e32 v41, s44, v205
	v_lshlrev_b32_e32 v216, 16, v206
	v_and_b32_e32 v206, 0xffff0000, v206
	v_lshlrev_b32_e32 v217, 16, v207
	v_and_b32_e32 v207, 0xffff0000, v207
	v_fmac_f32_e32 v6, s44, v216
	v_fmac_f32_e32 v7, s44, v206
	v_fmac_f32_e32 v8, s44, v217
	v_fmac_f32_e32 v9, s44, v207
	v_mov_b32_dpp v220, v6 quad_perm:[1,0,3,2] row_mask:0xf bank_mask:0xf
	v_mov_b32_dpp v221, v7 quad_perm:[1,0,3,2] row_mask:0xf bank_mask:0xf
	v_mov_b32_dpp v222, v8 quad_perm:[1,0,3,2] row_mask:0xf bank_mask:0xf
	v_mov_b32_dpp v223, v9 quad_perm:[1,0,3,2] row_mask:0xf bank_mask:0xf
	v_mov_b32_dpp v224, v38 quad_perm:[1,0,3,2] row_mask:0xf bank_mask:0xf
	v_mov_b32_dpp v225, v39 quad_perm:[1,0,3,2] row_mask:0xf bank_mask:0xf
	v_mov_b32_dpp v226, v40 quad_perm:[1,0,3,2] row_mask:0xf bank_mask:0xf
	v_mov_b32_dpp v227, v41 quad_perm:[1,0,3,2] row_mask:0xf bank_mask:0xf
	v_cndmask_b32_e32 v6, v224, v6, vcc
	v_cndmask_b32_e32 v7, v225, v7, vcc
	v_cndmask_b32_e32 v8, v226, v8, vcc
	v_cndmask_b32_e32 v9, v227, v9, vcc
	v_cndmask_b32_e32 v38, v38, v220, vcc
	v_cndmask_b32_e32 v39, v39, v221, vcc
	v_cndmask_b32_e32 v40, v40, v222, vcc
	v_cndmask_b32_e32 v41, v41, v223, vcc
	global_store_dwordx4 v[140:141], v[38:41], off offset:128
	global_store_dwordx4 v[142:143], v[6:9], off offset:128
	v_lshl_add_u64 v[140:141], v[140:141], 0, s[10:11]
	v_lshl_add_u64 v[142:143], v[142:143], 0, s[10:11]
	s_waitcnt vmcnt(29)
	v_permlane16_swap_b32_e32 v208, v210
	v_permlane16_swap_b32_e32 v209, v211
	v_lshlrev_b32_e32 v216, 16, v208
	v_and_b32_e32 v208, 0xffff0000, v208
	v_lshlrev_b32_e32 v217, 16, v209
	v_and_b32_e32 v209, 0xffff0000, v209
	v_fmac_f32_e32 v98, s44, v216
	v_fmac_f32_e32 v99, s44, v208
	v_fmac_f32_e32 v100, s44, v217
	v_fmac_f32_e32 v101, s44, v209
	v_lshlrev_b32_e32 v216, 16, v210
	v_and_b32_e32 v210, 0xffff0000, v210
	v_lshlrev_b32_e32 v217, 16, v211
	v_and_b32_e32 v211, 0xffff0000, v211
	v_fmac_f32_e32 v66, s44, v216
	v_fmac_f32_e32 v67, s44, v210
	v_fmac_f32_e32 v68, s44, v217
	v_fmac_f32_e32 v69, s44, v211
	v_mov_b32_dpp v220, v66 quad_perm:[1,0,3,2] row_mask:0xf bank_mask:0xf
	v_mov_b32_dpp v221, v67 quad_perm:[1,0,3,2] row_mask:0xf bank_mask:0xf
	v_mov_b32_dpp v222, v68 quad_perm:[1,0,3,2] row_mask:0xf bank_mask:0xf
	v_mov_b32_dpp v223, v69 quad_perm:[1,0,3,2] row_mask:0xf bank_mask:0xf
	v_mov_b32_dpp v224, v98 quad_perm:[1,0,3,2] row_mask:0xf bank_mask:0xf
	v_mov_b32_dpp v225, v99 quad_perm:[1,0,3,2] row_mask:0xf bank_mask:0xf
	v_mov_b32_dpp v226, v100 quad_perm:[1,0,3,2] row_mask:0xf bank_mask:0xf
	v_mov_b32_dpp v227, v101 quad_perm:[1,0,3,2] row_mask:0xf bank_mask:0xf
	v_cndmask_b32_e32 v66, v224, v66, vcc
	v_cndmask_b32_e32 v67, v225, v67, vcc
	v_cndmask_b32_e32 v68, v226, v68, vcc
	v_cndmask_b32_e32 v69, v227, v69, vcc
	v_cndmask_b32_e32 v98, v98, v220, vcc
	v_cndmask_b32_e32 v99, v99, v221, vcc
	v_cndmask_b32_e32 v100, v100, v222, vcc
	v_cndmask_b32_e32 v101, v101, v223, vcc
	global_store_dwordx4 v[140:141], v[98:101], off
	global_store_dwordx4 v[142:143], v[66:69], off
	s_waitcnt vmcnt(30)
	v_permlane16_swap_b32_e32 v212, v214
	v_permlane16_swap_b32_e32 v213, v215
	v_lshlrev_b32_e32 v216, 16, v212
	v_and_b32_e32 v212, 0xffff0000, v212
	v_lshlrev_b32_e32 v217, 16, v213
	v_and_b32_e32 v213, 0xffff0000, v213
	v_fmac_f32_e32 v34, s44, v216
	v_fmac_f32_e32 v35, s44, v212
	v_fmac_f32_e32 v36, s44, v217
	v_fmac_f32_e32 v37, s44, v213
	v_lshlrev_b32_e32 v216, 16, v214
	v_and_b32_e32 v214, 0xffff0000, v214
	v_lshlrev_b32_e32 v217, 16, v215
	v_and_b32_e32 v215, 0xffff0000, v215
	v_fmac_f32_e32 v2, s44, v216
	v_fmac_f32_e32 v3, s44, v214
	v_fmac_f32_e32 v4, s44, v217
	v_fmac_f32_e32 v5, s44, v215
	v_mov_b32_dpp v220, v2 quad_perm:[1,0,3,2] row_mask:0xf bank_mask:0xf
	v_mov_b32_dpp v221, v3 quad_perm:[1,0,3,2] row_mask:0xf bank_mask:0xf
	v_mov_b32_dpp v222, v4 quad_perm:[1,0,3,2] row_mask:0xf bank_mask:0xf
	v_mov_b32_dpp v223, v5 quad_perm:[1,0,3,2] row_mask:0xf bank_mask:0xf
	v_mov_b32_dpp v224, v34 quad_perm:[1,0,3,2] row_mask:0xf bank_mask:0xf
	v_mov_b32_dpp v225, v35 quad_perm:[1,0,3,2] row_mask:0xf bank_mask:0xf
	v_mov_b32_dpp v226, v36 quad_perm:[1,0,3,2] row_mask:0xf bank_mask:0xf
	v_mov_b32_dpp v227, v37 quad_perm:[1,0,3,2] row_mask:0xf bank_mask:0xf
	v_cndmask_b32_e32 v2, v224, v2, vcc
	v_cndmask_b32_e32 v3, v225, v3, vcc
	v_cndmask_b32_e32 v4, v226, v4, vcc
	v_cndmask_b32_e32 v5, v227, v5, vcc
	v_cndmask_b32_e32 v34, v34, v220, vcc
	v_cndmask_b32_e32 v35, v35, v221, vcc
	v_cndmask_b32_e32 v36, v36, v222, vcc
	v_cndmask_b32_e32 v37, v37, v223, vcc
	global_store_dwordx4 v[140:141], v[34:37], off offset:128
	global_store_dwordx4 v[142:143], v[2:5], off offset:128
	v_readlane_b32 s39, v250, 7
	s_cmpk_lg_u32 s39, 0x200
	s_cbranch_scc1 .LBB0_41
	v_readlane_b32 s40, v250, 0
	s_lshr_b32 s41, s40, 3
	s_and_b32 s40, s40, 7
	s_mul_i32 s40, s40, 22
	s_add_i32 s40, s40, s41
	s_cmp_lt_u32 s41, 22
	s_movk_i32 s38, 0x4000
	s_branch .LBB0_41

;     ...
;   for (int kt = 0; kt < nk; kt++) {
;     if (kt + 1 < nk) asm volatile("s_waitcnt vmcnt(6)" ::: "memory");
;     else asm volatile("s_waitcnt vmcnt(0)" ::: "memory");
;     __builtin_amdgcn_s_barrier();
;     asm volatile("" ::: "memory");
;     if (kt + 2 < nk) G2_STAGE(kt + 2);
;     const char* cS = smem + (kt % 3) * 24576;
;     bf16x8 xa[8], wb[4];
; #pragma unroll
;     for (int f = 0; f < 8; f++) xa[f] = *(const bf16x8*)(cS + aoff + f * 1024);
; #pragma unroll
;     for (int f = 0; f < 4; f++) wb[f] = *(const bf16x8*)(cS + boff + f * 1024);
; #pragma unroll
;     for (int nf = 0; nf < 4; nf++)
; #pragma unroll
;       for (int mf = 0; mf < 8; mf++)
;         acc[nf][mf] = __builtin_amdgcn_mfma_f32_16x16x32_bf16(wb[nf], xa[mf], acc[nf][mf], 0, 0, 0);
;   }
.Lt10_loop:
	.p2align 3
	s_waitcnt vmcnt(6) lgkmcnt(0)
	s_barrier
	s_setprio 1
	v_add_u32_e32 v144, s36, v136
	v_mfma_f32_16x16x32_bf16 v[126:129], v[184:187], v[146:149], v[126:129]
	ds_read_b128 v[200:203], v144 offset:0
	v_mfma_f32_16x16x32_bf16 v[122:125], v[184:187], v[152:155], v[122:125]
	ds_read_b128 v[204:207], v144 offset:1024
	v_mfma_f32_16x16x32_bf16 v[118:121], v[184:187], v[156:159], v[118:121]
	ds_read_b128 v[208:211], v144 offset:2048
	v_mfma_f32_16x16x32_bf16 v[114:117], v[184:187], v[162:165], v[114:117]
	ds_read_b128 v[212:215], v144 offset:3072
	v_mfma_f32_16x16x32_bf16 v[110:113], v[184:187], v[166:169], v[110:113]
	ds_read_b128 v[216:219], v144 offset:4096
	v_mfma_f32_16x16x32_bf16 v[106:109], v[184:187], v[170:173], v[106:109]
	ds_read_b128 v[220:223], v144 offset:5120
	v_mfma_f32_16x16x32_bf16 v[102:105], v[184:187], v[176:179], v[102:105]
	ds_read_b128 v[224:227], v144 offset:6144
	v_mfma_f32_16x16x32_bf16 v[98:101], v[184:187], v[180:183], v[98:101]
	ds_read_b128 v[228:231], v144 offset:7168
	v_mfma_f32_16x16x32_bf16 v[94:97], v[188:191], v[146:149], v[94:97]
	v_add_u32_e64 v144, s36, v137
	v_mfma_f32_16x16x32_bf16 v[90:93], v[188:191], v[152:155], v[90:93]
	v_mfma_f32_16x16x32_bf16 v[86:89], v[188:191], v[156:159], v[86:89]
	ds_read_b128 v[232:235], v144 offset:16384
	v_mfma_f32_16x16x32_bf16 v[82:85], v[188:191], v[162:165], v[82:85]
	ds_read_b128 v[236:239], v144 offset:17408
	v_mfma_f32_16x16x32_bf16 v[78:81], v[188:191], v[166:169], v[78:81]
	ds_read_b128 v[240:243], v144 offset:18432
	v_mfma_f32_16x16x32_bf16 v[74:77], v[188:191], v[170:173], v[74:77]
	ds_read_b128 v[244:247], v144 offset:19456
	v_mfma_f32_16x16x32_bf16 v[70:73], v[188:191], v[176:179], v[70:73]
	s_add_i32 s38, s43, s37
	s_mov_b32 m0, s38
	v_lshl_add_u64 v[142:143], v[132:133], 0, s[2:3]
	v_mfma_f32_16x16x32_bf16 v[66:69], v[188:191], v[180:183], v[66:69]
	global_load_lds_dwordx4 v[132:133], off
	s_add_i32 m0, m0, 0x1000
	v_mfma_f32_16x16x32_bf16 v[62:65], v[192:195], v[146:149], v[62:65]
	v_mfma_f32_16x16x32_bf16 v[58:61], v[192:195], v[152:155], v[58:61]
	v_mfma_f32_16x16x32_bf16 v[54:57], v[192:195], v[156:159], v[54:57]
	global_load_lds_dwordx4 v[142:143], off
	v_lshl_add_u64 v[142:143], v[142:143], 0, s[2:3]
	s_add_i32 m0, m0, 0x1000
	v_mfma_f32_16x16x32_bf16 v[50:53], v[192:195], v[162:165], v[50:53]
	v_mfma_f32_16x16x32_bf16 v[46:49], v[192:195], v[166:169], v[46:49]
	v_mfma_f32_16x16x32_bf16 v[42:45], v[192:195], v[170:173], v[42:45]
	global_load_lds_dwordx4 v[142:143], off
	v_lshl_add_u64 v[142:143], v[142:143], 0, s[2:3]
	s_add_i32 m0, m0, 0x1000
	v_mfma_f32_16x16x32_bf16 v[38:41], v[192:195], v[176:179], v[38:41]
	v_mfma_f32_16x16x32_bf16 v[34:37], v[192:195], v[180:183], v[34:37]
	s_setprio 0
	s_nop 0
	v_mfma_f32_16x16x32_bf16 v[30:33], v[196:199], v[146:149], v[30:33]
	global_load_lds_dwordx4 v[142:143], off
	s_add_i32 m0, m0, 0x1000
	v_lshl_add_u64 v[142:143], v[134:135], 0, s[2:3]
	v_mfma_f32_16x16x32_bf16 v[26:29], v[196:199], v[152:155], v[26:29]
	v_mfma_f32_16x16x32_bf16 v[22:25], v[196:199], v[156:159], v[22:25]
	v_mfma_f32_16x16x32_bf16 v[18:21], v[196:199], v[162:165], v[18:21]
	global_load_lds_dwordx4 v[134:135], off
	s_add_i32 m0, m0, 0x1000
	v_lshl_add_u64 v[132:133], v[132:133], 0, s[14:15]
	v_mfma_f32_16x16x32_bf16 v[14:17], v[196:199], v[166:169], v[14:17]
	v_mfma_f32_16x16x32_bf16 v[10:13], v[196:199], v[170:173], v[10:13]
	v_mfma_f32_16x16x32_bf16 v[6:9], v[196:199], v[176:179], v[6:9]
	global_load_lds_dwordx4 v[142:143], off
	v_lshl_add_u64 v[134:135], v[134:135], 0, s[10:11]
	v_mfma_f32_16x16x32_bf16 v[2:5], v[196:199], v[180:183], v[2:5]
	s_mov_b32 s37, s36
	s_nop 0
	s_add_i32 s36, s36, 0x6000
	s_cmp_eq_u32 s36, 0x12000
	s_cselect_b32 s36, 0, s36
	s_nop 0
	.p2align 3
	s_waitcnt vmcnt(6) lgkmcnt(0)
	s_barrier
	s_setprio 1
	v_add_u32_e32 v144, s36, v136
	v_mfma_f32_16x16x32_bf16 v[126:129], v[232:235], v[200:203], v[126:129]
	ds_read_b128 v[146:149], v144 offset:0
	v_mfma_f32_16x16x32_bf16 v[122:125], v[232:235], v[204:207], v[122:125]
	ds_read_b128 v[152:155], v144 offset:1024
	v_mfma_f32_16x16x32_bf16 v[118:121], v[232:235], v[208:211], v[118:121]
	ds_read_b128 v[156:159], v144 offset:2048
	v_mfma_f32_16x16x32_bf16 v[114:117], v[232:235], v[212:215], v[114:117]
	ds_read_b128 v[162:165], v144 offset:3072
	v_mfma_f32_16x16x32_bf16 v[110:113], v[232:235], v[216:219], v[110:113]
	ds_read_b128 v[166:169], v144 offset:4096
	v_mfma_f32_16x16x32_bf16 v[106:109], v[232:235], v[220:223], v[106:109]
	ds_read_b128 v[170:173], v144 offset:5120
	v_mfma_f32_16x16x32_bf16 v[102:105], v[232:235], v[224:227], v[102:105]
	ds_read_b128 v[176:179], v144 offset:6144
	v_mfma_f32_16x16x32_bf16 v[98:101], v[232:235], v[228:231], v[98:101]
	ds_read_b128 v[180:183], v144 offset:7168
	v_mfma_f32_16x16x32_bf16 v[94:97], v[236:239], v[200:203], v[94:97]
	v_add_u32_e64 v144, s36, v137
	v_mfma_f32_16x16x32_bf16 v[90:93], v[236:239], v[204:207], v[90:93]
	v_mfma_f32_16x16x32_bf16 v[86:89], v[236:239], v[208:211], v[86:89]
	ds_read_b128 v[184:187], v144 offset:16384
	v_mfma_f32_16x16x32_bf16 v[82:85], v[236:239], v[212:215], v[82:85]
	ds_read_b128 v[188:191], v144 offset:17408
	v_mfma_f32_16x16x32_bf16 v[78:81], v[236:239], v[216:219], v[78:81]
	ds_read_b128 v[192:195], v144 offset:18432
	v_mfma_f32_16x16x32_bf16 v[74:77], v[236:239], v[220:223], v[74:77]
	ds_read_b128 v[196:199], v144 offset:19456
	v_mfma_f32_16x16x32_bf16 v[70:73], v[236:239], v[224:227], v[70:73]
	s_add_i32 s38, s43, s37
	s_mov_b32 m0, s38
	v_lshl_add_u64 v[142:143], v[132:133], 0, s[2:3]
	v_mfma_f32_16x16x32_bf16 v[66:69], v[236:239], v[228:231], v[66:69]
;     ...
;   for (int kt = 0; kt < nk; kt++) {
;     if (kt + 1 < nk) asm volatile("s_waitcnt vmcnt(6)" ::: "memory");
;     else asm volatile("s_waitcnt vmcnt(0)" ::: "memory");
;     __builtin_amdgcn_s_barrier();
;     asm volatile("" ::: "memory");
;     if (kt + 2 < nk) G2_STAGE(kt + 2);
;     const char* cS = smem + (kt % 3) * 24576;
;     bf16x8 xa[8], wb[4];
; #pragma unroll
;     for (int f = 0; f < 8; f++) xa[f] = *(const bf16x8*)(cS + aoff + f * 1024);
; #pragma unroll
;     for (int f = 0; f < 4; f++) wb[f] = *(const bf16x8*)(cS + boff + f * 1024);
; #pragma unroll
;     for (int nf = 0; nf < 4; nf++)
; #pragma unroll
;       for (int mf = 0; mf < 8; mf++)
;         acc[nf][mf] = __builtin_amdgcn_mfma_f32_16x16x32_bf16(wb[nf], xa[mf], acc[nf][mf], 0, 0, 0);
;   }
	global_load_lds_dwordx4 v[132:133], off
	s_add_i32 m0, m0, 0x1000
	v_mfma_f32_16x16x32_bf16 v[62:65], v[240:243], v[200:203], v[62:65]
	v_mfma_f32_16x16x32_bf16 v[58:61], v[240:243], v[204:207], v[58:61]
	v_mfma_f32_16x16x32_bf16 v[54:57], v[240:243], v[208:211], v[54:57]
	global_load_lds_dwordx4 v[142:143], off
	v_lshl_add_u64 v[142:143], v[142:143], 0, s[2:3]
	s_add_i32 m0, m0, 0x1000
	v_mfma_f32_16x16x32_bf16 v[50:53], v[240:243], v[212:215], v[50:53]
	v_mfma_f32_16x16x32_bf16 v[46:49], v[240:243], v[216:219], v[46:49]
	v_mfma_f32_16x16x32_bf16 v[42:45], v[240:243], v[220:223], v[42:45]
	global_load_lds_dwordx4 v[142:143], off
	v_lshl_add_u64 v[142:143], v[142:143], 0, s[2:3]
	s_add_i32 m0, m0, 0x1000
	v_mfma_f32_16x16x32_bf16 v[38:41], v[240:243], v[224:227], v[38:41]
	v_mfma_f32_16x16x32_bf16 v[34:37], v[240:243], v[228:231], v[34:37]
	s_setprio 0
	s_nop 0
	v_mfma_f32_16x16x32_bf16 v[30:33], v[244:247], v[200:203], v[30:33]
	global_load_lds_dwordx4 v[142:143], off
	s_add_i32 m0, m0, 0x1000
	v_lshl_add_u64 v[142:143], v[134:135], 0, s[2:3]
	v_mfma_f32_16x16x32_bf16 v[26:29], v[244:247], v[204:207], v[26:29]
	v_mfma_f32_16x16x32_bf16 v[22:25], v[244:247], v[208:211], v[22:25]
	v_mfma_f32_16x16x32_bf16 v[18:21], v[244:247], v[212:215], v[18:21]
	global_load_lds_dwordx4 v[134:135], off
	s_add_i32 m0, m0, 0x1000
	v_lshl_add_u64 v[132:133], v[132:133], 0, s[14:15]
	v_mfma_f32_16x16x32_bf16 v[14:17], v[244:247], v[216:219], v[14:17]
	v_mfma_f32_16x16x32_bf16 v[10:13], v[244:247], v[220:223], v[10:13]
	v_mfma_f32_16x16x32_bf16 v[6:9], v[244:247], v[224:227], v[6:9]
	global_load_lds_dwordx4 v[142:143], off
	v_lshl_add_u64 v[134:135], v[134:135], 0, s[10:11]
	v_mfma_f32_16x16x32_bf16 v[2:5], v[244:247], v[228:231], v[2:5]
	s_mov_b32 s37, s36
	s_nop 0
	s_add_i32 s36, s36, 0x6000
	s_cmp_eq_u32 s36, 0x12000
	s_cselect_b32 s36, 0, s36
	s_nop 0
	s_sub_i32 s9, s9, 1
	s_cmp_lg_u32 s9, 0
	s_cbranch_scc1 .Lt10_loop
	.p2align 3
	s_waitcnt vmcnt(6) lgkmcnt(0)
	s_barrier
	s_setprio 1
	v_add_u32_e32 v144, s36, v136
	v_mfma_f32_16x16x32_bf16 v[126:129], v[184:187], v[146:149], v[126:129]
	ds_read_b128 v[200:203], v144 offset:0
	v_mfma_f32_16x16x32_bf16 v[122:125], v[184:187], v[152:155], v[122:125]
	ds_read_b128 v[204:207], v144 offset:1024
	v_mfma_f32_16x16x32_bf16 v[118:121], v[184:187], v[156:159], v[118:121]
	ds_read_b128 v[208:211], v144 offset:2048
	v_mfma_f32_16x16x32_bf16 v[114:117], v[184:187], v[162:165], v[114:117]
	ds_read_b128 v[212:215], v144 offset:3072
	v_mfma_f32_16x16x32_bf16 v[110:113], v[184:187], v[166:169], v[110:113]
	ds_read_b128 v[216:219], v144 offset:4096
	v_mfma_f32_16x16x32_bf16 v[106:109], v[184:187], v[170:173], v[106:109]
	ds_read_b128 v[220:223], v144 offset:5120
	v_mfma_f32_16x16x32_bf16 v[102:105], v[184:187], v[176:179], v[102:105]
	ds_read_b128 v[224:227], v144 offset:6144
	v_mfma_f32_16x16x32_bf16 v[98:101], v[184:187], v[180:183], v[98:101]
	ds_read_b128 v[228:231], v144 offset:7168
	v_mfma_f32_16x16x32_bf16 v[94:97], v[188:191], v[146:149], v[94:97]
	v_add_u32_e64 v144, s36, v137
	v_mfma_f32_16x16x32_bf16 v[90:93], v[188:191], v[152:155], v[90:93]
	v_mfma_f32_16x16x32_bf16 v[86:89], v[188:191], v[156:159], v[86:89]
	ds_read_b128 v[232:235], v144 offset:16384
	v_mfma_f32_16x16x32_bf16 v[82:85], v[188:191], v[162:165], v[82:85]
	ds_read_b128 v[236:239], v144 offset:17408
	v_mfma_f32_16x16x32_bf16 v[78:81], v[188:191], v[166:169], v[78:81]
	ds_read_b128 v[240:243], v144 offset:18432
	v_mfma_f32_16x16x32_bf16 v[74:77], v[188:191], v[170:173], v[74:77]
	ds_read_b128 v[244:247], v144 offset:19456
	v_mfma_f32_16x16x32_bf16 v[70:73], v[188:191], v[176:179], v[70:73]
	s_add_i32 s38, s43, s37
	s_mov_b32 m0, s38
	v_lshl_add_u64 v[142:143], v[132:133], 0, s[2:3]
	v_mfma_f32_16x16x32_bf16 v[66:69], v[188:191], v[180:183], v[66:69]
	global_load_lds_dwordx4 v[132:133], off
	s_add_i32 m0, m0, 0x1000
	v_mfma_f32_16x16x32_bf16 v[62:65], v[192:195], v[146:149], v[62:65]
	v_mfma_f32_16x16x32_bf16 v[58:61], v[192:195], v[152:155], v[58:61]
	v_mfma_f32_16x16x32_bf16 v[54:57], v[192:195], v[156:159], v[54:57]
	global_load_lds_dwordx4 v[142:143], off
	v_lshl_add_u64 v[142:143], v[142:143], 0, s[2:3]
	s_add_i32 m0, m0, 0x1000
	v_mfma_f32_16x16x32_bf16 v[50:53], v[192:195], v[162:165], v[50:53]
	v_mfma_f32_16x16x32_bf16 v[46:49], v[192:195], v[166:169], v[46:49]
	v_mfma_f32_16x16x32_bf16 v[42:45], v[192:195], v[170:173], v[42:45]
	global_load_lds_dwordx4 v[142:143], off
	v_lshl_add_u64 v[142:143], v[142:143], 0, s[2:3]
	s_add_i32 m0, m0, 0x1000
	v_mfma_f32_16x16x32_bf16 v[38:41], v[192:195], v[176:179], v[38:41]
	v_mfma_f32_16x16x32_bf16 v[34:37], v[192:195], v[180:183], v[34:37]
	s_setprio 0
	s_nop 0
	v_mfma_f32_16x16x32_bf16 v[30:33], v[196:199], v[146:149], v[30:33]
	global_load_lds_dwordx4 v[142:143], off
	s_add_i32 m0, m0, 0x1000
	v_lshl_add_u64 v[142:143], v[134:135], 0, s[2:3]
	v_mfma_f32_16x16x32_bf16 v[26:29], v[196:199], v[152:155], v[26:29]
	v_mfma_f32_16x16x32_bf16 v[22:25], v[196:199], v[156:159], v[22:25]
	v_mfma_f32_16x16x32_bf16 v[18:21], v[196:199], v[162:165], v[18:21]
	global_load_lds_dwordx4 v[134:135], off
	s_add_i32 m0, m0, 0x1000
	v_lshl_add_u64 v[132:133], v[132:133], 0, s[14:15]
	v_mfma_f32_16x16x32_bf16 v[14:17], v[196:199], v[166:169], v[14:17]
	v_mfma_f32_16x16x32_bf16 v[10:13], v[196:199], v[170:173], v[10:13]
	v_mfma_f32_16x16x32_bf16 v[6:9], v[196:199], v[176:179], v[6:9]
	global_load_lds_dwordx4 v[142:143], off
	v_lshl_add_u64 v[134:135], v[134:135], 0, s[10:11]
	v_mfma_f32_16x16x32_bf16 v[2:5], v[196:199], v[180:183], v[2:5]
	s_mov_b32 s37, s36
	s_nop 0
	s_add_i32 s36, s36, 0x6000
	s_cmp_eq_u32 s36, 0x12000
	s_cselect_b32 s36, 0, s36
	s_nop 0
	.p2align 3
	s_waitcnt vmcnt(6) lgkmcnt(0)
	s_barrier
;     ...
;   for (int kt = 0; kt < nk; kt++) {
;     if (kt + 1 < nk) asm volatile("s_waitcnt vmcnt(6)" ::: "memory");
;     else asm volatile("s_waitcnt vmcnt(0)" ::: "memory");
;     __builtin_amdgcn_s_barrier();
;     asm volatile("" ::: "memory");
;     if (kt + 2 < nk) G2_STAGE(kt + 2);
;     const char* cS = smem + (kt % 3) * 24576;
;     bf16x8 xa[8], wb[4];
; #pragma unroll
;     for (int f = 0; f < 8; f++) xa[f] = *(const bf16x8*)(cS + aoff + f * 1024);
; #pragma unroll
;     for (int f = 0; f < 4; f++) wb[f] = *(const bf16x8*)(cS + boff + f * 1024);
; #pragma unroll
;     for (int nf = 0; nf < 4; nf++)
; #pragma unroll
;       for (int mf = 0; mf < 8; mf++)
;         acc[nf][mf] = __builtin_amdgcn_mfma_f32_16x16x32_bf16(wb[nf], xa[mf], acc[nf][mf], 0, 0, 0);
;   }
	s_setprio 1
	v_add_u32_e32 v144, s36, v136
	v_mfma_f32_16x16x32_bf16 v[126:129], v[232:235], v[200:203], v[126:129]
	ds_read_b128 v[146:149], v144 offset:0
	v_mfma_f32_16x16x32_bf16 v[122:125], v[232:235], v[204:207], v[122:125]
	ds_read_b128 v[152:155], v144 offset:1024
	v_mfma_f32_16x16x32_bf16 v[118:121], v[232:235], v[208:211], v[118:121]
	ds_read_b128 v[156:159], v144 offset:2048
	v_mfma_f32_16x16x32_bf16 v[114:117], v[232:235], v[212:215], v[114:117]
	ds_read_b128 v[162:165], v144 offset:3072
	v_mfma_f32_16x16x32_bf16 v[110:113], v[232:235], v[216:219], v[110:113]
	ds_read_b128 v[166:169], v144 offset:4096
	v_mfma_f32_16x16x32_bf16 v[106:109], v[232:235], v[220:223], v[106:109]
	ds_read_b128 v[170:173], v144 offset:5120
	v_mfma_f32_16x16x32_bf16 v[102:105], v[232:235], v[224:227], v[102:105]
	ds_read_b128 v[176:179], v144 offset:6144
	v_mfma_f32_16x16x32_bf16 v[98:101], v[232:235], v[228:231], v[98:101]
	ds_read_b128 v[180:183], v144 offset:7168
	v_mfma_f32_16x16x32_bf16 v[94:97], v[236:239], v[200:203], v[94:97]
	v_add_u32_e64 v144, s36, v137
	v_mfma_f32_16x16x32_bf16 v[90:93], v[236:239], v[204:207], v[90:93]
	v_mfma_f32_16x16x32_bf16 v[86:89], v[236:239], v[208:211], v[86:89]
	ds_read_b128 v[184:187], v144 offset:16384
	v_mfma_f32_16x16x32_bf16 v[82:85], v[236:239], v[212:215], v[82:85]
	ds_read_b128 v[188:191], v144 offset:17408
	v_mfma_f32_16x16x32_bf16 v[78:81], v[236:239], v[216:219], v[78:81]
	ds_read_b128 v[192:195], v144 offset:18432
	v_mfma_f32_16x16x32_bf16 v[74:77], v[236:239], v[220:223], v[74:77]
	ds_read_b128 v[196:199], v144 offset:19456
	v_mfma_f32_16x16x32_bf16 v[70:73], v[236:239], v[224:227], v[70:73]
	v_mfma_f32_16x16x32_bf16 v[66:69], v[236:239], v[228:231], v[66:69]
	v_mfma_f32_16x16x32_bf16 v[62:65], v[240:243], v[200:203], v[62:65]
	v_mfma_f32_16x16x32_bf16 v[58:61], v[240:243], v[204:207], v[58:61]
	v_mfma_f32_16x16x32_bf16 v[54:57], v[240:243], v[208:211], v[54:57]
	v_mfma_f32_16x16x32_bf16 v[50:53], v[240:243], v[212:215], v[50:53]
	v_mfma_f32_16x16x32_bf16 v[46:49], v[240:243], v[216:219], v[46:49]
	v_mfma_f32_16x16x32_bf16 v[42:45], v[240:243], v[220:223], v[42:45]
	v_mfma_f32_16x16x32_bf16 v[38:41], v[240:243], v[224:227], v[38:41]
	v_mfma_f32_16x16x32_bf16 v[34:37], v[240:243], v[228:231], v[34:37]
	s_setprio 0
	s_nop 0
	v_mfma_f32_16x16x32_bf16 v[30:33], v[244:247], v[200:203], v[30:33]
	v_mfma_f32_16x16x32_bf16 v[26:29], v[244:247], v[204:207], v[26:29]
	v_mfma_f32_16x16x32_bf16 v[22:25], v[244:247], v[208:211], v[22:25]
	v_mfma_f32_16x16x32_bf16 v[18:21], v[244:247], v[212:215], v[18:21]
	v_mfma_f32_16x16x32_bf16 v[14:17], v[244:247], v[216:219], v[14:17]
	v_mfma_f32_16x16x32_bf16 v[10:13], v[244:247], v[220:223], v[10:13]
	v_mfma_f32_16x16x32_bf16 v[6:9], v[244:247], v[224:227], v[6:9]
	v_mfma_f32_16x16x32_bf16 v[2:5], v[244:247], v[228:231], v[2:5]
	s_mov_b32 s37, s36
	s_nop 0
	s_add_i32 s36, s36, 0x6000
	s_cmp_eq_u32 s36, 0x12000
	s_cselect_b32 s36, 0, s36
	s_nop 0
	.p2align 3
	s_waitcnt vmcnt(0) lgkmcnt(0)
	s_barrier
	s_setprio 1
	v_add_u32_e32 v144, s36, v136
	v_mfma_f32_16x16x32_bf16 v[126:129], v[184:187], v[146:149], v[126:129]
	ds_read_b128 v[200:203], v144 offset:0
	v_mfma_f32_16x16x32_bf16 v[122:125], v[184:187], v[152:155], v[122:125]
	ds_read_b128 v[204:207], v144 offset:1024
	v_mfma_f32_16x16x32_bf16 v[118:121], v[184:187], v[156:159], v[118:121]
	ds_read_b128 v[208:211], v144 offset:2048
	v_mfma_f32_16x16x32_bf16 v[114:117], v[184:187], v[162:165], v[114:117]
	ds_read_b128 v[212:215], v144 offset:3072
	v_mfma_f32_16x16x32_bf16 v[110:113], v[184:187], v[166:169], v[110:113]
	ds_read_b128 v[216:219], v144 offset:4096
	v_mfma_f32_16x16x32_bf16 v[106:109], v[184:187], v[170:173], v[106:109]
	ds_read_b128 v[220:223], v144 offset:5120
	v_mfma_f32_16x16x32_bf16 v[102:105], v[184:187], v[176:179], v[102:105]
	ds_read_b128 v[224:227], v144 offset:6144
	v_mfma_f32_16x16x32_bf16 v[98:101], v[184:187], v[180:183], v[98:101]
	ds_read_b128 v[228:231], v144 offset:7168
	v_mfma_f32_16x16x32_bf16 v[94:97], v[188:191], v[146:149], v[94:97]
	v_add_u32_e64 v144, s36, v137
	v_mfma_f32_16x16x32_bf16 v[90:93], v[188:191], v[152:155], v[90:93]
	v_mfma_f32_16x16x32_bf16 v[86:89], v[188:191], v[156:159], v[86:89]
	ds_read_b128 v[232:235], v144 offset:16384
	v_mfma_f32_16x16x32_bf16 v[82:85], v[188:191], v[162:165], v[82:85]
	ds_read_b128 v[236:239], v144 offset:17408
	v_mfma_f32_16x16x32_bf16 v[78:81], v[188:191], v[166:169], v[78:81]
	ds_read_b128 v[240:243], v144 offset:18432
	v_mfma_f32_16x16x32_bf16 v[74:77], v[188:191], v[170:173], v[74:77]
	ds_read_b128 v[244:247], v144 offset:19456
	v_mfma_f32_16x16x32_bf16 v[70:73], v[188:191], v[176:179], v[70:73]
	v_mfma_f32_16x16x32_bf16 v[66:69], v[188:191], v[180:183], v[66:69]
	v_mfma_f32_16x16x32_bf16 v[62:65], v[192:195], v[146:149], v[62:65]
	v_mfma_f32_16x16x32_bf16 v[58:61], v[192:195], v[152:155], v[58:61]
	v_mfma_f32_16x16x32_bf16 v[54:57], v[192:195], v[156:159], v[54:57]
	v_mfma_f32_16x16x32_bf16 v[50:53], v[192:195], v[162:165], v[50:53]
	v_mfma_f32_16x16x32_bf16 v[46:49], v[192:195], v[166:169], v[46:49]
	v_mfma_f32_16x16x32_bf16 v[42:45], v[192:195], v[170:173], v[42:45]
	v_mfma_f32_16x16x32_bf16 v[38:41], v[192:195], v[176:179], v[38:41]
	v_mfma_f32_16x16x32_bf16 v[34:37], v[192:195], v[180:183], v[34:37]
	s_setprio 0
	s_nop 0
	v_mfma_f32_16x16x32_bf16 v[30:33], v[196:199], v[146:149], v[30:33]
	v_mfma_f32_16x16x32_bf16 v[26:29], v[196:199], v[152:155], v[26:29]
	v_mfma_f32_16x16x32_bf16 v[22:25], v[196:199], v[156:159], v[22:25]
	v_mfma_f32_16x16x32_bf16 v[18:21], v[196:199], v[162:165], v[18:21]
	v_mfma_f32_16x16x32_bf16 v[14:17], v[196:199], v[166:169], v[14:17]
	v_mfma_f32_16x16x32_bf16 v[10:13], v[196:199], v[170:173], v[10:13]
	v_mfma_f32_16x16x32_bf16 v[6:9], v[196:199], v[176:179], v[6:9]
	v_mfma_f32_16x16x32_bf16 v[2:5], v[196:199], v[180:183], v[2:5]
	s_mov_b32 s37, s36
	s_nop 0
	s_add_i32 s36, s36, 0x6000
	s_cmp_eq_u32 s36, 0x12000
	s_cselect_b32 s36, 0, s36
	s_nop 0
	.p2align 3
	s_waitcnt lgkmcnt(0)
; DEVI unsigned pack2(float a, float b) { return __builtin_bit_cast(unsigned, __builtin_convertvector((f32x2_t){a, b}, bf16x2_t)); }
; DEVI float siluf_(float x) { return x * __builtin_amdgcn_rcpf(1.f + __expf(-x)); }
;     ...
;     for (int nf = 0; nf < 4; nf++)
; #pragma unroll
;       for (int mf = 0; mf < 8; mf++)
;         acc[nf][mf] = __builtin_amdgcn_mfma_f32_16x16x32_bf16(wb[nf], xa[mf], acc[nf][mf], 0, 0, 0);
;     ...
; #pragma unroll
;   for (int mf = 0; mf < 8; mf++) {
;     const int row = m0 + wm * 128 + mf * 16 + r16;
;     if (EPI == EPI_SWIGLU) {
; #pragma unroll
;       for (int nf = 0; nf < 2; nf++) {
;         const int hcol = (n0 >> 1) + wn * 32 + nf * 16 + quad * 4;
;         f32x4 g = acc[nf][mf], u = acc[nf + 2][mf];
;         u32x2 pk;
;         pk[0] = pack2(siluf_(g[0]) * u[0], siluf_(g[1]) * u[1]);
;         pk[1] = pack2(siluf_(g[2]) * u[2], siluf_(g[3]) * u[3]);
;         *(u32x2*)(outb + (size_t)row * DFF + hcol) = pk;
;       }
	s_nop 0
	v_mfma_f32_16x16x32_bf16 v[126:129], v[232:235], v[200:203], v[126:129]
	v_mfma_f32_16x16x32_bf16 v[122:125], v[232:235], v[204:207], v[122:125]
	v_mfma_f32_16x16x32_bf16 v[118:121], v[232:235], v[208:211], v[118:121]
	v_mfma_f32_16x16x32_bf16 v[114:117], v[232:235], v[212:215], v[114:117]
	v_mfma_f32_16x16x32_bf16 v[110:113], v[232:235], v[216:219], v[110:113]
	v_mfma_f32_16x16x32_bf16 v[106:109], v[232:235], v[220:223], v[106:109]
	v_mfma_f32_16x16x32_bf16 v[102:105], v[232:235], v[224:227], v[102:105]
	v_mfma_f32_16x16x32_bf16 v[98:101], v[232:235], v[228:231], v[98:101]
	v_mfma_f32_16x16x32_bf16 v[94:97], v[236:239], v[200:203], v[94:97]
	v_mfma_f32_16x16x32_bf16 v[90:93], v[236:239], v[204:207], v[90:93]
	v_mfma_f32_16x16x32_bf16 v[86:89], v[236:239], v[208:211], v[86:89]
	v_mfma_f32_16x16x32_bf16 v[82:85], v[236:239], v[212:215], v[82:85]
	v_mfma_f32_16x16x32_bf16 v[78:81], v[236:239], v[216:219], v[78:81]
	v_mfma_f32_16x16x32_bf16 v[74:77], v[236:239], v[220:223], v[74:77]
	v_mfma_f32_16x16x32_bf16 v[70:73], v[236:239], v[224:227], v[70:73]
	v_mfma_f32_16x16x32_bf16 v[66:69], v[236:239], v[228:231], v[66:69]
	v_mfma_f32_16x16x32_bf16 v[62:65], v[240:243], v[200:203], v[62:65]
	v_mfma_f32_16x16x32_bf16 v[58:61], v[240:243], v[204:207], v[58:61]
	v_mfma_f32_16x16x32_bf16 v[54:57], v[240:243], v[208:211], v[54:57]
	v_mfma_f32_16x16x32_bf16 v[50:53], v[240:243], v[212:215], v[50:53]
	v_mfma_f32_16x16x32_bf16 v[46:49], v[240:243], v[216:219], v[46:49]
	v_mfma_f32_16x16x32_bf16 v[42:45], v[240:243], v[220:223], v[42:45]
	v_mfma_f32_16x16x32_bf16 v[38:41], v[240:243], v[224:227], v[38:41]
	v_mfma_f32_16x16x32_bf16 v[34:37], v[240:243], v[228:231], v[34:37]
	v_mfma_f32_16x16x32_bf16 v[30:33], v[244:247], v[200:203], v[30:33]
	v_mfma_f32_16x16x32_bf16 v[26:29], v[244:247], v[204:207], v[26:29]
	v_mfma_f32_16x16x32_bf16 v[22:25], v[244:247], v[208:211], v[22:25]
	v_mfma_f32_16x16x32_bf16 v[18:21], v[244:247], v[212:215], v[18:21]
	v_mfma_f32_16x16x32_bf16 v[14:17], v[244:247], v[216:219], v[14:17]
	v_mfma_f32_16x16x32_bf16 v[10:13], v[244:247], v[220:223], v[10:13]
	v_mfma_f32_16x16x32_bf16 v[6:9], v[244:247], v[224:227], v[6:9]
	v_mfma_f32_16x16x32_bf16 v[2:5], v[244:247], v[228:231], v[2:5]
	s_mov_b32 m0, s39
	s_mov_b32 s10, 0x16000
	s_mov_b32 s11, 0
	s_mov_b32 s40, 0xbfb8aa3b
	s_nop 7
	v_mov_b32_e32 v224, s40
	v_mov_b32_e32 v225, s40
	v_mov_b32_e32 v226, 1.0
	v_mov_b32_e32 v227, 1.0
	v_pk_mul_f32 v[216:217], v[126:127], v[224:225]
	v_pk_mul_f32 v[218:219], v[128:129], v[224:225]
	v_exp_f32_e32 v216, v216
	v_exp_f32_e32 v217, v217
	v_exp_f32_e32 v218, v218
	v_exp_f32_e32 v219, v219
	v_pk_add_f32 v[216:217], v[216:217], v[226:227]
	v_pk_add_f32 v[218:219], v[218:219], v[226:227]
	v_rcp_f32_e32 v216, v216
	v_rcp_f32_e32 v217, v217
	v_rcp_f32_e32 v218, v218
	v_rcp_f32_e32 v219, v219
	v_pk_mul_f32 v[126:127], v[126:127], v[216:217]
	v_pk_mul_f32 v[128:129], v[128:129], v[218:219]
	v_pk_mul_f32 v[126:127], v[126:127], v[62:63]
	v_pk_mul_f32 v[128:129], v[128:129], v[64:65]
	v_pk_mul_f32 v[220:221], v[94:95], v[224:225]
	v_pk_mul_f32 v[222:223], v[96:97], v[224:225]
	v_exp_f32_e32 v220, v220
	v_exp_f32_e32 v221, v221
	v_exp_f32_e32 v222, v222
	v_exp_f32_e32 v223, v223
	v_pk_add_f32 v[220:221], v[220:221], v[226:227]
	v_pk_add_f32 v[222:223], v[222:223], v[226:227]
	v_rcp_f32_e32 v220, v220
	v_rcp_f32_e32 v221, v221
	v_rcp_f32_e32 v222, v222
	v_rcp_f32_e32 v223, v223
	v_pk_mul_f32 v[94:95], v[94:95], v[220:221]
	v_pk_mul_f32 v[96:97], v[96:97], v[222:223]
	v_pk_mul_f32 v[94:95], v[94:95], v[30:31]
	v_pk_mul_f32 v[96:97], v[96:97], v[32:33]
	v_cvt_pk_bf16_f32 v126, v126, v127
	v_cvt_pk_bf16_f32 v127, v128, v129
	v_cvt_pk_bf16_f32 v128, v94, v95
	v_cvt_pk_bf16_f32 v129, v96, v97
	s_nop 1
	v_permlane16_swap_b32_e32 v126, v128
	v_permlane16_swap_b32_e32 v127, v129
	global_store_dwordx4 v[140:141], v[126:129], off
	v_lshl_add_u64 v[140:141], v[140:141], 0, s[10:11]
	v_pk_mul_f32 v[216:217], v[122:123], v[224:225]
	v_pk_mul_f32 v[218:219], v[124:125], v[224:225]
	v_exp_f32_e32 v216, v216
	v_exp_f32_e32 v217, v217
	v_exp_f32_e32 v218, v218
	v_exp_f32_e32 v219, v219
	v_pk_add_f32 v[216:217], v[216:217], v[226:227]
	v_pk_add_f32 v[218:219], v[218:219], v[226:227]
	v_rcp_f32_e32 v216, v216
	v_rcp_f32_e32 v217, v217
	v_rcp_f32_e32 v218, v218
	v_rcp_f32_e32 v219, v219
	v_pk_mul_f32 v[122:123], v[122:123], v[216:217]
	v_pk_mul_f32 v[124:125], v[124:125], v[218:219]
	v_pk_mul_f32 v[122:123], v[122:123], v[58:59]
	v_pk_mul_f32 v[124:125], v[124:125], v[60:61]
	v_pk_mul_f32 v[220:221], v[90:91], v[224:225]
	v_pk_mul_f32 v[222:223], v[92:93], v[224:225]
	v_exp_f32_e32 v220, v220
	v_exp_f32_e32 v221, v221
	v_exp_f32_e32 v222, v222
	v_exp_f32_e32 v223, v223
	v_pk_add_f32 v[220:221], v[220:221], v[226:227]
	v_pk_add_f32 v[222:223], v[222:223], v[226:227]
	v_rcp_f32_e32 v220, v220
	v_rcp_f32_e32 v221, v221
	v_rcp_f32_e32 v222, v222
	v_rcp_f32_e32 v223, v223
	v_pk_mul_f32 v[90:91], v[90:91], v[220:221]
	v_pk_mul_f32 v[92:93], v[92:93], v[222:223]
	v_pk_mul_f32 v[90:91], v[90:91], v[26:27]
	v_pk_mul_f32 v[92:93], v[92:93], v[28:29]
	v_cvt_pk_bf16_f32 v122, v122, v123
	v_cvt_pk_bf16_f32 v123, v124, v125
	v_cvt_pk_bf16_f32 v124, v90, v91
	v_cvt_pk_bf16_f32 v125, v92, v93
	s_nop 1
	v_permlane16_swap_b32_e32 v122, v124
	v_permlane16_swap_b32_e32 v123, v125
	global_store_dwordx4 v[140:141], v[122:125], off
	v_lshl_add_u64 v[140:141], v[140:141], 0, s[10:11]
	v_pk_mul_f32 v[216:217], v[118:119], v[224:225]
	v_pk_mul_f32 v[218:219], v[120:121], v[224:225]
	v_exp_f32_e32 v216, v216
	v_exp_f32_e32 v217, v217
	v_exp_f32_e32 v218, v218
	v_exp_f32_e32 v219, v219
; DEVI unsigned pack2(float a, float b) { return __builtin_bit_cast(unsigned, __builtin_convertvector((f32x2_t){a, b}, bf16x2_t)); }
; DEVI float siluf_(float x) { return x * __builtin_amdgcn_rcpf(1.f + __expf(-x)); }
;     ...
; #pragma unroll
;   for (int mf = 0; mf < 8; mf++) {
;     const int row = m0 + wm * 128 + mf * 16 + r16;
;     if (EPI == EPI_SWIGLU) {
; #pragma unroll
;       for (int nf = 0; nf < 2; nf++) {
;         const int hcol = (n0 >> 1) + wn * 32 + nf * 16 + quad * 4;
;         f32x4 g = acc[nf][mf], u = acc[nf + 2][mf];
;         u32x2 pk;
;         pk[0] = pack2(siluf_(g[0]) * u[0], siluf_(g[1]) * u[1]);
;         pk[1] = pack2(siluf_(g[2]) * u[2], siluf_(g[3]) * u[3]);
;         *(u32x2*)(outb + (size_t)row * DFF + hcol) = pk;
;       }
	v_pk_add_f32 v[216:217], v[216:217], v[226:227]
	v_pk_add_f32 v[218:219], v[218:219], v[226:227]
	v_rcp_f32_e32 v216, v216
	v_rcp_f32_e32 v217, v217
	v_rcp_f32_e32 v218, v218
	v_rcp_f32_e32 v219, v219
	v_pk_mul_f32 v[118:119], v[118:119], v[216:217]
	v_pk_mul_f32 v[120:121], v[120:121], v[218:219]
	v_pk_mul_f32 v[118:119], v[118:119], v[54:55]
	v_pk_mul_f32 v[120:121], v[120:121], v[56:57]
	v_pk_mul_f32 v[220:221], v[86:87], v[224:225]
	v_pk_mul_f32 v[222:223], v[88:89], v[224:225]
	v_exp_f32_e32 v220, v220
	v_exp_f32_e32 v221, v221
	v_exp_f32_e32 v222, v222
	v_exp_f32_e32 v223, v223
	v_pk_add_f32 v[220:221], v[220:221], v[226:227]
	v_pk_add_f32 v[222:223], v[222:223], v[226:227]
	v_rcp_f32_e32 v220, v220
	v_rcp_f32_e32 v221, v221
	v_rcp_f32_e32 v222, v222
	v_rcp_f32_e32 v223, v223
	v_pk_mul_f32 v[86:87], v[86:87], v[220:221]
	v_pk_mul_f32 v[88:89], v[88:89], v[222:223]
	v_pk_mul_f32 v[86:87], v[86:87], v[22:23]
	v_pk_mul_f32 v[88:89], v[88:89], v[24:25]
	v_cvt_pk_bf16_f32 v118, v118, v119
	v_cvt_pk_bf16_f32 v119, v120, v121
	v_cvt_pk_bf16_f32 v120, v86, v87
	v_cvt_pk_bf16_f32 v121, v88, v89
	s_nop 1
	v_permlane16_swap_b32_e32 v118, v120
	v_permlane16_swap_b32_e32 v119, v121
	global_store_dwordx4 v[140:141], v[118:121], off
	v_lshl_add_u64 v[140:141], v[140:141], 0, s[10:11]
	v_pk_mul_f32 v[216:217], v[114:115], v[224:225]
	v_pk_mul_f32 v[218:219], v[116:117], v[224:225]
	v_exp_f32_e32 v216, v216
	v_exp_f32_e32 v217, v217
	v_exp_f32_e32 v218, v218
	v_exp_f32_e32 v219, v219
	v_pk_add_f32 v[216:217], v[216:217], v[226:227]
	v_pk_add_f32 v[218:219], v[218:219], v[226:227]
	v_rcp_f32_e32 v216, v216
	v_rcp_f32_e32 v217, v217
	v_rcp_f32_e32 v218, v218
	v_rcp_f32_e32 v219, v219
	v_pk_mul_f32 v[114:115], v[114:115], v[216:217]
	v_pk_mul_f32 v[116:117], v[116:117], v[218:219]
	v_pk_mul_f32 v[114:115], v[114:115], v[50:51]
	v_pk_mul_f32 v[116:117], v[116:117], v[52:53]
	v_pk_mul_f32 v[220:221], v[82:83], v[224:225]
	v_pk_mul_f32 v[222:223], v[84:85], v[224:225]
	v_exp_f32_e32 v220, v220
	v_exp_f32_e32 v221, v221
	v_exp_f32_e32 v222, v222
	v_exp_f32_e32 v223, v223
	v_pk_add_f32 v[220:221], v[220:221], v[226:227]
	v_pk_add_f32 v[222:223], v[222:223], v[226:227]
	v_rcp_f32_e32 v220, v220
	v_rcp_f32_e32 v221, v221
	v_rcp_f32_e32 v222, v222
	v_rcp_f32_e32 v223, v223
	v_pk_mul_f32 v[82:83], v[82:83], v[220:221]
	v_pk_mul_f32 v[84:85], v[84:85], v[222:223]
	v_pk_mul_f32 v[82:83], v[82:83], v[18:19]
	v_pk_mul_f32 v[84:85], v[84:85], v[20:21]
	v_cvt_pk_bf16_f32 v114, v114, v115
	v_cvt_pk_bf16_f32 v115, v116, v117
	v_cvt_pk_bf16_f32 v116, v82, v83
	v_cvt_pk_bf16_f32 v117, v84, v85
	s_nop 1
	v_permlane16_swap_b32_e32 v114, v116
	v_permlane16_swap_b32_e32 v115, v117
	global_store_dwordx4 v[140:141], v[114:117], off
	v_lshl_add_u64 v[140:141], v[140:141], 0, s[10:11]
	v_pk_mul_f32 v[216:217], v[110:111], v[224:225]
	v_pk_mul_f32 v[218:219], v[112:113], v[224:225]
	v_exp_f32_e32 v216, v216
	v_exp_f32_e32 v217, v217
	v_exp_f32_e32 v218, v218
	v_exp_f32_e32 v219, v219
	v_pk_add_f32 v[216:217], v[216:217], v[226:227]
	v_pk_add_f32 v[218:219], v[218:219], v[226:227]
	v_rcp_f32_e32 v216, v216
	v_rcp_f32_e32 v217, v217
	v_rcp_f32_e32 v218, v218
	v_rcp_f32_e32 v219, v219
	v_pk_mul_f32 v[110:111], v[110:111], v[216:217]
	v_pk_mul_f32 v[112:113], v[112:113], v[218:219]
	v_pk_mul_f32 v[110:111], v[110:111], v[46:47]
	v_pk_mul_f32 v[112:113], v[112:113], v[48:49]
	v_pk_mul_f32 v[220:221], v[78:79], v[224:225]
	v_pk_mul_f32 v[222:223], v[80:81], v[224:225]
	v_exp_f32_e32 v220, v220
	v_exp_f32_e32 v221, v221
	v_exp_f32_e32 v222, v222
	v_exp_f32_e32 v223, v223
	v_pk_add_f32 v[220:221], v[220:221], v[226:227]
	v_pk_add_f32 v[222:223], v[222:223], v[226:227]
	v_rcp_f32_e32 v220, v220
	v_rcp_f32_e32 v221, v221
	v_rcp_f32_e32 v222, v222
	v_rcp_f32_e32 v223, v223
	v_pk_mul_f32 v[78:79], v[78:79], v[220:221]
	v_pk_mul_f32 v[80:81], v[80:81], v[222:223]
	v_pk_mul_f32 v[78:79], v[78:79], v[14:15]
	v_pk_mul_f32 v[80:81], v[80:81], v[16:17]
	v_cvt_pk_bf16_f32 v110, v110, v111
	v_cvt_pk_bf16_f32 v111, v112, v113
	v_cvt_pk_bf16_f32 v112, v78, v79
	v_cvt_pk_bf16_f32 v113, v80, v81
	s_nop 1
	v_permlane16_swap_b32_e32 v110, v112
	v_permlane16_swap_b32_e32 v111, v113
	global_store_dwordx4 v[140:141], v[110:113], off
	v_lshl_add_u64 v[140:141], v[140:141], 0, s[10:11]
	v_pk_mul_f32 v[216:217], v[106:107], v[224:225]
	v_pk_mul_f32 v[218:219], v[108:109], v[224:225]
	v_exp_f32_e32 v216, v216
; DEVI unsigned pack2(float a, float b) { return __builtin_bit_cast(unsigned, __builtin_convertvector((f32x2_t){a, b}, bf16x2_t)); }
; DEVI float siluf_(float x) { return x * __builtin_amdgcn_rcpf(1.f + __expf(-x)); }
; DEVI int xcd_first_tile() { return (blockIdx.x & 7) * (gridDim.x >> 3) + (blockIdx.x >> 3); }
;     ...
; #pragma unroll
;   for (int mf = 0; mf < 8; mf++) {
;     const int row = m0 + wm * 128 + mf * 16 + r16;
;     if (EPI == EPI_SWIGLU) {
; #pragma unroll
;       for (int nf = 0; nf < 2; nf++) {
;         const int hcol = (n0 >> 1) + wn * 32 + nf * 16 + quad * 4;
;         f32x4 g = acc[nf][mf], u = acc[nf + 2][mf];
;         u32x2 pk;
;         pk[0] = pack2(siluf_(g[0]) * u[0], siluf_(g[1]) * u[1]);
;         pk[1] = pack2(siluf_(g[2]) * u[2], siluf_(g[3]) * u[3]);
;         *(u32x2*)(outb + (size_t)row * DFF + hcol) = pk;
;       }
; DEVI void run_phase(const Params& p, int ph, char* smem) {
;     ...
;       for (int t = xcd_first_tile(); t < 66 * 44; t += xcd_tile_step()) {
;         int mt_, nt_; tile_coords(t, 66, 44, mt_, nt_);
;         gemm_tile256<EPI_SWIGLU>(p, xb, 1024, Bt, 1024, mt_ * 256, nt_ * 128, hb, DFF, smem);
	v_exp_f32_e32 v217, v217
	v_exp_f32_e32 v218, v218
	v_exp_f32_e32 v219, v219
	v_pk_add_f32 v[216:217], v[216:217], v[226:227]
	v_pk_add_f32 v[218:219], v[218:219], v[226:227]
	v_rcp_f32_e32 v216, v216
	v_rcp_f32_e32 v217, v217
	v_rcp_f32_e32 v218, v218
	v_rcp_f32_e32 v219, v219
	v_pk_mul_f32 v[106:107], v[106:107], v[216:217]
	v_pk_mul_f32 v[108:109], v[108:109], v[218:219]
	v_pk_mul_f32 v[106:107], v[106:107], v[42:43]
	v_pk_mul_f32 v[108:109], v[108:109], v[44:45]
	v_pk_mul_f32 v[220:221], v[74:75], v[224:225]
	v_pk_mul_f32 v[222:223], v[76:77], v[224:225]
	v_exp_f32_e32 v220, v220
	v_exp_f32_e32 v221, v221
	v_exp_f32_e32 v222, v222
	v_exp_f32_e32 v223, v223
	v_pk_add_f32 v[220:221], v[220:221], v[226:227]
	v_pk_add_f32 v[222:223], v[222:223], v[226:227]
	v_rcp_f32_e32 v220, v220
	v_rcp_f32_e32 v221, v221
	v_rcp_f32_e32 v222, v222
	v_rcp_f32_e32 v223, v223
	v_pk_mul_f32 v[74:75], v[74:75], v[220:221]
	v_pk_mul_f32 v[76:77], v[76:77], v[222:223]
	v_pk_mul_f32 v[74:75], v[74:75], v[10:11]
	v_pk_mul_f32 v[76:77], v[76:77], v[12:13]
	v_cvt_pk_bf16_f32 v106, v106, v107
	v_cvt_pk_bf16_f32 v107, v108, v109
	v_cvt_pk_bf16_f32 v108, v74, v75
	v_cvt_pk_bf16_f32 v109, v76, v77
	s_nop 1
	v_permlane16_swap_b32_e32 v106, v108
	v_permlane16_swap_b32_e32 v107, v109
	global_store_dwordx4 v[140:141], v[106:109], off
	v_lshl_add_u64 v[140:141], v[140:141], 0, s[10:11]
	v_pk_mul_f32 v[216:217], v[102:103], v[224:225]
	v_pk_mul_f32 v[218:219], v[104:105], v[224:225]
	v_exp_f32_e32 v216, v216
	v_exp_f32_e32 v217, v217
	v_exp_f32_e32 v218, v218
	v_exp_f32_e32 v219, v219
	v_pk_add_f32 v[216:217], v[216:217], v[226:227]
	v_pk_add_f32 v[218:219], v[218:219], v[226:227]
	v_rcp_f32_e32 v216, v216
	v_rcp_f32_e32 v217, v217
	v_rcp_f32_e32 v218, v218
	v_rcp_f32_e32 v219, v219
	v_pk_mul_f32 v[102:103], v[102:103], v[216:217]
	v_pk_mul_f32 v[104:105], v[104:105], v[218:219]
	v_pk_mul_f32 v[102:103], v[102:103], v[38:39]
	v_pk_mul_f32 v[104:105], v[104:105], v[40:41]
	v_pk_mul_f32 v[220:221], v[70:71], v[224:225]
	v_pk_mul_f32 v[222:223], v[72:73], v[224:225]
	v_exp_f32_e32 v220, v220
	v_exp_f32_e32 v221, v221
	v_exp_f32_e32 v222, v222
	v_exp_f32_e32 v223, v223
	v_pk_add_f32 v[220:221], v[220:221], v[226:227]
	v_pk_add_f32 v[222:223], v[222:223], v[226:227]
	v_rcp_f32_e32 v220, v220
	v_rcp_f32_e32 v221, v221
	v_rcp_f32_e32 v222, v222
	v_rcp_f32_e32 v223, v223
	v_pk_mul_f32 v[70:71], v[70:71], v[220:221]
	v_pk_mul_f32 v[72:73], v[72:73], v[222:223]
	v_pk_mul_f32 v[70:71], v[70:71], v[6:7]
	v_pk_mul_f32 v[72:73], v[72:73], v[8:9]
	v_cvt_pk_bf16_f32 v102, v102, v103
	v_cvt_pk_bf16_f32 v103, v104, v105
	v_cvt_pk_bf16_f32 v104, v70, v71
	v_cvt_pk_bf16_f32 v105, v72, v73
	s_nop 1
	v_permlane16_swap_b32_e32 v102, v104
	v_permlane16_swap_b32_e32 v103, v105
	global_store_dwordx4 v[140:141], v[102:105], off
	v_lshl_add_u64 v[140:141], v[140:141], 0, s[10:11]
	v_pk_mul_f32 v[216:217], v[98:99], v[224:225]
	v_pk_mul_f32 v[218:219], v[100:101], v[224:225]
	v_exp_f32_e32 v216, v216
	v_exp_f32_e32 v217, v217
	v_exp_f32_e32 v218, v218
	v_exp_f32_e32 v219, v219
	v_pk_add_f32 v[216:217], v[216:217], v[226:227]
	v_pk_add_f32 v[218:219], v[218:219], v[226:227]
	v_rcp_f32_e32 v216, v216
	v_rcp_f32_e32 v217, v217
	v_rcp_f32_e32 v218, v218
	v_rcp_f32_e32 v219, v219
	v_pk_mul_f32 v[98:99], v[98:99], v[216:217]
	v_pk_mul_f32 v[100:101], v[100:101], v[218:219]
	v_pk_mul_f32 v[98:99], v[98:99], v[34:35]
	v_pk_mul_f32 v[100:101], v[100:101], v[36:37]
	v_pk_mul_f32 v[220:221], v[66:67], v[224:225]
	v_pk_mul_f32 v[222:223], v[68:69], v[224:225]
	v_exp_f32_e32 v220, v220
	v_exp_f32_e32 v221, v221
	v_exp_f32_e32 v222, v222
	v_exp_f32_e32 v223, v223
	v_pk_add_f32 v[220:221], v[220:221], v[226:227]
	v_pk_add_f32 v[222:223], v[222:223], v[226:227]
	v_rcp_f32_e32 v220, v220
	v_rcp_f32_e32 v221, v221
	v_rcp_f32_e32 v222, v222
	v_rcp_f32_e32 v223, v223
	v_pk_mul_f32 v[66:67], v[66:67], v[220:221]
	v_pk_mul_f32 v[68:69], v[68:69], v[222:223]
	v_pk_mul_f32 v[66:67], v[66:67], v[2:3]
	v_pk_mul_f32 v[68:69], v[68:69], v[4:5]
	v_cvt_pk_bf16_f32 v98, v98, v99
	v_cvt_pk_bf16_f32 v99, v100, v101
	v_cvt_pk_bf16_f32 v100, v66, v67
	v_cvt_pk_bf16_f32 v101, v68, v69
	s_nop 1
	v_permlane16_swap_b32_e32 v98, v100
	v_permlane16_swap_b32_e32 v99, v101
	global_store_dwordx4 v[140:141], v[98:101], off
	v_readlane_b32 s42, v250, 7
	s_add_i32 s8, s8, s42
	s_cmpk_gt_i32 s8, 0xb57
	s_cbranch_scc0 .LBB0_124
	s_branch .LBB0_131

; #define LAS __attribute__((address_space(3)))
;     ...
;   const int nk = (nk_part < 0) ? (K >> 5) : nk_part;
;   const int lrow = tid >> 2, lpc = tid & 3;
;   const int lch = lpc ^ ((0x78 >> (((lrow >> 2) & 3) * 2)) & 3);
;   const u16* ga = A + (size_t)(m0 + lrow) * lda + kbeg + lch * 8;
;   const u16* gb = Bt + (size_t)(n0 + lrow) * K + kbeg + lch * 8;
;   const size_t ga1 = (size_t)64 * lda, gb1 = (size_t)64 * K;
;   const unsigned lds0 = (unsigned)(uintptr_t)(LAS char*)smem + (unsigned)__builtin_amdgcn_readfirstlane(wid) * 1024u;
;     ...
;   __syncthreads();
;   G2_STAGE(0); G2_STAGE(1);
; DEVI void run_phase(const Params& p, int ph, char* smem) {
;     ...
;         } else {
;           const int u_ = t - 512, tl_ = u_ / 11, q_ = u_ - tl_ * 11;
;           gemm_tile256<EPI_RESID_ATOMIC>(p, hb, DFF, Bt, DFF, (64 + (tl_ & 1)) * 256, (tl_ >> 1) * 128, nullptr, 0, smem, q_ * 256, 8, q_);
.LBB0_147:
	s_cmpk_gt_i32 s38, 0x1ff
	s_mov_b64 s[2:3], -1
	s_cbranch_scc0 .LBB0_208
	s_setprio 2
	s_sub_i32 s98, s38, 512
	s_lshr_b32 s41, s98, 1
	s_and_b32 s99, s98, 1
	s_lshr_b32 s13, s41, 1
	s_and_b32 s41, s41, 1
	s_add_i32 s41, s41, 64
	v_readlane_b32 s2, v250, 5
	v_readlane_b32 s3, v250, 6
	v_readlane_b32 s98, v254, 62
	s_mul_i32 s1, s41, 0x20000
	s_add_u32 s4, s2, s1
	s_addc_u32 s5, s3, 0
	s_add_u32 s4, s4, 0xe700000
	s_addc_u32 s5, s5, 0
	s_mul_i32 s1, s98, 0x80000
	s_mul_i32 s12, s13, 0x10000
	s_add_i32 s1, s1, s12
	s_add_u32 s8, s2, s1
	s_addc_u32 s9, s3, 0
	s_add_u32 s8, s8, 0x16c00000
	s_addc_u32 s9, s9, 0
	s_mul_i32 s1, s99, 256
	s_add_u32 s4, s4, s1
	s_addc_u32 s5, s5, 0
	s_mul_i32 s1, s99, 512
	s_add_u32 s8, s8, s1
	s_addc_u32 s9, s9, 0
	s_movk_i32 s0, 0x78
	v_lshrrev_b32_e32 v0, 2, v145
	v_and_b32_e32 v131, 3, v145
	v_bfe_u32 v136, v145, 4, 2
	v_lshlrev_b32_e32 v136, 1, v136
	v_lshrrev_b32_e64 v136, v136, s0
	v_and_b32_e32 v136, 3, v136
	v_xor_b32_e32 v131, v131, v136
	v_lshlrev_b32_e32 v131, 4, v131
	s_movk_i32 s12, 0x200
	v_mad_u32_u24 v0, v0, s12, v131
	v_bfe_u32 v137, v145, 2, 1
	s_movk_i32 s12, 0x1c0
	v_mul_u32_u24_e32 v136, s12, v137
	v_sub_u32_e32 v136, v0, v136
	v_mov_b32_e32 v137, 0
	v_lshl_add_u64 v[134:135], s[8:9], 0, v[136:137]
	v_bfe_u32 v137, v145, 2, 1
	s_mov_b32 s10, 64
	s_mov_b32 s11, 0
	v_lshl_add_u64 v[132:133], s[4:5], 0, v[0:1]
	v_bfe_u32 v136, v145, 2, 2
	v_lshlrev_b32_e32 v136, 1, v136
	v_lshrrev_b32_e64 v136, v136, s0
	v_and_b32_e32 v136, 3, v136
	v_bfe_u32 v137, v145, 4, 2
	v_xor_b32_e32 v136, v136, v137
	v_lshlrev_b32_e32 v136, 4, v136
	v_and_b32_e32 v131, 15, v145
	v_lshl_or_b32 v136, v131, 6, v136
	v_bfe_u32 v137, v145, 6, 1
	v_lshl_or_b32 v137, v137, 12, v136
	v_lshrrev_b32_e32 v0, 7, v145
	v_lshl_or_b32 v136, v0, 13, v136
	v_and_b32_e32 v140, 1, v131
	v_lshl_or_b32 v131, v0, 7, v131
	v_bfe_u32 v0, v145, 4, 2
	v_lshlrev_b32_e32 v0, 3, v0
	v_bfe_u32 v141, v145, 6, 1
	s_lshl_b32 s1, s41, 19
	s_lshl_b32 s12, s13, 8
	s_add_i32 s1, s1, s12
	s_add_u32 s4, s2, s1
	s_addc_u32 s5, s3, 0
	s_add_u32 s4, s4, 0x4200000
	s_addc_u32 s5, s5, 0
	v_lshlrev_b32_e32 v138, 11, v131
	v_lshl_add_u32 v138, v141, 7, v138
	v_bfe_u32 v139, v145, 4, 1
	v_lshl_add_u32 v138, v139, 5, v138
	v_bfe_u32 v139, v145, 5, 1
	v_lshl_add_u32 v138, v139, 4, v138
	v_mov_b32_e32 v139, 0
	v_lshl_add_u64 v[138:139], s[4:5], 0, v[138:139]
	s_and_b32 s1, s41, 1
	s_lshl_b32 s1, s1, 20
	s_lshl_b32 s12, s99, 21
	s_add_i32 s1, s1, s12
	s_lshl_b32 s12, s13, 9
	s_add_i32 s1, s1, s12
	s_add_u32 s8, s2, s1
	s_addc_u32 s9, s3, 0
	s_add_u32 s8, s8, 0x1dcc0000
	s_addc_u32 s9, s9, 0
	v_lshlrev_b32_e32 v140, 12, v131
	v_lshl_add_u32 v140, v141, 8, v140
	v_lshl_add_u32 v140, v0, 1, v140
	v_mov_b32_e32 v141, 0
	v_lshl_add_u64 v[140:141], s[8:9], 0, v[140:141]
	s_mov_b32 s2, 0x8000
	s_mov_b32 s3, 0
	v_lshrrev_b32_e32 v0, 6, v145
	v_lshlrev_b32_e32 v0, 10, v0
	s_nop 0
	v_readfirstlane_b32 s98, v0
	s_mov_b32 s39, m0
	s_mov_b32 s4, 128
	s_mov_b32 s5, 0
	s_barrier
	s_add_i32 s13, s98, 0x0
	s_mov_b32 m0, s13
	v_lshl_add_u64 v[142:143], v[132:133], 0, s[2:3]
	global_load_lds_dwordx4 v[132:133], off
	s_add_i32 m0, m0, 0x1000
	s_nop 0
	global_load_lds_dwordx4 v[142:143], off
	v_lshl_add_u64 v[142:143], v[142:143], 0, s[2:3]
	s_add_i32 m0, m0, 0x1000
	s_nop 0
	global_load_lds_dwordx4 v[142:143], off
	v_lshl_add_u64 v[142:143], v[142:143], 0, s[2:3]
	s_add_i32 m0, m0, 0x1000
	s_nop 0
	global_load_lds_dwordx4 v[142:143], off
	s_add_i32 m0, m0, 0x1000
	v_lshl_add_u64 v[142:143], v[134:135], 0, s[2:3]
	s_nop 0
	global_load_lds_dwordx4 v[134:135], off
	s_add_i32 m0, m0, 0x1000
	v_lshl_add_u64 v[132:133], v[132:133], 0, s[10:11]
	s_nop 0
	global_load_lds_dwordx4 v[142:143], off
	v_lshl_add_u64 v[134:135], v[134:135], 0, s[4:5]
	s_nop 0
	s_add_i32 s13, s98, 0x6000
	s_mov_b32 m0, s13
	v_lshl_add_u64 v[142:143], v[132:133], 0, s[2:3]
	global_load_lds_dwordx4 v[132:133], off
	s_add_i32 m0, m0, 0x1000
	s_nop 0
	global_load_lds_dwordx4 v[142:143], off
	v_lshl_add_u64 v[142:143], v[142:143], 0, s[2:3]
	s_add_i32 m0, m0, 0x1000
	s_nop 0
	global_load_lds_dwordx4 v[142:143], off
	v_lshl_add_u64 v[142:143], v[142:143], 0, s[2:3]
	s_add_i32 m0, m0, 0x1000
	s_nop 0
	global_load_lds_dwordx4 v[142:143], off
	s_add_i32 m0, m0, 0x1000
	v_lshl_add_u64 v[142:143], v[134:135], 0, s[2:3]
	s_nop 0
	global_load_lds_dwordx4 v[134:135], off
	s_add_i32 m0, m0, 0x1000
	v_lshl_add_u64 v[132:133], v[132:133], 0, s[10:11]
	s_nop 0
	global_load_lds_dwordx4 v[142:143], off
	v_lshl_add_u64 v[134:135], v[134:135], 0, s[4:5]
	s_nop 0
	s_add_i32 s13, s98, 0xc000
	s_mov_b32 m0, s13
	v_lshl_add_u64 v[142:143], v[132:133], 0, s[2:3]
	global_load_lds_dwordx4 v[132:133], off
	s_add_i32 m0, m0, 0x1000
	s_nop 0
	global_load_lds_dwordx4 v[142:143], off
	v_lshl_add_u64 v[142:143], v[142:143], 0, s[2:3]
	s_add_i32 m0, m0, 0x1000
	s_nop 0
	global_load_lds_dwordx4 v[142:143], off
	v_lshl_add_u64 v[142:143], v[142:143], 0, s[2:3]
	s_add_i32 m0, m0, 0x1000
	s_nop 0
	global_load_lds_dwordx4 v[142:143], off
	s_add_i32 m0, m0, 0x1000
	v_lshl_add_u64 v[142:143], v[134:135], 0, s[2:3]
	s_nop 0
	global_load_lds_dwordx4 v[134:135], off
	s_add_i32 m0, m0, 0x1000
	v_lshl_add_u64 v[132:133], v[132:133], 0, s[10:11]
	s_nop 0
	global_load_lds_dwordx4 v[142:143], off
	v_lshl_add_u64 v[134:135], v[134:135], 0, s[4:5]
	s_nop 0
	v_mov_b32_e32 v2, 0
	v_mov_b32_e32 v3, 0
	v_mov_b32_e32 v4, 0
	v_mov_b32_e32 v5, 0
	v_mov_b32_e32 v6, 0
	v_mov_b32_e32 v7, 0
	v_mov_b32_e32 v8, 0
	v_mov_b32_e32 v9, 0
	v_mov_b32_e32 v10, 0
	v_mov_b32_e32 v11, 0
	v_mov_b32_e32 v12, 0
	v_mov_b32_e32 v13, 0
	v_mov_b32_e32 v14, 0
	v_mov_b32_e32 v15, 0
;     ...
;   __syncthreads();
;   G2_STAGE(0); G2_STAGE(1);
;   const int fsw = (0x78 >> (((r16 >> 2) & 3) * 2)) & 3;
;   const int aoff = (wm * 128 + r16) * 64 + ((quad ^ fsw) << 4);
;   const int boff = 16384 + (wn * 64 + r16) * 64 + ((quad ^ fsw) << 4);
;   for (int kt = 0; kt < nk; kt++) {
;     if (kt + 1 < nk) asm volatile("s_waitcnt vmcnt(6)" ::: "memory");
;     else asm volatile("s_waitcnt vmcnt(0)" ::: "memory");
;     __builtin_amdgcn_s_barrier();
;     asm volatile("" ::: "memory");
;     if (kt + 2 < nk) G2_STAGE(kt + 2);
;     const char* cS = smem + (kt % 3) * 24576;
;     bf16x8 xa[8], wb[4];
; #pragma unroll
;     for (int f = 0; f < 8; f++) xa[f] = *(const bf16x8*)(cS + aoff + f * 1024);
; #pragma unroll
;     for (int f = 0; f < 4; f++) wb[f] = *(const bf16x8*)(cS + boff + f * 1024);
; #pragma unroll
;     for (int nf = 0; nf < 4; nf++)
; #pragma unroll
;       for (int mf = 0; mf < 8; mf++)
;         acc[nf][mf] = __builtin_amdgcn_mfma_f32_16x16x32_bf16(wb[nf], xa[mf], acc[nf][mf], 0, 0, 0);
;   }
	v_mov_b32_e32 v16, 0
	v_mov_b32_e32 v17, 0
	v_mov_b32_e32 v18, 0
	v_mov_b32_e32 v19, 0
	v_mov_b32_e32 v20, 0
	v_mov_b32_e32 v21, 0
	v_mov_b32_e32 v22, 0
	v_mov_b32_e32 v23, 0
	v_mov_b32_e32 v24, 0
	v_mov_b32_e32 v25, 0
	v_mov_b32_e32 v26, 0
	v_mov_b32_e32 v27, 0
	v_mov_b32_e32 v28, 0
	v_mov_b32_e32 v29, 0
	v_mov_b32_e32 v30, 0
	v_mov_b32_e32 v31, 0
	v_mov_b32_e32 v32, 0
	v_mov_b32_e32 v33, 0
	v_mov_b32_e32 v34, 0
	v_mov_b32_e32 v35, 0
	v_mov_b32_e32 v36, 0
	v_mov_b32_e32 v37, 0
	v_mov_b32_e32 v38, 0
	v_mov_b32_e32 v39, 0
	v_mov_b32_e32 v40, 0
	v_mov_b32_e32 v41, 0
	v_mov_b32_e32 v42, 0
	v_mov_b32_e32 v43, 0
	v_mov_b32_e32 v44, 0
	v_mov_b32_e32 v45, 0
	v_mov_b32_e32 v46, 0
	v_mov_b32_e32 v47, 0
	v_mov_b32_e32 v48, 0
	v_mov_b32_e32 v49, 0
	v_mov_b32_e32 v50, 0
	v_mov_b32_e32 v51, 0
	v_mov_b32_e32 v52, 0
	v_mov_b32_e32 v53, 0
	v_mov_b32_e32 v54, 0
	v_mov_b32_e32 v55, 0
	v_mov_b32_e32 v56, 0
	v_mov_b32_e32 v57, 0
	v_mov_b32_e32 v58, 0
	v_mov_b32_e32 v59, 0
	v_mov_b32_e32 v60, 0
	v_mov_b32_e32 v61, 0
	v_mov_b32_e32 v62, 0
	v_mov_b32_e32 v63, 0
	v_mov_b32_e32 v64, 0
	v_mov_b32_e32 v65, 0
	v_mov_b32_e32 v66, 0
	v_mov_b32_e32 v67, 0
	v_mov_b32_e32 v68, 0
	v_mov_b32_e32 v69, 0
	v_mov_b32_e32 v70, 0
	v_mov_b32_e32 v71, 0
	v_mov_b32_e32 v72, 0
	v_mov_b32_e32 v73, 0
	v_mov_b32_e32 v74, 0
	v_mov_b32_e32 v75, 0
	v_mov_b32_e32 v76, 0
	v_mov_b32_e32 v77, 0
	v_mov_b32_e32 v78, 0
	v_mov_b32_e32 v79, 0
	v_mov_b32_e32 v80, 0
	v_mov_b32_e32 v81, 0
	v_mov_b32_e32 v82, 0
	v_mov_b32_e32 v83, 0
	v_mov_b32_e32 v84, 0
	v_mov_b32_e32 v85, 0
	v_mov_b32_e32 v86, 0
	v_mov_b32_e32 v87, 0
	v_mov_b32_e32 v88, 0
	v_mov_b32_e32 v89, 0
	v_mov_b32_e32 v90, 0
	v_mov_b32_e32 v91, 0
	v_mov_b32_e32 v92, 0
	v_mov_b32_e32 v93, 0
	v_mov_b32_e32 v94, 0
	v_mov_b32_e32 v95, 0
	v_mov_b32_e32 v96, 0
	v_mov_b32_e32 v97, 0
	v_mov_b32_e32 v98, 0
	v_mov_b32_e32 v99, 0
	v_mov_b32_e32 v100, 0
	v_mov_b32_e32 v101, 0
	v_mov_b32_e32 v102, 0
	v_mov_b32_e32 v103, 0
	v_mov_b32_e32 v104, 0
	v_mov_b32_e32 v105, 0
	v_mov_b32_e32 v106, 0
	v_mov_b32_e32 v107, 0
	v_mov_b32_e32 v108, 0
	v_mov_b32_e32 v109, 0
	v_mov_b32_e32 v110, 0
	v_mov_b32_e32 v111, 0
	v_mov_b32_e32 v112, 0
	v_mov_b32_e32 v113, 0
	v_mov_b32_e32 v114, 0
	v_mov_b32_e32 v115, 0
	v_mov_b32_e32 v116, 0
	v_mov_b32_e32 v117, 0
	v_mov_b32_e32 v118, 0
	v_mov_b32_e32 v119, 0
	v_mov_b32_e32 v120, 0
	v_mov_b32_e32 v121, 0
	v_mov_b32_e32 v122, 0
	v_mov_b32_e32 v123, 0
	v_mov_b32_e32 v124, 0
	v_mov_b32_e32 v125, 0
	v_mov_b32_e32 v126, 0
	v_mov_b32_e32 v127, 0
	v_mov_b32_e32 v128, 0
	v_mov_b32_e32 v129, 0
	s_setprio 0
	s_waitcnt vmcnt(12)
	s_barrier
	ds_read_b128 v[146:149], v136 offset:0
	ds_read_b128 v[152:155], v136 offset:1024
	ds_read_b128 v[156:159], v136 offset:2048
	ds_read_b128 v[162:165], v136 offset:3072
	ds_read_b128 v[166:169], v136 offset:4096
	ds_read_b128 v[170:173], v136 offset:5120
	ds_read_b128 v[176:179], v136 offset:6144
	ds_read_b128 v[180:183], v136 offset:7168
	ds_read_b128 v[184:187], v137 offset:16384
	ds_read_b128 v[188:191], v137 offset:17408
	ds_read_b128 v[192:195], v137 offset:18432
	ds_read_b128 v[196:199], v137 offset:19456
	s_movk_i32 s1, 0x6000
	s_mov_b32 s12, 0
	.p2align 3
	s_waitcnt vmcnt(6) lgkmcnt(0)
	s_barrier
	s_setprio 1
	v_add_u32_e32 v144, s1, v136
	v_mfma_f32_16x16x32_bf16 v[126:129], v[184:187], v[146:149], v[126:129]
	ds_read_b128 v[200:203], v144 offset:0
	v_mfma_f32_16x16x32_bf16 v[122:125], v[184:187], v[152:155], v[122:125]
	ds_read_b128 v[204:207], v144 offset:1024
	v_mfma_f32_16x16x32_bf16 v[118:121], v[184:187], v[156:159], v[118:121]
	ds_read_b128 v[208:211], v144 offset:2048
	v_mfma_f32_16x16x32_bf16 v[114:117], v[184:187], v[162:165], v[114:117]
	ds_read_b128 v[212:215], v144 offset:3072
	v_mfma_f32_16x16x32_bf16 v[110:113], v[184:187], v[166:169], v[110:113]
	ds_read_b128 v[216:219], v144 offset:4096
	v_mfma_f32_16x16x32_bf16 v[106:109], v[184:187], v[170:173], v[106:109]
	ds_read_b128 v[220:223], v144 offset:5120
	v_mfma_f32_16x16x32_bf16 v[102:105], v[184:187], v[176:179], v[102:105]
	ds_read_b128 v[224:227], v144 offset:6144
	v_mfma_f32_16x16x32_bf16 v[98:101], v[184:187], v[180:183], v[98:101]
	ds_read_b128 v[228:231], v144 offset:7168
	v_mfma_f32_16x16x32_bf16 v[94:97], v[188:191], v[146:149], v[94:97]
	v_add_u32_e64 v144, s1, v137
	v_mfma_f32_16x16x32_bf16 v[90:93], v[188:191], v[152:155], v[90:93]
	v_mfma_f32_16x16x32_bf16 v[86:89], v[188:191], v[156:159], v[86:89]
	ds_read_b128 v[232:235], v144 offset:16384
	v_mfma_f32_16x16x32_bf16 v[82:85], v[188:191], v[162:165], v[82:85]
	ds_read_b128 v[236:239], v144 offset:17408
	v_mfma_f32_16x16x32_bf16 v[78:81], v[188:191], v[166:169], v[78:81]
	ds_read_b128 v[240:243], v144 offset:18432
	v_mfma_f32_16x16x32_bf16 v[74:77], v[188:191], v[170:173], v[74:77]
	ds_read_b128 v[244:247], v144 offset:19456
	v_mfma_f32_16x16x32_bf16 v[70:73], v[188:191], v[176:179], v[70:73]
	s_add_i32 s13, s98, s12
	s_mov_b32 m0, s13
	v_lshl_add_u64 v[142:143], v[132:133], 0, s[2:3]
	v_mfma_f32_16x16x32_bf16 v[66:69], v[188:191], v[180:183], v[66:69]
	global_load_lds_dwordx4 v[132:133], off
	s_add_i32 m0, m0, 0x1000
	v_mfma_f32_16x16x32_bf16 v[62:65], v[192:195], v[146:149], v[62:65]
	v_mfma_f32_16x16x32_bf16 v[58:61], v[192:195], v[152:155], v[58:61]
	v_mfma_f32_16x16x32_bf16 v[54:57], v[192:195], v[156:159], v[54:57]
	global_load_lds_dwordx4 v[142:143], off
	v_lshl_add_u64 v[142:143], v[142:143], 0, s[2:3]
	s_add_i32 m0, m0, 0x1000
	v_mfma_f32_16x16x32_bf16 v[50:53], v[192:195], v[162:165], v[50:53]
	v_mfma_f32_16x16x32_bf16 v[46:49], v[192:195], v[166:169], v[46:49]
	v_mfma_f32_16x16x32_bf16 v[42:45], v[192:195], v[170:173], v[42:45]
	global_load_lds_dwordx4 v[142:143], off
	v_lshl_add_u64 v[142:143], v[142:143], 0, s[2:3]
	s_add_i32 m0, m0, 0x1000
	v_mfma_f32_16x16x32_bf16 v[38:41], v[192:195], v[176:179], v[38:41]
	v_mfma_f32_16x16x32_bf16 v[34:37], v[192:195], v[180:183], v[34:37]
	s_setprio 0
	s_nop 0
	v_mfma_f32_16x16x32_bf16 v[30:33], v[196:199], v[146:149], v[30:33]
	global_load_lds_dwordx4 v[142:143], off
	s_add_i32 m0, m0, 0x1000
	v_lshl_add_u64 v[142:143], v[134:135], 0, s[2:3]
	v_mfma_f32_16x16x32_bf16 v[26:29], v[196:199], v[152:155], v[26:29]
	v_mfma_f32_16x16x32_bf16 v[22:25], v[196:199], v[156:159], v[22:25]
	v_mfma_f32_16x16x32_bf16 v[18:21], v[196:199], v[162:165], v[18:21]
	global_load_lds_dwordx4 v[134:135], off
	s_add_i32 m0, m0, 0x1000
	v_lshl_add_u64 v[132:133], v[132:133], 0, s[10:11]
	v_mfma_f32_16x16x32_bf16 v[14:17], v[196:199], v[166:169], v[14:17]
	v_mfma_f32_16x16x32_bf16 v[10:13], v[196:199], v[170:173], v[10:13]
	v_mfma_f32_16x16x32_bf16 v[6:9], v[196:199], v[176:179], v[6:9]
	global_load_lds_dwordx4 v[142:143], off
	v_lshl_add_u64 v[134:135], v[134:135], 0, s[4:5]
	v_mfma_f32_16x16x32_bf16 v[2:5], v[196:199], v[180:183], v[2:5]
	s_mov_b32 s12, s1
	s_nop 0
	s_add_i32 s1, s1, 0x6000
	s_cmp_eq_u32 s1, 0x12000
	s_cselect_b32 s1, 0, s1
	s_nop 0
	.p2align 3
	s_waitcnt vmcnt(6) lgkmcnt(0)
	s_barrier
;     ...
;   for (int kt = 0; kt < nk; kt++) {
;     if (kt + 1 < nk) asm volatile("s_waitcnt vmcnt(6)" ::: "memory");
;     else asm volatile("s_waitcnt vmcnt(0)" ::: "memory");
;     __builtin_amdgcn_s_barrier();
;     asm volatile("" ::: "memory");
;     if (kt + 2 < nk) G2_STAGE(kt + 2);
;     const char* cS = smem + (kt % 3) * 24576;
;     bf16x8 xa[8], wb[4];
; #pragma unroll
;     for (int f = 0; f < 8; f++) xa[f] = *(const bf16x8*)(cS + aoff + f * 1024);
; #pragma unroll
;     for (int f = 0; f < 4; f++) wb[f] = *(const bf16x8*)(cS + boff + f * 1024);
; #pragma unroll
;     for (int nf = 0; nf < 4; nf++)
; #pragma unroll
;       for (int mf = 0; mf < 8; mf++)
;         acc[nf][mf] = __builtin_amdgcn_mfma_f32_16x16x32_bf16(wb[nf], xa[mf], acc[nf][mf], 0, 0, 0);
;   }
	s_setprio 1
	v_add_u32_e32 v144, s1, v136
	v_mfma_f32_16x16x32_bf16 v[126:129], v[232:235], v[200:203], v[126:129]
	ds_read_b128 v[146:149], v144 offset:0
	v_mfma_f32_16x16x32_bf16 v[122:125], v[232:235], v[204:207], v[122:125]
	ds_read_b128 v[152:155], v144 offset:1024
	v_mfma_f32_16x16x32_bf16 v[118:121], v[232:235], v[208:211], v[118:121]
	ds_read_b128 v[156:159], v144 offset:2048
	v_mfma_f32_16x16x32_bf16 v[114:117], v[232:235], v[212:215], v[114:117]
	ds_read_b128 v[162:165], v144 offset:3072
	v_mfma_f32_16x16x32_bf16 v[110:113], v[232:235], v[216:219], v[110:113]
	ds_read_b128 v[166:169], v144 offset:4096
	v_mfma_f32_16x16x32_bf16 v[106:109], v[232:235], v[220:223], v[106:109]
	ds_read_b128 v[170:173], v144 offset:5120
	v_mfma_f32_16x16x32_bf16 v[102:105], v[232:235], v[224:227], v[102:105]
	ds_read_b128 v[176:179], v144 offset:6144
	v_mfma_f32_16x16x32_bf16 v[98:101], v[232:235], v[228:231], v[98:101]
	ds_read_b128 v[180:183], v144 offset:7168
	v_mfma_f32_16x16x32_bf16 v[94:97], v[236:239], v[200:203], v[94:97]
	v_add_u32_e64 v144, s1, v137
	v_mfma_f32_16x16x32_bf16 v[90:93], v[236:239], v[204:207], v[90:93]
	v_mfma_f32_16x16x32_bf16 v[86:89], v[236:239], v[208:211], v[86:89]
	ds_read_b128 v[184:187], v144 offset:16384
	v_mfma_f32_16x16x32_bf16 v[82:85], v[236:239], v[212:215], v[82:85]
	ds_read_b128 v[188:191], v144 offset:17408
	v_mfma_f32_16x16x32_bf16 v[78:81], v[236:239], v[216:219], v[78:81]
	ds_read_b128 v[192:195], v144 offset:18432
	v_mfma_f32_16x16x32_bf16 v[74:77], v[236:239], v[220:223], v[74:77]
	ds_read_b128 v[196:199], v144 offset:19456
	v_mfma_f32_16x16x32_bf16 v[70:73], v[236:239], v[224:227], v[70:73]
	v_mfma_f32_16x16x32_bf16 v[66:69], v[236:239], v[228:231], v[66:69]
	v_mfma_f32_16x16x32_bf16 v[62:65], v[240:243], v[200:203], v[62:65]
	v_mfma_f32_16x16x32_bf16 v[58:61], v[240:243], v[204:207], v[58:61]
	v_mfma_f32_16x16x32_bf16 v[54:57], v[240:243], v[208:211], v[54:57]
	v_mfma_f32_16x16x32_bf16 v[50:53], v[240:243], v[212:215], v[50:53]
	v_mfma_f32_16x16x32_bf16 v[46:49], v[240:243], v[216:219], v[46:49]
	v_mfma_f32_16x16x32_bf16 v[42:45], v[240:243], v[220:223], v[42:45]
	v_mfma_f32_16x16x32_bf16 v[38:41], v[240:243], v[224:227], v[38:41]
	v_mfma_f32_16x16x32_bf16 v[34:37], v[240:243], v[228:231], v[34:37]
	s_setprio 0
	s_nop 0
	v_mfma_f32_16x16x32_bf16 v[30:33], v[244:247], v[200:203], v[30:33]
	v_mfma_f32_16x16x32_bf16 v[26:29], v[244:247], v[204:207], v[26:29]
	v_mfma_f32_16x16x32_bf16 v[22:25], v[244:247], v[208:211], v[22:25]
	v_mfma_f32_16x16x32_bf16 v[18:21], v[244:247], v[212:215], v[18:21]
	v_mfma_f32_16x16x32_bf16 v[14:17], v[244:247], v[216:219], v[14:17]
	v_mfma_f32_16x16x32_bf16 v[10:13], v[244:247], v[220:223], v[10:13]
	v_mfma_f32_16x16x32_bf16 v[6:9], v[244:247], v[224:227], v[6:9]
	v_mfma_f32_16x16x32_bf16 v[2:5], v[244:247], v[228:231], v[2:5]
	s_mov_b32 s12, s1
	s_nop 0
	s_add_i32 s1, s1, 0x6000
	s_cmp_eq_u32 s1, 0x12000
	s_cselect_b32 s1, 0, s1
	s_nop 0
	.p2align 3
	s_waitcnt vmcnt(0) lgkmcnt(0)
	s_barrier
	s_setprio 1
	v_add_u32_e32 v144, s1, v136
	v_mfma_f32_16x16x32_bf16 v[126:129], v[184:187], v[146:149], v[126:129]
	ds_read_b128 v[200:203], v144 offset:0
	v_mfma_f32_16x16x32_bf16 v[122:125], v[184:187], v[152:155], v[122:125]
	ds_read_b128 v[204:207], v144 offset:1024
	v_mfma_f32_16x16x32_bf16 v[118:121], v[184:187], v[156:159], v[118:121]
	ds_read_b128 v[208:211], v144 offset:2048
	v_mfma_f32_16x16x32_bf16 v[114:117], v[184:187], v[162:165], v[114:117]
	ds_read_b128 v[212:215], v144 offset:3072
	v_mfma_f32_16x16x32_bf16 v[110:113], v[184:187], v[166:169], v[110:113]
	ds_read_b128 v[216:219], v144 offset:4096
	v_mfma_f32_16x16x32_bf16 v[106:109], v[184:187], v[170:173], v[106:109]
	ds_read_b128 v[220:223], v144 offset:5120
	v_mfma_f32_16x16x32_bf16 v[102:105], v[184:187], v[176:179], v[102:105]
	ds_read_b128 v[224:227], v144 offset:6144
	v_mfma_f32_16x16x32_bf16 v[98:101], v[184:187], v[180:183], v[98:101]
	ds_read_b128 v[228:231], v144 offset:7168
	v_mfma_f32_16x16x32_bf16 v[94:97], v[188:191], v[146:149], v[94:97]
	v_add_u32_e64 v144, s1, v137
	v_mfma_f32_16x16x32_bf16 v[90:93], v[188:191], v[152:155], v[90:93]
	v_mfma_f32_16x16x32_bf16 v[86:89], v[188:191], v[156:159], v[86:89]
	ds_read_b128 v[232:235], v144 offset:16384
	v_mfma_f32_16x16x32_bf16 v[82:85], v[188:191], v[162:165], v[82:85]
	ds_read_b128 v[236:239], v144 offset:17408
	v_mfma_f32_16x16x32_bf16 v[78:81], v[188:191], v[166:169], v[78:81]
	ds_read_b128 v[240:243], v144 offset:18432
	v_mfma_f32_16x16x32_bf16 v[74:77], v[188:191], v[170:173], v[74:77]
	ds_read_b128 v[244:247], v144 offset:19456
	v_mfma_f32_16x16x32_bf16 v[70:73], v[188:191], v[176:179], v[70:73]
	v_mfma_f32_16x16x32_bf16 v[66:69], v[188:191], v[180:183], v[66:69]
	v_mfma_f32_16x16x32_bf16 v[62:65], v[192:195], v[146:149], v[62:65]
	v_mfma_f32_16x16x32_bf16 v[58:61], v[192:195], v[152:155], v[58:61]
	v_mfma_f32_16x16x32_bf16 v[54:57], v[192:195], v[156:159], v[54:57]
	v_mfma_f32_16x16x32_bf16 v[50:53], v[192:195], v[162:165], v[50:53]
	v_mfma_f32_16x16x32_bf16 v[46:49], v[192:195], v[166:169], v[46:49]
	v_mfma_f32_16x16x32_bf16 v[42:45], v[192:195], v[170:173], v[42:45]
	v_mfma_f32_16x16x32_bf16 v[38:41], v[192:195], v[176:179], v[38:41]
	v_mfma_f32_16x16x32_bf16 v[34:37], v[192:195], v[180:183], v[34:37]
	s_setprio 0
	s_nop 0
	v_mfma_f32_16x16x32_bf16 v[30:33], v[196:199], v[146:149], v[30:33]
	v_mfma_f32_16x16x32_bf16 v[26:29], v[196:199], v[152:155], v[26:29]
	v_mfma_f32_16x16x32_bf16 v[22:25], v[196:199], v[156:159], v[22:25]
	v_mfma_f32_16x16x32_bf16 v[18:21], v[196:199], v[162:165], v[18:21]
	v_mfma_f32_16x16x32_bf16 v[14:17], v[196:199], v[166:169], v[14:17]
	v_mfma_f32_16x16x32_bf16 v[10:13], v[196:199], v[170:173], v[10:13]
	v_mfma_f32_16x16x32_bf16 v[6:9], v[196:199], v[176:179], v[6:9]
	v_mfma_f32_16x16x32_bf16 v[2:5], v[196:199], v[180:183], v[2:5]
	s_mov_b32 s12, s1
	s_nop 0
	s_add_i32 s1, s1, 0x6000
	s_cmp_eq_u32 s1, 0x12000
	s_cselect_b32 s1, 0, s1
	s_nop 0
	s_mov_b32 s4, 0x8000
	s_mov_b32 s5, 0
	s_mov_b32 s8, 0x10000
	s_mov_b32 s9, 0
	s_mov_b32 s40, 0x3fd744fd
	.p2align 3
	s_waitcnt lgkmcnt(0)
; DEVI float blo(unsigned u) { return __uint_as_float(u << 16); }
; DEVI float bhi(unsigned u) { return __uint_as_float(u & 0xffff0000u); }
;     ...
;     for (int nf = 0; nf < 4; nf++)
; #pragma unroll
;       for (int mf = 0; mf < 8; mf++)
;         acc[nf][mf] = __builtin_amdgcn_mfma_f32_16x16x32_bf16(wb[nf], xa[mf], acc[nf][mf], 0, 0, 0);
;     ...
;         if (EPI == EPI_RESID || EPI == EPI_RESID_ATOMIC) {
;           f32x4 x = a;
;           if (EPI == EPI_RESID || kpart == 0) {
;             const u32x2 xr = *(const u32x2*)((const u16*)(p.ws + WS_XB) + (size_t)row * 1024 + col);
;             x[0] += ALPHA * blo(xr[0]); x[1] += ALPHA * bhi(xr[0]); x[2] += ALPHA * blo(xr[1]); x[3] += ALPHA * bhi(xr[1]);
;           }
;           if (EPI == EPI_RESID) *(f32x4*)((float*)(p.ws + WS_XF) + (size_t)row * 1024 + col) = x;
;           else *(f32x4*)((float*)(p.ws + WS_SLAB) + ((size_t)kpart * 512 + (row - T_P)) * 1024 + col) = x;
	s_nop 0
	v_mfma_f32_16x16x32_bf16 v[126:129], v[232:235], v[200:203], v[126:129]
	v_mfma_f32_16x16x32_bf16 v[122:125], v[232:235], v[204:207], v[122:125]
	v_mfma_f32_16x16x32_bf16 v[118:121], v[232:235], v[208:211], v[118:121]
	v_mfma_f32_16x16x32_bf16 v[114:117], v[232:235], v[212:215], v[114:117]
	v_mfma_f32_16x16x32_bf16 v[110:113], v[232:235], v[216:219], v[110:113]
	v_mfma_f32_16x16x32_bf16 v[106:109], v[232:235], v[220:223], v[106:109]
	v_mfma_f32_16x16x32_bf16 v[102:105], v[232:235], v[224:227], v[102:105]
	v_mfma_f32_16x16x32_bf16 v[98:101], v[232:235], v[228:231], v[98:101]
	v_mfma_f32_16x16x32_bf16 v[94:97], v[236:239], v[200:203], v[94:97]
	v_mfma_f32_16x16x32_bf16 v[90:93], v[236:239], v[204:207], v[90:93]
	v_mfma_f32_16x16x32_bf16 v[86:89], v[236:239], v[208:211], v[86:89]
	v_mfma_f32_16x16x32_bf16 v[82:85], v[236:239], v[212:215], v[82:85]
	v_mfma_f32_16x16x32_bf16 v[78:81], v[236:239], v[216:219], v[78:81]
	v_mfma_f32_16x16x32_bf16 v[74:77], v[236:239], v[220:223], v[74:77]
	v_mfma_f32_16x16x32_bf16 v[70:73], v[236:239], v[224:227], v[70:73]
	v_mfma_f32_16x16x32_bf16 v[66:69], v[236:239], v[228:231], v[66:69]
	v_mfma_f32_16x16x32_bf16 v[62:65], v[240:243], v[200:203], v[62:65]
	v_mfma_f32_16x16x32_bf16 v[58:61], v[240:243], v[204:207], v[58:61]
	v_mfma_f32_16x16x32_bf16 v[54:57], v[240:243], v[208:211], v[54:57]
	v_mfma_f32_16x16x32_bf16 v[50:53], v[240:243], v[212:215], v[50:53]
	v_mfma_f32_16x16x32_bf16 v[46:49], v[240:243], v[216:219], v[46:49]
	v_mfma_f32_16x16x32_bf16 v[42:45], v[240:243], v[220:223], v[42:45]
	v_mfma_f32_16x16x32_bf16 v[38:41], v[240:243], v[224:227], v[38:41]
	v_mfma_f32_16x16x32_bf16 v[34:37], v[240:243], v[228:231], v[34:37]
	v_mfma_f32_16x16x32_bf16 v[30:33], v[244:247], v[200:203], v[30:33]
	v_mfma_f32_16x16x32_bf16 v[26:29], v[244:247], v[204:207], v[26:29]
	v_mfma_f32_16x16x32_bf16 v[22:25], v[244:247], v[208:211], v[22:25]
	v_mfma_f32_16x16x32_bf16 v[18:21], v[244:247], v[212:215], v[18:21]
	v_mfma_f32_16x16x32_bf16 v[14:17], v[244:247], v[216:219], v[14:17]
	v_mfma_f32_16x16x32_bf16 v[10:13], v[244:247], v[220:223], v[10:13]
	v_mfma_f32_16x16x32_bf16 v[6:9], v[244:247], v[224:227], v[6:9]
	v_mfma_f32_16x16x32_bf16 v[2:5], v[244:247], v[228:231], v[2:5]
	s_mov_b32 m0, s39
	s_cmp_eq_u32 s99, 0
	s_cbranch_scc1 .Lta8_first
	s_nop 7
	global_store_dwordx4 v[140:141], v[126:129], off offset:0
	global_store_dwordx4 v[140:141], v[94:97], off offset:64
	global_store_dwordx4 v[140:141], v[62:65], off offset:128
	global_store_dwordx4 v[140:141], v[30:33], off offset:192
	v_lshl_add_u64 v[140:141], v[140:141], 0, s[8:9]
	global_store_dwordx4 v[140:141], v[122:125], off offset:0
	global_store_dwordx4 v[140:141], v[90:93], off offset:64
	global_store_dwordx4 v[140:141], v[58:61], off offset:128
	global_store_dwordx4 v[140:141], v[26:29], off offset:192
	v_lshl_add_u64 v[140:141], v[140:141], 0, s[8:9]
	global_store_dwordx4 v[140:141], v[118:121], off offset:0
	global_store_dwordx4 v[140:141], v[86:89], off offset:64
	global_store_dwordx4 v[140:141], v[54:57], off offset:128
	global_store_dwordx4 v[140:141], v[22:25], off offset:192
	v_lshl_add_u64 v[140:141], v[140:141], 0, s[8:9]
	global_store_dwordx4 v[140:141], v[114:117], off offset:0
	global_store_dwordx4 v[140:141], v[82:85], off offset:64
	global_store_dwordx4 v[140:141], v[50:53], off offset:128
	global_store_dwordx4 v[140:141], v[18:21], off offset:192
	v_lshl_add_u64 v[140:141], v[140:141], 0, s[8:9]
	global_store_dwordx4 v[140:141], v[110:113], off offset:0
	global_store_dwordx4 v[140:141], v[78:81], off offset:64
	global_store_dwordx4 v[140:141], v[46:49], off offset:128
	global_store_dwordx4 v[140:141], v[14:17], off offset:192
	v_lshl_add_u64 v[140:141], v[140:141], 0, s[8:9]
	global_store_dwordx4 v[140:141], v[106:109], off offset:0
	global_store_dwordx4 v[140:141], v[74:77], off offset:64
	global_store_dwordx4 v[140:141], v[42:45], off offset:128
	global_store_dwordx4 v[140:141], v[10:13], off offset:192
	v_lshl_add_u64 v[140:141], v[140:141], 0, s[8:9]
	global_store_dwordx4 v[140:141], v[102:105], off offset:0
	global_store_dwordx4 v[140:141], v[70:73], off offset:64
	global_store_dwordx4 v[140:141], v[38:41], off offset:128
	global_store_dwordx4 v[140:141], v[6:9], off offset:192
	v_lshl_add_u64 v[140:141], v[140:141], 0, s[8:9]
	global_store_dwordx4 v[140:141], v[98:101], off offset:0
	global_store_dwordx4 v[140:141], v[66:69], off offset:64
	global_store_dwordx4 v[140:141], v[34:37], off offset:128
	global_store_dwordx4 v[140:141], v[2:5], off offset:192
	v_readlane_b32 s0, v250, 7
	s_cmpk_lg_u32 s0, 0x200
	s_cbranch_scc1 .Lta8_ar1
	s_mov_b32 s0, 1
	v_writelane_b32 v255, s0, 41
	v_readlane_b32 s1, v250, 0
	s_lshr_b32 s12, s1, 3
	s_and_b32 s1, s1, 7
	s_lshl_b32 s1, s1, 6
	s_add_i32 s1, s1, s12
	s_sub_i32 s38, s1, 0x200

;     ...
;   for (int kt = 0; kt < nk; kt++) {
;     if (kt + 1 < nk) asm volatile("s_waitcnt vmcnt(6)" ::: "memory");
;     else asm volatile("s_waitcnt vmcnt(0)" ::: "memory");
;     __builtin_amdgcn_s_barrier();
;     asm volatile("" ::: "memory");
;     if (kt + 2 < nk) G2_STAGE(kt + 2);
;     const char* cS = smem + (kt % 3) * 24576;
;     bf16x8 xa[8], wb[4];
; #pragma unroll
;     for (int f = 0; f < 8; f++) xa[f] = *(const bf16x8*)(cS + aoff + f * 1024);
; #pragma unroll
;     for (int f = 0; f < 4; f++) wb[f] = *(const bf16x8*)(cS + boff + f * 1024);
; #pragma unroll
;     for (int nf = 0; nf < 4; nf++)
; #pragma unroll
;       for (int mf = 0; mf < 8; mf++)
;         acc[nf][mf] = __builtin_amdgcn_mfma_f32_16x16x32_bf16(wb[nf], xa[mf], acc[nf][mf], 0, 0, 0);
;   }
.Lt8_loop:
	.p2align 3
	s_waitcnt vmcnt(6) lgkmcnt(0)
	s_barrier
	s_setprio 1
	v_add_u32_e32 v144, s40, v136
	v_mfma_f32_16x16x32_bf16 v[126:129], v[184:187], v[146:149], v[126:129]
	ds_read_b128 v[200:203], v144 offset:0
	v_mfma_f32_16x16x32_bf16 v[122:125], v[184:187], v[152:155], v[122:125]
	ds_read_b128 v[204:207], v144 offset:1024
	v_mfma_f32_16x16x32_bf16 v[118:121], v[184:187], v[156:159], v[118:121]
	ds_read_b128 v[208:211], v144 offset:2048
	v_mfma_f32_16x16x32_bf16 v[114:117], v[184:187], v[162:165], v[114:117]
	ds_read_b128 v[212:215], v144 offset:3072
	v_mfma_f32_16x16x32_bf16 v[110:113], v[184:187], v[166:169], v[110:113]
	ds_read_b128 v[216:219], v144 offset:4096
	v_mfma_f32_16x16x32_bf16 v[106:109], v[184:187], v[170:173], v[106:109]
	ds_read_b128 v[220:223], v144 offset:5120
	v_mfma_f32_16x16x32_bf16 v[102:105], v[184:187], v[176:179], v[102:105]
	ds_read_b128 v[224:227], v144 offset:6144
	v_mfma_f32_16x16x32_bf16 v[98:101], v[184:187], v[180:183], v[98:101]
	ds_read_b128 v[228:231], v144 offset:7168
	v_mfma_f32_16x16x32_bf16 v[94:97], v[188:191], v[146:149], v[94:97]
	v_add_u32_e64 v144, s40, v137
	v_mfma_f32_16x16x32_bf16 v[90:93], v[188:191], v[152:155], v[90:93]
	v_mfma_f32_16x16x32_bf16 v[86:89], v[188:191], v[156:159], v[86:89]
	ds_read_b128 v[232:235], v144 offset:16384
	v_mfma_f32_16x16x32_bf16 v[82:85], v[188:191], v[162:165], v[82:85]
	ds_read_b128 v[236:239], v144 offset:17408
	v_mfma_f32_16x16x32_bf16 v[78:81], v[188:191], v[166:169], v[78:81]
	ds_read_b128 v[240:243], v144 offset:18432
	v_mfma_f32_16x16x32_bf16 v[74:77], v[188:191], v[170:173], v[74:77]
	ds_read_b128 v[244:247], v144 offset:19456
	v_mfma_f32_16x16x32_bf16 v[70:73], v[188:191], v[176:179], v[70:73]
	s_add_i32 s42, s46, s41
	s_mov_b32 m0, s42
	v_lshl_add_u64 v[142:143], v[132:133], 0, s[2:3]
	v_mfma_f32_16x16x32_bf16 v[66:69], v[188:191], v[180:183], v[66:69]
	global_load_lds_dwordx4 v[132:133], off
	s_add_i32 m0, m0, 0x1000
	v_mfma_f32_16x16x32_bf16 v[62:65], v[192:195], v[146:149], v[62:65]
	v_mfma_f32_16x16x32_bf16 v[58:61], v[192:195], v[152:155], v[58:61]
	v_mfma_f32_16x16x32_bf16 v[54:57], v[192:195], v[156:159], v[54:57]
	global_load_lds_dwordx4 v[142:143], off
	v_lshl_add_u64 v[142:143], v[142:143], 0, s[2:3]
	s_add_i32 m0, m0, 0x1000
	v_mfma_f32_16x16x32_bf16 v[50:53], v[192:195], v[162:165], v[50:53]
	v_mfma_f32_16x16x32_bf16 v[46:49], v[192:195], v[166:169], v[46:49]
	v_mfma_f32_16x16x32_bf16 v[42:45], v[192:195], v[170:173], v[42:45]
	global_load_lds_dwordx4 v[142:143], off
	v_lshl_add_u64 v[142:143], v[142:143], 0, s[2:3]
	s_add_i32 m0, m0, 0x1000
	v_mfma_f32_16x16x32_bf16 v[38:41], v[192:195], v[176:179], v[38:41]
	v_mfma_f32_16x16x32_bf16 v[34:37], v[192:195], v[180:183], v[34:37]
	s_setprio 0
	s_nop 0
	v_mfma_f32_16x16x32_bf16 v[30:33], v[196:199], v[146:149], v[30:33]
	global_load_lds_dwordx4 v[142:143], off
	s_add_i32 m0, m0, 0x1000
	v_lshl_add_u64 v[142:143], v[134:135], 0, s[2:3]
	v_mfma_f32_16x16x32_bf16 v[26:29], v[196:199], v[152:155], v[26:29]
	v_mfma_f32_16x16x32_bf16 v[22:25], v[196:199], v[156:159], v[22:25]
	v_mfma_f32_16x16x32_bf16 v[18:21], v[196:199], v[162:165], v[18:21]
	global_load_lds_dwordx4 v[134:135], off
	s_add_i32 m0, m0, 0x1000
	v_lshl_add_u64 v[132:133], v[132:133], 0, s[12:13]
	v_mfma_f32_16x16x32_bf16 v[14:17], v[196:199], v[166:169], v[14:17]
	v_mfma_f32_16x16x32_bf16 v[10:13], v[196:199], v[170:173], v[10:13]
	v_mfma_f32_16x16x32_bf16 v[6:9], v[196:199], v[176:179], v[6:9]
	global_load_lds_dwordx4 v[142:143], off
	v_lshl_add_u64 v[134:135], v[134:135], 0, s[4:5]
	v_mfma_f32_16x16x32_bf16 v[2:5], v[196:199], v[180:183], v[2:5]
	s_mov_b32 s41, s40
	s_nop 0
	s_add_i32 s40, s40, 0x6000
	s_cmp_eq_u32 s40, 0x12000
	s_cselect_b32 s40, 0, s40
	s_nop 0
	.p2align 3
	s_waitcnt vmcnt(6) lgkmcnt(0)
	s_barrier
	s_setprio 1
	v_add_u32_e32 v144, s40, v136
	v_mfma_f32_16x16x32_bf16 v[126:129], v[232:235], v[200:203], v[126:129]
	ds_read_b128 v[146:149], v144 offset:0
	v_mfma_f32_16x16x32_bf16 v[122:125], v[232:235], v[204:207], v[122:125]
	ds_read_b128 v[152:155], v144 offset:1024
	v_mfma_f32_16x16x32_bf16 v[118:121], v[232:235], v[208:211], v[118:121]
	ds_read_b128 v[156:159], v144 offset:2048
	v_mfma_f32_16x16x32_bf16 v[114:117], v[232:235], v[212:215], v[114:117]
	ds_read_b128 v[162:165], v144 offset:3072
	v_mfma_f32_16x16x32_bf16 v[110:113], v[232:235], v[216:219], v[110:113]
	ds_read_b128 v[166:169], v144 offset:4096
	v_mfma_f32_16x16x32_bf16 v[106:109], v[232:235], v[220:223], v[106:109]
	ds_read_b128 v[170:173], v144 offset:5120
	v_mfma_f32_16x16x32_bf16 v[102:105], v[232:235], v[224:227], v[102:105]
	ds_read_b128 v[176:179], v144 offset:6144
	v_mfma_f32_16x16x32_bf16 v[98:101], v[232:235], v[228:231], v[98:101]
	ds_read_b128 v[180:183], v144 offset:7168
	v_mfma_f32_16x16x32_bf16 v[94:97], v[236:239], v[200:203], v[94:97]
	v_add_u32_e64 v144, s40, v137
	v_mfma_f32_16x16x32_bf16 v[90:93], v[236:239], v[204:207], v[90:93]
	v_mfma_f32_16x16x32_bf16 v[86:89], v[236:239], v[208:211], v[86:89]
	ds_read_b128 v[184:187], v144 offset:16384
	v_mfma_f32_16x16x32_bf16 v[82:85], v[236:239], v[212:215], v[82:85]
	ds_read_b128 v[188:191], v144 offset:17408
	v_mfma_f32_16x16x32_bf16 v[78:81], v[236:239], v[216:219], v[78:81]
	ds_read_b128 v[192:195], v144 offset:18432
	v_mfma_f32_16x16x32_bf16 v[74:77], v[236:239], v[220:223], v[74:77]
	ds_read_b128 v[196:199], v144 offset:19456
	v_mfma_f32_16x16x32_bf16 v[70:73], v[236:239], v[224:227], v[70:73]
	s_add_i32 s42, s46, s41
	s_mov_b32 m0, s42
	v_lshl_add_u64 v[142:143], v[132:133], 0, s[2:3]
	v_mfma_f32_16x16x32_bf16 v[66:69], v[236:239], v[228:231], v[66:69]
;     ...
;   for (int kt = 0; kt < nk; kt++) {
;     if (kt + 1 < nk) asm volatile("s_waitcnt vmcnt(6)" ::: "memory");
;     else asm volatile("s_waitcnt vmcnt(0)" ::: "memory");
;     __builtin_amdgcn_s_barrier();
;     asm volatile("" ::: "memory");
;     if (kt + 2 < nk) G2_STAGE(kt + 2);
;     const char* cS = smem + (kt % 3) * 24576;
;     bf16x8 xa[8], wb[4];
; #pragma unroll
;     for (int f = 0; f < 8; f++) xa[f] = *(const bf16x8*)(cS + aoff + f * 1024);
; #pragma unroll
;     for (int f = 0; f < 4; f++) wb[f] = *(const bf16x8*)(cS + boff + f * 1024);
; #pragma unroll
;     for (int nf = 0; nf < 4; nf++)
; #pragma unroll
;       for (int mf = 0; mf < 8; mf++)
;         acc[nf][mf] = __builtin_amdgcn_mfma_f32_16x16x32_bf16(wb[nf], xa[mf], acc[nf][mf], 0, 0, 0);
;   }
	global_load_lds_dwordx4 v[132:133], off
	s_add_i32 m0, m0, 0x1000
	v_mfma_f32_16x16x32_bf16 v[62:65], v[240:243], v[200:203], v[62:65]
	v_mfma_f32_16x16x32_bf16 v[58:61], v[240:243], v[204:207], v[58:61]
	v_mfma_f32_16x16x32_bf16 v[54:57], v[240:243], v[208:211], v[54:57]
	global_load_lds_dwordx4 v[142:143], off
	v_lshl_add_u64 v[142:143], v[142:143], 0, s[2:3]
	s_add_i32 m0, m0, 0x1000
	v_mfma_f32_16x16x32_bf16 v[50:53], v[240:243], v[212:215], v[50:53]
	v_mfma_f32_16x16x32_bf16 v[46:49], v[240:243], v[216:219], v[46:49]
	v_mfma_f32_16x16x32_bf16 v[42:45], v[240:243], v[220:223], v[42:45]
	global_load_lds_dwordx4 v[142:143], off
	v_lshl_add_u64 v[142:143], v[142:143], 0, s[2:3]
	s_add_i32 m0, m0, 0x1000
	v_mfma_f32_16x16x32_bf16 v[38:41], v[240:243], v[224:227], v[38:41]
	v_mfma_f32_16x16x32_bf16 v[34:37], v[240:243], v[228:231], v[34:37]
	s_setprio 0
	s_nop 0
	v_mfma_f32_16x16x32_bf16 v[30:33], v[244:247], v[200:203], v[30:33]
	global_load_lds_dwordx4 v[142:143], off
	s_add_i32 m0, m0, 0x1000
	v_lshl_add_u64 v[142:143], v[134:135], 0, s[2:3]
	v_mfma_f32_16x16x32_bf16 v[26:29], v[244:247], v[204:207], v[26:29]
	v_mfma_f32_16x16x32_bf16 v[22:25], v[244:247], v[208:211], v[22:25]
	v_mfma_f32_16x16x32_bf16 v[18:21], v[244:247], v[212:215], v[18:21]
	global_load_lds_dwordx4 v[134:135], off
	s_add_i32 m0, m0, 0x1000
	v_lshl_add_u64 v[132:133], v[132:133], 0, s[12:13]
	v_mfma_f32_16x16x32_bf16 v[14:17], v[244:247], v[216:219], v[14:17]
	v_mfma_f32_16x16x32_bf16 v[10:13], v[244:247], v[220:223], v[10:13]
	v_mfma_f32_16x16x32_bf16 v[6:9], v[244:247], v[224:227], v[6:9]
	global_load_lds_dwordx4 v[142:143], off
	v_lshl_add_u64 v[134:135], v[134:135], 0, s[4:5]
	v_mfma_f32_16x16x32_bf16 v[2:5], v[244:247], v[228:231], v[2:5]
	s_mov_b32 s41, s40
	s_nop 0
	s_add_i32 s40, s40, 0x6000
	s_cmp_eq_u32 s40, 0x12000
	s_cselect_b32 s40, 0, s40
	s_nop 0
	s_sub_i32 s39, s39, 1
	s_cmp_lg_u32 s39, 0
	s_cbranch_scc1 .Lt8_loop
	.p2align 3
	s_waitcnt vmcnt(6) lgkmcnt(0)
	s_barrier
	s_setprio 1
	v_add_u32_e32 v144, s40, v136
	v_mfma_f32_16x16x32_bf16 v[126:129], v[184:187], v[146:149], v[126:129]
	ds_read_b128 v[200:203], v144 offset:0
	v_mfma_f32_16x16x32_bf16 v[122:125], v[184:187], v[152:155], v[122:125]
	ds_read_b128 v[204:207], v144 offset:1024
	v_mfma_f32_16x16x32_bf16 v[118:121], v[184:187], v[156:159], v[118:121]
	ds_read_b128 v[208:211], v144 offset:2048
	v_mfma_f32_16x16x32_bf16 v[114:117], v[184:187], v[162:165], v[114:117]
	ds_read_b128 v[212:215], v144 offset:3072
	v_mfma_f32_16x16x32_bf16 v[110:113], v[184:187], v[166:169], v[110:113]
	ds_read_b128 v[216:219], v144 offset:4096
	v_mfma_f32_16x16x32_bf16 v[106:109], v[184:187], v[170:173], v[106:109]
	ds_read_b128 v[220:223], v144 offset:5120
	v_mfma_f32_16x16x32_bf16 v[102:105], v[184:187], v[176:179], v[102:105]
	ds_read_b128 v[224:227], v144 offset:6144
	v_mfma_f32_16x16x32_bf16 v[98:101], v[184:187], v[180:183], v[98:101]
	ds_read_b128 v[228:231], v144 offset:7168
	v_mfma_f32_16x16x32_bf16 v[94:97], v[188:191], v[146:149], v[94:97]
	v_add_u32_e64 v144, s40, v137
	v_mfma_f32_16x16x32_bf16 v[90:93], v[188:191], v[152:155], v[90:93]
	v_mfma_f32_16x16x32_bf16 v[86:89], v[188:191], v[156:159], v[86:89]
	ds_read_b128 v[232:235], v144 offset:16384
	v_mfma_f32_16x16x32_bf16 v[82:85], v[188:191], v[162:165], v[82:85]
	ds_read_b128 v[236:239], v144 offset:17408
	v_mfma_f32_16x16x32_bf16 v[78:81], v[188:191], v[166:169], v[78:81]
	ds_read_b128 v[240:243], v144 offset:18432
	v_mfma_f32_16x16x32_bf16 v[74:77], v[188:191], v[170:173], v[74:77]
	ds_read_b128 v[244:247], v144 offset:19456
	v_mfma_f32_16x16x32_bf16 v[70:73], v[188:191], v[176:179], v[70:73]
	s_add_i32 s42, s46, s41
	s_mov_b32 m0, s42
	v_lshl_add_u64 v[142:143], v[132:133], 0, s[2:3]
	v_mfma_f32_16x16x32_bf16 v[66:69], v[188:191], v[180:183], v[66:69]
	global_load_lds_dwordx4 v[132:133], off
	s_add_i32 m0, m0, 0x1000
	v_mfma_f32_16x16x32_bf16 v[62:65], v[192:195], v[146:149], v[62:65]
	v_mfma_f32_16x16x32_bf16 v[58:61], v[192:195], v[152:155], v[58:61]
	v_mfma_f32_16x16x32_bf16 v[54:57], v[192:195], v[156:159], v[54:57]
	global_load_lds_dwordx4 v[142:143], off
	v_lshl_add_u64 v[142:143], v[142:143], 0, s[2:3]
	s_add_i32 m0, m0, 0x1000
	v_mfma_f32_16x16x32_bf16 v[50:53], v[192:195], v[162:165], v[50:53]
	v_mfma_f32_16x16x32_bf16 v[46:49], v[192:195], v[166:169], v[46:49]
	v_mfma_f32_16x16x32_bf16 v[42:45], v[192:195], v[170:173], v[42:45]
	global_load_lds_dwordx4 v[142:143], off
	v_lshl_add_u64 v[142:143], v[142:143], 0, s[2:3]
	s_add_i32 m0, m0, 0x1000
	v_mfma_f32_16x16x32_bf16 v[38:41], v[192:195], v[176:179], v[38:41]
	v_mfma_f32_16x16x32_bf16 v[34:37], v[192:195], v[180:183], v[34:37]
	s_setprio 0
	s_nop 0
	v_mfma_f32_16x16x32_bf16 v[30:33], v[196:199], v[146:149], v[30:33]
	global_load_lds_dwordx4 v[142:143], off
	s_add_i32 m0, m0, 0x1000
	v_lshl_add_u64 v[142:143], v[134:135], 0, s[2:3]
	v_mfma_f32_16x16x32_bf16 v[26:29], v[196:199], v[152:155], v[26:29]
	v_mfma_f32_16x16x32_bf16 v[22:25], v[196:199], v[156:159], v[22:25]
	v_mfma_f32_16x16x32_bf16 v[18:21], v[196:199], v[162:165], v[18:21]
	global_load_lds_dwordx4 v[134:135], off
	s_add_i32 m0, m0, 0x1000
	v_lshl_add_u64 v[132:133], v[132:133], 0, s[12:13]
	v_mfma_f32_16x16x32_bf16 v[14:17], v[196:199], v[166:169], v[14:17]
	v_mfma_f32_16x16x32_bf16 v[10:13], v[196:199], v[170:173], v[10:13]
	v_mfma_f32_16x16x32_bf16 v[6:9], v[196:199], v[176:179], v[6:9]
	global_load_lds_dwordx4 v[142:143], off
	v_lshl_add_u64 v[134:135], v[134:135], 0, s[4:5]
	v_mfma_f32_16x16x32_bf16 v[2:5], v[196:199], v[180:183], v[2:5]
	s_mov_b32 s41, s40
	s_nop 0
	s_add_i32 s40, s40, 0x6000
	s_cmp_eq_u32 s40, 0x12000
	s_cselect_b32 s40, 0, s40
	s_nop 0
	.p2align 3
	s_waitcnt vmcnt(6) lgkmcnt(0)
	s_barrier
;     ...
;   for (int kt = 0; kt < nk; kt++) {
;     if (kt + 1 < nk) asm volatile("s_waitcnt vmcnt(6)" ::: "memory");
;     else asm volatile("s_waitcnt vmcnt(0)" ::: "memory");
;     __builtin_amdgcn_s_barrier();
;     asm volatile("" ::: "memory");
;     if (kt + 2 < nk) G2_STAGE(kt + 2);
;     const char* cS = smem + (kt % 3) * 24576;
;     bf16x8 xa[8], wb[4];
; #pragma unroll
;     for (int f = 0; f < 8; f++) xa[f] = *(const bf16x8*)(cS + aoff + f * 1024);
; #pragma unroll
;     for (int f = 0; f < 4; f++) wb[f] = *(const bf16x8*)(cS + boff + f * 1024);
; #pragma unroll
;     for (int nf = 0; nf < 4; nf++)
; #pragma unroll
;       for (int mf = 0; mf < 8; mf++)
;         acc[nf][mf] = __builtin_amdgcn_mfma_f32_16x16x32_bf16(wb[nf], xa[mf], acc[nf][mf], 0, 0, 0);
;   }
	s_setprio 1
	v_add_u32_e32 v144, s40, v136
	v_mfma_f32_16x16x32_bf16 v[126:129], v[232:235], v[200:203], v[126:129]
	ds_read_b128 v[146:149], v144 offset:0
	v_mfma_f32_16x16x32_bf16 v[122:125], v[232:235], v[204:207], v[122:125]
	ds_read_b128 v[152:155], v144 offset:1024
	v_mfma_f32_16x16x32_bf16 v[118:121], v[232:235], v[208:211], v[118:121]
	ds_read_b128 v[156:159], v144 offset:2048
	v_mfma_f32_16x16x32_bf16 v[114:117], v[232:235], v[212:215], v[114:117]
	ds_read_b128 v[162:165], v144 offset:3072
	v_mfma_f32_16x16x32_bf16 v[110:113], v[232:235], v[216:219], v[110:113]
	ds_read_b128 v[166:169], v144 offset:4096
	v_mfma_f32_16x16x32_bf16 v[106:109], v[232:235], v[220:223], v[106:109]
	ds_read_b128 v[170:173], v144 offset:5120
	v_mfma_f32_16x16x32_bf16 v[102:105], v[232:235], v[224:227], v[102:105]
	ds_read_b128 v[176:179], v144 offset:6144
	v_mfma_f32_16x16x32_bf16 v[98:101], v[232:235], v[228:231], v[98:101]
	ds_read_b128 v[180:183], v144 offset:7168
	v_mfma_f32_16x16x32_bf16 v[94:97], v[236:239], v[200:203], v[94:97]
	v_add_u32_e64 v144, s40, v137
	v_mfma_f32_16x16x32_bf16 v[90:93], v[236:239], v[204:207], v[90:93]
	v_mfma_f32_16x16x32_bf16 v[86:89], v[236:239], v[208:211], v[86:89]
	ds_read_b128 v[184:187], v144 offset:16384
	v_mfma_f32_16x16x32_bf16 v[82:85], v[236:239], v[212:215], v[82:85]
	ds_read_b128 v[188:191], v144 offset:17408
	v_mfma_f32_16x16x32_bf16 v[78:81], v[236:239], v[216:219], v[78:81]
	ds_read_b128 v[192:195], v144 offset:18432
	v_mfma_f32_16x16x32_bf16 v[74:77], v[236:239], v[220:223], v[74:77]
	ds_read_b128 v[196:199], v144 offset:19456
	v_mfma_f32_16x16x32_bf16 v[70:73], v[236:239], v[224:227], v[70:73]
	v_mfma_f32_16x16x32_bf16 v[66:69], v[236:239], v[228:231], v[66:69]
	v_mfma_f32_16x16x32_bf16 v[62:65], v[240:243], v[200:203], v[62:65]
	v_mfma_f32_16x16x32_bf16 v[58:61], v[240:243], v[204:207], v[58:61]
	v_mfma_f32_16x16x32_bf16 v[54:57], v[240:243], v[208:211], v[54:57]
	v_mfma_f32_16x16x32_bf16 v[50:53], v[240:243], v[212:215], v[50:53]
	v_mfma_f32_16x16x32_bf16 v[46:49], v[240:243], v[216:219], v[46:49]
	v_mfma_f32_16x16x32_bf16 v[42:45], v[240:243], v[220:223], v[42:45]
	v_mfma_f32_16x16x32_bf16 v[38:41], v[240:243], v[224:227], v[38:41]
	v_mfma_f32_16x16x32_bf16 v[34:37], v[240:243], v[228:231], v[34:37]
	s_setprio 0
	s_nop 0
	v_mfma_f32_16x16x32_bf16 v[30:33], v[244:247], v[200:203], v[30:33]
	v_mfma_f32_16x16x32_bf16 v[26:29], v[244:247], v[204:207], v[26:29]
	v_mfma_f32_16x16x32_bf16 v[22:25], v[244:247], v[208:211], v[22:25]
	v_mfma_f32_16x16x32_bf16 v[18:21], v[244:247], v[212:215], v[18:21]
	v_mfma_f32_16x16x32_bf16 v[14:17], v[244:247], v[216:219], v[14:17]
	v_mfma_f32_16x16x32_bf16 v[10:13], v[244:247], v[220:223], v[10:13]
	v_mfma_f32_16x16x32_bf16 v[6:9], v[244:247], v[224:227], v[6:9]
	v_mfma_f32_16x16x32_bf16 v[2:5], v[244:247], v[228:231], v[2:5]
	s_mov_b32 s41, s40
	s_nop 0
	s_add_i32 s40, s40, 0x6000
	s_cmp_eq_u32 s40, 0x12000
	s_cselect_b32 s40, 0, s40
	s_nop 0
	.p2align 3
	s_waitcnt vmcnt(0) lgkmcnt(0)
	s_barrier
	s_setprio 1
	v_add_u32_e32 v144, s40, v136
	v_mfma_f32_16x16x32_bf16 v[126:129], v[184:187], v[146:149], v[126:129]
	ds_read_b128 v[200:203], v144 offset:0
	v_mfma_f32_16x16x32_bf16 v[122:125], v[184:187], v[152:155], v[122:125]
	ds_read_b128 v[204:207], v144 offset:1024
	v_mfma_f32_16x16x32_bf16 v[118:121], v[184:187], v[156:159], v[118:121]
	ds_read_b128 v[208:211], v144 offset:2048
	v_mfma_f32_16x16x32_bf16 v[114:117], v[184:187], v[162:165], v[114:117]
	ds_read_b128 v[212:215], v144 offset:3072
	v_mfma_f32_16x16x32_bf16 v[110:113], v[184:187], v[166:169], v[110:113]
	ds_read_b128 v[216:219], v144 offset:4096
	v_mfma_f32_16x16x32_bf16 v[106:109], v[184:187], v[170:173], v[106:109]
	ds_read_b128 v[220:223], v144 offset:5120
	v_mfma_f32_16x16x32_bf16 v[102:105], v[184:187], v[176:179], v[102:105]
	ds_read_b128 v[224:227], v144 offset:6144
	v_mfma_f32_16x16x32_bf16 v[98:101], v[184:187], v[180:183], v[98:101]
	ds_read_b128 v[228:231], v144 offset:7168
	v_mfma_f32_16x16x32_bf16 v[94:97], v[188:191], v[146:149], v[94:97]
	v_add_u32_e64 v144, s40, v137
	v_mfma_f32_16x16x32_bf16 v[90:93], v[188:191], v[152:155], v[90:93]
	v_mfma_f32_16x16x32_bf16 v[86:89], v[188:191], v[156:159], v[86:89]
	ds_read_b128 v[232:235], v144 offset:16384
	v_mfma_f32_16x16x32_bf16 v[82:85], v[188:191], v[162:165], v[82:85]
	ds_read_b128 v[236:239], v144 offset:17408
	v_mfma_f32_16x16x32_bf16 v[78:81], v[188:191], v[166:169], v[78:81]
	ds_read_b128 v[240:243], v144 offset:18432
	v_mfma_f32_16x16x32_bf16 v[74:77], v[188:191], v[170:173], v[74:77]
	ds_read_b128 v[244:247], v144 offset:19456
	v_mfma_f32_16x16x32_bf16 v[70:73], v[188:191], v[176:179], v[70:73]
	v_mfma_f32_16x16x32_bf16 v[66:69], v[188:191], v[180:183], v[66:69]
	v_mfma_f32_16x16x32_bf16 v[62:65], v[192:195], v[146:149], v[62:65]
	v_mfma_f32_16x16x32_bf16 v[58:61], v[192:195], v[152:155], v[58:61]
	v_mfma_f32_16x16x32_bf16 v[54:57], v[192:195], v[156:159], v[54:57]
	v_mfma_f32_16x16x32_bf16 v[50:53], v[192:195], v[162:165], v[50:53]
	v_mfma_f32_16x16x32_bf16 v[46:49], v[192:195], v[166:169], v[46:49]
	v_mfma_f32_16x16x32_bf16 v[42:45], v[192:195], v[170:173], v[42:45]
	v_mfma_f32_16x16x32_bf16 v[38:41], v[192:195], v[176:179], v[38:41]
	v_mfma_f32_16x16x32_bf16 v[34:37], v[192:195], v[180:183], v[34:37]
	s_setprio 0
	s_nop 0
	v_mfma_f32_16x16x32_bf16 v[30:33], v[196:199], v[146:149], v[30:33]
	v_mfma_f32_16x16x32_bf16 v[26:29], v[196:199], v[152:155], v[26:29]
	v_mfma_f32_16x16x32_bf16 v[22:25], v[196:199], v[156:159], v[22:25]
	v_mfma_f32_16x16x32_bf16 v[18:21], v[196:199], v[162:165], v[18:21]
	v_mfma_f32_16x16x32_bf16 v[14:17], v[196:199], v[166:169], v[14:17]
	v_mfma_f32_16x16x32_bf16 v[10:13], v[196:199], v[170:173], v[10:13]
	v_mfma_f32_16x16x32_bf16 v[6:9], v[196:199], v[176:179], v[6:9]
	v_mfma_f32_16x16x32_bf16 v[2:5], v[196:199], v[180:183], v[2:5]
	s_mov_b32 s41, s40
	s_nop 0
	s_add_i32 s40, s40, 0x6000
	s_cmp_eq_u32 s40, 0x12000
	s_cselect_b32 s40, 0, s40
	s_nop 0
	s_mov_b32 s4, 0x8000
	s_mov_b32 s5, 0
	s_mov_b32 s10, 0x10000
	s_mov_b32 s11, 0
	s_mov_b32 s44, 0x3fd744fd
	.p2align 3
	s_waitcnt lgkmcnt(0)
; DEVI float blo(unsigned u) { return __uint_as_float(u << 16); }
; DEVI float bhi(unsigned u) { return __uint_as_float(u & 0xffff0000u); }
;     ...
;     for (int nf = 0; nf < 4; nf++)
; #pragma unroll
;       for (int mf = 0; mf < 8; mf++)
;         acc[nf][mf] = __builtin_amdgcn_mfma_f32_16x16x32_bf16(wb[nf], xa[mf], acc[nf][mf], 0, 0, 0);
;     ...
; #pragma unroll
;       for (int nf = 0; nf < 4; nf++) {
;         const int col = n0 + wn * 64 + nf * 16 + quad * 4;
;         f32x4 a = acc[nf][mf];
;         if (EPI == EPI_RESID || EPI == EPI_RESID_ATOMIC) {
;           f32x4 x = a;
;           if (EPI == EPI_RESID || kpart == 0) {
;             const u32x2 xr = *(const u32x2*)((const u16*)(p.ws + WS_XB) + (size_t)row * 1024 + col);
;             x[0] += ALPHA * blo(xr[0]); x[1] += ALPHA * bhi(xr[0]); x[2] += ALPHA * blo(xr[1]); x[3] += ALPHA * bhi(xr[1]);
;           }
;           if (EPI == EPI_RESID) *(f32x4*)((float*)(p.ws + WS_XF) + (size_t)row * 1024 + col) = x;
;           else *(f32x4*)((float*)(p.ws + WS_SLAB) + ((size_t)kpart * 512 + (row - T_P)) * 1024 + col) = x;
	s_nop 0
	v_mfma_f32_16x16x32_bf16 v[126:129], v[232:235], v[200:203], v[126:129]
	v_mfma_f32_16x16x32_bf16 v[122:125], v[232:235], v[204:207], v[122:125]
	v_mfma_f32_16x16x32_bf16 v[118:121], v[232:235], v[208:211], v[118:121]
	v_mfma_f32_16x16x32_bf16 v[114:117], v[232:235], v[212:215], v[114:117]
	v_mfma_f32_16x16x32_bf16 v[110:113], v[232:235], v[216:219], v[110:113]
	global_load_dwordx4 v[146:149], v[138:139], off offset:0
	v_mfma_f32_16x16x32_bf16 v[106:109], v[232:235], v[220:223], v[106:109]
	v_mfma_f32_16x16x32_bf16 v[102:105], v[232:235], v[224:227], v[102:105]
	global_load_dwordx4 v[152:155], v[138:139], off offset:64
	v_mfma_f32_16x16x32_bf16 v[98:101], v[232:235], v[228:231], v[98:101]
	v_lshl_add_u64 v[138:139], v[138:139], 0, s[4:5]
	v_mfma_f32_16x16x32_bf16 v[94:97], v[236:239], v[200:203], v[94:97]
	global_load_dwordx4 v[156:159], v[138:139], off offset:0
	v_mfma_f32_16x16x32_bf16 v[90:93], v[236:239], v[204:207], v[90:93]
	v_mfma_f32_16x16x32_bf16 v[86:89], v[236:239], v[208:211], v[86:89]
	global_load_dwordx4 v[162:165], v[138:139], off offset:64
	v_mfma_f32_16x16x32_bf16 v[82:85], v[236:239], v[212:215], v[82:85]
	v_lshl_add_u64 v[138:139], v[138:139], 0, s[4:5]
	v_mfma_f32_16x16x32_bf16 v[78:81], v[236:239], v[216:219], v[78:81]
	global_load_dwordx4 v[166:169], v[138:139], off offset:0
	v_mfma_f32_16x16x32_bf16 v[74:77], v[236:239], v[220:223], v[74:77]
	v_mfma_f32_16x16x32_bf16 v[70:73], v[236:239], v[224:227], v[70:73]
	global_load_dwordx4 v[170:173], v[138:139], off offset:64
	v_mfma_f32_16x16x32_bf16 v[66:69], v[236:239], v[228:231], v[66:69]
	v_lshl_add_u64 v[138:139], v[138:139], 0, s[4:5]
	v_mfma_f32_16x16x32_bf16 v[62:65], v[240:243], v[200:203], v[62:65]
	global_load_dwordx4 v[176:179], v[138:139], off offset:0
	v_mfma_f32_16x16x32_bf16 v[58:61], v[240:243], v[204:207], v[58:61]
	v_mfma_f32_16x16x32_bf16 v[54:57], v[240:243], v[208:211], v[54:57]
	global_load_dwordx4 v[180:183], v[138:139], off offset:64
	v_mfma_f32_16x16x32_bf16 v[50:53], v[240:243], v[212:215], v[50:53]
	v_lshl_add_u64 v[138:139], v[138:139], 0, s[4:5]
	v_mfma_f32_16x16x32_bf16 v[46:49], v[240:243], v[216:219], v[46:49]
	global_load_dwordx4 v[184:187], v[138:139], off offset:0
	v_mfma_f32_16x16x32_bf16 v[42:45], v[240:243], v[220:223], v[42:45]
	v_mfma_f32_16x16x32_bf16 v[38:41], v[240:243], v[224:227], v[38:41]
	global_load_dwordx4 v[188:191], v[138:139], off offset:64
	v_mfma_f32_16x16x32_bf16 v[34:37], v[240:243], v[228:231], v[34:37]
	v_lshl_add_u64 v[138:139], v[138:139], 0, s[4:5]
	v_mfma_f32_16x16x32_bf16 v[30:33], v[244:247], v[200:203], v[30:33]
	global_load_dwordx4 v[192:195], v[138:139], off offset:0
	v_mfma_f32_16x16x32_bf16 v[26:29], v[244:247], v[204:207], v[26:29]
	v_mfma_f32_16x16x32_bf16 v[22:25], v[244:247], v[208:211], v[22:25]
	global_load_dwordx4 v[196:199], v[138:139], off offset:64
	v_mfma_f32_16x16x32_bf16 v[18:21], v[244:247], v[212:215], v[18:21]
	v_lshl_add_u64 v[138:139], v[138:139], 0, s[4:5]
	v_mfma_f32_16x16x32_bf16 v[14:17], v[244:247], v[216:219], v[14:17]
	v_mfma_f32_16x16x32_bf16 v[10:13], v[244:247], v[220:223], v[10:13]
	v_mfma_f32_16x16x32_bf16 v[6:9], v[244:247], v[224:227], v[6:9]
	v_mfma_f32_16x16x32_bf16 v[2:5], v[244:247], v[228:231], v[2:5]
	s_mov_b32 m0, s43
	global_load_dwordx4 v[200:203], v[138:139], off offset:0
	global_load_dwordx4 v[204:207], v[138:139], off offset:64
	v_lshl_add_u64 v[138:139], v[138:139], 0, s[4:5]
	global_load_dwordx4 v[208:211], v[138:139], off offset:0
	global_load_dwordx4 v[212:215], v[138:139], off offset:64
	v_lshl_add_u64 v[138:139], v[138:139], 0, s[4:5]
	s_nop 7
	v_and_b32_e32 v228, 1, v145
	v_cmp_ne_u32_e32 vcc, 0, v228
	v_mov_b32_e32 v229, 0xfffff040
	v_cndmask_b32_e32 v230, 0, v229, vcc
	v_ashrrev_i32_e32 v231, 31, v230
	v_lshl_add_u64 v[140:141], v[140:141], 0, v[230:231]
	v_add_co_u32_e32 v142, vcc, 0x1000, v140
	s_nop 0
	v_addc_co_u32_e32 v143, vcc, 0, v141, vcc
	v_cmp_ne_u32_e32 vcc, 0, v228
	s_waitcnt vmcnt(15)
	v_permlane16_swap_b32_e32 v146, v148
	v_permlane16_swap_b32_e32 v147, v149
	v_lshlrev_b32_e32 v216, 16, v146
	v_and_b32_e32 v146, 0xffff0000, v146
	v_lshlrev_b32_e32 v217, 16, v147
	v_and_b32_e32 v147, 0xffff0000, v147
	v_fmac_f32_e32 v126, s44, v216
	v_fmac_f32_e32 v127, s44, v146
	v_fmac_f32_e32 v128, s44, v217
	v_fmac_f32_e32 v129, s44, v147
	v_lshlrev_b32_e32 v216, 16, v148
	v_and_b32_e32 v148, 0xffff0000, v148
	v_lshlrev_b32_e32 v217, 16, v149
	v_and_b32_e32 v149, 0xffff0000, v149
	v_fmac_f32_e32 v94, s44, v216
	v_fmac_f32_e32 v95, s44, v148
	v_fmac_f32_e32 v96, s44, v217
	v_fmac_f32_e32 v97, s44, v149
	v_mov_b32_dpp v220, v94 quad_perm:[1,0,3,2] row_mask:0xf bank_mask:0xf
	v_mov_b32_dpp v221, v95 quad_perm:[1,0,3,2] row_mask:0xf bank_mask:0xf
	v_mov_b32_dpp v222, v96 quad_perm:[1,0,3,2] row_mask:0xf bank_mask:0xf
	v_mov_b32_dpp v223, v97 quad_perm:[1,0,3,2] row_mask:0xf bank_mask:0xf
	v_mov_b32_dpp v224, v126 quad_perm:[1,0,3,2] row_mask:0xf bank_mask:0xf
	v_mov_b32_dpp v225, v127 quad_perm:[1,0,3,2] row_mask:0xf bank_mask:0xf
	v_mov_b32_dpp v226, v128 quad_perm:[1,0,3,2] row_mask:0xf bank_mask:0xf
	v_mov_b32_dpp v227, v129 quad_perm:[1,0,3,2] row_mask:0xf bank_mask:0xf
	v_cndmask_b32_e32 v94, v224, v94, vcc
	v_cndmask_b32_e32 v95, v225, v95, vcc
	v_cndmask_b32_e32 v96, v226, v96, vcc
	v_cndmask_b32_e32 v97, v227, v97, vcc
	v_cndmask_b32_e32 v126, v126, v220, vcc
	v_cndmask_b32_e32 v127, v127, v221, vcc
	v_cndmask_b32_e32 v128, v128, v222, vcc
	v_cndmask_b32_e32 v129, v129, v223, vcc
	global_store_dwordx4 v[140:141], v[126:129], off
	global_store_dwordx4 v[142:143], v[94:97], off
	s_waitcnt vmcnt(16)
; DEVI float blo(unsigned u) { return __uint_as_float(u << 16); }
; DEVI float bhi(unsigned u) { return __uint_as_float(u & 0xffff0000u); }
;     ...
;         if (EPI == EPI_RESID || EPI == EPI_RESID_ATOMIC) {
;           f32x4 x = a;
;           if (EPI == EPI_RESID || kpart == 0) {
;             const u32x2 xr = *(const u32x2*)((const u16*)(p.ws + WS_XB) + (size_t)row * 1024 + col);
;             x[0] += ALPHA * blo(xr[0]); x[1] += ALPHA * bhi(xr[0]); x[2] += ALPHA * blo(xr[1]); x[3] += ALPHA * bhi(xr[1]);
;           }
;           if (EPI == EPI_RESID) *(f32x4*)((float*)(p.ws + WS_XF) + (size_t)row * 1024 + col) = x;
;           else *(f32x4*)((float*)(p.ws + WS_SLAB) + ((size_t)kpart * 512 + (row - T_P)) * 1024 + col) = x;
	v_permlane16_swap_b32_e32 v152, v154
	v_permlane16_swap_b32_e32 v153, v155
	v_lshlrev_b32_e32 v216, 16, v152
	v_and_b32_e32 v152, 0xffff0000, v152
	v_lshlrev_b32_e32 v217, 16, v153
	v_and_b32_e32 v153, 0xffff0000, v153
	v_fmac_f32_e32 v62, s44, v216
	v_fmac_f32_e32 v63, s44, v152
	v_fmac_f32_e32 v64, s44, v217
	v_fmac_f32_e32 v65, s44, v153
	v_lshlrev_b32_e32 v216, 16, v154
	v_and_b32_e32 v154, 0xffff0000, v154
	v_lshlrev_b32_e32 v217, 16, v155
	v_and_b32_e32 v155, 0xffff0000, v155
	v_fmac_f32_e32 v30, s44, v216
	v_fmac_f32_e32 v31, s44, v154
	v_fmac_f32_e32 v32, s44, v217
	v_fmac_f32_e32 v33, s44, v155
	v_mov_b32_dpp v220, v30 quad_perm:[1,0,3,2] row_mask:0xf bank_mask:0xf
	v_mov_b32_dpp v221, v31 quad_perm:[1,0,3,2] row_mask:0xf bank_mask:0xf
	v_mov_b32_dpp v222, v32 quad_perm:[1,0,3,2] row_mask:0xf bank_mask:0xf
	v_mov_b32_dpp v223, v33 quad_perm:[1,0,3,2] row_mask:0xf bank_mask:0xf
	v_mov_b32_dpp v224, v62 quad_perm:[1,0,3,2] row_mask:0xf bank_mask:0xf
	v_mov_b32_dpp v225, v63 quad_perm:[1,0,3,2] row_mask:0xf bank_mask:0xf
	v_mov_b32_dpp v226, v64 quad_perm:[1,0,3,2] row_mask:0xf bank_mask:0xf
	v_mov_b32_dpp v227, v65 quad_perm:[1,0,3,2] row_mask:0xf bank_mask:0xf
	v_cndmask_b32_e32 v30, v224, v30, vcc
	v_cndmask_b32_e32 v31, v225, v31, vcc
	v_cndmask_b32_e32 v32, v226, v32, vcc
	v_cndmask_b32_e32 v33, v227, v33, vcc
	v_cndmask_b32_e32 v62, v62, v220, vcc
	v_cndmask_b32_e32 v63, v63, v221, vcc
	v_cndmask_b32_e32 v64, v64, v222, vcc
	v_cndmask_b32_e32 v65, v65, v223, vcc
	global_store_dwordx4 v[140:141], v[62:65], off offset:128
	global_store_dwordx4 v[142:143], v[30:33], off offset:128
	v_lshl_add_u64 v[140:141], v[140:141], 0, s[10:11]
	v_lshl_add_u64 v[142:143], v[142:143], 0, s[10:11]
	s_waitcnt vmcnt(17)
	v_permlane16_swap_b32_e32 v156, v158
	v_permlane16_swap_b32_e32 v157, v159
	v_lshlrev_b32_e32 v216, 16, v156
	v_and_b32_e32 v156, 0xffff0000, v156
	v_lshlrev_b32_e32 v217, 16, v157
	v_and_b32_e32 v157, 0xffff0000, v157
	v_fmac_f32_e32 v122, s44, v216
	v_fmac_f32_e32 v123, s44, v156
	v_fmac_f32_e32 v124, s44, v217
	v_fmac_f32_e32 v125, s44, v157
	v_lshlrev_b32_e32 v216, 16, v158
	v_and_b32_e32 v158, 0xffff0000, v158
	v_lshlrev_b32_e32 v217, 16, v159
	v_and_b32_e32 v159, 0xffff0000, v159
	v_fmac_f32_e32 v90, s44, v216
	v_fmac_f32_e32 v91, s44, v158
	v_fmac_f32_e32 v92, s44, v217
	v_fmac_f32_e32 v93, s44, v159
	v_mov_b32_dpp v220, v90 quad_perm:[1,0,3,2] row_mask:0xf bank_mask:0xf
	v_mov_b32_dpp v221, v91 quad_perm:[1,0,3,2] row_mask:0xf bank_mask:0xf
	v_mov_b32_dpp v222, v92 quad_perm:[1,0,3,2] row_mask:0xf bank_mask:0xf
	v_mov_b32_dpp v223, v93 quad_perm:[1,0,3,2] row_mask:0xf bank_mask:0xf
	v_mov_b32_dpp v224, v122 quad_perm:[1,0,3,2] row_mask:0xf bank_mask:0xf
	v_mov_b32_dpp v225, v123 quad_perm:[1,0,3,2] row_mask:0xf bank_mask:0xf
	v_mov_b32_dpp v226, v124 quad_perm:[1,0,3,2] row_mask:0xf bank_mask:0xf
	v_mov_b32_dpp v227, v125 quad_perm:[1,0,3,2] row_mask:0xf bank_mask:0xf
	v_cndmask_b32_e32 v90, v224, v90, vcc
	v_cndmask_b32_e32 v91, v225, v91, vcc
	v_cndmask_b32_e32 v92, v226, v92, vcc
	v_cndmask_b32_e32 v93, v227, v93, vcc
	v_cndmask_b32_e32 v122, v122, v220, vcc
	v_cndmask_b32_e32 v123, v123, v221, vcc
	v_cndmask_b32_e32 v124, v124, v222, vcc
	v_cndmask_b32_e32 v125, v125, v223, vcc
	global_store_dwordx4 v[140:141], v[122:125], off
	global_store_dwordx4 v[142:143], v[90:93], off
	s_waitcnt vmcnt(18)
	v_permlane16_swap_b32_e32 v162, v164
	v_permlane16_swap_b32_e32 v163, v165
	v_lshlrev_b32_e32 v216, 16, v162
	v_and_b32_e32 v162, 0xffff0000, v162
	v_lshlrev_b32_e32 v217, 16, v163
	v_and_b32_e32 v163, 0xffff0000, v163
	v_fmac_f32_e32 v58, s44, v216
	v_fmac_f32_e32 v59, s44, v162
	v_fmac_f32_e32 v60, s44, v217
	v_fmac_f32_e32 v61, s44, v163
	v_lshlrev_b32_e32 v216, 16, v164
	v_and_b32_e32 v164, 0xffff0000, v164
	v_lshlrev_b32_e32 v217, 16, v165
	v_and_b32_e32 v165, 0xffff0000, v165
	v_fmac_f32_e32 v26, s44, v216
	v_fmac_f32_e32 v27, s44, v164
	v_fmac_f32_e32 v28, s44, v217
	v_fmac_f32_e32 v29, s44, v165
	v_mov_b32_dpp v220, v26 quad_perm:[1,0,3,2] row_mask:0xf bank_mask:0xf
	v_mov_b32_dpp v221, v27 quad_perm:[1,0,3,2] row_mask:0xf bank_mask:0xf
	v_mov_b32_dpp v222, v28 quad_perm:[1,0,3,2] row_mask:0xf bank_mask:0xf
	v_mov_b32_dpp v223, v29 quad_perm:[1,0,3,2] row_mask:0xf bank_mask:0xf
	v_mov_b32_dpp v224, v58 quad_perm:[1,0,3,2] row_mask:0xf bank_mask:0xf
	v_mov_b32_dpp v225, v59 quad_perm:[1,0,3,2] row_mask:0xf bank_mask:0xf
	v_mov_b32_dpp v226, v60 quad_perm:[1,0,3,2] row_mask:0xf bank_mask:0xf
	v_mov_b32_dpp v227, v61 quad_perm:[1,0,3,2] row_mask:0xf bank_mask:0xf
	v_cndmask_b32_e32 v26, v224, v26, vcc
	v_cndmask_b32_e32 v27, v225, v27, vcc
	v_cndmask_b32_e32 v28, v226, v28, vcc
	v_cndmask_b32_e32 v29, v227, v29, vcc
	v_cndmask_b32_e32 v58, v58, v220, vcc
	v_cndmask_b32_e32 v59, v59, v221, vcc
	v_cndmask_b32_e32 v60, v60, v222, vcc
	v_cndmask_b32_e32 v61, v61, v223, vcc
	global_store_dwordx4 v[140:141], v[58:61], off offset:128
	global_store_dwordx4 v[142:143], v[26:29], off offset:128
	v_lshl_add_u64 v[140:141], v[140:141], 0, s[10:11]
	v_lshl_add_u64 v[142:143], v[142:143], 0, s[10:11]
	s_waitcnt vmcnt(19)
; DEVI float blo(unsigned u) { return __uint_as_float(u << 16); }
; DEVI float bhi(unsigned u) { return __uint_as_float(u & 0xffff0000u); }
;     ...
;         if (EPI == EPI_RESID || EPI == EPI_RESID_ATOMIC) {
;           f32x4 x = a;
;           if (EPI == EPI_RESID || kpart == 0) {
;             const u32x2 xr = *(const u32x2*)((const u16*)(p.ws + WS_XB) + (size_t)row * 1024 + col);
;             x[0] += ALPHA * blo(xr[0]); x[1] += ALPHA * bhi(xr[0]); x[2] += ALPHA * blo(xr[1]); x[3] += ALPHA * bhi(xr[1]);
;           }
;           if (EPI == EPI_RESID) *(f32x4*)((float*)(p.ws + WS_XF) + (size_t)row * 1024 + col) = x;
;           else *(f32x4*)((float*)(p.ws + WS_SLAB) + ((size_t)kpart * 512 + (row - T_P)) * 1024 + col) = x;
	v_permlane16_swap_b32_e32 v166, v168
	v_permlane16_swap_b32_e32 v167, v169
	v_lshlrev_b32_e32 v216, 16, v166
	v_and_b32_e32 v166, 0xffff0000, v166
	v_lshlrev_b32_e32 v217, 16, v167
	v_and_b32_e32 v167, 0xffff0000, v167
	v_fmac_f32_e32 v118, s44, v216
	v_fmac_f32_e32 v119, s44, v166
	v_fmac_f32_e32 v120, s44, v217
	v_fmac_f32_e32 v121, s44, v167
	v_lshlrev_b32_e32 v216, 16, v168
	v_and_b32_e32 v168, 0xffff0000, v168
	v_lshlrev_b32_e32 v217, 16, v169
	v_and_b32_e32 v169, 0xffff0000, v169
	v_fmac_f32_e32 v86, s44, v216
	v_fmac_f32_e32 v87, s44, v168
	v_fmac_f32_e32 v88, s44, v217
	v_fmac_f32_e32 v89, s44, v169
	v_mov_b32_dpp v220, v86 quad_perm:[1,0,3,2] row_mask:0xf bank_mask:0xf
	v_mov_b32_dpp v221, v87 quad_perm:[1,0,3,2] row_mask:0xf bank_mask:0xf
	v_mov_b32_dpp v222, v88 quad_perm:[1,0,3,2] row_mask:0xf bank_mask:0xf
	v_mov_b32_dpp v223, v89 quad_perm:[1,0,3,2] row_mask:0xf bank_mask:0xf
	v_mov_b32_dpp v224, v118 quad_perm:[1,0,3,2] row_mask:0xf bank_mask:0xf
	v_mov_b32_dpp v225, v119 quad_perm:[1,0,3,2] row_mask:0xf bank_mask:0xf
	v_mov_b32_dpp v226, v120 quad_perm:[1,0,3,2] row_mask:0xf bank_mask:0xf
	v_mov_b32_dpp v227, v121 quad_perm:[1,0,3,2] row_mask:0xf bank_mask:0xf
	v_cndmask_b32_e32 v86, v224, v86, vcc
	v_cndmask_b32_e32 v87, v225, v87, vcc
	v_cndmask_b32_e32 v88, v226, v88, vcc
	v_cndmask_b32_e32 v89, v227, v89, vcc
	v_cndmask_b32_e32 v118, v118, v220, vcc
	v_cndmask_b32_e32 v119, v119, v221, vcc
	v_cndmask_b32_e32 v120, v120, v222, vcc
	v_cndmask_b32_e32 v121, v121, v223, vcc
	global_store_dwordx4 v[140:141], v[118:121], off
	global_store_dwordx4 v[142:143], v[86:89], off
	s_waitcnt vmcnt(20)
	v_permlane16_swap_b32_e32 v170, v172
	v_permlane16_swap_b32_e32 v171, v173
	v_lshlrev_b32_e32 v216, 16, v170
	v_and_b32_e32 v170, 0xffff0000, v170
	v_lshlrev_b32_e32 v217, 16, v171
	v_and_b32_e32 v171, 0xffff0000, v171
	v_fmac_f32_e32 v54, s44, v216
	v_fmac_f32_e32 v55, s44, v170
	v_fmac_f32_e32 v56, s44, v217
	v_fmac_f32_e32 v57, s44, v171
	v_lshlrev_b32_e32 v216, 16, v172
	v_and_b32_e32 v172, 0xffff0000, v172
	v_lshlrev_b32_e32 v217, 16, v173
	v_and_b32_e32 v173, 0xffff0000, v173
	v_fmac_f32_e32 v22, s44, v216
	v_fmac_f32_e32 v23, s44, v172
	v_fmac_f32_e32 v24, s44, v217
	v_fmac_f32_e32 v25, s44, v173
	v_mov_b32_dpp v220, v22 quad_perm:[1,0,3,2] row_mask:0xf bank_mask:0xf
	v_mov_b32_dpp v221, v23 quad_perm:[1,0,3,2] row_mask:0xf bank_mask:0xf
	v_mov_b32_dpp v222, v24 quad_perm:[1,0,3,2] row_mask:0xf bank_mask:0xf
	v_mov_b32_dpp v223, v25 quad_perm:[1,0,3,2] row_mask:0xf bank_mask:0xf
	v_mov_b32_dpp v224, v54 quad_perm:[1,0,3,2] row_mask:0xf bank_mask:0xf
	v_mov_b32_dpp v225, v55 quad_perm:[1,0,3,2] row_mask:0xf bank_mask:0xf
	v_mov_b32_dpp v226, v56 quad_perm:[1,0,3,2] row_mask:0xf bank_mask:0xf
	v_mov_b32_dpp v227, v57 quad_perm:[1,0,3,2] row_mask:0xf bank_mask:0xf
	v_cndmask_b32_e32 v22, v224, v22, vcc
	v_cndmask_b32_e32 v23, v225, v23, vcc
	v_cndmask_b32_e32 v24, v226, v24, vcc
	v_cndmask_b32_e32 v25, v227, v25, vcc
	v_cndmask_b32_e32 v54, v54, v220, vcc
	v_cndmask_b32_e32 v55, v55, v221, vcc
	v_cndmask_b32_e32 v56, v56, v222, vcc
	v_cndmask_b32_e32 v57, v57, v223, vcc
	global_store_dwordx4 v[140:141], v[54:57], off offset:128
	global_store_dwordx4 v[142:143], v[22:25], off offset:128
	v_lshl_add_u64 v[140:141], v[140:141], 0, s[10:11]
	v_lshl_add_u64 v[142:143], v[142:143], 0, s[10:11]
	s_waitcnt vmcnt(21)
	v_permlane16_swap_b32_e32 v176, v178
	v_permlane16_swap_b32_e32 v177, v179
	v_lshlrev_b32_e32 v216, 16, v176
	v_and_b32_e32 v176, 0xffff0000, v176
	v_lshlrev_b32_e32 v217, 16, v177
	v_and_b32_e32 v177, 0xffff0000, v177
	v_fmac_f32_e32 v114, s44, v216
	v_fmac_f32_e32 v115, s44, v176
	v_fmac_f32_e32 v116, s44, v217
	v_fmac_f32_e32 v117, s44, v177
	v_lshlrev_b32_e32 v216, 16, v178
	v_and_b32_e32 v178, 0xffff0000, v178
	v_lshlrev_b32_e32 v217, 16, v179
	v_and_b32_e32 v179, 0xffff0000, v179
	v_fmac_f32_e32 v82, s44, v216
	v_fmac_f32_e32 v83, s44, v178
	v_fmac_f32_e32 v84, s44, v217
	v_fmac_f32_e32 v85, s44, v179
	v_mov_b32_dpp v220, v82 quad_perm:[1,0,3,2] row_mask:0xf bank_mask:0xf
	v_mov_b32_dpp v221, v83 quad_perm:[1,0,3,2] row_mask:0xf bank_mask:0xf
	v_mov_b32_dpp v222, v84 quad_perm:[1,0,3,2] row_mask:0xf bank_mask:0xf
	v_mov_b32_dpp v223, v85 quad_perm:[1,0,3,2] row_mask:0xf bank_mask:0xf
	v_mov_b32_dpp v224, v114 quad_perm:[1,0,3,2] row_mask:0xf bank_mask:0xf
	v_mov_b32_dpp v225, v115 quad_perm:[1,0,3,2] row_mask:0xf bank_mask:0xf
	v_mov_b32_dpp v226, v116 quad_perm:[1,0,3,2] row_mask:0xf bank_mask:0xf
	v_mov_b32_dpp v227, v117 quad_perm:[1,0,3,2] row_mask:0xf bank_mask:0xf
	v_cndmask_b32_e32 v82, v224, v82, vcc
	v_cndmask_b32_e32 v83, v225, v83, vcc
	v_cndmask_b32_e32 v84, v226, v84, vcc
	v_cndmask_b32_e32 v85, v227, v85, vcc
	v_cndmask_b32_e32 v114, v114, v220, vcc
	v_cndmask_b32_e32 v115, v115, v221, vcc
	v_cndmask_b32_e32 v116, v116, v222, vcc
	v_cndmask_b32_e32 v117, v117, v223, vcc
	global_store_dwordx4 v[140:141], v[114:117], off
	global_store_dwordx4 v[142:143], v[82:85], off
	s_waitcnt vmcnt(22)
; DEVI float blo(unsigned u) { return __uint_as_float(u << 16); }
; DEVI float bhi(unsigned u) { return __uint_as_float(u & 0xffff0000u); }
;     ...
;         if (EPI == EPI_RESID || EPI == EPI_RESID_ATOMIC) {
;           f32x4 x = a;
;           if (EPI == EPI_RESID || kpart == 0) {
;             const u32x2 xr = *(const u32x2*)((const u16*)(p.ws + WS_XB) + (size_t)row * 1024 + col);
;             x[0] += ALPHA * blo(xr[0]); x[1] += ALPHA * bhi(xr[0]); x[2] += ALPHA * blo(xr[1]); x[3] += ALPHA * bhi(xr[1]);
;           }
;           if (EPI == EPI_RESID) *(f32x4*)((float*)(p.ws + WS_XF) + (size_t)row * 1024 + col) = x;
;           else *(f32x4*)((float*)(p.ws + WS_SLAB) + ((size_t)kpart * 512 + (row - T_P)) * 1024 + col) = x;
	v_permlane16_swap_b32_e32 v180, v182
	v_permlane16_swap_b32_e32 v181, v183
	v_lshlrev_b32_e32 v216, 16, v180
	v_and_b32_e32 v180, 0xffff0000, v180
	v_lshlrev_b32_e32 v217, 16, v181
	v_and_b32_e32 v181, 0xffff0000, v181
	v_fmac_f32_e32 v50, s44, v216
	v_fmac_f32_e32 v51, s44, v180
	v_fmac_f32_e32 v52, s44, v217
	v_fmac_f32_e32 v53, s44, v181
	v_lshlrev_b32_e32 v216, 16, v182
	v_and_b32_e32 v182, 0xffff0000, v182
	v_lshlrev_b32_e32 v217, 16, v183
	v_and_b32_e32 v183, 0xffff0000, v183
	v_fmac_f32_e32 v18, s44, v216
	v_fmac_f32_e32 v19, s44, v182
	v_fmac_f32_e32 v20, s44, v217
	v_fmac_f32_e32 v21, s44, v183
	v_mov_b32_dpp v220, v18 quad_perm:[1,0,3,2] row_mask:0xf bank_mask:0xf
	v_mov_b32_dpp v221, v19 quad_perm:[1,0,3,2] row_mask:0xf bank_mask:0xf
	v_mov_b32_dpp v222, v20 quad_perm:[1,0,3,2] row_mask:0xf bank_mask:0xf
	v_mov_b32_dpp v223, v21 quad_perm:[1,0,3,2] row_mask:0xf bank_mask:0xf
	v_mov_b32_dpp v224, v50 quad_perm:[1,0,3,2] row_mask:0xf bank_mask:0xf
	v_mov_b32_dpp v225, v51 quad_perm:[1,0,3,2] row_mask:0xf bank_mask:0xf
	v_mov_b32_dpp v226, v52 quad_perm:[1,0,3,2] row_mask:0xf bank_mask:0xf
	v_mov_b32_dpp v227, v53 quad_perm:[1,0,3,2] row_mask:0xf bank_mask:0xf
	v_cndmask_b32_e32 v18, v224, v18, vcc
	v_cndmask_b32_e32 v19, v225, v19, vcc
	v_cndmask_b32_e32 v20, v226, v20, vcc
	v_cndmask_b32_e32 v21, v227, v21, vcc
	v_cndmask_b32_e32 v50, v50, v220, vcc
	v_cndmask_b32_e32 v51, v51, v221, vcc
	v_cndmask_b32_e32 v52, v52, v222, vcc
	v_cndmask_b32_e32 v53, v53, v223, vcc
	global_store_dwordx4 v[140:141], v[50:53], off offset:128
	global_store_dwordx4 v[142:143], v[18:21], off offset:128
	v_lshl_add_u64 v[140:141], v[140:141], 0, s[10:11]
	v_lshl_add_u64 v[142:143], v[142:143], 0, s[10:11]
	s_waitcnt vmcnt(23)
	v_permlane16_swap_b32_e32 v184, v186
	v_permlane16_swap_b32_e32 v185, v187
	v_lshlrev_b32_e32 v216, 16, v184
	v_and_b32_e32 v184, 0xffff0000, v184
	v_lshlrev_b32_e32 v217, 16, v185
	v_and_b32_e32 v185, 0xffff0000, v185
	v_fmac_f32_e32 v110, s44, v216
	v_fmac_f32_e32 v111, s44, v184
	v_fmac_f32_e32 v112, s44, v217
	v_fmac_f32_e32 v113, s44, v185
	v_lshlrev_b32_e32 v216, 16, v186
	v_and_b32_e32 v186, 0xffff0000, v186
	v_lshlrev_b32_e32 v217, 16, v187
	v_and_b32_e32 v187, 0xffff0000, v187
	v_fmac_f32_e32 v78, s44, v216
	v_fmac_f32_e32 v79, s44, v186
	v_fmac_f32_e32 v80, s44, v217
	v_fmac_f32_e32 v81, s44, v187
	v_mov_b32_dpp v220, v78 quad_perm:[1,0,3,2] row_mask:0xf bank_mask:0xf
	v_mov_b32_dpp v221, v79 quad_perm:[1,0,3,2] row_mask:0xf bank_mask:0xf
	v_mov_b32_dpp v222, v80 quad_perm:[1,0,3,2] row_mask:0xf bank_mask:0xf
	v_mov_b32_dpp v223, v81 quad_perm:[1,0,3,2] row_mask:0xf bank_mask:0xf
	v_mov_b32_dpp v224, v110 quad_perm:[1,0,3,2] row_mask:0xf bank_mask:0xf
	v_mov_b32_dpp v225, v111 quad_perm:[1,0,3,2] row_mask:0xf bank_mask:0xf
	v_mov_b32_dpp v226, v112 quad_perm:[1,0,3,2] row_mask:0xf bank_mask:0xf
	v_mov_b32_dpp v227, v113 quad_perm:[1,0,3,2] row_mask:0xf bank_mask:0xf
	v_cndmask_b32_e32 v78, v224, v78, vcc
	v_cndmask_b32_e32 v79, v225, v79, vcc
	v_cndmask_b32_e32 v80, v226, v80, vcc
	v_cndmask_b32_e32 v81, v227, v81, vcc
	v_cndmask_b32_e32 v110, v110, v220, vcc
	v_cndmask_b32_e32 v111, v111, v221, vcc
	v_cndmask_b32_e32 v112, v112, v222, vcc
	v_cndmask_b32_e32 v113, v113, v223, vcc
	global_store_dwordx4 v[140:141], v[110:113], off
	global_store_dwordx4 v[142:143], v[78:81], off
	s_waitcnt vmcnt(24)
	v_permlane16_swap_b32_e32 v188, v190
	v_permlane16_swap_b32_e32 v189, v191
	v_lshlrev_b32_e32 v216, 16, v188
	v_and_b32_e32 v188, 0xffff0000, v188
	v_lshlrev_b32_e32 v217, 16, v189
	v_and_b32_e32 v189, 0xffff0000, v189
	v_fmac_f32_e32 v46, s44, v216
	v_fmac_f32_e32 v47, s44, v188
	v_fmac_f32_e32 v48, s44, v217
	v_fmac_f32_e32 v49, s44, v189
	v_lshlrev_b32_e32 v216, 16, v190
	v_and_b32_e32 v190, 0xffff0000, v190
	v_lshlrev_b32_e32 v217, 16, v191
	v_and_b32_e32 v191, 0xffff0000, v191
	v_fmac_f32_e32 v14, s44, v216
	v_fmac_f32_e32 v15, s44, v190
	v_fmac_f32_e32 v16, s44, v217
	v_fmac_f32_e32 v17, s44, v191
	v_mov_b32_dpp v220, v14 quad_perm:[1,0,3,2] row_mask:0xf bank_mask:0xf
	v_mov_b32_dpp v221, v15 quad_perm:[1,0,3,2] row_mask:0xf bank_mask:0xf
	v_mov_b32_dpp v222, v16 quad_perm:[1,0,3,2] row_mask:0xf bank_mask:0xf
	v_mov_b32_dpp v223, v17 quad_perm:[1,0,3,2] row_mask:0xf bank_mask:0xf
	v_mov_b32_dpp v224, v46 quad_perm:[1,0,3,2] row_mask:0xf bank_mask:0xf
	v_mov_b32_dpp v225, v47 quad_perm:[1,0,3,2] row_mask:0xf bank_mask:0xf
	v_mov_b32_dpp v226, v48 quad_perm:[1,0,3,2] row_mask:0xf bank_mask:0xf
	v_mov_b32_dpp v227, v49 quad_perm:[1,0,3,2] row_mask:0xf bank_mask:0xf
	v_cndmask_b32_e32 v14, v224, v14, vcc
	v_cndmask_b32_e32 v15, v225, v15, vcc
	v_cndmask_b32_e32 v16, v226, v16, vcc
	v_cndmask_b32_e32 v17, v227, v17, vcc
	v_cndmask_b32_e32 v46, v46, v220, vcc
	v_cndmask_b32_e32 v47, v47, v221, vcc
	v_cndmask_b32_e32 v48, v48, v222, vcc
	v_cndmask_b32_e32 v49, v49, v223, vcc
	global_store_dwordx4 v[140:141], v[46:49], off offset:128
	global_store_dwordx4 v[142:143], v[14:17], off offset:128
	v_lshl_add_u64 v[140:141], v[140:141], 0, s[10:11]
	v_lshl_add_u64 v[142:143], v[142:143], 0, s[10:11]
	s_waitcnt vmcnt(25)
; DEVI float blo(unsigned u) { return __uint_as_float(u << 16); }
; DEVI float bhi(unsigned u) { return __uint_as_float(u & 0xffff0000u); }
;     ...
;         if (EPI == EPI_RESID || EPI == EPI_RESID_ATOMIC) {
;           f32x4 x = a;
;           if (EPI == EPI_RESID || kpart == 0) {
;             const u32x2 xr = *(const u32x2*)((const u16*)(p.ws + WS_XB) + (size_t)row * 1024 + col);
;             x[0] += ALPHA * blo(xr[0]); x[1] += ALPHA * bhi(xr[0]); x[2] += ALPHA * blo(xr[1]); x[3] += ALPHA * bhi(xr[1]);
;           }
;           if (EPI == EPI_RESID) *(f32x4*)((float*)(p.ws + WS_XF) + (size_t)row * 1024 + col) = x;
;           else *(f32x4*)((float*)(p.ws + WS_SLAB) + ((size_t)kpart * 512 + (row - T_P)) * 1024 + col) = x;
	v_permlane16_swap_b32_e32 v192, v194
	v_permlane16_swap_b32_e32 v193, v195
	v_lshlrev_b32_e32 v216, 16, v192
	v_and_b32_e32 v192, 0xffff0000, v192
	v_lshlrev_b32_e32 v217, 16, v193
	v_and_b32_e32 v193, 0xffff0000, v193
	v_fmac_f32_e32 v106, s44, v216
	v_fmac_f32_e32 v107, s44, v192
	v_fmac_f32_e32 v108, s44, v217
	v_fmac_f32_e32 v109, s44, v193
	v_lshlrev_b32_e32 v216, 16, v194
	v_and_b32_e32 v194, 0xffff0000, v194
	v_lshlrev_b32_e32 v217, 16, v195
	v_and_b32_e32 v195, 0xffff0000, v195
	v_fmac_f32_e32 v74, s44, v216
	v_fmac_f32_e32 v75, s44, v194
	v_fmac_f32_e32 v76, s44, v217
	v_fmac_f32_e32 v77, s44, v195
	v_mov_b32_dpp v220, v74 quad_perm:[1,0,3,2] row_mask:0xf bank_mask:0xf
	v_mov_b32_dpp v221, v75 quad_perm:[1,0,3,2] row_mask:0xf bank_mask:0xf
	v_mov_b32_dpp v222, v76 quad_perm:[1,0,3,2] row_mask:0xf bank_mask:0xf
	v_mov_b32_dpp v223, v77 quad_perm:[1,0,3,2] row_mask:0xf bank_mask:0xf
	v_mov_b32_dpp v224, v106 quad_perm:[1,0,3,2] row_mask:0xf bank_mask:0xf
	v_mov_b32_dpp v225, v107 quad_perm:[1,0,3,2] row_mask:0xf bank_mask:0xf
	v_mov_b32_dpp v226, v108 quad_perm:[1,0,3,2] row_mask:0xf bank_mask:0xf
	v_mov_b32_dpp v227, v109 quad_perm:[1,0,3,2] row_mask:0xf bank_mask:0xf
	v_cndmask_b32_e32 v74, v224, v74, vcc
	v_cndmask_b32_e32 v75, v225, v75, vcc
	v_cndmask_b32_e32 v76, v226, v76, vcc
	v_cndmask_b32_e32 v77, v227, v77, vcc
	v_cndmask_b32_e32 v106, v106, v220, vcc
	v_cndmask_b32_e32 v107, v107, v221, vcc
	v_cndmask_b32_e32 v108, v108, v222, vcc
	v_cndmask_b32_e32 v109, v109, v223, vcc
	global_store_dwordx4 v[140:141], v[106:109], off
	global_store_dwordx4 v[142:143], v[74:77], off
	s_waitcnt vmcnt(26)
	v_permlane16_swap_b32_e32 v196, v198
	v_permlane16_swap_b32_e32 v197, v199
	v_lshlrev_b32_e32 v216, 16, v196
	v_and_b32_e32 v196, 0xffff0000, v196
	v_lshlrev_b32_e32 v217, 16, v197
	v_and_b32_e32 v197, 0xffff0000, v197
	v_fmac_f32_e32 v42, s44, v216
	v_fmac_f32_e32 v43, s44, v196
	v_fmac_f32_e32 v44, s44, v217
	v_fmac_f32_e32 v45, s44, v197
	v_lshlrev_b32_e32 v216, 16, v198
	v_and_b32_e32 v198, 0xffff0000, v198
	v_lshlrev_b32_e32 v217, 16, v199
	v_and_b32_e32 v199, 0xffff0000, v199
	v_fmac_f32_e32 v10, s44, v216
	v_fmac_f32_e32 v11, s44, v198
	v_fmac_f32_e32 v12, s44, v217
	v_fmac_f32_e32 v13, s44, v199
	v_mov_b32_dpp v220, v10 quad_perm:[1,0,3,2] row_mask:0xf bank_mask:0xf
	v_mov_b32_dpp v221, v11 quad_perm:[1,0,3,2] row_mask:0xf bank_mask:0xf
	v_mov_b32_dpp v222, v12 quad_perm:[1,0,3,2] row_mask:0xf bank_mask:0xf
	v_mov_b32_dpp v223, v13 quad_perm:[1,0,3,2] row_mask:0xf bank_mask:0xf
	v_mov_b32_dpp v224, v42 quad_perm:[1,0,3,2] row_mask:0xf bank_mask:0xf
	v_mov_b32_dpp v225, v43 quad_perm:[1,0,3,2] row_mask:0xf bank_mask:0xf
	v_mov_b32_dpp v226, v44 quad_perm:[1,0,3,2] row_mask:0xf bank_mask:0xf
	v_mov_b32_dpp v227, v45 quad_perm:[1,0,3,2] row_mask:0xf bank_mask:0xf
	v_cndmask_b32_e32 v10, v224, v10, vcc
	v_cndmask_b32_e32 v11, v225, v11, vcc
	v_cndmask_b32_e32 v12, v226, v12, vcc
	v_cndmask_b32_e32 v13, v227, v13, vcc
	v_cndmask_b32_e32 v42, v42, v220, vcc
	v_cndmask_b32_e32 v43, v43, v221, vcc
	v_cndmask_b32_e32 v44, v44, v222, vcc
	v_cndmask_b32_e32 v45, v45, v223, vcc
	global_store_dwordx4 v[140:141], v[42:45], off offset:128
	global_store_dwordx4 v[142:143], v[10:13], off offset:128
	v_lshl_add_u64 v[140:141], v[140:141], 0, s[10:11]
	v_lshl_add_u64 v[142:143], v[142:143], 0, s[10:11]
	s_waitcnt vmcnt(27)
	v_permlane16_swap_b32_e32 v200, v202
	v_permlane16_swap_b32_e32 v201, v203
	v_lshlrev_b32_e32 v216, 16, v200
	v_and_b32_e32 v200, 0xffff0000, v200
	v_lshlrev_b32_e32 v217, 16, v201
	v_and_b32_e32 v201, 0xffff0000, v201
	v_fmac_f32_e32 v102, s44, v216
	v_fmac_f32_e32 v103, s44, v200
	v_fmac_f32_e32 v104, s44, v217
	v_fmac_f32_e32 v105, s44, v201
	v_lshlrev_b32_e32 v216, 16, v202
	v_and_b32_e32 v202, 0xffff0000, v202
	v_lshlrev_b32_e32 v217, 16, v203
	v_and_b32_e32 v203, 0xffff0000, v203
	v_fmac_f32_e32 v70, s44, v216
	v_fmac_f32_e32 v71, s44, v202
	v_fmac_f32_e32 v72, s44, v217
	v_fmac_f32_e32 v73, s44, v203
	v_mov_b32_dpp v220, v70 quad_perm:[1,0,3,2] row_mask:0xf bank_mask:0xf
	v_mov_b32_dpp v221, v71 quad_perm:[1,0,3,2] row_mask:0xf bank_mask:0xf
	v_mov_b32_dpp v222, v72 quad_perm:[1,0,3,2] row_mask:0xf bank_mask:0xf
	v_mov_b32_dpp v223, v73 quad_perm:[1,0,3,2] row_mask:0xf bank_mask:0xf
	v_mov_b32_dpp v224, v102 quad_perm:[1,0,3,2] row_mask:0xf bank_mask:0xf
	v_mov_b32_dpp v225, v103 quad_perm:[1,0,3,2] row_mask:0xf bank_mask:0xf
	v_mov_b32_dpp v226, v104 quad_perm:[1,0,3,2] row_mask:0xf bank_mask:0xf
	v_mov_b32_dpp v227, v105 quad_perm:[1,0,3,2] row_mask:0xf bank_mask:0xf
	v_cndmask_b32_e32 v70, v224, v70, vcc
	v_cndmask_b32_e32 v71, v225, v71, vcc
	v_cndmask_b32_e32 v72, v226, v72, vcc
	v_cndmask_b32_e32 v73, v227, v73, vcc
	v_cndmask_b32_e32 v102, v102, v220, vcc
	v_cndmask_b32_e32 v103, v103, v221, vcc
	v_cndmask_b32_e32 v104, v104, v222, vcc
	v_cndmask_b32_e32 v105, v105, v223, vcc
	global_store_dwordx4 v[140:141], v[102:105], off
	global_store_dwordx4 v[142:143], v[70:73], off
	s_waitcnt vmcnt(28)
; DEVI float blo(unsigned u) { return __uint_as_float(u << 16); }
; DEVI float bhi(unsigned u) { return __uint_as_float(u & 0xffff0000u); }
; DEVI int xcd_first_tile() { return (blockIdx.x & 7) * (gridDim.x >> 3) + (blockIdx.x >> 3); }
;     ...
;         if (EPI == EPI_RESID || EPI == EPI_RESID_ATOMIC) {
;           f32x4 x = a;
;           if (EPI == EPI_RESID || kpart == 0) {
;             const u32x2 xr = *(const u32x2*)((const u16*)(p.ws + WS_XB) + (size_t)row * 1024 + col);
;             x[0] += ALPHA * blo(xr[0]); x[1] += ALPHA * bhi(xr[0]); x[2] += ALPHA * blo(xr[1]); x[3] += ALPHA * bhi(xr[1]);
;           }
;           if (EPI == EPI_RESID) *(f32x4*)((float*)(p.ws + WS_XF) + (size_t)row * 1024 + col) = x;
;           else *(f32x4*)((float*)(p.ws + WS_SLAB) + ((size_t)kpart * 512 + (row - T_P)) * 1024 + col) = x;
; DEVI void run_phase(const Params& p, int ph, char* smem) {
;     ...
;       for (int t = xcd_first_tile(); t < 512 + 16 * 2; t += xcd_tile_step()) {
;         if (t < 512) {
;           int mt_, nt_; tile_coords(t, 64, 8, mt_, nt_);
;           gemm_tile256<EPI_RESID>(p, ox, 256, Bt, 256, mt_ * 256, nt_ * 128, nullptr, 0, smem);
;         } else {
;           const int u_ = t - 512, tl_ = u_ / 2, q_ = u_ - tl_ * 2;
;           gemm_tile256<EPI_RESID_ATOMIC>(p, ox, 256, Bt, 256, (64 + (tl_ & 1)) * 256, (tl_ >> 1) * 128, nullptr, 0, smem, q_ * 128, 4, q_);
;         }
;       }
	v_permlane16_swap_b32_e32 v204, v206
	v_permlane16_swap_b32_e32 v205, v207
	v_lshlrev_b32_e32 v216, 16, v204
	v_and_b32_e32 v204, 0xffff0000, v204
	v_lshlrev_b32_e32 v217, 16, v205
	v_and_b32_e32 v205, 0xffff0000, v205
	v_fmac_f32_e32 v38, s44, v216
	v_fmac_f32_e32 v39, s44, v204
	v_fmac_f32_e32 v40, s44, v217
	v_fmac_f32_e32 v41, s44, v205
	v_lshlrev_b32_e32 v216, 16, v206
	v_and_b32_e32 v206, 0xffff0000, v206
	v_lshlrev_b32_e32 v217, 16, v207
	v_and_b32_e32 v207, 0xffff0000, v207
	v_fmac_f32_e32 v6, s44, v216
	v_fmac_f32_e32 v7, s44, v206
	v_fmac_f32_e32 v8, s44, v217
	v_fmac_f32_e32 v9, s44, v207
	v_mov_b32_dpp v220, v6 quad_perm:[1,0,3,2] row_mask:0xf bank_mask:0xf
	v_mov_b32_dpp v221, v7 quad_perm:[1,0,3,2] row_mask:0xf bank_mask:0xf
	v_mov_b32_dpp v222, v8 quad_perm:[1,0,3,2] row_mask:0xf bank_mask:0xf
	v_mov_b32_dpp v223, v9 quad_perm:[1,0,3,2] row_mask:0xf bank_mask:0xf
	v_mov_b32_dpp v224, v38 quad_perm:[1,0,3,2] row_mask:0xf bank_mask:0xf
	v_mov_b32_dpp v225, v39 quad_perm:[1,0,3,2] row_mask:0xf bank_mask:0xf
	v_mov_b32_dpp v226, v40 quad_perm:[1,0,3,2] row_mask:0xf bank_mask:0xf
	v_mov_b32_dpp v227, v41 quad_perm:[1,0,3,2] row_mask:0xf bank_mask:0xf
	v_cndmask_b32_e32 v6, v224, v6, vcc
	v_cndmask_b32_e32 v7, v225, v7, vcc
	v_cndmask_b32_e32 v8, v226, v8, vcc
	v_cndmask_b32_e32 v9, v227, v9, vcc
	v_cndmask_b32_e32 v38, v38, v220, vcc
	v_cndmask_b32_e32 v39, v39, v221, vcc
	v_cndmask_b32_e32 v40, v40, v222, vcc
	v_cndmask_b32_e32 v41, v41, v223, vcc
	global_store_dwordx4 v[140:141], v[38:41], off offset:128
	global_store_dwordx4 v[142:143], v[6:9], off offset:128
	v_lshl_add_u64 v[140:141], v[140:141], 0, s[10:11]
	v_lshl_add_u64 v[142:143], v[142:143], 0, s[10:11]
	s_waitcnt vmcnt(29)
	v_permlane16_swap_b32_e32 v208, v210
	v_permlane16_swap_b32_e32 v209, v211
	v_lshlrev_b32_e32 v216, 16, v208
	v_and_b32_e32 v208, 0xffff0000, v208
	v_lshlrev_b32_e32 v217, 16, v209
	v_and_b32_e32 v209, 0xffff0000, v209
	v_fmac_f32_e32 v98, s44, v216
	v_fmac_f32_e32 v99, s44, v208
	v_fmac_f32_e32 v100, s44, v217
	v_fmac_f32_e32 v101, s44, v209
	v_lshlrev_b32_e32 v216, 16, v210
	v_and_b32_e32 v210, 0xffff0000, v210
	v_lshlrev_b32_e32 v217, 16, v211
	v_and_b32_e32 v211, 0xffff0000, v211
	v_fmac_f32_e32 v66, s44, v216
	v_fmac_f32_e32 v67, s44, v210
	v_fmac_f32_e32 v68, s44, v217
	v_fmac_f32_e32 v69, s44, v211
	v_mov_b32_dpp v220, v66 quad_perm:[1,0,3,2] row_mask:0xf bank_mask:0xf
	v_mov_b32_dpp v221, v67 quad_perm:[1,0,3,2] row_mask:0xf bank_mask:0xf
	v_mov_b32_dpp v222, v68 quad_perm:[1,0,3,2] row_mask:0xf bank_mask:0xf
	v_mov_b32_dpp v223, v69 quad_perm:[1,0,3,2] row_mask:0xf bank_mask:0xf
	v_mov_b32_dpp v224, v98 quad_perm:[1,0,3,2] row_mask:0xf bank_mask:0xf
	v_mov_b32_dpp v225, v99 quad_perm:[1,0,3,2] row_mask:0xf bank_mask:0xf
	v_mov_b32_dpp v226, v100 quad_perm:[1,0,3,2] row_mask:0xf bank_mask:0xf
	v_mov_b32_dpp v227, v101 quad_perm:[1,0,3,2] row_mask:0xf bank_mask:0xf
	v_cndmask_b32_e32 v66, v224, v66, vcc
	v_cndmask_b32_e32 v67, v225, v67, vcc
	v_cndmask_b32_e32 v68, v226, v68, vcc
	v_cndmask_b32_e32 v69, v227, v69, vcc
	v_cndmask_b32_e32 v98, v98, v220, vcc
	v_cndmask_b32_e32 v99, v99, v221, vcc
	v_cndmask_b32_e32 v100, v100, v222, vcc
	v_cndmask_b32_e32 v101, v101, v223, vcc
	global_store_dwordx4 v[140:141], v[98:101], off
	global_store_dwordx4 v[142:143], v[66:69], off
	s_waitcnt vmcnt(30)
	v_permlane16_swap_b32_e32 v212, v214
	v_permlane16_swap_b32_e32 v213, v215
	v_lshlrev_b32_e32 v216, 16, v212
	v_and_b32_e32 v212, 0xffff0000, v212
	v_lshlrev_b32_e32 v217, 16, v213
	v_and_b32_e32 v213, 0xffff0000, v213
	v_fmac_f32_e32 v34, s44, v216
	v_fmac_f32_e32 v35, s44, v212
	v_fmac_f32_e32 v36, s44, v217
	v_fmac_f32_e32 v37, s44, v213
	v_lshlrev_b32_e32 v216, 16, v214
	v_and_b32_e32 v214, 0xffff0000, v214
	v_lshlrev_b32_e32 v217, 16, v215
	v_and_b32_e32 v215, 0xffff0000, v215
	v_fmac_f32_e32 v2, s44, v216
	v_fmac_f32_e32 v3, s44, v214
	v_fmac_f32_e32 v4, s44, v217
	v_fmac_f32_e32 v5, s44, v215
	v_mov_b32_dpp v220, v2 quad_perm:[1,0,3,2] row_mask:0xf bank_mask:0xf
	v_mov_b32_dpp v221, v3 quad_perm:[1,0,3,2] row_mask:0xf bank_mask:0xf
	v_mov_b32_dpp v222, v4 quad_perm:[1,0,3,2] row_mask:0xf bank_mask:0xf
	v_mov_b32_dpp v223, v5 quad_perm:[1,0,3,2] row_mask:0xf bank_mask:0xf
	v_mov_b32_dpp v224, v34 quad_perm:[1,0,3,2] row_mask:0xf bank_mask:0xf
	v_mov_b32_dpp v225, v35 quad_perm:[1,0,3,2] row_mask:0xf bank_mask:0xf
	v_mov_b32_dpp v226, v36 quad_perm:[1,0,3,2] row_mask:0xf bank_mask:0xf
	v_mov_b32_dpp v227, v37 quad_perm:[1,0,3,2] row_mask:0xf bank_mask:0xf
	v_cndmask_b32_e32 v2, v224, v2, vcc
	v_cndmask_b32_e32 v3, v225, v3, vcc
	v_cndmask_b32_e32 v4, v226, v4, vcc
	v_cndmask_b32_e32 v5, v227, v5, vcc
	v_cndmask_b32_e32 v34, v34, v220, vcc
	v_cndmask_b32_e32 v35, v35, v221, vcc
	v_cndmask_b32_e32 v36, v36, v222, vcc
	v_cndmask_b32_e32 v37, v37, v223, vcc
	global_store_dwordx4 v[140:141], v[34:37], off offset:128
	global_store_dwordx4 v[142:143], v[2:5], off offset:128
	v_readlane_b32 s39, v250, 7
	s_cmpk_lg_u32 s39, 0x200
	s_cbranch_scc1 .LBB0_146
	v_readlane_b32 s40, v250, 0
	s_lshr_b32 s41, s40, 3
	s_and_b32 s40, s40, 7
	s_mul_i32 s40, s40, 4
	s_add_i32 s40, s40, s41
	s_cmp_lt_u32 s41, 4
	s_movk_i32 s38, 0x4000
	s_branch .LBB0_146

; #define LAS __attribute__((address_space(3)))
;     ...
;   const int nk = (nk_part < 0) ? (K >> 5) : nk_part;
;   const int lrow = tid >> 2, lpc = tid & 3;
;   const int lch = lpc ^ ((0x78 >> (((lrow >> 2) & 3) * 2)) & 3);
;   const u16* ga = A + (size_t)(m0 + lrow) * lda + kbeg + lch * 8;
;   const u16* gb = Bt + (size_t)(n0 + lrow) * K + kbeg + lch * 8;
;   const size_t ga1 = (size_t)64 * lda, gb1 = (size_t)64 * K;
;   const unsigned lds0 = (unsigned)(uintptr_t)(LAS char*)smem + (unsigned)__builtin_amdgcn_readfirstlane(wid) * 1024u;
;     ...
;   __syncthreads();
;   G2_STAGE(0); G2_STAGE(1);
; DEVI void run_phase(const Params& p, int ph, char* smem) {
;     ...
;           const int u_ = t - 512, tl_ = u_ / 8, q_ = u_ - tl_ * 8;
;           gemm_tile256<EPI_RESID_ATOMIC>(p, mix, 1024, Bt, 1024, (64 + (tl_ & 1)) * 256, (tl_ >> 1) * 128, nullptr, 0, smem, q_ * 128, 4, q_);
.LBB0_758:
	s_cmpk_gt_i32 s39, 0x1ff
	s_mov_b64 s[2:3], -1
	s_cbranch_scc0 .LBB0_812
	s_setprio 2
	s_sub_i32 s43, s39, 512
	s_lshr_b32 s42, s43, 3
	s_and_b32 s98, s43, 7
	s_lshr_b32 s15, s42, 1
	s_and_b32 s42, s42, 1
	s_add_i32 s42, s42, 64
	v_readlane_b32 s2, v250, 5
	v_readlane_b32 s3, v250, 6
	v_readlane_b32 s43, v254, 62
	s_mul_i32 s1, s42, 0x80000
	s_add_u32 s4, s2, s1
	s_addc_u32 s5, s3, 0
	s_add_u32 s4, s4, 0xb580000
	s_addc_u32 s5, s5, 0
	s_mul_i32 s1, s43, 0x200000
	s_mul_i32 s14, s15, 0x40000
	s_add_i32 s1, s1, s14
	s_add_u32 s10, s2, s1
	s_addc_u32 s11, s3, 0
	s_add_u32 s10, s10, 0x15e00000
	s_addc_u32 s11, s11, 0
	s_mul_i32 s1, s98, 256
	s_add_u32 s4, s4, s1
	s_addc_u32 s5, s5, 0
	s_mul_i32 s1, s98, 512
	s_add_u32 s10, s10, s1
	s_addc_u32 s11, s11, 0
	s_movk_i32 s0, 0x78
	v_lshrrev_b32_e32 v0, 2, v145
	v_and_b32_e32 v131, 3, v145
	v_bfe_u32 v136, v145, 4, 2
	v_lshlrev_b32_e32 v136, 1, v136
	v_lshrrev_b32_e64 v136, v136, s0
	v_and_b32_e32 v136, 3, v136
	v_xor_b32_e32 v131, v131, v136
	v_lshlrev_b32_e32 v131, 4, v131
	s_movk_i32 s14, 0x800
	v_mad_u32_u24 v0, v0, s14, v131
	v_bfe_u32 v137, v145, 2, 1
	s_movk_i32 s14, 0x7c0
	v_mul_u32_u24_e32 v136, s14, v137
	v_sub_u32_e32 v136, v0, v136
	v_mov_b32_e32 v137, 0
	v_lshl_add_u64 v[134:135], s[10:11], 0, v[136:137]
	v_bfe_u32 v137, v145, 2, 1
	s_mov_b32 s12, 64
	s_mov_b32 s13, 0
	v_lshl_add_u64 v[132:133], s[4:5], 0, v[0:1]
	v_bfe_u32 v136, v145, 2, 2
	v_lshlrev_b32_e32 v136, 1, v136
	v_lshrrev_b32_e64 v136, v136, s0
	v_and_b32_e32 v136, 3, v136
	v_bfe_u32 v137, v145, 4, 2
	v_xor_b32_e32 v136, v136, v137
	v_lshlrev_b32_e32 v136, 4, v136
	v_and_b32_e32 v131, 15, v145
	v_lshl_or_b32 v136, v131, 6, v136
	v_bfe_u32 v137, v145, 6, 1
	v_lshl_or_b32 v137, v137, 12, v136
	v_lshrrev_b32_e32 v0, 7, v145
	v_lshl_or_b32 v136, v0, 13, v136
	v_and_b32_e32 v140, 1, v131
	v_lshl_or_b32 v131, v0, 7, v131
	v_bfe_u32 v0, v145, 4, 2
	v_lshlrev_b32_e32 v0, 3, v0
	v_bfe_u32 v141, v145, 6, 1
	s_lshl_b32 s1, s42, 19
	s_lshl_b32 s14, s15, 8
	s_add_i32 s1, s1, s14
	s_add_u32 s4, s2, s1
	s_addc_u32 s5, s3, 0
	s_add_u32 s4, s4, 0x4200000
	s_addc_u32 s5, s5, 0
	v_lshlrev_b32_e32 v138, 11, v131
	v_lshl_add_u32 v138, v141, 7, v138
	v_bfe_u32 v139, v145, 4, 1
	v_lshl_add_u32 v138, v139, 5, v138
	v_bfe_u32 v139, v145, 5, 1
	v_lshl_add_u32 v138, v139, 4, v138
	v_mov_b32_e32 v139, 0
	v_lshl_add_u64 v[138:139], s[4:5], 0, v[138:139]
	s_and_b32 s1, s42, 1
	s_lshl_b32 s1, s1, 20
	s_lshl_b32 s14, s98, 21
	s_add_i32 s1, s1, s14
	s_lshl_b32 s14, s15, 9
	s_add_i32 s1, s1, s14
	s_add_u32 s10, s2, s1
	s_addc_u32 s11, s3, 0
	s_add_u32 s10, s10, 0x1dcc0000
	s_addc_u32 s11, s11, 0
	v_lshlrev_b32_e32 v140, 12, v131
	v_lshl_add_u32 v140, v141, 8, v140
	v_lshl_add_u32 v140, v0, 1, v140
	v_mov_b32_e32 v141, 0
	v_lshl_add_u64 v[140:141], s[10:11], 0, v[140:141]
	s_mov_b32 s2, 0x20000
	s_mov_b32 s3, 0
	v_lshrrev_b32_e32 v0, 6, v145
	v_lshlrev_b32_e32 v0, 10, v0
	s_nop 0
	v_readfirstlane_b32 s43, v0
	s_mov_b32 s40, m0
	s_mov_b32 s4, 128
	s_mov_b32 s5, 0
	s_barrier
	s_add_i32 s15, s43, 0x0
	s_mov_b32 m0, s15
	v_lshl_add_u64 v[142:143], v[132:133], 0, s[2:3]
	global_load_lds_dwordx4 v[132:133], off
	s_add_i32 m0, m0, 0x1000
	s_nop 0
	global_load_lds_dwordx4 v[142:143], off
	v_lshl_add_u64 v[142:143], v[142:143], 0, s[2:3]
	s_add_i32 m0, m0, 0x1000
	s_nop 0
	global_load_lds_dwordx4 v[142:143], off
	v_lshl_add_u64 v[142:143], v[142:143], 0, s[2:3]
	s_add_i32 m0, m0, 0x1000
	s_nop 0
	global_load_lds_dwordx4 v[142:143], off
	s_add_i32 m0, m0, 0x1000
	v_lshl_add_u64 v[142:143], v[134:135], 0, s[2:3]
	s_nop 0
	global_load_lds_dwordx4 v[134:135], off
	s_add_i32 m0, m0, 0x1000
	v_lshl_add_u64 v[132:133], v[132:133], 0, s[12:13]
	s_nop 0
	global_load_lds_dwordx4 v[142:143], off
	v_lshl_add_u64 v[134:135], v[134:135], 0, s[4:5]
	s_nop 0
	s_add_i32 s15, s43, 0x6000
	s_mov_b32 m0, s15
	v_lshl_add_u64 v[142:143], v[132:133], 0, s[2:3]
	global_load_lds_dwordx4 v[132:133], off
	s_add_i32 m0, m0, 0x1000
	s_nop 0
	global_load_lds_dwordx4 v[142:143], off
	v_lshl_add_u64 v[142:143], v[142:143], 0, s[2:3]
	s_add_i32 m0, m0, 0x1000
	s_nop 0
	global_load_lds_dwordx4 v[142:143], off
	v_lshl_add_u64 v[142:143], v[142:143], 0, s[2:3]
	s_add_i32 m0, m0, 0x1000
	s_nop 0
	global_load_lds_dwordx4 v[142:143], off
	s_add_i32 m0, m0, 0x1000
	v_lshl_add_u64 v[142:143], v[134:135], 0, s[2:3]
	s_nop 0
	global_load_lds_dwordx4 v[134:135], off
	s_add_i32 m0, m0, 0x1000
	v_lshl_add_u64 v[132:133], v[132:133], 0, s[12:13]
	s_nop 0
	global_load_lds_dwordx4 v[142:143], off
	v_lshl_add_u64 v[134:135], v[134:135], 0, s[4:5]
	s_nop 0
	s_add_i32 s15, s43, 0xc000
	s_mov_b32 m0, s15
	v_lshl_add_u64 v[142:143], v[132:133], 0, s[2:3]
	global_load_lds_dwordx4 v[132:133], off
	s_add_i32 m0, m0, 0x1000
	s_nop 0
	global_load_lds_dwordx4 v[142:143], off
	v_lshl_add_u64 v[142:143], v[142:143], 0, s[2:3]
	s_add_i32 m0, m0, 0x1000
	s_nop 0
	global_load_lds_dwordx4 v[142:143], off
	v_lshl_add_u64 v[142:143], v[142:143], 0, s[2:3]
	s_add_i32 m0, m0, 0x1000
	s_nop 0
	global_load_lds_dwordx4 v[142:143], off
	s_add_i32 m0, m0, 0x1000
	v_lshl_add_u64 v[142:143], v[134:135], 0, s[2:3]
	s_nop 0
	global_load_lds_dwordx4 v[134:135], off
	s_add_i32 m0, m0, 0x1000
	v_lshl_add_u64 v[132:133], v[132:133], 0, s[12:13]
	s_nop 0
	global_load_lds_dwordx4 v[142:143], off
	v_lshl_add_u64 v[134:135], v[134:135], 0, s[4:5]
	s_nop 0
	v_mov_b32_e32 v2, 0
	v_mov_b32_e32 v3, 0
	v_mov_b32_e32 v4, 0
	v_mov_b32_e32 v5, 0
	v_mov_b32_e32 v6, 0
	v_mov_b32_e32 v7, 0
	v_mov_b32_e32 v8, 0
	v_mov_b32_e32 v9, 0
	v_mov_b32_e32 v10, 0
	v_mov_b32_e32 v11, 0
	v_mov_b32_e32 v12, 0
	v_mov_b32_e32 v13, 0
	v_mov_b32_e32 v14, 0
;     ...
;   f32x4 acc[4][8];
; #pragma unroll
;   for (int i = 0; i < 4; i++)
; #pragma unroll
;     for (int j = 0; j < 8; j++) acc[i][j] = (f32x4){0.f, 0.f, 0.f, 0.f};
;     ...
;   for (int kt = 0; kt < nk; kt++) {
;     if (kt + 1 < nk) asm volatile("s_waitcnt vmcnt(6)" ::: "memory");
;     else asm volatile("s_waitcnt vmcnt(0)" ::: "memory");
;     __builtin_amdgcn_s_barrier();
;     asm volatile("" ::: "memory");
;     if (kt + 2 < nk) G2_STAGE(kt + 2);
;     const char* cS = smem + (kt % 3) * 24576;
;     bf16x8 xa[8], wb[4];
; #pragma unroll
;     for (int f = 0; f < 8; f++) xa[f] = *(const bf16x8*)(cS + aoff + f * 1024);
; #pragma unroll
;     for (int f = 0; f < 4; f++) wb[f] = *(const bf16x8*)(cS + boff + f * 1024);
; #pragma unroll
;     for (int nf = 0; nf < 4; nf++)
; #pragma unroll
;       for (int mf = 0; mf < 8; mf++)
;         acc[nf][mf] = __builtin_amdgcn_mfma_f32_16x16x32_bf16(wb[nf], xa[mf], acc[nf][mf], 0, 0, 0);
	v_mov_b32_e32 v15, 0
	v_mov_b32_e32 v16, 0
	v_mov_b32_e32 v17, 0
	v_mov_b32_e32 v18, 0
	v_mov_b32_e32 v19, 0
	v_mov_b32_e32 v20, 0
	v_mov_b32_e32 v21, 0
	v_mov_b32_e32 v22, 0
	v_mov_b32_e32 v23, 0
	v_mov_b32_e32 v24, 0
	v_mov_b32_e32 v25, 0
	v_mov_b32_e32 v26, 0
	v_mov_b32_e32 v27, 0
	v_mov_b32_e32 v28, 0
	v_mov_b32_e32 v29, 0
	v_mov_b32_e32 v30, 0
	v_mov_b32_e32 v31, 0
	v_mov_b32_e32 v32, 0
	v_mov_b32_e32 v33, 0
	v_mov_b32_e32 v34, 0
	v_mov_b32_e32 v35, 0
	v_mov_b32_e32 v36, 0
	v_mov_b32_e32 v37, 0
	v_mov_b32_e32 v38, 0
	v_mov_b32_e32 v39, 0
	v_mov_b32_e32 v40, 0
	v_mov_b32_e32 v41, 0
	v_mov_b32_e32 v42, 0
	v_mov_b32_e32 v43, 0
	v_mov_b32_e32 v44, 0
	v_mov_b32_e32 v45, 0
	v_mov_b32_e32 v46, 0
	v_mov_b32_e32 v47, 0
	v_mov_b32_e32 v48, 0
	v_mov_b32_e32 v49, 0
	v_mov_b32_e32 v50, 0
	v_mov_b32_e32 v51, 0
	v_mov_b32_e32 v52, 0
	v_mov_b32_e32 v53, 0
	v_mov_b32_e32 v54, 0
	v_mov_b32_e32 v55, 0
	v_mov_b32_e32 v56, 0
	v_mov_b32_e32 v57, 0
	v_mov_b32_e32 v58, 0
	v_mov_b32_e32 v59, 0
	v_mov_b32_e32 v60, 0
	v_mov_b32_e32 v61, 0
	v_mov_b32_e32 v62, 0
	v_mov_b32_e32 v63, 0
	v_mov_b32_e32 v64, 0
	v_mov_b32_e32 v65, 0
	v_mov_b32_e32 v66, 0
	v_mov_b32_e32 v67, 0
	v_mov_b32_e32 v68, 0
	v_mov_b32_e32 v69, 0
	v_mov_b32_e32 v70, 0
	v_mov_b32_e32 v71, 0
	v_mov_b32_e32 v72, 0
	v_mov_b32_e32 v73, 0
	v_mov_b32_e32 v74, 0
	v_mov_b32_e32 v75, 0
	v_mov_b32_e32 v76, 0
	v_mov_b32_e32 v77, 0
	v_mov_b32_e32 v78, 0
	v_mov_b32_e32 v79, 0
	v_mov_b32_e32 v80, 0
	v_mov_b32_e32 v81, 0
	v_mov_b32_e32 v82, 0
	v_mov_b32_e32 v83, 0
	v_mov_b32_e32 v84, 0
	v_mov_b32_e32 v85, 0
	v_mov_b32_e32 v86, 0
	v_mov_b32_e32 v87, 0
	v_mov_b32_e32 v88, 0
	v_mov_b32_e32 v89, 0
	v_mov_b32_e32 v90, 0
	v_mov_b32_e32 v91, 0
	v_mov_b32_e32 v92, 0
	v_mov_b32_e32 v93, 0
	v_mov_b32_e32 v94, 0
	v_mov_b32_e32 v95, 0
	v_mov_b32_e32 v96, 0
	v_mov_b32_e32 v97, 0
	v_mov_b32_e32 v98, 0
	v_mov_b32_e32 v99, 0
	v_mov_b32_e32 v100, 0
	v_mov_b32_e32 v101, 0
	v_mov_b32_e32 v102, 0
	v_mov_b32_e32 v103, 0
	v_mov_b32_e32 v104, 0
	v_mov_b32_e32 v105, 0
	v_mov_b32_e32 v106, 0
	v_mov_b32_e32 v107, 0
	v_mov_b32_e32 v108, 0
	v_mov_b32_e32 v109, 0
	v_mov_b32_e32 v110, 0
	v_mov_b32_e32 v111, 0
	v_mov_b32_e32 v112, 0
	v_mov_b32_e32 v113, 0
	v_mov_b32_e32 v114, 0
	v_mov_b32_e32 v115, 0
	v_mov_b32_e32 v116, 0
	v_mov_b32_e32 v117, 0
	v_mov_b32_e32 v118, 0
	v_mov_b32_e32 v119, 0
	v_mov_b32_e32 v120, 0
	v_mov_b32_e32 v121, 0
	v_mov_b32_e32 v122, 0
	v_mov_b32_e32 v123, 0
	v_mov_b32_e32 v124, 0
	v_mov_b32_e32 v125, 0
	v_mov_b32_e32 v126, 0
	v_mov_b32_e32 v127, 0
	v_mov_b32_e32 v128, 0
	v_mov_b32_e32 v129, 0
	s_setprio 0
	s_waitcnt vmcnt(12)
	s_barrier
	ds_read_b128 v[146:149], v136 offset:0
	ds_read_b128 v[152:155], v136 offset:1024
	ds_read_b128 v[156:159], v136 offset:2048
	ds_read_b128 v[162:165], v136 offset:3072
	ds_read_b128 v[166:169], v136 offset:4096
	ds_read_b128 v[170:173], v136 offset:5120
	ds_read_b128 v[176:179], v136 offset:6144
	ds_read_b128 v[180:183], v136 offset:7168
	ds_read_b128 v[184:187], v137 offset:16384
	ds_read_b128 v[188:191], v137 offset:17408
	ds_read_b128 v[192:195], v137 offset:18432
	ds_read_b128 v[196:199], v137 offset:19456
	s_movk_i32 s1, 0x6000
	s_mov_b32 s14, 0
	.p2align 3
	s_waitcnt vmcnt(6) lgkmcnt(0)
	s_barrier
	s_setprio 1
	v_add_u32_e32 v144, s1, v136
	v_mfma_f32_16x16x32_bf16 v[126:129], v[184:187], v[146:149], v[126:129]
	ds_read_b128 v[200:203], v144 offset:0
	v_mfma_f32_16x16x32_bf16 v[122:125], v[184:187], v[152:155], v[122:125]
	ds_read_b128 v[204:207], v144 offset:1024
	v_mfma_f32_16x16x32_bf16 v[118:121], v[184:187], v[156:159], v[118:121]
	ds_read_b128 v[208:211], v144 offset:2048
	v_mfma_f32_16x16x32_bf16 v[114:117], v[184:187], v[162:165], v[114:117]
	ds_read_b128 v[212:215], v144 offset:3072
	v_mfma_f32_16x16x32_bf16 v[110:113], v[184:187], v[166:169], v[110:113]
	ds_read_b128 v[216:219], v144 offset:4096
	v_mfma_f32_16x16x32_bf16 v[106:109], v[184:187], v[170:173], v[106:109]
	ds_read_b128 v[220:223], v144 offset:5120
	v_mfma_f32_16x16x32_bf16 v[102:105], v[184:187], v[176:179], v[102:105]
	ds_read_b128 v[224:227], v144 offset:6144
	v_mfma_f32_16x16x32_bf16 v[98:101], v[184:187], v[180:183], v[98:101]
	ds_read_b128 v[228:231], v144 offset:7168
	v_mfma_f32_16x16x32_bf16 v[94:97], v[188:191], v[146:149], v[94:97]
	v_add_u32_e64 v144, s1, v137
	v_mfma_f32_16x16x32_bf16 v[90:93], v[188:191], v[152:155], v[90:93]
	v_mfma_f32_16x16x32_bf16 v[86:89], v[188:191], v[156:159], v[86:89]
	ds_read_b128 v[232:235], v144 offset:16384
	v_mfma_f32_16x16x32_bf16 v[82:85], v[188:191], v[162:165], v[82:85]
	ds_read_b128 v[236:239], v144 offset:17408
	v_mfma_f32_16x16x32_bf16 v[78:81], v[188:191], v[166:169], v[78:81]
	ds_read_b128 v[240:243], v144 offset:18432
	v_mfma_f32_16x16x32_bf16 v[74:77], v[188:191], v[170:173], v[74:77]
	ds_read_b128 v[244:247], v144 offset:19456
	v_mfma_f32_16x16x32_bf16 v[70:73], v[188:191], v[176:179], v[70:73]
	s_add_i32 s15, s43, s14
	s_mov_b32 m0, s15
	v_lshl_add_u64 v[142:143], v[132:133], 0, s[2:3]
	v_mfma_f32_16x16x32_bf16 v[66:69], v[188:191], v[180:183], v[66:69]
	global_load_lds_dwordx4 v[132:133], off
	s_add_i32 m0, m0, 0x1000
	v_mfma_f32_16x16x32_bf16 v[62:65], v[192:195], v[146:149], v[62:65]
	v_mfma_f32_16x16x32_bf16 v[58:61], v[192:195], v[152:155], v[58:61]
	v_mfma_f32_16x16x32_bf16 v[54:57], v[192:195], v[156:159], v[54:57]
	global_load_lds_dwordx4 v[142:143], off
	v_lshl_add_u64 v[142:143], v[142:143], 0, s[2:3]
	s_add_i32 m0, m0, 0x1000
	v_mfma_f32_16x16x32_bf16 v[50:53], v[192:195], v[162:165], v[50:53]
	v_mfma_f32_16x16x32_bf16 v[46:49], v[192:195], v[166:169], v[46:49]
	v_mfma_f32_16x16x32_bf16 v[42:45], v[192:195], v[170:173], v[42:45]
	global_load_lds_dwordx4 v[142:143], off
	v_lshl_add_u64 v[142:143], v[142:143], 0, s[2:3]
	s_add_i32 m0, m0, 0x1000
	v_mfma_f32_16x16x32_bf16 v[38:41], v[192:195], v[176:179], v[38:41]
	v_mfma_f32_16x16x32_bf16 v[34:37], v[192:195], v[180:183], v[34:37]
	s_setprio 0
	s_nop 0
	v_mfma_f32_16x16x32_bf16 v[30:33], v[196:199], v[146:149], v[30:33]
	global_load_lds_dwordx4 v[142:143], off
	s_add_i32 m0, m0, 0x1000
	v_lshl_add_u64 v[142:143], v[134:135], 0, s[2:3]
	v_mfma_f32_16x16x32_bf16 v[26:29], v[196:199], v[152:155], v[26:29]
	v_mfma_f32_16x16x32_bf16 v[22:25], v[196:199], v[156:159], v[22:25]
	v_mfma_f32_16x16x32_bf16 v[18:21], v[196:199], v[162:165], v[18:21]
	global_load_lds_dwordx4 v[134:135], off
	s_add_i32 m0, m0, 0x1000
	v_lshl_add_u64 v[132:133], v[132:133], 0, s[12:13]
	v_mfma_f32_16x16x32_bf16 v[14:17], v[196:199], v[166:169], v[14:17]
	v_mfma_f32_16x16x32_bf16 v[10:13], v[196:199], v[170:173], v[10:13]
	v_mfma_f32_16x16x32_bf16 v[6:9], v[196:199], v[176:179], v[6:9]
	global_load_lds_dwordx4 v[142:143], off
	v_lshl_add_u64 v[134:135], v[134:135], 0, s[4:5]
	v_mfma_f32_16x16x32_bf16 v[2:5], v[196:199], v[180:183], v[2:5]
	s_mov_b32 s14, s1
	s_nop 0
	s_add_i32 s1, s1, 0x6000
	s_cmp_eq_u32 s1, 0x12000
	s_cselect_b32 s1, 0, s1
	s_nop 0
	.p2align 3
	s_waitcnt vmcnt(6) lgkmcnt(0)
	s_barrier
;     ...
;   for (int kt = 0; kt < nk; kt++) {
;     if (kt + 1 < nk) asm volatile("s_waitcnt vmcnt(6)" ::: "memory");
;     else asm volatile("s_waitcnt vmcnt(0)" ::: "memory");
;     __builtin_amdgcn_s_barrier();
;     asm volatile("" ::: "memory");
;     if (kt + 2 < nk) G2_STAGE(kt + 2);
;     const char* cS = smem + (kt % 3) * 24576;
;     bf16x8 xa[8], wb[4];
; #pragma unroll
;     for (int f = 0; f < 8; f++) xa[f] = *(const bf16x8*)(cS + aoff + f * 1024);
; #pragma unroll
;     for (int f = 0; f < 4; f++) wb[f] = *(const bf16x8*)(cS + boff + f * 1024);
; #pragma unroll
;     for (int nf = 0; nf < 4; nf++)
; #pragma unroll
;       for (int mf = 0; mf < 8; mf++)
;         acc[nf][mf] = __builtin_amdgcn_mfma_f32_16x16x32_bf16(wb[nf], xa[mf], acc[nf][mf], 0, 0, 0);
	s_setprio 1
	v_add_u32_e32 v144, s1, v136
	v_mfma_f32_16x16x32_bf16 v[126:129], v[232:235], v[200:203], v[126:129]
	ds_read_b128 v[146:149], v144 offset:0
	v_mfma_f32_16x16x32_bf16 v[122:125], v[232:235], v[204:207], v[122:125]
	ds_read_b128 v[152:155], v144 offset:1024
	v_mfma_f32_16x16x32_bf16 v[118:121], v[232:235], v[208:211], v[118:121]
	ds_read_b128 v[156:159], v144 offset:2048
	v_mfma_f32_16x16x32_bf16 v[114:117], v[232:235], v[212:215], v[114:117]
	ds_read_b128 v[162:165], v144 offset:3072
	v_mfma_f32_16x16x32_bf16 v[110:113], v[232:235], v[216:219], v[110:113]
	ds_read_b128 v[166:169], v144 offset:4096
	v_mfma_f32_16x16x32_bf16 v[106:109], v[232:235], v[220:223], v[106:109]
	ds_read_b128 v[170:173], v144 offset:5120
	v_mfma_f32_16x16x32_bf16 v[102:105], v[232:235], v[224:227], v[102:105]
	ds_read_b128 v[176:179], v144 offset:6144
	v_mfma_f32_16x16x32_bf16 v[98:101], v[232:235], v[228:231], v[98:101]
	ds_read_b128 v[180:183], v144 offset:7168
	v_mfma_f32_16x16x32_bf16 v[94:97], v[236:239], v[200:203], v[94:97]
	v_add_u32_e64 v144, s1, v137
	v_mfma_f32_16x16x32_bf16 v[90:93], v[236:239], v[204:207], v[90:93]
	v_mfma_f32_16x16x32_bf16 v[86:89], v[236:239], v[208:211], v[86:89]
	ds_read_b128 v[184:187], v144 offset:16384
	v_mfma_f32_16x16x32_bf16 v[82:85], v[236:239], v[212:215], v[82:85]
	ds_read_b128 v[188:191], v144 offset:17408
	v_mfma_f32_16x16x32_bf16 v[78:81], v[236:239], v[216:219], v[78:81]
	ds_read_b128 v[192:195], v144 offset:18432
	v_mfma_f32_16x16x32_bf16 v[74:77], v[236:239], v[220:223], v[74:77]
	ds_read_b128 v[196:199], v144 offset:19456
	v_mfma_f32_16x16x32_bf16 v[70:73], v[236:239], v[224:227], v[70:73]
	v_mfma_f32_16x16x32_bf16 v[66:69], v[236:239], v[228:231], v[66:69]
	v_mfma_f32_16x16x32_bf16 v[62:65], v[240:243], v[200:203], v[62:65]
	v_mfma_f32_16x16x32_bf16 v[58:61], v[240:243], v[204:207], v[58:61]
	v_mfma_f32_16x16x32_bf16 v[54:57], v[240:243], v[208:211], v[54:57]
	v_mfma_f32_16x16x32_bf16 v[50:53], v[240:243], v[212:215], v[50:53]
	v_mfma_f32_16x16x32_bf16 v[46:49], v[240:243], v[216:219], v[46:49]
	v_mfma_f32_16x16x32_bf16 v[42:45], v[240:243], v[220:223], v[42:45]
	v_mfma_f32_16x16x32_bf16 v[38:41], v[240:243], v[224:227], v[38:41]
	v_mfma_f32_16x16x32_bf16 v[34:37], v[240:243], v[228:231], v[34:37]
	s_setprio 0
	s_nop 0
	v_mfma_f32_16x16x32_bf16 v[30:33], v[244:247], v[200:203], v[30:33]
	v_mfma_f32_16x16x32_bf16 v[26:29], v[244:247], v[204:207], v[26:29]
	v_mfma_f32_16x16x32_bf16 v[22:25], v[244:247], v[208:211], v[22:25]
	v_mfma_f32_16x16x32_bf16 v[18:21], v[244:247], v[212:215], v[18:21]
	v_mfma_f32_16x16x32_bf16 v[14:17], v[244:247], v[216:219], v[14:17]
	v_mfma_f32_16x16x32_bf16 v[10:13], v[244:247], v[220:223], v[10:13]
	v_mfma_f32_16x16x32_bf16 v[6:9], v[244:247], v[224:227], v[6:9]
	v_mfma_f32_16x16x32_bf16 v[2:5], v[244:247], v[228:231], v[2:5]
	s_mov_b32 s14, s1
	s_nop 0
	s_add_i32 s1, s1, 0x6000
	s_cmp_eq_u32 s1, 0x12000
	s_cselect_b32 s1, 0, s1
	s_nop 0
	.p2align 3
	s_waitcnt vmcnt(0) lgkmcnt(0)
	s_barrier
	s_setprio 1
	v_add_u32_e32 v144, s1, v136
	v_mfma_f32_16x16x32_bf16 v[126:129], v[184:187], v[146:149], v[126:129]
	ds_read_b128 v[200:203], v144 offset:0
	v_mfma_f32_16x16x32_bf16 v[122:125], v[184:187], v[152:155], v[122:125]
	ds_read_b128 v[204:207], v144 offset:1024
	v_mfma_f32_16x16x32_bf16 v[118:121], v[184:187], v[156:159], v[118:121]
	ds_read_b128 v[208:211], v144 offset:2048
	v_mfma_f32_16x16x32_bf16 v[114:117], v[184:187], v[162:165], v[114:117]
	ds_read_b128 v[212:215], v144 offset:3072
	v_mfma_f32_16x16x32_bf16 v[110:113], v[184:187], v[166:169], v[110:113]
	ds_read_b128 v[216:219], v144 offset:4096
	v_mfma_f32_16x16x32_bf16 v[106:109], v[184:187], v[170:173], v[106:109]
	ds_read_b128 v[220:223], v144 offset:5120
	v_mfma_f32_16x16x32_bf16 v[102:105], v[184:187], v[176:179], v[102:105]
	ds_read_b128 v[224:227], v144 offset:6144
	v_mfma_f32_16x16x32_bf16 v[98:101], v[184:187], v[180:183], v[98:101]
	ds_read_b128 v[228:231], v144 offset:7168
	v_mfma_f32_16x16x32_bf16 v[94:97], v[188:191], v[146:149], v[94:97]
	v_add_u32_e64 v144, s1, v137
	v_mfma_f32_16x16x32_bf16 v[90:93], v[188:191], v[152:155], v[90:93]
	v_mfma_f32_16x16x32_bf16 v[86:89], v[188:191], v[156:159], v[86:89]
	ds_read_b128 v[232:235], v144 offset:16384
	v_mfma_f32_16x16x32_bf16 v[82:85], v[188:191], v[162:165], v[82:85]
	ds_read_b128 v[236:239], v144 offset:17408
	v_mfma_f32_16x16x32_bf16 v[78:81], v[188:191], v[166:169], v[78:81]
	ds_read_b128 v[240:243], v144 offset:18432
	v_mfma_f32_16x16x32_bf16 v[74:77], v[188:191], v[170:173], v[74:77]
	ds_read_b128 v[244:247], v144 offset:19456
	v_mfma_f32_16x16x32_bf16 v[70:73], v[188:191], v[176:179], v[70:73]
	v_mfma_f32_16x16x32_bf16 v[66:69], v[188:191], v[180:183], v[66:69]
	v_mfma_f32_16x16x32_bf16 v[62:65], v[192:195], v[146:149], v[62:65]
	v_mfma_f32_16x16x32_bf16 v[58:61], v[192:195], v[152:155], v[58:61]
	v_mfma_f32_16x16x32_bf16 v[54:57], v[192:195], v[156:159], v[54:57]
	v_mfma_f32_16x16x32_bf16 v[50:53], v[192:195], v[162:165], v[50:53]
	v_mfma_f32_16x16x32_bf16 v[46:49], v[192:195], v[166:169], v[46:49]
	v_mfma_f32_16x16x32_bf16 v[42:45], v[192:195], v[170:173], v[42:45]
	v_mfma_f32_16x16x32_bf16 v[38:41], v[192:195], v[176:179], v[38:41]
	v_mfma_f32_16x16x32_bf16 v[34:37], v[192:195], v[180:183], v[34:37]
	s_setprio 0
	s_nop 0
	v_mfma_f32_16x16x32_bf16 v[30:33], v[196:199], v[146:149], v[30:33]
	v_mfma_f32_16x16x32_bf16 v[26:29], v[196:199], v[152:155], v[26:29]
	v_mfma_f32_16x16x32_bf16 v[22:25], v[196:199], v[156:159], v[22:25]
	v_mfma_f32_16x16x32_bf16 v[18:21], v[196:199], v[162:165], v[18:21]
	v_mfma_f32_16x16x32_bf16 v[14:17], v[196:199], v[166:169], v[14:17]
	v_mfma_f32_16x16x32_bf16 v[10:13], v[196:199], v[170:173], v[10:13]
	v_mfma_f32_16x16x32_bf16 v[6:9], v[196:199], v[176:179], v[6:9]
	v_mfma_f32_16x16x32_bf16 v[2:5], v[196:199], v[180:183], v[2:5]
	s_mov_b32 s14, s1
	s_nop 0
	s_add_i32 s1, s1, 0x6000
	s_cmp_eq_u32 s1, 0x12000
	s_cselect_b32 s1, 0, s1
	s_nop 0
	s_mov_b32 s4, 0x8000
	s_mov_b32 s5, 0
	s_mov_b32 s10, 0x10000
	s_mov_b32 s11, 0
	s_mov_b32 s41, 0x3fd744fd
	.p2align 3
	s_waitcnt lgkmcnt(0)
; DEVI float blo(unsigned u) { return __uint_as_float(u << 16); }
; DEVI float bhi(unsigned u) { return __uint_as_float(u & 0xffff0000u); }
;     ...
;     for (int nf = 0; nf < 4; nf++)
; #pragma unroll
;       for (int mf = 0; mf < 8; mf++)
;         acc[nf][mf] = __builtin_amdgcn_mfma_f32_16x16x32_bf16(wb[nf], xa[mf], acc[nf][mf], 0, 0, 0);
;     ...
;         if (EPI == EPI_RESID || EPI == EPI_RESID_ATOMIC) {
;           f32x4 x = a;
;           if (EPI == EPI_RESID || kpart == 0) {
;             const u32x2 xr = *(const u32x2*)((const u16*)(p.ws + WS_XB) + (size_t)row * 1024 + col);
;             x[0] += ALPHA * blo(xr[0]); x[1] += ALPHA * bhi(xr[0]); x[2] += ALPHA * blo(xr[1]); x[3] += ALPHA * bhi(xr[1]);
;           }
;           if (EPI == EPI_RESID) *(f32x4*)((float*)(p.ws + WS_XF) + (size_t)row * 1024 + col) = x;
;           else *(f32x4*)((float*)(p.ws + WS_SLAB) + ((size_t)kpart * 512 + (row - T_P)) * 1024 + col) = x;
	s_nop 0
	v_mfma_f32_16x16x32_bf16 v[126:129], v[232:235], v[200:203], v[126:129]
	v_mfma_f32_16x16x32_bf16 v[122:125], v[232:235], v[204:207], v[122:125]
	v_mfma_f32_16x16x32_bf16 v[118:121], v[232:235], v[208:211], v[118:121]
	v_mfma_f32_16x16x32_bf16 v[114:117], v[232:235], v[212:215], v[114:117]
	v_mfma_f32_16x16x32_bf16 v[110:113], v[232:235], v[216:219], v[110:113]
	v_mfma_f32_16x16x32_bf16 v[106:109], v[232:235], v[220:223], v[106:109]
	v_mfma_f32_16x16x32_bf16 v[102:105], v[232:235], v[224:227], v[102:105]
	v_mfma_f32_16x16x32_bf16 v[98:101], v[232:235], v[228:231], v[98:101]
	v_mfma_f32_16x16x32_bf16 v[94:97], v[236:239], v[200:203], v[94:97]
	v_mfma_f32_16x16x32_bf16 v[90:93], v[236:239], v[204:207], v[90:93]
	v_mfma_f32_16x16x32_bf16 v[86:89], v[236:239], v[208:211], v[86:89]
	v_mfma_f32_16x16x32_bf16 v[82:85], v[236:239], v[212:215], v[82:85]
	v_mfma_f32_16x16x32_bf16 v[78:81], v[236:239], v[216:219], v[78:81]
	v_mfma_f32_16x16x32_bf16 v[74:77], v[236:239], v[220:223], v[74:77]
	v_mfma_f32_16x16x32_bf16 v[70:73], v[236:239], v[224:227], v[70:73]
	v_mfma_f32_16x16x32_bf16 v[66:69], v[236:239], v[228:231], v[66:69]
	v_mfma_f32_16x16x32_bf16 v[62:65], v[240:243], v[200:203], v[62:65]
	v_mfma_f32_16x16x32_bf16 v[58:61], v[240:243], v[204:207], v[58:61]
	v_mfma_f32_16x16x32_bf16 v[54:57], v[240:243], v[208:211], v[54:57]
	v_mfma_f32_16x16x32_bf16 v[50:53], v[240:243], v[212:215], v[50:53]
	v_mfma_f32_16x16x32_bf16 v[46:49], v[240:243], v[216:219], v[46:49]
	v_mfma_f32_16x16x32_bf16 v[42:45], v[240:243], v[220:223], v[42:45]
	v_mfma_f32_16x16x32_bf16 v[38:41], v[240:243], v[224:227], v[38:41]
	v_mfma_f32_16x16x32_bf16 v[34:37], v[240:243], v[228:231], v[34:37]
	v_mfma_f32_16x16x32_bf16 v[30:33], v[244:247], v[200:203], v[30:33]
	v_mfma_f32_16x16x32_bf16 v[26:29], v[244:247], v[204:207], v[26:29]
	v_mfma_f32_16x16x32_bf16 v[22:25], v[244:247], v[208:211], v[22:25]
	v_mfma_f32_16x16x32_bf16 v[18:21], v[244:247], v[212:215], v[18:21]
	v_mfma_f32_16x16x32_bf16 v[14:17], v[244:247], v[216:219], v[14:17]
	v_mfma_f32_16x16x32_bf16 v[10:13], v[244:247], v[220:223], v[10:13]
	v_mfma_f32_16x16x32_bf16 v[6:9], v[244:247], v[224:227], v[6:9]
	v_mfma_f32_16x16x32_bf16 v[2:5], v[244:247], v[228:231], v[2:5]
	s_mov_b32 m0, s40
	s_cmp_eq_u32 s98, 0
	s_cbranch_scc1 .Lta4_first
	s_nop 7
	global_store_dwordx4 v[140:141], v[126:129], off offset:0
	global_store_dwordx4 v[140:141], v[94:97], off offset:64
	global_store_dwordx4 v[140:141], v[62:65], off offset:128
	global_store_dwordx4 v[140:141], v[30:33], off offset:192
	v_lshl_add_u64 v[140:141], v[140:141], 0, s[10:11]
	global_store_dwordx4 v[140:141], v[122:125], off offset:0
	global_store_dwordx4 v[140:141], v[90:93], off offset:64
	global_store_dwordx4 v[140:141], v[58:61], off offset:128
	global_store_dwordx4 v[140:141], v[26:29], off offset:192
	v_lshl_add_u64 v[140:141], v[140:141], 0, s[10:11]
	global_store_dwordx4 v[140:141], v[118:121], off offset:0
	global_store_dwordx4 v[140:141], v[86:89], off offset:64
	global_store_dwordx4 v[140:141], v[54:57], off offset:128
	global_store_dwordx4 v[140:141], v[22:25], off offset:192
	v_lshl_add_u64 v[140:141], v[140:141], 0, s[10:11]
	global_store_dwordx4 v[140:141], v[114:117], off offset:0
	global_store_dwordx4 v[140:141], v[82:85], off offset:64
	global_store_dwordx4 v[140:141], v[50:53], off offset:128
	global_store_dwordx4 v[140:141], v[18:21], off offset:192
	v_lshl_add_u64 v[140:141], v[140:141], 0, s[10:11]
	global_store_dwordx4 v[140:141], v[110:113], off offset:0
	global_store_dwordx4 v[140:141], v[78:81], off offset:64
	global_store_dwordx4 v[140:141], v[46:49], off offset:128
	global_store_dwordx4 v[140:141], v[14:17], off offset:192
	v_lshl_add_u64 v[140:141], v[140:141], 0, s[10:11]
	global_store_dwordx4 v[140:141], v[106:109], off offset:0
	global_store_dwordx4 v[140:141], v[74:77], off offset:64
	global_store_dwordx4 v[140:141], v[42:45], off offset:128
	global_store_dwordx4 v[140:141], v[10:13], off offset:192
	v_lshl_add_u64 v[140:141], v[140:141], 0, s[10:11]
	global_store_dwordx4 v[140:141], v[102:105], off offset:0
	global_store_dwordx4 v[140:141], v[70:73], off offset:64
	global_store_dwordx4 v[140:141], v[38:41], off offset:128
	global_store_dwordx4 v[140:141], v[6:9], off offset:192
	v_lshl_add_u64 v[140:141], v[140:141], 0, s[10:11]
	global_store_dwordx4 v[140:141], v[98:101], off offset:0
	global_store_dwordx4 v[140:141], v[66:69], off offset:64
	global_store_dwordx4 v[140:141], v[34:37], off offset:128
	global_store_dwordx4 v[140:141], v[2:5], off offset:192
	v_readlane_b32 s0, v250, 7
	s_cmpk_lg_u32 s0, 0x200
	s_cbranch_scc1 .Lta4_ar1
	s_mov_b32 s0, 1
	v_writelane_b32 v255, s0, 41
	v_readlane_b32 s1, v250, 0
	s_lshr_b32 s14, s1, 3
	s_and_b32 s1, s1, 7
	s_lshl_b32 s1, s1, 6
	s_add_i32 s1, s1, s14
	s_sub_i32 s39, s1, 0x200

;     ...
;   for (int kt = 0; kt < nk; kt++) {
;     if (kt + 1 < nk) asm volatile("s_waitcnt vmcnt(6)" ::: "memory");
;     else asm volatile("s_waitcnt vmcnt(0)" ::: "memory");
;     __builtin_amdgcn_s_barrier();
;     asm volatile("" ::: "memory");
;     if (kt + 2 < nk) G2_STAGE(kt + 2);
;     const char* cS = smem + (kt % 3) * 24576;
;     bf16x8 xa[8], wb[4];
; #pragma unroll
;     for (int f = 0; f < 8; f++) xa[f] = *(const bf16x8*)(cS + aoff + f * 1024);
; #pragma unroll
;     for (int f = 0; f < 4; f++) wb[f] = *(const bf16x8*)(cS + boff + f * 1024);
; #pragma unroll
;     for (int nf = 0; nf < 4; nf++)
; #pragma unroll
;       for (int mf = 0; mf < 8; mf++)
;         acc[nf][mf] = __builtin_amdgcn_mfma_f32_16x16x32_bf16(wb[nf], xa[mf], acc[nf][mf], 0, 0, 0);
.Lt4_loop:
	.p2align 3
	s_waitcnt vmcnt(6) lgkmcnt(0)
	s_barrier
	s_setprio 1
	v_add_u32_e32 v144, s41, v136
	v_mfma_f32_16x16x32_bf16 v[126:129], v[184:187], v[146:149], v[126:129]
	ds_read_b128 v[200:203], v144 offset:0
	v_mfma_f32_16x16x32_bf16 v[122:125], v[184:187], v[152:155], v[122:125]
	ds_read_b128 v[204:207], v144 offset:1024
	v_mfma_f32_16x16x32_bf16 v[118:121], v[184:187], v[156:159], v[118:121]
	ds_read_b128 v[208:211], v144 offset:2048
	v_mfma_f32_16x16x32_bf16 v[114:117], v[184:187], v[162:165], v[114:117]
	ds_read_b128 v[212:215], v144 offset:3072
	v_mfma_f32_16x16x32_bf16 v[110:113], v[184:187], v[166:169], v[110:113]
	ds_read_b128 v[216:219], v144 offset:4096
	v_mfma_f32_16x16x32_bf16 v[106:109], v[184:187], v[170:173], v[106:109]
	ds_read_b128 v[220:223], v144 offset:5120
	v_mfma_f32_16x16x32_bf16 v[102:105], v[184:187], v[176:179], v[102:105]
	ds_read_b128 v[224:227], v144 offset:6144
	v_mfma_f32_16x16x32_bf16 v[98:101], v[184:187], v[180:183], v[98:101]
	ds_read_b128 v[228:231], v144 offset:7168
	v_mfma_f32_16x16x32_bf16 v[94:97], v[188:191], v[146:149], v[94:97]
	v_add_u32_e64 v144, s41, v137
	v_mfma_f32_16x16x32_bf16 v[90:93], v[188:191], v[152:155], v[90:93]
	v_mfma_f32_16x16x32_bf16 v[86:89], v[188:191], v[156:159], v[86:89]
	ds_read_b128 v[232:235], v144 offset:16384
	v_mfma_f32_16x16x32_bf16 v[82:85], v[188:191], v[162:165], v[82:85]
	ds_read_b128 v[236:239], v144 offset:17408
	v_mfma_f32_16x16x32_bf16 v[78:81], v[188:191], v[166:169], v[78:81]
	ds_read_b128 v[240:243], v144 offset:18432
	v_mfma_f32_16x16x32_bf16 v[74:77], v[188:191], v[170:173], v[74:77]
	ds_read_b128 v[244:247], v144 offset:19456
	v_mfma_f32_16x16x32_bf16 v[70:73], v[188:191], v[176:179], v[70:73]
	s_add_i32 s43, s47, s42
	s_mov_b32 m0, s43
	v_lshl_add_u64 v[142:143], v[132:133], 0, s[2:3]
	v_mfma_f32_16x16x32_bf16 v[66:69], v[188:191], v[180:183], v[66:69]
	global_load_lds_dwordx4 v[132:133], off
	s_add_i32 m0, m0, 0x1000
	v_mfma_f32_16x16x32_bf16 v[62:65], v[192:195], v[146:149], v[62:65]
	v_mfma_f32_16x16x32_bf16 v[58:61], v[192:195], v[152:155], v[58:61]
	v_mfma_f32_16x16x32_bf16 v[54:57], v[192:195], v[156:159], v[54:57]
	global_load_lds_dwordx4 v[142:143], off
	v_lshl_add_u64 v[142:143], v[142:143], 0, s[2:3]
	s_add_i32 m0, m0, 0x1000
	v_mfma_f32_16x16x32_bf16 v[50:53], v[192:195], v[162:165], v[50:53]
	v_mfma_f32_16x16x32_bf16 v[46:49], v[192:195], v[166:169], v[46:49]
	v_mfma_f32_16x16x32_bf16 v[42:45], v[192:195], v[170:173], v[42:45]
	global_load_lds_dwordx4 v[142:143], off
	v_lshl_add_u64 v[142:143], v[142:143], 0, s[2:3]
	s_add_i32 m0, m0, 0x1000
	v_mfma_f32_16x16x32_bf16 v[38:41], v[192:195], v[176:179], v[38:41]
	v_mfma_f32_16x16x32_bf16 v[34:37], v[192:195], v[180:183], v[34:37]
	s_setprio 0
	s_nop 0
	v_mfma_f32_16x16x32_bf16 v[30:33], v[196:199], v[146:149], v[30:33]
	global_load_lds_dwordx4 v[142:143], off
	s_add_i32 m0, m0, 0x1000
	v_lshl_add_u64 v[142:143], v[134:135], 0, s[2:3]
	v_mfma_f32_16x16x32_bf16 v[26:29], v[196:199], v[152:155], v[26:29]
	v_mfma_f32_16x16x32_bf16 v[22:25], v[196:199], v[156:159], v[22:25]
	v_mfma_f32_16x16x32_bf16 v[18:21], v[196:199], v[162:165], v[18:21]
	global_load_lds_dwordx4 v[134:135], off
	s_add_i32 m0, m0, 0x1000
	v_lshl_add_u64 v[132:133], v[132:133], 0, s[12:13]
	v_mfma_f32_16x16x32_bf16 v[14:17], v[196:199], v[166:169], v[14:17]
	v_mfma_f32_16x16x32_bf16 v[10:13], v[196:199], v[170:173], v[10:13]
	v_mfma_f32_16x16x32_bf16 v[6:9], v[196:199], v[176:179], v[6:9]
	global_load_lds_dwordx4 v[142:143], off
	v_lshl_add_u64 v[134:135], v[134:135], 0, s[4:5]
	v_mfma_f32_16x16x32_bf16 v[2:5], v[196:199], v[180:183], v[2:5]
	s_mov_b32 s42, s41
	s_nop 0
	s_add_i32 s41, s41, 0x6000
	s_cmp_eq_u32 s41, 0x12000
	s_cselect_b32 s41, 0, s41
	s_nop 0
	.p2align 3
	s_waitcnt vmcnt(6) lgkmcnt(0)
	s_barrier
	s_setprio 1
	v_add_u32_e32 v144, s41, v136
	v_mfma_f32_16x16x32_bf16 v[126:129], v[232:235], v[200:203], v[126:129]
	ds_read_b128 v[146:149], v144 offset:0
	v_mfma_f32_16x16x32_bf16 v[122:125], v[232:235], v[204:207], v[122:125]
	ds_read_b128 v[152:155], v144 offset:1024
	v_mfma_f32_16x16x32_bf16 v[118:121], v[232:235], v[208:211], v[118:121]
	ds_read_b128 v[156:159], v144 offset:2048
	v_mfma_f32_16x16x32_bf16 v[114:117], v[232:235], v[212:215], v[114:117]
	ds_read_b128 v[162:165], v144 offset:3072
	v_mfma_f32_16x16x32_bf16 v[110:113], v[232:235], v[216:219], v[110:113]
	ds_read_b128 v[166:169], v144 offset:4096
	v_mfma_f32_16x16x32_bf16 v[106:109], v[232:235], v[220:223], v[106:109]
	ds_read_b128 v[170:173], v144 offset:5120
	v_mfma_f32_16x16x32_bf16 v[102:105], v[232:235], v[224:227], v[102:105]
	ds_read_b128 v[176:179], v144 offset:6144
	v_mfma_f32_16x16x32_bf16 v[98:101], v[232:235], v[228:231], v[98:101]
	ds_read_b128 v[180:183], v144 offset:7168
	v_mfma_f32_16x16x32_bf16 v[94:97], v[236:239], v[200:203], v[94:97]
	v_add_u32_e64 v144, s41, v137
	v_mfma_f32_16x16x32_bf16 v[90:93], v[236:239], v[204:207], v[90:93]
	v_mfma_f32_16x16x32_bf16 v[86:89], v[236:239], v[208:211], v[86:89]
	ds_read_b128 v[184:187], v144 offset:16384
	v_mfma_f32_16x16x32_bf16 v[82:85], v[236:239], v[212:215], v[82:85]
	ds_read_b128 v[188:191], v144 offset:17408
	v_mfma_f32_16x16x32_bf16 v[78:81], v[236:239], v[216:219], v[78:81]
	ds_read_b128 v[192:195], v144 offset:18432
	v_mfma_f32_16x16x32_bf16 v[74:77], v[236:239], v[220:223], v[74:77]
	ds_read_b128 v[196:199], v144 offset:19456
	v_mfma_f32_16x16x32_bf16 v[70:73], v[236:239], v[224:227], v[70:73]
	s_add_i32 s43, s47, s42
	s_mov_b32 m0, s43
	v_lshl_add_u64 v[142:143], v[132:133], 0, s[2:3]
	v_mfma_f32_16x16x32_bf16 v[66:69], v[236:239], v[228:231], v[66:69]
;     ...
;   for (int kt = 0; kt < nk; kt++) {
;     if (kt + 1 < nk) asm volatile("s_waitcnt vmcnt(6)" ::: "memory");
;     else asm volatile("s_waitcnt vmcnt(0)" ::: "memory");
;     __builtin_amdgcn_s_barrier();
;     asm volatile("" ::: "memory");
;     if (kt + 2 < nk) G2_STAGE(kt + 2);
;     const char* cS = smem + (kt % 3) * 24576;
;     bf16x8 xa[8], wb[4];
; #pragma unroll
;     for (int f = 0; f < 8; f++) xa[f] = *(const bf16x8*)(cS + aoff + f * 1024);
; #pragma unroll
;     for (int f = 0; f < 4; f++) wb[f] = *(const bf16x8*)(cS + boff + f * 1024);
; #pragma unroll
;     for (int nf = 0; nf < 4; nf++)
; #pragma unroll
;       for (int mf = 0; mf < 8; mf++)
;         acc[nf][mf] = __builtin_amdgcn_mfma_f32_16x16x32_bf16(wb[nf], xa[mf], acc[nf][mf], 0, 0, 0);
	global_load_lds_dwordx4 v[132:133], off
	s_add_i32 m0, m0, 0x1000
	v_mfma_f32_16x16x32_bf16 v[62:65], v[240:243], v[200:203], v[62:65]
	v_mfma_f32_16x16x32_bf16 v[58:61], v[240:243], v[204:207], v[58:61]
	v_mfma_f32_16x16x32_bf16 v[54:57], v[240:243], v[208:211], v[54:57]
	global_load_lds_dwordx4 v[142:143], off
	v_lshl_add_u64 v[142:143], v[142:143], 0, s[2:3]
	s_add_i32 m0, m0, 0x1000
	v_mfma_f32_16x16x32_bf16 v[50:53], v[240:243], v[212:215], v[50:53]
	v_mfma_f32_16x16x32_bf16 v[46:49], v[240:243], v[216:219], v[46:49]
	v_mfma_f32_16x16x32_bf16 v[42:45], v[240:243], v[220:223], v[42:45]
	global_load_lds_dwordx4 v[142:143], off
	v_lshl_add_u64 v[142:143], v[142:143], 0, s[2:3]
	s_add_i32 m0, m0, 0x1000
	v_mfma_f32_16x16x32_bf16 v[38:41], v[240:243], v[224:227], v[38:41]
	v_mfma_f32_16x16x32_bf16 v[34:37], v[240:243], v[228:231], v[34:37]
	s_setprio 0
	s_nop 0
	v_mfma_f32_16x16x32_bf16 v[30:33], v[244:247], v[200:203], v[30:33]
	global_load_lds_dwordx4 v[142:143], off
	s_add_i32 m0, m0, 0x1000
	v_lshl_add_u64 v[142:143], v[134:135], 0, s[2:3]
	v_mfma_f32_16x16x32_bf16 v[26:29], v[244:247], v[204:207], v[26:29]
	v_mfma_f32_16x16x32_bf16 v[22:25], v[244:247], v[208:211], v[22:25]
	v_mfma_f32_16x16x32_bf16 v[18:21], v[244:247], v[212:215], v[18:21]
	global_load_lds_dwordx4 v[134:135], off
	s_add_i32 m0, m0, 0x1000
	v_lshl_add_u64 v[132:133], v[132:133], 0, s[12:13]
	v_mfma_f32_16x16x32_bf16 v[14:17], v[244:247], v[216:219], v[14:17]
	v_mfma_f32_16x16x32_bf16 v[10:13], v[244:247], v[220:223], v[10:13]
	v_mfma_f32_16x16x32_bf16 v[6:9], v[244:247], v[224:227], v[6:9]
	global_load_lds_dwordx4 v[142:143], off
	v_lshl_add_u64 v[134:135], v[134:135], 0, s[4:5]
	v_mfma_f32_16x16x32_bf16 v[2:5], v[244:247], v[228:231], v[2:5]
	s_mov_b32 s42, s41
	s_nop 0
	s_add_i32 s41, s41, 0x6000
	s_cmp_eq_u32 s41, 0x12000
	s_cselect_b32 s41, 0, s41
	s_nop 0
	s_sub_i32 s40, s40, 1
	s_cmp_lg_u32 s40, 0
	s_cbranch_scc1 .Lt4_loop
	.p2align 3
	s_waitcnt vmcnt(6) lgkmcnt(0)
	s_barrier
	s_setprio 1
	v_add_u32_e32 v144, s41, v136
	v_mfma_f32_16x16x32_bf16 v[126:129], v[184:187], v[146:149], v[126:129]
	ds_read_b128 v[200:203], v144 offset:0
	v_mfma_f32_16x16x32_bf16 v[122:125], v[184:187], v[152:155], v[122:125]
	ds_read_b128 v[204:207], v144 offset:1024
	v_mfma_f32_16x16x32_bf16 v[118:121], v[184:187], v[156:159], v[118:121]
	ds_read_b128 v[208:211], v144 offset:2048
	v_mfma_f32_16x16x32_bf16 v[114:117], v[184:187], v[162:165], v[114:117]
	ds_read_b128 v[212:215], v144 offset:3072
	v_mfma_f32_16x16x32_bf16 v[110:113], v[184:187], v[166:169], v[110:113]
	ds_read_b128 v[216:219], v144 offset:4096
	v_mfma_f32_16x16x32_bf16 v[106:109], v[184:187], v[170:173], v[106:109]
	ds_read_b128 v[220:223], v144 offset:5120
	v_mfma_f32_16x16x32_bf16 v[102:105], v[184:187], v[176:179], v[102:105]
	ds_read_b128 v[224:227], v144 offset:6144
	v_mfma_f32_16x16x32_bf16 v[98:101], v[184:187], v[180:183], v[98:101]
	ds_read_b128 v[228:231], v144 offset:7168
	v_mfma_f32_16x16x32_bf16 v[94:97], v[188:191], v[146:149], v[94:97]
	v_add_u32_e64 v144, s41, v137
	v_mfma_f32_16x16x32_bf16 v[90:93], v[188:191], v[152:155], v[90:93]
	v_mfma_f32_16x16x32_bf16 v[86:89], v[188:191], v[156:159], v[86:89]
	ds_read_b128 v[232:235], v144 offset:16384
	v_mfma_f32_16x16x32_bf16 v[82:85], v[188:191], v[162:165], v[82:85]
	ds_read_b128 v[236:239], v144 offset:17408
	v_mfma_f32_16x16x32_bf16 v[78:81], v[188:191], v[166:169], v[78:81]
	ds_read_b128 v[240:243], v144 offset:18432
	v_mfma_f32_16x16x32_bf16 v[74:77], v[188:191], v[170:173], v[74:77]
	ds_read_b128 v[244:247], v144 offset:19456
	v_mfma_f32_16x16x32_bf16 v[70:73], v[188:191], v[176:179], v[70:73]
	s_add_i32 s43, s47, s42
	s_mov_b32 m0, s43
	v_lshl_add_u64 v[142:143], v[132:133], 0, s[2:3]
	v_mfma_f32_16x16x32_bf16 v[66:69], v[188:191], v[180:183], v[66:69]
	global_load_lds_dwordx4 v[132:133], off
	s_add_i32 m0, m0, 0x1000
	v_mfma_f32_16x16x32_bf16 v[62:65], v[192:195], v[146:149], v[62:65]
	v_mfma_f32_16x16x32_bf16 v[58:61], v[192:195], v[152:155], v[58:61]
	v_mfma_f32_16x16x32_bf16 v[54:57], v[192:195], v[156:159], v[54:57]
	global_load_lds_dwordx4 v[142:143], off
	v_lshl_add_u64 v[142:143], v[142:143], 0, s[2:3]
	s_add_i32 m0, m0, 0x1000
	v_mfma_f32_16x16x32_bf16 v[50:53], v[192:195], v[162:165], v[50:53]
	v_mfma_f32_16x16x32_bf16 v[46:49], v[192:195], v[166:169], v[46:49]
	v_mfma_f32_16x16x32_bf16 v[42:45], v[192:195], v[170:173], v[42:45]
	global_load_lds_dwordx4 v[142:143], off
	v_lshl_add_u64 v[142:143], v[142:143], 0, s[2:3]
	s_add_i32 m0, m0, 0x1000
	v_mfma_f32_16x16x32_bf16 v[38:41], v[192:195], v[176:179], v[38:41]
	v_mfma_f32_16x16x32_bf16 v[34:37], v[192:195], v[180:183], v[34:37]
	s_setprio 0
	s_nop 0
	v_mfma_f32_16x16x32_bf16 v[30:33], v[196:199], v[146:149], v[30:33]
	global_load_lds_dwordx4 v[142:143], off
	s_add_i32 m0, m0, 0x1000
	v_lshl_add_u64 v[142:143], v[134:135], 0, s[2:3]
	v_mfma_f32_16x16x32_bf16 v[26:29], v[196:199], v[152:155], v[26:29]
	v_mfma_f32_16x16x32_bf16 v[22:25], v[196:199], v[156:159], v[22:25]
	v_mfma_f32_16x16x32_bf16 v[18:21], v[196:199], v[162:165], v[18:21]
	global_load_lds_dwordx4 v[134:135], off
	s_add_i32 m0, m0, 0x1000
	v_lshl_add_u64 v[132:133], v[132:133], 0, s[12:13]
	v_mfma_f32_16x16x32_bf16 v[14:17], v[196:199], v[166:169], v[14:17]
	v_mfma_f32_16x16x32_bf16 v[10:13], v[196:199], v[170:173], v[10:13]
	v_mfma_f32_16x16x32_bf16 v[6:9], v[196:199], v[176:179], v[6:9]
	global_load_lds_dwordx4 v[142:143], off
	v_lshl_add_u64 v[134:135], v[134:135], 0, s[4:5]
	v_mfma_f32_16x16x32_bf16 v[2:5], v[196:199], v[180:183], v[2:5]
	s_mov_b32 s42, s41
	s_nop 0
	s_add_i32 s41, s41, 0x6000
	s_cmp_eq_u32 s41, 0x12000
	s_cselect_b32 s41, 0, s41
	s_nop 0
	.p2align 3
	s_waitcnt vmcnt(6) lgkmcnt(0)
	s_barrier
;     ...
;   for (int kt = 0; kt < nk; kt++) {
;     if (kt + 1 < nk) asm volatile("s_waitcnt vmcnt(6)" ::: "memory");
;     else asm volatile("s_waitcnt vmcnt(0)" ::: "memory");
;     __builtin_amdgcn_s_barrier();
;     asm volatile("" ::: "memory");
;     if (kt + 2 < nk) G2_STAGE(kt + 2);
;     const char* cS = smem + (kt % 3) * 24576;
;     bf16x8 xa[8], wb[4];
; #pragma unroll
;     for (int f = 0; f < 8; f++) xa[f] = *(const bf16x8*)(cS + aoff + f * 1024);
; #pragma unroll
;     for (int f = 0; f < 4; f++) wb[f] = *(const bf16x8*)(cS + boff + f * 1024);
; #pragma unroll
;     for (int nf = 0; nf < 4; nf++)
; #pragma unroll
;       for (int mf = 0; mf < 8; mf++)
;         acc[nf][mf] = __builtin_amdgcn_mfma_f32_16x16x32_bf16(wb[nf], xa[mf], acc[nf][mf], 0, 0, 0);
	s_setprio 1
	v_add_u32_e32 v144, s41, v136
	v_mfma_f32_16x16x32_bf16 v[126:129], v[232:235], v[200:203], v[126:129]
	ds_read_b128 v[146:149], v144 offset:0
	v_mfma_f32_16x16x32_bf16 v[122:125], v[232:235], v[204:207], v[122:125]
	ds_read_b128 v[152:155], v144 offset:1024
	v_mfma_f32_16x16x32_bf16 v[118:121], v[232:235], v[208:211], v[118:121]
	ds_read_b128 v[156:159], v144 offset:2048
	v_mfma_f32_16x16x32_bf16 v[114:117], v[232:235], v[212:215], v[114:117]
	ds_read_b128 v[162:165], v144 offset:3072
	v_mfma_f32_16x16x32_bf16 v[110:113], v[232:235], v[216:219], v[110:113]
	ds_read_b128 v[166:169], v144 offset:4096
	v_mfma_f32_16x16x32_bf16 v[106:109], v[232:235], v[220:223], v[106:109]
	ds_read_b128 v[170:173], v144 offset:5120
	v_mfma_f32_16x16x32_bf16 v[102:105], v[232:235], v[224:227], v[102:105]
	ds_read_b128 v[176:179], v144 offset:6144
	v_mfma_f32_16x16x32_bf16 v[98:101], v[232:235], v[228:231], v[98:101]
	ds_read_b128 v[180:183], v144 offset:7168
	v_mfma_f32_16x16x32_bf16 v[94:97], v[236:239], v[200:203], v[94:97]
	v_add_u32_e64 v144, s41, v137
	v_mfma_f32_16x16x32_bf16 v[90:93], v[236:239], v[204:207], v[90:93]
	v_mfma_f32_16x16x32_bf16 v[86:89], v[236:239], v[208:211], v[86:89]
	ds_read_b128 v[184:187], v144 offset:16384
	v_mfma_f32_16x16x32_bf16 v[82:85], v[236:239], v[212:215], v[82:85]
	ds_read_b128 v[188:191], v144 offset:17408
	v_mfma_f32_16x16x32_bf16 v[78:81], v[236:239], v[216:219], v[78:81]
	ds_read_b128 v[192:195], v144 offset:18432
	v_mfma_f32_16x16x32_bf16 v[74:77], v[236:239], v[220:223], v[74:77]
	ds_read_b128 v[196:199], v144 offset:19456
	v_mfma_f32_16x16x32_bf16 v[70:73], v[236:239], v[224:227], v[70:73]
	v_mfma_f32_16x16x32_bf16 v[66:69], v[236:239], v[228:231], v[66:69]
	v_mfma_f32_16x16x32_bf16 v[62:65], v[240:243], v[200:203], v[62:65]
	v_mfma_f32_16x16x32_bf16 v[58:61], v[240:243], v[204:207], v[58:61]
	v_mfma_f32_16x16x32_bf16 v[54:57], v[240:243], v[208:211], v[54:57]
	v_mfma_f32_16x16x32_bf16 v[50:53], v[240:243], v[212:215], v[50:53]
	v_mfma_f32_16x16x32_bf16 v[46:49], v[240:243], v[216:219], v[46:49]
	v_mfma_f32_16x16x32_bf16 v[42:45], v[240:243], v[220:223], v[42:45]
	v_mfma_f32_16x16x32_bf16 v[38:41], v[240:243], v[224:227], v[38:41]
	v_mfma_f32_16x16x32_bf16 v[34:37], v[240:243], v[228:231], v[34:37]
	s_setprio 0
	s_nop 0
	v_mfma_f32_16x16x32_bf16 v[30:33], v[244:247], v[200:203], v[30:33]
	v_mfma_f32_16x16x32_bf16 v[26:29], v[244:247], v[204:207], v[26:29]
	v_mfma_f32_16x16x32_bf16 v[22:25], v[244:247], v[208:211], v[22:25]
	v_mfma_f32_16x16x32_bf16 v[18:21], v[244:247], v[212:215], v[18:21]
	v_mfma_f32_16x16x32_bf16 v[14:17], v[244:247], v[216:219], v[14:17]
	v_mfma_f32_16x16x32_bf16 v[10:13], v[244:247], v[220:223], v[10:13]
	v_mfma_f32_16x16x32_bf16 v[6:9], v[244:247], v[224:227], v[6:9]
	v_mfma_f32_16x16x32_bf16 v[2:5], v[244:247], v[228:231], v[2:5]
	s_mov_b32 s42, s41
	s_nop 0
	s_add_i32 s41, s41, 0x6000
	s_cmp_eq_u32 s41, 0x12000
	s_cselect_b32 s41, 0, s41
	s_nop 0
	.p2align 3
	s_waitcnt vmcnt(0) lgkmcnt(0)
	s_barrier
	s_setprio 1
	v_add_u32_e32 v144, s41, v136
	v_mfma_f32_16x16x32_bf16 v[126:129], v[184:187], v[146:149], v[126:129]
	ds_read_b128 v[200:203], v144 offset:0
	v_mfma_f32_16x16x32_bf16 v[122:125], v[184:187], v[152:155], v[122:125]
	ds_read_b128 v[204:207], v144 offset:1024
	v_mfma_f32_16x16x32_bf16 v[118:121], v[184:187], v[156:159], v[118:121]
	ds_read_b128 v[208:211], v144 offset:2048
	v_mfma_f32_16x16x32_bf16 v[114:117], v[184:187], v[162:165], v[114:117]
	ds_read_b128 v[212:215], v144 offset:3072
	v_mfma_f32_16x16x32_bf16 v[110:113], v[184:187], v[166:169], v[110:113]
	ds_read_b128 v[216:219], v144 offset:4096
	v_mfma_f32_16x16x32_bf16 v[106:109], v[184:187], v[170:173], v[106:109]
	ds_read_b128 v[220:223], v144 offset:5120
	v_mfma_f32_16x16x32_bf16 v[102:105], v[184:187], v[176:179], v[102:105]
	ds_read_b128 v[224:227], v144 offset:6144
	v_mfma_f32_16x16x32_bf16 v[98:101], v[184:187], v[180:183], v[98:101]
	ds_read_b128 v[228:231], v144 offset:7168
	v_mfma_f32_16x16x32_bf16 v[94:97], v[188:191], v[146:149], v[94:97]
	v_add_u32_e64 v144, s41, v137
	v_mfma_f32_16x16x32_bf16 v[90:93], v[188:191], v[152:155], v[90:93]
	v_mfma_f32_16x16x32_bf16 v[86:89], v[188:191], v[156:159], v[86:89]
	ds_read_b128 v[232:235], v144 offset:16384
	v_mfma_f32_16x16x32_bf16 v[82:85], v[188:191], v[162:165], v[82:85]
	ds_read_b128 v[236:239], v144 offset:17408
	v_mfma_f32_16x16x32_bf16 v[78:81], v[188:191], v[166:169], v[78:81]
	ds_read_b128 v[240:243], v144 offset:18432
	v_mfma_f32_16x16x32_bf16 v[74:77], v[188:191], v[170:173], v[74:77]
	ds_read_b128 v[244:247], v144 offset:19456
	v_mfma_f32_16x16x32_bf16 v[70:73], v[188:191], v[176:179], v[70:73]
	v_mfma_f32_16x16x32_bf16 v[66:69], v[188:191], v[180:183], v[66:69]
	v_mfma_f32_16x16x32_bf16 v[62:65], v[192:195], v[146:149], v[62:65]
	v_mfma_f32_16x16x32_bf16 v[58:61], v[192:195], v[152:155], v[58:61]
	v_mfma_f32_16x16x32_bf16 v[54:57], v[192:195], v[156:159], v[54:57]
	v_mfma_f32_16x16x32_bf16 v[50:53], v[192:195], v[162:165], v[50:53]
	v_mfma_f32_16x16x32_bf16 v[46:49], v[192:195], v[166:169], v[46:49]
	v_mfma_f32_16x16x32_bf16 v[42:45], v[192:195], v[170:173], v[42:45]
	v_mfma_f32_16x16x32_bf16 v[38:41], v[192:195], v[176:179], v[38:41]
	v_mfma_f32_16x16x32_bf16 v[34:37], v[192:195], v[180:183], v[34:37]
	s_setprio 0
	s_nop 0
	v_mfma_f32_16x16x32_bf16 v[30:33], v[196:199], v[146:149], v[30:33]
	v_mfma_f32_16x16x32_bf16 v[26:29], v[196:199], v[152:155], v[26:29]
	v_mfma_f32_16x16x32_bf16 v[22:25], v[196:199], v[156:159], v[22:25]
	v_mfma_f32_16x16x32_bf16 v[18:21], v[196:199], v[162:165], v[18:21]
	v_mfma_f32_16x16x32_bf16 v[14:17], v[196:199], v[166:169], v[14:17]
	v_mfma_f32_16x16x32_bf16 v[10:13], v[196:199], v[170:173], v[10:13]
	v_mfma_f32_16x16x32_bf16 v[6:9], v[196:199], v[176:179], v[6:9]
	v_mfma_f32_16x16x32_bf16 v[2:5], v[196:199], v[180:183], v[2:5]
	s_mov_b32 s42, s41
	s_nop 0
	s_add_i32 s41, s41, 0x6000
	s_cmp_eq_u32 s41, 0x12000
	s_cselect_b32 s41, 0, s41
	s_nop 0
	s_mov_b32 s4, 0x8000
	s_mov_b32 s5, 0
	s_mov_b32 s10, 0x10000
	s_mov_b32 s11, 0
	s_mov_b32 s45, 0x3fd744fd
	.p2align 3
	s_waitcnt lgkmcnt(0)
; DEVI float blo(unsigned u) { return __uint_as_float(u << 16); }
; DEVI float bhi(unsigned u) { return __uint_as_float(u & 0xffff0000u); }
;     ...
;     for (int nf = 0; nf < 4; nf++)
; #pragma unroll
;       for (int mf = 0; mf < 8; mf++)
;         acc[nf][mf] = __builtin_amdgcn_mfma_f32_16x16x32_bf16(wb[nf], xa[mf], acc[nf][mf], 0, 0, 0);
;     ...
;         if (EPI == EPI_RESID || EPI == EPI_RESID_ATOMIC) {
;           f32x4 x = a;
;           if (EPI == EPI_RESID || kpart == 0) {
;             const u32x2 xr = *(const u32x2*)((const u16*)(p.ws + WS_XB) + (size_t)row * 1024 + col);
;             x[0] += ALPHA * blo(xr[0]); x[1] += ALPHA * bhi(xr[0]); x[2] += ALPHA * blo(xr[1]); x[3] += ALPHA * bhi(xr[1]);
;           }
;           if (EPI == EPI_RESID) *(f32x4*)((float*)(p.ws + WS_XF) + (size_t)row * 1024 + col) = x;
	s_nop 0
	v_mfma_f32_16x16x32_bf16 v[126:129], v[232:235], v[200:203], v[126:129]
	v_mfma_f32_16x16x32_bf16 v[122:125], v[232:235], v[204:207], v[122:125]
	v_mfma_f32_16x16x32_bf16 v[118:121], v[232:235], v[208:211], v[118:121]
	v_mfma_f32_16x16x32_bf16 v[114:117], v[232:235], v[212:215], v[114:117]
	v_mfma_f32_16x16x32_bf16 v[110:113], v[232:235], v[216:219], v[110:113]
	global_load_dwordx4 v[146:149], v[138:139], off offset:0
	v_mfma_f32_16x16x32_bf16 v[106:109], v[232:235], v[220:223], v[106:109]
	v_mfma_f32_16x16x32_bf16 v[102:105], v[232:235], v[224:227], v[102:105]
	global_load_dwordx4 v[152:155], v[138:139], off offset:128
	v_mfma_f32_16x16x32_bf16 v[98:101], v[232:235], v[228:231], v[98:101]
	v_lshl_add_u64 v[138:139], v[138:139], 0, s[4:5]
	v_mfma_f32_16x16x32_bf16 v[94:97], v[236:239], v[200:203], v[94:97]
	global_load_dwordx4 v[156:159], v[138:139], off offset:0
	v_mfma_f32_16x16x32_bf16 v[90:93], v[236:239], v[204:207], v[90:93]
	v_mfma_f32_16x16x32_bf16 v[86:89], v[236:239], v[208:211], v[86:89]
	global_load_dwordx4 v[162:165], v[138:139], off offset:128
	v_mfma_f32_16x16x32_bf16 v[82:85], v[236:239], v[212:215], v[82:85]
	v_lshl_add_u64 v[138:139], v[138:139], 0, s[4:5]
	v_mfma_f32_16x16x32_bf16 v[78:81], v[236:239], v[216:219], v[78:81]
	global_load_dwordx4 v[166:169], v[138:139], off offset:0
	v_mfma_f32_16x16x32_bf16 v[74:77], v[236:239], v[220:223], v[74:77]
	v_mfma_f32_16x16x32_bf16 v[70:73], v[236:239], v[224:227], v[70:73]
	global_load_dwordx4 v[170:173], v[138:139], off offset:128
	v_mfma_f32_16x16x32_bf16 v[66:69], v[236:239], v[228:231], v[66:69]
	v_lshl_add_u64 v[138:139], v[138:139], 0, s[4:5]
	v_mfma_f32_16x16x32_bf16 v[62:65], v[240:243], v[200:203], v[62:65]
	global_load_dwordx4 v[176:179], v[138:139], off offset:0
	v_mfma_f32_16x16x32_bf16 v[58:61], v[240:243], v[204:207], v[58:61]
	v_mfma_f32_16x16x32_bf16 v[54:57], v[240:243], v[208:211], v[54:57]
	global_load_dwordx4 v[180:183], v[138:139], off offset:128
	v_mfma_f32_16x16x32_bf16 v[50:53], v[240:243], v[212:215], v[50:53]
	v_lshl_add_u64 v[138:139], v[138:139], 0, s[4:5]
	v_mfma_f32_16x16x32_bf16 v[46:49], v[240:243], v[216:219], v[46:49]
	global_load_dwordx4 v[184:187], v[138:139], off offset:0
	v_mfma_f32_16x16x32_bf16 v[42:45], v[240:243], v[220:223], v[42:45]
	v_mfma_f32_16x16x32_bf16 v[38:41], v[240:243], v[224:227], v[38:41]
	global_load_dwordx4 v[188:191], v[138:139], off offset:128
	v_mfma_f32_16x16x32_bf16 v[34:37], v[240:243], v[228:231], v[34:37]
	v_lshl_add_u64 v[138:139], v[138:139], 0, s[4:5]
	v_mfma_f32_16x16x32_bf16 v[30:33], v[244:247], v[200:203], v[30:33]
	global_load_dwordx4 v[192:195], v[138:139], off offset:0
	v_mfma_f32_16x16x32_bf16 v[26:29], v[244:247], v[204:207], v[26:29]
	v_mfma_f32_16x16x32_bf16 v[22:25], v[244:247], v[208:211], v[22:25]
	global_load_dwordx4 v[196:199], v[138:139], off offset:128
	v_mfma_f32_16x16x32_bf16 v[18:21], v[244:247], v[212:215], v[18:21]
	v_lshl_add_u64 v[138:139], v[138:139], 0, s[4:5]
	v_mfma_f32_16x16x32_bf16 v[14:17], v[244:247], v[216:219], v[14:17]
	v_mfma_f32_16x16x32_bf16 v[10:13], v[244:247], v[220:223], v[10:13]
	v_mfma_f32_16x16x32_bf16 v[6:9], v[244:247], v[224:227], v[6:9]
	v_mfma_f32_16x16x32_bf16 v[2:5], v[244:247], v[228:231], v[2:5]
	s_mov_b32 m0, s44
	global_load_dwordx4 v[200:203], v[138:139], off offset:0
	global_load_dwordx4 v[204:207], v[138:139], off offset:128
	v_lshl_add_u64 v[138:139], v[138:139], 0, s[4:5]
	global_load_dwordx4 v[208:211], v[138:139], off offset:0
	global_load_dwordx4 v[212:215], v[138:139], off offset:128
	v_lshl_add_u64 v[138:139], v[138:139], 0, s[4:5]
	s_nop 7
	v_and_b32_e32 v228, 1, v145
	v_cmp_ne_u32_e32 vcc, 0, v228
	v_mov_b32_e32 v229, 0xfffff040
	v_cndmask_b32_e32 v230, 0, v229, vcc
	v_ashrrev_i32_e32 v231, 31, v230
	v_lshl_add_u64 v[140:141], v[140:141], 0, v[230:231]
	v_add_co_u32_e32 v142, vcc, 0x1000, v140
	s_nop 0
	v_addc_co_u32_e32 v143, vcc, 0, v141, vcc
	v_cmp_ne_u32_e32 vcc, 0, v228
	s_waitcnt vmcnt(15)
	v_permlane16_swap_b32_e32 v146, v148
	v_permlane16_swap_b32_e32 v147, v149
	v_lshlrev_b32_e32 v216, 16, v146
	v_and_b32_e32 v146, 0xffff0000, v146
	v_lshlrev_b32_e32 v217, 16, v147
	v_and_b32_e32 v147, 0xffff0000, v147
	v_fmac_f32_e32 v126, s45, v216
	v_fmac_f32_e32 v127, s45, v146
	v_fmac_f32_e32 v128, s45, v217
	v_fmac_f32_e32 v129, s45, v147
	v_lshlrev_b32_e32 v216, 16, v148
	v_and_b32_e32 v148, 0xffff0000, v148
	v_lshlrev_b32_e32 v217, 16, v149
	v_and_b32_e32 v149, 0xffff0000, v149
	v_fmac_f32_e32 v94, s45, v216
	v_fmac_f32_e32 v95, s45, v148
	v_fmac_f32_e32 v96, s45, v217
	v_fmac_f32_e32 v97, s45, v149
	v_mov_b32_dpp v220, v94 quad_perm:[1,0,3,2] row_mask:0xf bank_mask:0xf
	v_mov_b32_dpp v221, v95 quad_perm:[1,0,3,2] row_mask:0xf bank_mask:0xf
	v_mov_b32_dpp v222, v96 quad_perm:[1,0,3,2] row_mask:0xf bank_mask:0xf
	v_mov_b32_dpp v223, v97 quad_perm:[1,0,3,2] row_mask:0xf bank_mask:0xf
	v_mov_b32_dpp v224, v126 quad_perm:[1,0,3,2] row_mask:0xf bank_mask:0xf
	v_mov_b32_dpp v225, v127 quad_perm:[1,0,3,2] row_mask:0xf bank_mask:0xf
	v_mov_b32_dpp v226, v128 quad_perm:[1,0,3,2] row_mask:0xf bank_mask:0xf
	v_mov_b32_dpp v227, v129 quad_perm:[1,0,3,2] row_mask:0xf bank_mask:0xf
	v_cndmask_b32_e32 v94, v224, v94, vcc
	v_cndmask_b32_e32 v95, v225, v95, vcc
	v_cndmask_b32_e32 v96, v226, v96, vcc
	v_cndmask_b32_e32 v97, v227, v97, vcc
	v_cndmask_b32_e32 v126, v126, v220, vcc
	v_cndmask_b32_e32 v127, v127, v221, vcc
	v_cndmask_b32_e32 v128, v128, v222, vcc
	v_cndmask_b32_e32 v129, v129, v223, vcc
	global_store_dwordx4 v[140:141], v[126:129], off
	global_store_dwordx4 v[142:143], v[94:97], off
	s_waitcnt vmcnt(16)
; DEVI float blo(unsigned u) { return __uint_as_float(u << 16); }
; DEVI float bhi(unsigned u) { return __uint_as_float(u & 0xffff0000u); }
;     ...
;         if (EPI == EPI_RESID || EPI == EPI_RESID_ATOMIC) {
;           f32x4 x = a;
;           if (EPI == EPI_RESID || kpart == 0) {
;             const u32x2 xr = *(const u32x2*)((const u16*)(p.ws + WS_XB) + (size_t)row * 1024 + col);
;             x[0] += ALPHA * blo(xr[0]); x[1] += ALPHA * bhi(xr[0]); x[2] += ALPHA * blo(xr[1]); x[3] += ALPHA * bhi(xr[1]);
;           }
;           if (EPI == EPI_RESID) *(f32x4*)((float*)(p.ws + WS_XF) + (size_t)row * 1024 + col) = x;
;           else *(f32x4*)((float*)(p.ws + WS_SLAB) + ((size_t)kpart * 512 + (row - T_P)) * 1024 + col) = x;
	v_permlane16_swap_b32_e32 v152, v154
	v_permlane16_swap_b32_e32 v153, v155
	v_lshlrev_b32_e32 v216, 16, v152
	v_and_b32_e32 v152, 0xffff0000, v152
	v_lshlrev_b32_e32 v217, 16, v153
	v_and_b32_e32 v153, 0xffff0000, v153
	v_fmac_f32_e32 v62, s45, v216
	v_fmac_f32_e32 v63, s45, v152
	v_fmac_f32_e32 v64, s45, v217
	v_fmac_f32_e32 v65, s45, v153
	v_lshlrev_b32_e32 v216, 16, v154
	v_and_b32_e32 v154, 0xffff0000, v154
	v_lshlrev_b32_e32 v217, 16, v155
	v_and_b32_e32 v155, 0xffff0000, v155
	v_fmac_f32_e32 v30, s45, v216
	v_fmac_f32_e32 v31, s45, v154
	v_fmac_f32_e32 v32, s45, v217
	v_fmac_f32_e32 v33, s45, v155
	v_mov_b32_dpp v220, v30 quad_perm:[1,0,3,2] row_mask:0xf bank_mask:0xf
	v_mov_b32_dpp v221, v31 quad_perm:[1,0,3,2] row_mask:0xf bank_mask:0xf
	v_mov_b32_dpp v222, v32 quad_perm:[1,0,3,2] row_mask:0xf bank_mask:0xf
	v_mov_b32_dpp v223, v33 quad_perm:[1,0,3,2] row_mask:0xf bank_mask:0xf
	v_mov_b32_dpp v224, v62 quad_perm:[1,0,3,2] row_mask:0xf bank_mask:0xf
	v_mov_b32_dpp v225, v63 quad_perm:[1,0,3,2] row_mask:0xf bank_mask:0xf
	v_mov_b32_dpp v226, v64 quad_perm:[1,0,3,2] row_mask:0xf bank_mask:0xf
	v_mov_b32_dpp v227, v65 quad_perm:[1,0,3,2] row_mask:0xf bank_mask:0xf
	v_cndmask_b32_e32 v30, v224, v30, vcc
	v_cndmask_b32_e32 v31, v225, v31, vcc
	v_cndmask_b32_e32 v32, v226, v32, vcc
	v_cndmask_b32_e32 v33, v227, v33, vcc
	v_cndmask_b32_e32 v62, v62, v220, vcc
	v_cndmask_b32_e32 v63, v63, v221, vcc
	v_cndmask_b32_e32 v64, v64, v222, vcc
	v_cndmask_b32_e32 v65, v65, v223, vcc
	global_store_dwordx4 v[140:141], v[62:65], off offset:128
	global_store_dwordx4 v[142:143], v[30:33], off offset:128
	v_lshl_add_u64 v[140:141], v[140:141], 0, s[10:11]
	v_lshl_add_u64 v[142:143], v[142:143], 0, s[10:11]
	s_waitcnt vmcnt(17)
	v_permlane16_swap_b32_e32 v156, v158
	v_permlane16_swap_b32_e32 v157, v159
	v_lshlrev_b32_e32 v216, 16, v156
	v_and_b32_e32 v156, 0xffff0000, v156
	v_lshlrev_b32_e32 v217, 16, v157
	v_and_b32_e32 v157, 0xffff0000, v157
	v_fmac_f32_e32 v122, s45, v216
	v_fmac_f32_e32 v123, s45, v156
	v_fmac_f32_e32 v124, s45, v217
	v_fmac_f32_e32 v125, s45, v157
	v_lshlrev_b32_e32 v216, 16, v158
	v_and_b32_e32 v158, 0xffff0000, v158
	v_lshlrev_b32_e32 v217, 16, v159
	v_and_b32_e32 v159, 0xffff0000, v159
	v_fmac_f32_e32 v90, s45, v216
	v_fmac_f32_e32 v91, s45, v158
	v_fmac_f32_e32 v92, s45, v217
	v_fmac_f32_e32 v93, s45, v159
	v_mov_b32_dpp v220, v90 quad_perm:[1,0,3,2] row_mask:0xf bank_mask:0xf
	v_mov_b32_dpp v221, v91 quad_perm:[1,0,3,2] row_mask:0xf bank_mask:0xf
	v_mov_b32_dpp v222, v92 quad_perm:[1,0,3,2] row_mask:0xf bank_mask:0xf
	v_mov_b32_dpp v223, v93 quad_perm:[1,0,3,2] row_mask:0xf bank_mask:0xf
	v_mov_b32_dpp v224, v122 quad_perm:[1,0,3,2] row_mask:0xf bank_mask:0xf
	v_mov_b32_dpp v225, v123 quad_perm:[1,0,3,2] row_mask:0xf bank_mask:0xf
	v_mov_b32_dpp v226, v124 quad_perm:[1,0,3,2] row_mask:0xf bank_mask:0xf
	v_mov_b32_dpp v227, v125 quad_perm:[1,0,3,2] row_mask:0xf bank_mask:0xf
	v_cndmask_b32_e32 v90, v224, v90, vcc
	v_cndmask_b32_e32 v91, v225, v91, vcc
	v_cndmask_b32_e32 v92, v226, v92, vcc
	v_cndmask_b32_e32 v93, v227, v93, vcc
	v_cndmask_b32_e32 v122, v122, v220, vcc
	v_cndmask_b32_e32 v123, v123, v221, vcc
	v_cndmask_b32_e32 v124, v124, v222, vcc
	v_cndmask_b32_e32 v125, v125, v223, vcc
	global_store_dwordx4 v[140:141], v[122:125], off
	global_store_dwordx4 v[142:143], v[90:93], off
	s_waitcnt vmcnt(18)
	v_permlane16_swap_b32_e32 v162, v164
	v_permlane16_swap_b32_e32 v163, v165
	v_lshlrev_b32_e32 v216, 16, v162
	v_and_b32_e32 v162, 0xffff0000, v162
	v_lshlrev_b32_e32 v217, 16, v163
	v_and_b32_e32 v163, 0xffff0000, v163
	v_fmac_f32_e32 v58, s45, v216
	v_fmac_f32_e32 v59, s45, v162
	v_fmac_f32_e32 v60, s45, v217
	v_fmac_f32_e32 v61, s45, v163
	v_lshlrev_b32_e32 v216, 16, v164
	v_and_b32_e32 v164, 0xffff0000, v164
	v_lshlrev_b32_e32 v217, 16, v165
	v_and_b32_e32 v165, 0xffff0000, v165
	v_fmac_f32_e32 v26, s45, v216
	v_fmac_f32_e32 v27, s45, v164
	v_fmac_f32_e32 v28, s45, v217
	v_fmac_f32_e32 v29, s45, v165
	v_mov_b32_dpp v220, v26 quad_perm:[1,0,3,2] row_mask:0xf bank_mask:0xf
	v_mov_b32_dpp v221, v27 quad_perm:[1,0,3,2] row_mask:0xf bank_mask:0xf
	v_mov_b32_dpp v222, v28 quad_perm:[1,0,3,2] row_mask:0xf bank_mask:0xf
	v_mov_b32_dpp v223, v29 quad_perm:[1,0,3,2] row_mask:0xf bank_mask:0xf
	v_mov_b32_dpp v224, v58 quad_perm:[1,0,3,2] row_mask:0xf bank_mask:0xf
	v_mov_b32_dpp v225, v59 quad_perm:[1,0,3,2] row_mask:0xf bank_mask:0xf
	v_mov_b32_dpp v226, v60 quad_perm:[1,0,3,2] row_mask:0xf bank_mask:0xf
	v_mov_b32_dpp v227, v61 quad_perm:[1,0,3,2] row_mask:0xf bank_mask:0xf
	v_cndmask_b32_e32 v26, v224, v26, vcc
	v_cndmask_b32_e32 v27, v225, v27, vcc
	v_cndmask_b32_e32 v28, v226, v28, vcc
	v_cndmask_b32_e32 v29, v227, v29, vcc
	v_cndmask_b32_e32 v58, v58, v220, vcc
	v_cndmask_b32_e32 v59, v59, v221, vcc
	v_cndmask_b32_e32 v60, v60, v222, vcc
	v_cndmask_b32_e32 v61, v61, v223, vcc
	global_store_dwordx4 v[140:141], v[58:61], off offset:128
	global_store_dwordx4 v[142:143], v[26:29], off offset:128
	v_lshl_add_u64 v[140:141], v[140:141], 0, s[10:11]
	v_lshl_add_u64 v[142:143], v[142:143], 0, s[10:11]
	s_waitcnt vmcnt(19)
; DEVI float blo(unsigned u) { return __uint_as_float(u << 16); }
; DEVI float bhi(unsigned u) { return __uint_as_float(u & 0xffff0000u); }
;     ...
;         if (EPI == EPI_RESID || EPI == EPI_RESID_ATOMIC) {
;           f32x4 x = a;
;           if (EPI == EPI_RESID || kpart == 0) {
;             const u32x2 xr = *(const u32x2*)((const u16*)(p.ws + WS_XB) + (size_t)row * 1024 + col);
;             x[0] += ALPHA * blo(xr[0]); x[1] += ALPHA * bhi(xr[0]); x[2] += ALPHA * blo(xr[1]); x[3] += ALPHA * bhi(xr[1]);
;           }
;           if (EPI == EPI_RESID) *(f32x4*)((float*)(p.ws + WS_XF) + (size_t)row * 1024 + col) = x;
;           else *(f32x4*)((float*)(p.ws + WS_SLAB) + ((size_t)kpart * 512 + (row - T_P)) * 1024 + col) = x;
	v_permlane16_swap_b32_e32 v166, v168
	v_permlane16_swap_b32_e32 v167, v169
	v_lshlrev_b32_e32 v216, 16, v166
	v_and_b32_e32 v166, 0xffff0000, v166
	v_lshlrev_b32_e32 v217, 16, v167
	v_and_b32_e32 v167, 0xffff0000, v167
	v_fmac_f32_e32 v118, s45, v216
	v_fmac_f32_e32 v119, s45, v166
	v_fmac_f32_e32 v120, s45, v217
	v_fmac_f32_e32 v121, s45, v167
	v_lshlrev_b32_e32 v216, 16, v168
	v_and_b32_e32 v168, 0xffff0000, v168
	v_lshlrev_b32_e32 v217, 16, v169
	v_and_b32_e32 v169, 0xffff0000, v169
	v_fmac_f32_e32 v86, s45, v216
	v_fmac_f32_e32 v87, s45, v168
	v_fmac_f32_e32 v88, s45, v217
	v_fmac_f32_e32 v89, s45, v169
	v_mov_b32_dpp v220, v86 quad_perm:[1,0,3,2] row_mask:0xf bank_mask:0xf
	v_mov_b32_dpp v221, v87 quad_perm:[1,0,3,2] row_mask:0xf bank_mask:0xf
	v_mov_b32_dpp v222, v88 quad_perm:[1,0,3,2] row_mask:0xf bank_mask:0xf
	v_mov_b32_dpp v223, v89 quad_perm:[1,0,3,2] row_mask:0xf bank_mask:0xf
	v_mov_b32_dpp v224, v118 quad_perm:[1,0,3,2] row_mask:0xf bank_mask:0xf
	v_mov_b32_dpp v225, v119 quad_perm:[1,0,3,2] row_mask:0xf bank_mask:0xf
	v_mov_b32_dpp v226, v120 quad_perm:[1,0,3,2] row_mask:0xf bank_mask:0xf
	v_mov_b32_dpp v227, v121 quad_perm:[1,0,3,2] row_mask:0xf bank_mask:0xf
	v_cndmask_b32_e32 v86, v224, v86, vcc
	v_cndmask_b32_e32 v87, v225, v87, vcc
	v_cndmask_b32_e32 v88, v226, v88, vcc
	v_cndmask_b32_e32 v89, v227, v89, vcc
	v_cndmask_b32_e32 v118, v118, v220, vcc
	v_cndmask_b32_e32 v119, v119, v221, vcc
	v_cndmask_b32_e32 v120, v120, v222, vcc
	v_cndmask_b32_e32 v121, v121, v223, vcc
	global_store_dwordx4 v[140:141], v[118:121], off
	global_store_dwordx4 v[142:143], v[86:89], off
	s_waitcnt vmcnt(20)
	v_permlane16_swap_b32_e32 v170, v172
	v_permlane16_swap_b32_e32 v171, v173
	v_lshlrev_b32_e32 v216, 16, v170
	v_and_b32_e32 v170, 0xffff0000, v170
	v_lshlrev_b32_e32 v217, 16, v171
	v_and_b32_e32 v171, 0xffff0000, v171
	v_fmac_f32_e32 v54, s45, v216
	v_fmac_f32_e32 v55, s45, v170
	v_fmac_f32_e32 v56, s45, v217
	v_fmac_f32_e32 v57, s45, v171
	v_lshlrev_b32_e32 v216, 16, v172
	v_and_b32_e32 v172, 0xffff0000, v172
	v_lshlrev_b32_e32 v217, 16, v173
	v_and_b32_e32 v173, 0xffff0000, v173
	v_fmac_f32_e32 v22, s45, v216
	v_fmac_f32_e32 v23, s45, v172
	v_fmac_f32_e32 v24, s45, v217
	v_fmac_f32_e32 v25, s45, v173
	v_mov_b32_dpp v220, v22 quad_perm:[1,0,3,2] row_mask:0xf bank_mask:0xf
	v_mov_b32_dpp v221, v23 quad_perm:[1,0,3,2] row_mask:0xf bank_mask:0xf
	v_mov_b32_dpp v222, v24 quad_perm:[1,0,3,2] row_mask:0xf bank_mask:0xf
	v_mov_b32_dpp v223, v25 quad_perm:[1,0,3,2] row_mask:0xf bank_mask:0xf
	v_mov_b32_dpp v224, v54 quad_perm:[1,0,3,2] row_mask:0xf bank_mask:0xf
	v_mov_b32_dpp v225, v55 quad_perm:[1,0,3,2] row_mask:0xf bank_mask:0xf
	v_mov_b32_dpp v226, v56 quad_perm:[1,0,3,2] row_mask:0xf bank_mask:0xf
	v_mov_b32_dpp v227, v57 quad_perm:[1,0,3,2] row_mask:0xf bank_mask:0xf
	v_cndmask_b32_e32 v22, v224, v22, vcc
	v_cndmask_b32_e32 v23, v225, v23, vcc
	v_cndmask_b32_e32 v24, v226, v24, vcc
	v_cndmask_b32_e32 v25, v227, v25, vcc
	v_cndmask_b32_e32 v54, v54, v220, vcc
	v_cndmask_b32_e32 v55, v55, v221, vcc
	v_cndmask_b32_e32 v56, v56, v222, vcc
	v_cndmask_b32_e32 v57, v57, v223, vcc
	global_store_dwordx4 v[140:141], v[54:57], off offset:128
	global_store_dwordx4 v[142:143], v[22:25], off offset:128
	v_lshl_add_u64 v[140:141], v[140:141], 0, s[10:11]
	v_lshl_add_u64 v[142:143], v[142:143], 0, s[10:11]
	s_waitcnt vmcnt(21)
	v_permlane16_swap_b32_e32 v176, v178
	v_permlane16_swap_b32_e32 v177, v179
	v_lshlrev_b32_e32 v216, 16, v176
	v_and_b32_e32 v176, 0xffff0000, v176
	v_lshlrev_b32_e32 v217, 16, v177
	v_and_b32_e32 v177, 0xffff0000, v177
	v_fmac_f32_e32 v114, s45, v216
	v_fmac_f32_e32 v115, s45, v176
	v_fmac_f32_e32 v116, s45, v217
	v_fmac_f32_e32 v117, s45, v177
	v_lshlrev_b32_e32 v216, 16, v178
	v_and_b32_e32 v178, 0xffff0000, v178
	v_lshlrev_b32_e32 v217, 16, v179
	v_and_b32_e32 v179, 0xffff0000, v179
	v_fmac_f32_e32 v82, s45, v216
	v_fmac_f32_e32 v83, s45, v178
	v_fmac_f32_e32 v84, s45, v217
	v_fmac_f32_e32 v85, s45, v179
	v_mov_b32_dpp v220, v82 quad_perm:[1,0,3,2] row_mask:0xf bank_mask:0xf
	v_mov_b32_dpp v221, v83 quad_perm:[1,0,3,2] row_mask:0xf bank_mask:0xf
	v_mov_b32_dpp v222, v84 quad_perm:[1,0,3,2] row_mask:0xf bank_mask:0xf
	v_mov_b32_dpp v223, v85 quad_perm:[1,0,3,2] row_mask:0xf bank_mask:0xf
	v_mov_b32_dpp v224, v114 quad_perm:[1,0,3,2] row_mask:0xf bank_mask:0xf
	v_mov_b32_dpp v225, v115 quad_perm:[1,0,3,2] row_mask:0xf bank_mask:0xf
	v_mov_b32_dpp v226, v116 quad_perm:[1,0,3,2] row_mask:0xf bank_mask:0xf
	v_mov_b32_dpp v227, v117 quad_perm:[1,0,3,2] row_mask:0xf bank_mask:0xf
	v_cndmask_b32_e32 v82, v224, v82, vcc
	v_cndmask_b32_e32 v83, v225, v83, vcc
	v_cndmask_b32_e32 v84, v226, v84, vcc
	v_cndmask_b32_e32 v85, v227, v85, vcc
	v_cndmask_b32_e32 v114, v114, v220, vcc
	v_cndmask_b32_e32 v115, v115, v221, vcc
	v_cndmask_b32_e32 v116, v116, v222, vcc
	v_cndmask_b32_e32 v117, v117, v223, vcc
	global_store_dwordx4 v[140:141], v[114:117], off
	global_store_dwordx4 v[142:143], v[82:85], off
	s_waitcnt vmcnt(22)
; DEVI float blo(unsigned u) { return __uint_as_float(u << 16); }
; DEVI float bhi(unsigned u) { return __uint_as_float(u & 0xffff0000u); }
;     ...
;         if (EPI == EPI_RESID || EPI == EPI_RESID_ATOMIC) {
;           f32x4 x = a;
;           if (EPI == EPI_RESID || kpart == 0) {
;             const u32x2 xr = *(const u32x2*)((const u16*)(p.ws + WS_XB) + (size_t)row * 1024 + col);
;             x[0] += ALPHA * blo(xr[0]); x[1] += ALPHA * bhi(xr[0]); x[2] += ALPHA * blo(xr[1]); x[3] += ALPHA * bhi(xr[1]);
;           }
;           if (EPI == EPI_RESID) *(f32x4*)((float*)(p.ws + WS_XF) + (size_t)row * 1024 + col) = x;
;           else *(f32x4*)((float*)(p.ws + WS_SLAB) + ((size_t)kpart * 512 + (row - T_P)) * 1024 + col) = x;
	v_permlane16_swap_b32_e32 v180, v182
	v_permlane16_swap_b32_e32 v181, v183
	v_lshlrev_b32_e32 v216, 16, v180
	v_and_b32_e32 v180, 0xffff0000, v180
	v_lshlrev_b32_e32 v217, 16, v181
	v_and_b32_e32 v181, 0xffff0000, v181
	v_fmac_f32_e32 v50, s45, v216
	v_fmac_f32_e32 v51, s45, v180
	v_fmac_f32_e32 v52, s45, v217
	v_fmac_f32_e32 v53, s45, v181
	v_lshlrev_b32_e32 v216, 16, v182
	v_and_b32_e32 v182, 0xffff0000, v182
	v_lshlrev_b32_e32 v217, 16, v183
	v_and_b32_e32 v183, 0xffff0000, v183
	v_fmac_f32_e32 v18, s45, v216
	v_fmac_f32_e32 v19, s45, v182
	v_fmac_f32_e32 v20, s45, v217
	v_fmac_f32_e32 v21, s45, v183
	v_mov_b32_dpp v220, v18 quad_perm:[1,0,3,2] row_mask:0xf bank_mask:0xf
	v_mov_b32_dpp v221, v19 quad_perm:[1,0,3,2] row_mask:0xf bank_mask:0xf
	v_mov_b32_dpp v222, v20 quad_perm:[1,0,3,2] row_mask:0xf bank_mask:0xf
	v_mov_b32_dpp v223, v21 quad_perm:[1,0,3,2] row_mask:0xf bank_mask:0xf
	v_mov_b32_dpp v224, v50 quad_perm:[1,0,3,2] row_mask:0xf bank_mask:0xf
	v_mov_b32_dpp v225, v51 quad_perm:[1,0,3,2] row_mask:0xf bank_mask:0xf
	v_mov_b32_dpp v226, v52 quad_perm:[1,0,3,2] row_mask:0xf bank_mask:0xf
	v_mov_b32_dpp v227, v53 quad_perm:[1,0,3,2] row_mask:0xf bank_mask:0xf
	v_cndmask_b32_e32 v18, v224, v18, vcc
	v_cndmask_b32_e32 v19, v225, v19, vcc
	v_cndmask_b32_e32 v20, v226, v20, vcc
	v_cndmask_b32_e32 v21, v227, v21, vcc
	v_cndmask_b32_e32 v50, v50, v220, vcc
	v_cndmask_b32_e32 v51, v51, v221, vcc
	v_cndmask_b32_e32 v52, v52, v222, vcc
	v_cndmask_b32_e32 v53, v53, v223, vcc
	global_store_dwordx4 v[140:141], v[50:53], off offset:128
	global_store_dwordx4 v[142:143], v[18:21], off offset:128
	v_lshl_add_u64 v[140:141], v[140:141], 0, s[10:11]
	v_lshl_add_u64 v[142:143], v[142:143], 0, s[10:11]
	s_waitcnt vmcnt(23)
	v_permlane16_swap_b32_e32 v184, v186
	v_permlane16_swap_b32_e32 v185, v187
	v_lshlrev_b32_e32 v216, 16, v184
	v_and_b32_e32 v184, 0xffff0000, v184
	v_lshlrev_b32_e32 v217, 16, v185
	v_and_b32_e32 v185, 0xffff0000, v185
	v_fmac_f32_e32 v110, s45, v216
	v_fmac_f32_e32 v111, s45, v184
	v_fmac_f32_e32 v112, s45, v217
	v_fmac_f32_e32 v113, s45, v185
	v_lshlrev_b32_e32 v216, 16, v186
	v_and_b32_e32 v186, 0xffff0000, v186
	v_lshlrev_b32_e32 v217, 16, v187
	v_and_b32_e32 v187, 0xffff0000, v187
	v_fmac_f32_e32 v78, s45, v216
	v_fmac_f32_e32 v79, s45, v186
	v_fmac_f32_e32 v80, s45, v217
	v_fmac_f32_e32 v81, s45, v187
	v_mov_b32_dpp v220, v78 quad_perm:[1,0,3,2] row_mask:0xf bank_mask:0xf
	v_mov_b32_dpp v221, v79 quad_perm:[1,0,3,2] row_mask:0xf bank_mask:0xf
	v_mov_b32_dpp v222, v80 quad_perm:[1,0,3,2] row_mask:0xf bank_mask:0xf
	v_mov_b32_dpp v223, v81 quad_perm:[1,0,3,2] row_mask:0xf bank_mask:0xf
	v_mov_b32_dpp v224, v110 quad_perm:[1,0,3,2] row_mask:0xf bank_mask:0xf
	v_mov_b32_dpp v225, v111 quad_perm:[1,0,3,2] row_mask:0xf bank_mask:0xf
	v_mov_b32_dpp v226, v112 quad_perm:[1,0,3,2] row_mask:0xf bank_mask:0xf
	v_mov_b32_dpp v227, v113 quad_perm:[1,0,3,2] row_mask:0xf bank_mask:0xf
	v_cndmask_b32_e32 v78, v224, v78, vcc
	v_cndmask_b32_e32 v79, v225, v79, vcc
	v_cndmask_b32_e32 v80, v226, v80, vcc
	v_cndmask_b32_e32 v81, v227, v81, vcc
	v_cndmask_b32_e32 v110, v110, v220, vcc
	v_cndmask_b32_e32 v111, v111, v221, vcc
	v_cndmask_b32_e32 v112, v112, v222, vcc
	v_cndmask_b32_e32 v113, v113, v223, vcc
	global_store_dwordx4 v[140:141], v[110:113], off
	global_store_dwordx4 v[142:143], v[78:81], off
	s_waitcnt vmcnt(24)
	v_permlane16_swap_b32_e32 v188, v190
	v_permlane16_swap_b32_e32 v189, v191
	v_lshlrev_b32_e32 v216, 16, v188
	v_and_b32_e32 v188, 0xffff0000, v188
	v_lshlrev_b32_e32 v217, 16, v189
	v_and_b32_e32 v189, 0xffff0000, v189
	v_fmac_f32_e32 v46, s45, v216
	v_fmac_f32_e32 v47, s45, v188
	v_fmac_f32_e32 v48, s45, v217
	v_fmac_f32_e32 v49, s45, v189
	v_lshlrev_b32_e32 v216, 16, v190
	v_and_b32_e32 v190, 0xffff0000, v190
	v_lshlrev_b32_e32 v217, 16, v191
	v_and_b32_e32 v191, 0xffff0000, v191
	v_fmac_f32_e32 v14, s45, v216
	v_fmac_f32_e32 v15, s45, v190
	v_fmac_f32_e32 v16, s45, v217
	v_fmac_f32_e32 v17, s45, v191
	v_mov_b32_dpp v220, v14 quad_perm:[1,0,3,2] row_mask:0xf bank_mask:0xf
	v_mov_b32_dpp v221, v15 quad_perm:[1,0,3,2] row_mask:0xf bank_mask:0xf
	v_mov_b32_dpp v222, v16 quad_perm:[1,0,3,2] row_mask:0xf bank_mask:0xf
	v_mov_b32_dpp v223, v17 quad_perm:[1,0,3,2] row_mask:0xf bank_mask:0xf
	v_mov_b32_dpp v224, v46 quad_perm:[1,0,3,2] row_mask:0xf bank_mask:0xf
	v_mov_b32_dpp v225, v47 quad_perm:[1,0,3,2] row_mask:0xf bank_mask:0xf
	v_mov_b32_dpp v226, v48 quad_perm:[1,0,3,2] row_mask:0xf bank_mask:0xf
	v_mov_b32_dpp v227, v49 quad_perm:[1,0,3,2] row_mask:0xf bank_mask:0xf
	v_cndmask_b32_e32 v14, v224, v14, vcc
	v_cndmask_b32_e32 v15, v225, v15, vcc
	v_cndmask_b32_e32 v16, v226, v16, vcc
	v_cndmask_b32_e32 v17, v227, v17, vcc
	v_cndmask_b32_e32 v46, v46, v220, vcc
	v_cndmask_b32_e32 v47, v47, v221, vcc
	v_cndmask_b32_e32 v48, v48, v222, vcc
	v_cndmask_b32_e32 v49, v49, v223, vcc
	global_store_dwordx4 v[140:141], v[46:49], off offset:128
	global_store_dwordx4 v[142:143], v[14:17], off offset:128
	v_lshl_add_u64 v[140:141], v[140:141], 0, s[10:11]
	v_lshl_add_u64 v[142:143], v[142:143], 0, s[10:11]
	s_waitcnt vmcnt(25)
; DEVI float blo(unsigned u) { return __uint_as_float(u << 16); }
; DEVI float bhi(unsigned u) { return __uint_as_float(u & 0xffff0000u); }
;     ...
;         if (EPI == EPI_RESID || EPI == EPI_RESID_ATOMIC) {
;           f32x4 x = a;
;           if (EPI == EPI_RESID || kpart == 0) {
;             const u32x2 xr = *(const u32x2*)((const u16*)(p.ws + WS_XB) + (size_t)row * 1024 + col);
;             x[0] += ALPHA * blo(xr[0]); x[1] += ALPHA * bhi(xr[0]); x[2] += ALPHA * blo(xr[1]); x[3] += ALPHA * bhi(xr[1]);
;           }
;           if (EPI == EPI_RESID) *(f32x4*)((float*)(p.ws + WS_XF) + (size_t)row * 1024 + col) = x;
;           else *(f32x4*)((float*)(p.ws + WS_SLAB) + ((size_t)kpart * 512 + (row - T_P)) * 1024 + col) = x;
	v_permlane16_swap_b32_e32 v192, v194
	v_permlane16_swap_b32_e32 v193, v195
	v_lshlrev_b32_e32 v216, 16, v192
	v_and_b32_e32 v192, 0xffff0000, v192
	v_lshlrev_b32_e32 v217, 16, v193
	v_and_b32_e32 v193, 0xffff0000, v193
	v_fmac_f32_e32 v106, s45, v216
	v_fmac_f32_e32 v107, s45, v192
	v_fmac_f32_e32 v108, s45, v217
	v_fmac_f32_e32 v109, s45, v193
	v_lshlrev_b32_e32 v216, 16, v194
	v_and_b32_e32 v194, 0xffff0000, v194
	v_lshlrev_b32_e32 v217, 16, v195
	v_and_b32_e32 v195, 0xffff0000, v195
	v_fmac_f32_e32 v74, s45, v216
	v_fmac_f32_e32 v75, s45, v194
	v_fmac_f32_e32 v76, s45, v217
	v_fmac_f32_e32 v77, s45, v195
	v_mov_b32_dpp v220, v74 quad_perm:[1,0,3,2] row_mask:0xf bank_mask:0xf
	v_mov_b32_dpp v221, v75 quad_perm:[1,0,3,2] row_mask:0xf bank_mask:0xf
	v_mov_b32_dpp v222, v76 quad_perm:[1,0,3,2] row_mask:0xf bank_mask:0xf
	v_mov_b32_dpp v223, v77 quad_perm:[1,0,3,2] row_mask:0xf bank_mask:0xf
	v_mov_b32_dpp v224, v106 quad_perm:[1,0,3,2] row_mask:0xf bank_mask:0xf
	v_mov_b32_dpp v225, v107 quad_perm:[1,0,3,2] row_mask:0xf bank_mask:0xf
	v_mov_b32_dpp v226, v108 quad_perm:[1,0,3,2] row_mask:0xf bank_mask:0xf
	v_mov_b32_dpp v227, v109 quad_perm:[1,0,3,2] row_mask:0xf bank_mask:0xf
	v_cndmask_b32_e32 v74, v224, v74, vcc
	v_cndmask_b32_e32 v75, v225, v75, vcc
	v_cndmask_b32_e32 v76, v226, v76, vcc
	v_cndmask_b32_e32 v77, v227, v77, vcc
	v_cndmask_b32_e32 v106, v106, v220, vcc
	v_cndmask_b32_e32 v107, v107, v221, vcc
	v_cndmask_b32_e32 v108, v108, v222, vcc
	v_cndmask_b32_e32 v109, v109, v223, vcc
	global_store_dwordx4 v[140:141], v[106:109], off
	global_store_dwordx4 v[142:143], v[74:77], off
	s_waitcnt vmcnt(26)
	v_permlane16_swap_b32_e32 v196, v198
	v_permlane16_swap_b32_e32 v197, v199
	v_lshlrev_b32_e32 v216, 16, v196
	v_and_b32_e32 v196, 0xffff0000, v196
	v_lshlrev_b32_e32 v217, 16, v197
	v_and_b32_e32 v197, 0xffff0000, v197
	v_fmac_f32_e32 v42, s45, v216
	v_fmac_f32_e32 v43, s45, v196
	v_fmac_f32_e32 v44, s45, v217
	v_fmac_f32_e32 v45, s45, v197
	v_lshlrev_b32_e32 v216, 16, v198
	v_and_b32_e32 v198, 0xffff0000, v198
	v_lshlrev_b32_e32 v217, 16, v199
	v_and_b32_e32 v199, 0xffff0000, v199
	v_fmac_f32_e32 v10, s45, v216
	v_fmac_f32_e32 v11, s45, v198
	v_fmac_f32_e32 v12, s45, v217
	v_fmac_f32_e32 v13, s45, v199
	v_mov_b32_dpp v220, v10 quad_perm:[1,0,3,2] row_mask:0xf bank_mask:0xf
	v_mov_b32_dpp v221, v11 quad_perm:[1,0,3,2] row_mask:0xf bank_mask:0xf
	v_mov_b32_dpp v222, v12 quad_perm:[1,0,3,2] row_mask:0xf bank_mask:0xf
	v_mov_b32_dpp v223, v13 quad_perm:[1,0,3,2] row_mask:0xf bank_mask:0xf
	v_mov_b32_dpp v224, v42 quad_perm:[1,0,3,2] row_mask:0xf bank_mask:0xf
	v_mov_b32_dpp v225, v43 quad_perm:[1,0,3,2] row_mask:0xf bank_mask:0xf
	v_mov_b32_dpp v226, v44 quad_perm:[1,0,3,2] row_mask:0xf bank_mask:0xf
	v_mov_b32_dpp v227, v45 quad_perm:[1,0,3,2] row_mask:0xf bank_mask:0xf
	v_cndmask_b32_e32 v10, v224, v10, vcc
	v_cndmask_b32_e32 v11, v225, v11, vcc
	v_cndmask_b32_e32 v12, v226, v12, vcc
	v_cndmask_b32_e32 v13, v227, v13, vcc
	v_cndmask_b32_e32 v42, v42, v220, vcc
	v_cndmask_b32_e32 v43, v43, v221, vcc
	v_cndmask_b32_e32 v44, v44, v222, vcc
	v_cndmask_b32_e32 v45, v45, v223, vcc
	global_store_dwordx4 v[140:141], v[42:45], off offset:128
	global_store_dwordx4 v[142:143], v[10:13], off offset:128
	v_lshl_add_u64 v[140:141], v[140:141], 0, s[10:11]
	v_lshl_add_u64 v[142:143], v[142:143], 0, s[10:11]
	s_waitcnt vmcnt(27)
	v_permlane16_swap_b32_e32 v200, v202
	v_permlane16_swap_b32_e32 v201, v203
	v_lshlrev_b32_e32 v216, 16, v200
	v_and_b32_e32 v200, 0xffff0000, v200
	v_lshlrev_b32_e32 v217, 16, v201
	v_and_b32_e32 v201, 0xffff0000, v201
	v_fmac_f32_e32 v102, s45, v216
	v_fmac_f32_e32 v103, s45, v200
	v_fmac_f32_e32 v104, s45, v217
	v_fmac_f32_e32 v105, s45, v201
	v_lshlrev_b32_e32 v216, 16, v202
	v_and_b32_e32 v202, 0xffff0000, v202
	v_lshlrev_b32_e32 v217, 16, v203
	v_and_b32_e32 v203, 0xffff0000, v203
	v_fmac_f32_e32 v70, s45, v216
	v_fmac_f32_e32 v71, s45, v202
	v_fmac_f32_e32 v72, s45, v217
	v_fmac_f32_e32 v73, s45, v203
	v_mov_b32_dpp v220, v70 quad_perm:[1,0,3,2] row_mask:0xf bank_mask:0xf
	v_mov_b32_dpp v221, v71 quad_perm:[1,0,3,2] row_mask:0xf bank_mask:0xf
	v_mov_b32_dpp v222, v72 quad_perm:[1,0,3,2] row_mask:0xf bank_mask:0xf
	v_mov_b32_dpp v223, v73 quad_perm:[1,0,3,2] row_mask:0xf bank_mask:0xf
	v_mov_b32_dpp v224, v102 quad_perm:[1,0,3,2] row_mask:0xf bank_mask:0xf
	v_mov_b32_dpp v225, v103 quad_perm:[1,0,3,2] row_mask:0xf bank_mask:0xf
	v_mov_b32_dpp v226, v104 quad_perm:[1,0,3,2] row_mask:0xf bank_mask:0xf
	v_mov_b32_dpp v227, v105 quad_perm:[1,0,3,2] row_mask:0xf bank_mask:0xf
	v_cndmask_b32_e32 v70, v224, v70, vcc
	v_cndmask_b32_e32 v71, v225, v71, vcc
	v_cndmask_b32_e32 v72, v226, v72, vcc
	v_cndmask_b32_e32 v73, v227, v73, vcc
	v_cndmask_b32_e32 v102, v102, v220, vcc
	v_cndmask_b32_e32 v103, v103, v221, vcc
	v_cndmask_b32_e32 v104, v104, v222, vcc
	v_cndmask_b32_e32 v105, v105, v223, vcc
	global_store_dwordx4 v[140:141], v[102:105], off
	global_store_dwordx4 v[142:143], v[70:73], off
	s_waitcnt vmcnt(28)
; DEVI float blo(unsigned u) { return __uint_as_float(u << 16); }
; DEVI float bhi(unsigned u) { return __uint_as_float(u & 0xffff0000u); }
; DEVI int xcd_first_tile() { return (blockIdx.x & 7) * (gridDim.x >> 3) + (blockIdx.x >> 3); }
;     ...
;         if (EPI == EPI_RESID || EPI == EPI_RESID_ATOMIC) {
;           f32x4 x = a;
;           if (EPI == EPI_RESID || kpart == 0) {
;             const u32x2 xr = *(const u32x2*)((const u16*)(p.ws + WS_XB) + (size_t)row * 1024 + col);
;             x[0] += ALPHA * blo(xr[0]); x[1] += ALPHA * bhi(xr[0]); x[2] += ALPHA * blo(xr[1]); x[3] += ALPHA * bhi(xr[1]);
;           }
;           if (EPI == EPI_RESID) *(f32x4*)((float*)(p.ws + WS_XF) + (size_t)row * 1024 + col) = x;
;           else *(f32x4*)((float*)(p.ws + WS_SLAB) + ((size_t)kpart * 512 + (row - T_P)) * 1024 + col) = x;
; DEVI void run_phase(const Params& p, int ph, char* smem) {
;     ...
;       for (int t = xcd_first_tile(); t < 512 + 16 * 8; t += xcd_tile_step()) {
;         if (t < 512) {
;           int mt_, nt_; tile_coords(t, 64, 8, mt_, nt_);
;           gemm_tile256<EPI_RESID>(p, mix, 1024, Bt, 1024, mt_ * 256, nt_ * 128, nullptr, 0, smem);
;         } else {
;           const int u_ = t - 512, tl_ = u_ / 8, q_ = u_ - tl_ * 8;
;           gemm_tile256<EPI_RESID_ATOMIC>(p, mix, 1024, Bt, 1024, (64 + (tl_ & 1)) * 256, (tl_ >> 1) * 128, nullptr, 0, smem, q_ * 128, 4, q_);
;         }
	v_permlane16_swap_b32_e32 v204, v206
	v_permlane16_swap_b32_e32 v205, v207
	v_lshlrev_b32_e32 v216, 16, v204
	v_and_b32_e32 v204, 0xffff0000, v204
	v_lshlrev_b32_e32 v217, 16, v205
	v_and_b32_e32 v205, 0xffff0000, v205
	v_fmac_f32_e32 v38, s45, v216
	v_fmac_f32_e32 v39, s45, v204
	v_fmac_f32_e32 v40, s45, v217
	v_fmac_f32_e32 v41, s45, v205
	v_lshlrev_b32_e32 v216, 16, v206
	v_and_b32_e32 v206, 0xffff0000, v206
	v_lshlrev_b32_e32 v217, 16, v207
	v_and_b32_e32 v207, 0xffff0000, v207
	v_fmac_f32_e32 v6, s45, v216
	v_fmac_f32_e32 v7, s45, v206
	v_fmac_f32_e32 v8, s45, v217
	v_fmac_f32_e32 v9, s45, v207
	v_mov_b32_dpp v220, v6 quad_perm:[1,0,3,2] row_mask:0xf bank_mask:0xf
	v_mov_b32_dpp v221, v7 quad_perm:[1,0,3,2] row_mask:0xf bank_mask:0xf
	v_mov_b32_dpp v222, v8 quad_perm:[1,0,3,2] row_mask:0xf bank_mask:0xf
	v_mov_b32_dpp v223, v9 quad_perm:[1,0,3,2] row_mask:0xf bank_mask:0xf
	v_mov_b32_dpp v224, v38 quad_perm:[1,0,3,2] row_mask:0xf bank_mask:0xf
	v_mov_b32_dpp v225, v39 quad_perm:[1,0,3,2] row_mask:0xf bank_mask:0xf
	v_mov_b32_dpp v226, v40 quad_perm:[1,0,3,2] row_mask:0xf bank_mask:0xf
	v_mov_b32_dpp v227, v41 quad_perm:[1,0,3,2] row_mask:0xf bank_mask:0xf
	v_cndmask_b32_e32 v6, v224, v6, vcc
	v_cndmask_b32_e32 v7, v225, v7, vcc
	v_cndmask_b32_e32 v8, v226, v8, vcc
	v_cndmask_b32_e32 v9, v227, v9, vcc
	v_cndmask_b32_e32 v38, v38, v220, vcc
	v_cndmask_b32_e32 v39, v39, v221, vcc
	v_cndmask_b32_e32 v40, v40, v222, vcc
	v_cndmask_b32_e32 v41, v41, v223, vcc
	global_store_dwordx4 v[140:141], v[38:41], off offset:128
	global_store_dwordx4 v[142:143], v[6:9], off offset:128
	v_lshl_add_u64 v[140:141], v[140:141], 0, s[10:11]
	v_lshl_add_u64 v[142:143], v[142:143], 0, s[10:11]
	s_waitcnt vmcnt(29)
	v_permlane16_swap_b32_e32 v208, v210
	v_permlane16_swap_b32_e32 v209, v211
	v_lshlrev_b32_e32 v216, 16, v208
	v_and_b32_e32 v208, 0xffff0000, v208
	v_lshlrev_b32_e32 v217, 16, v209
	v_and_b32_e32 v209, 0xffff0000, v209
	v_fmac_f32_e32 v98, s45, v216
	v_fmac_f32_e32 v99, s45, v208
	v_fmac_f32_e32 v100, s45, v217
	v_fmac_f32_e32 v101, s45, v209
	v_lshlrev_b32_e32 v216, 16, v210
	v_and_b32_e32 v210, 0xffff0000, v210
	v_lshlrev_b32_e32 v217, 16, v211
	v_and_b32_e32 v211, 0xffff0000, v211
	v_fmac_f32_e32 v66, s45, v216
	v_fmac_f32_e32 v67, s45, v210
	v_fmac_f32_e32 v68, s45, v217
	v_fmac_f32_e32 v69, s45, v211
	v_mov_b32_dpp v220, v66 quad_perm:[1,0,3,2] row_mask:0xf bank_mask:0xf
	v_mov_b32_dpp v221, v67 quad_perm:[1,0,3,2] row_mask:0xf bank_mask:0xf
	v_mov_b32_dpp v222, v68 quad_perm:[1,0,3,2] row_mask:0xf bank_mask:0xf
	v_mov_b32_dpp v223, v69 quad_perm:[1,0,3,2] row_mask:0xf bank_mask:0xf
	v_mov_b32_dpp v224, v98 quad_perm:[1,0,3,2] row_mask:0xf bank_mask:0xf
	v_mov_b32_dpp v225, v99 quad_perm:[1,0,3,2] row_mask:0xf bank_mask:0xf
	v_mov_b32_dpp v226, v100 quad_perm:[1,0,3,2] row_mask:0xf bank_mask:0xf
	v_mov_b32_dpp v227, v101 quad_perm:[1,0,3,2] row_mask:0xf bank_mask:0xf
	v_cndmask_b32_e32 v66, v224, v66, vcc
	v_cndmask_b32_e32 v67, v225, v67, vcc
	v_cndmask_b32_e32 v68, v226, v68, vcc
	v_cndmask_b32_e32 v69, v227, v69, vcc
	v_cndmask_b32_e32 v98, v98, v220, vcc
	v_cndmask_b32_e32 v99, v99, v221, vcc
	v_cndmask_b32_e32 v100, v100, v222, vcc
	v_cndmask_b32_e32 v101, v101, v223, vcc
	global_store_dwordx4 v[140:141], v[98:101], off
	global_store_dwordx4 v[142:143], v[66:69], off
	s_waitcnt vmcnt(30)
	v_permlane16_swap_b32_e32 v212, v214
	v_permlane16_swap_b32_e32 v213, v215
	v_lshlrev_b32_e32 v216, 16, v212
	v_and_b32_e32 v212, 0xffff0000, v212
	v_lshlrev_b32_e32 v217, 16, v213
	v_and_b32_e32 v213, 0xffff0000, v213
	v_fmac_f32_e32 v34, s45, v216
	v_fmac_f32_e32 v35, s45, v212
	v_fmac_f32_e32 v36, s45, v217
	v_fmac_f32_e32 v37, s45, v213
	v_lshlrev_b32_e32 v216, 16, v214
	v_and_b32_e32 v214, 0xffff0000, v214
	v_lshlrev_b32_e32 v217, 16, v215
	v_and_b32_e32 v215, 0xffff0000, v215
	v_fmac_f32_e32 v2, s45, v216
	v_fmac_f32_e32 v3, s45, v214
	v_fmac_f32_e32 v4, s45, v217
	v_fmac_f32_e32 v5, s45, v215
	v_mov_b32_dpp v220, v2 quad_perm:[1,0,3,2] row_mask:0xf bank_mask:0xf
	v_mov_b32_dpp v221, v3 quad_perm:[1,0,3,2] row_mask:0xf bank_mask:0xf
	v_mov_b32_dpp v222, v4 quad_perm:[1,0,3,2] row_mask:0xf bank_mask:0xf
	v_mov_b32_dpp v223, v5 quad_perm:[1,0,3,2] row_mask:0xf bank_mask:0xf
	v_mov_b32_dpp v224, v34 quad_perm:[1,0,3,2] row_mask:0xf bank_mask:0xf
	v_mov_b32_dpp v225, v35 quad_perm:[1,0,3,2] row_mask:0xf bank_mask:0xf
	v_mov_b32_dpp v226, v36 quad_perm:[1,0,3,2] row_mask:0xf bank_mask:0xf
	v_mov_b32_dpp v227, v37 quad_perm:[1,0,3,2] row_mask:0xf bank_mask:0xf
	v_cndmask_b32_e32 v2, v224, v2, vcc
	v_cndmask_b32_e32 v3, v225, v3, vcc
	v_cndmask_b32_e32 v4, v226, v4, vcc
	v_cndmask_b32_e32 v5, v227, v5, vcc
	v_cndmask_b32_e32 v34, v34, v220, vcc
	v_cndmask_b32_e32 v35, v35, v221, vcc
	v_cndmask_b32_e32 v36, v36, v222, vcc
	v_cndmask_b32_e32 v37, v37, v223, vcc
	global_store_dwordx4 v[140:141], v[34:37], off offset:128
	global_store_dwordx4 v[142:143], v[2:5], off offset:128
	v_readlane_b32 s40, v250, 7
	s_cmpk_lg_u32 s40, 0x200
	s_cbranch_scc1 .LBB0_757
	v_readlane_b32 s41, v250, 0
	s_lshr_b32 s42, s41, 3
	s_and_b32 s41, s41, 7
	s_mul_i32 s41, s41, 16
	s_add_i32 s41, s41, s42
	s_cmp_lt_u32 s42, 16
	s_movk_i32 s39, 0x4000
	s_branch .LBB0_757

; DEVI int xcd_first_tile() { return (blockIdx.x & 7) * (gridDim.x >> 3) + (blockIdx.x >> 3); }
;     ...
;   for (int kt = 0; kt < nk; kt++) {
;     if (kt + 1 < nk) asm volatile("s_waitcnt vmcnt(6)" ::: "memory");
;     else asm volatile("s_waitcnt vmcnt(0)" ::: "memory");
;     __builtin_amdgcn_s_barrier();
;     asm volatile("" ::: "memory");
;     if (kt + 2 < nk) G2_STAGE(kt + 2);
;     const char* cS = smem + (kt % 3) * 24576;
;     bf16x8 xa[8], wb[4];
; #pragma unroll
;     for (int f = 0; f < 8; f++) xa[f] = *(const bf16x8*)(cS + aoff + f * 1024);
; #pragma unroll
;     for (int f = 0; f < 4; f++) wb[f] = *(const bf16x8*)(cS + boff + f * 1024);
; #pragma unroll
;     for (int nf = 0; nf < 4; nf++)
; #pragma unroll
;       for (int mf = 0; mf < 8; mf++)
;         acc[nf][mf] = __builtin_amdgcn_mfma_f32_16x16x32_bf16(wb[nf], xa[mf], acc[nf][mf], 0, 0, 0);
; DEVI void run_phase(const Params& p, int ph, char* smem) {
;     ...
;       for (int t = xcd_first_tile(); t < n1 + n2; t += xcd_tile_step()) {
;         if (t < n1) { int mt_, nt_; tile_coords(t, 66, 20, mt_, nt_); gemm_tile256<EPI_BF16>(p, xb, 1024, Bt, 1024, mt_ * 256, nt_ * 128, proj, DIN, smem); }
.Lt0_loop:
	.p2align 3
	s_waitcnt vmcnt(6) lgkmcnt(0)
	s_barrier
	s_setprio 1
	v_add_u32_e32 v144, s38, v136
	v_mfma_f32_16x16x32_bf16 v[126:129], v[184:187], v[146:149], v[126:129]
	ds_read_b128 v[200:203], v144 offset:0
	v_mfma_f32_16x16x32_bf16 v[122:125], v[184:187], v[152:155], v[122:125]
	ds_read_b128 v[204:207], v144 offset:1024
	v_mfma_f32_16x16x32_bf16 v[118:121], v[184:187], v[156:159], v[118:121]
	ds_read_b128 v[208:211], v144 offset:2048
	v_mfma_f32_16x16x32_bf16 v[114:117], v[184:187], v[162:165], v[114:117]
	ds_read_b128 v[212:215], v144 offset:3072
	v_mfma_f32_16x16x32_bf16 v[110:113], v[184:187], v[166:169], v[110:113]
	ds_read_b128 v[216:219], v144 offset:4096
	v_mfma_f32_16x16x32_bf16 v[106:109], v[184:187], v[170:173], v[106:109]
	ds_read_b128 v[220:223], v144 offset:5120
	v_mfma_f32_16x16x32_bf16 v[102:105], v[184:187], v[176:179], v[102:105]
	ds_read_b128 v[224:227], v144 offset:6144
	v_mfma_f32_16x16x32_bf16 v[98:101], v[184:187], v[180:183], v[98:101]
	ds_read_b128 v[228:231], v144 offset:7168
	v_mfma_f32_16x16x32_bf16 v[94:97], v[188:191], v[146:149], v[94:97]
	v_add_u32_e64 v144, s38, v137
	v_mfma_f32_16x16x32_bf16 v[90:93], v[188:191], v[152:155], v[90:93]
	v_mfma_f32_16x16x32_bf16 v[86:89], v[188:191], v[156:159], v[86:89]
	ds_read_b128 v[232:235], v144 offset:16384
	v_mfma_f32_16x16x32_bf16 v[82:85], v[188:191], v[162:165], v[82:85]
	ds_read_b128 v[236:239], v144 offset:17408
	v_mfma_f32_16x16x32_bf16 v[78:81], v[188:191], v[166:169], v[78:81]
	ds_read_b128 v[240:243], v144 offset:18432
	v_mfma_f32_16x16x32_bf16 v[74:77], v[188:191], v[170:173], v[74:77]
	ds_read_b128 v[244:247], v144 offset:19456
	v_mfma_f32_16x16x32_bf16 v[70:73], v[188:191], v[176:179], v[70:73]
	s_add_i32 s40, s44, s39
	s_mov_b32 m0, s40
	v_lshl_add_u64 v[142:143], v[132:133], 0, s[2:3]
	v_mfma_f32_16x16x32_bf16 v[66:69], v[188:191], v[180:183], v[66:69]
	global_load_lds_dwordx4 v[132:133], off
	s_add_i32 m0, m0, 0x1000
	v_mfma_f32_16x16x32_bf16 v[62:65], v[192:195], v[146:149], v[62:65]
	v_mfma_f32_16x16x32_bf16 v[58:61], v[192:195], v[152:155], v[58:61]
	v_mfma_f32_16x16x32_bf16 v[54:57], v[192:195], v[156:159], v[54:57]
	global_load_lds_dwordx4 v[142:143], off
	v_lshl_add_u64 v[142:143], v[142:143], 0, s[2:3]
	s_add_i32 m0, m0, 0x1000
	v_mfma_f32_16x16x32_bf16 v[50:53], v[192:195], v[162:165], v[50:53]
	v_mfma_f32_16x16x32_bf16 v[46:49], v[192:195], v[166:169], v[46:49]
	v_mfma_f32_16x16x32_bf16 v[42:45], v[192:195], v[170:173], v[42:45]
	global_load_lds_dwordx4 v[142:143], off
	v_lshl_add_u64 v[142:143], v[142:143], 0, s[2:3]
	s_add_i32 m0, m0, 0x1000
	v_mfma_f32_16x16x32_bf16 v[38:41], v[192:195], v[176:179], v[38:41]
	v_mfma_f32_16x16x32_bf16 v[34:37], v[192:195], v[180:183], v[34:37]
	s_setprio 0
	s_nop 0
	v_mfma_f32_16x16x32_bf16 v[30:33], v[196:199], v[146:149], v[30:33]
	global_load_lds_dwordx4 v[142:143], off
	s_add_i32 m0, m0, 0x1000
	v_lshl_add_u64 v[142:143], v[134:135], 0, s[2:3]
	v_mfma_f32_16x16x32_bf16 v[26:29], v[196:199], v[152:155], v[26:29]
	v_mfma_f32_16x16x32_bf16 v[22:25], v[196:199], v[156:159], v[22:25]
	v_mfma_f32_16x16x32_bf16 v[18:21], v[196:199], v[162:165], v[18:21]
	global_load_lds_dwordx4 v[134:135], off
	s_add_i32 m0, m0, 0x1000
	v_lshl_add_u64 v[132:133], v[132:133], 0, s[36:37]
	v_mfma_f32_16x16x32_bf16 v[14:17], v[196:199], v[166:169], v[14:17]
	v_mfma_f32_16x16x32_bf16 v[10:13], v[196:199], v[170:173], v[10:13]
	v_mfma_f32_16x16x32_bf16 v[6:9], v[196:199], v[176:179], v[6:9]
	global_load_lds_dwordx4 v[142:143], off
	v_lshl_add_u64 v[134:135], v[134:135], 0, s[8:9]
	v_mfma_f32_16x16x32_bf16 v[2:5], v[196:199], v[180:183], v[2:5]
	s_mov_b32 s39, s38
	s_nop 0
	s_add_i32 s38, s38, 0x6000
	s_cmp_eq_u32 s38, 0x12000
	s_cselect_b32 s38, 0, s38
	s_nop 0
	.p2align 3
	s_waitcnt vmcnt(6) lgkmcnt(0)
	s_barrier
	s_setprio 1
	v_add_u32_e32 v144, s38, v136
	v_mfma_f32_16x16x32_bf16 v[126:129], v[232:235], v[200:203], v[126:129]
	ds_read_b128 v[146:149], v144 offset:0
	v_mfma_f32_16x16x32_bf16 v[122:125], v[232:235], v[204:207], v[122:125]
	ds_read_b128 v[152:155], v144 offset:1024
	v_mfma_f32_16x16x32_bf16 v[118:121], v[232:235], v[208:211], v[118:121]
	ds_read_b128 v[156:159], v144 offset:2048
	v_mfma_f32_16x16x32_bf16 v[114:117], v[232:235], v[212:215], v[114:117]
	ds_read_b128 v[162:165], v144 offset:3072
	v_mfma_f32_16x16x32_bf16 v[110:113], v[232:235], v[216:219], v[110:113]
	ds_read_b128 v[166:169], v144 offset:4096
	v_mfma_f32_16x16x32_bf16 v[106:109], v[232:235], v[220:223], v[106:109]
	ds_read_b128 v[170:173], v144 offset:5120
	v_mfma_f32_16x16x32_bf16 v[102:105], v[232:235], v[224:227], v[102:105]
	ds_read_b128 v[176:179], v144 offset:6144
	v_mfma_f32_16x16x32_bf16 v[98:101], v[232:235], v[228:231], v[98:101]
	ds_read_b128 v[180:183], v144 offset:7168
	v_mfma_f32_16x16x32_bf16 v[94:97], v[236:239], v[200:203], v[94:97]
	v_add_u32_e64 v144, s38, v137
	v_mfma_f32_16x16x32_bf16 v[90:93], v[236:239], v[204:207], v[90:93]
	v_mfma_f32_16x16x32_bf16 v[86:89], v[236:239], v[208:211], v[86:89]
	ds_read_b128 v[184:187], v144 offset:16384
	v_mfma_f32_16x16x32_bf16 v[82:85], v[236:239], v[212:215], v[82:85]
	ds_read_b128 v[188:191], v144 offset:17408
	v_mfma_f32_16x16x32_bf16 v[78:81], v[236:239], v[216:219], v[78:81]
	ds_read_b128 v[192:195], v144 offset:18432
	v_mfma_f32_16x16x32_bf16 v[74:77], v[236:239], v[220:223], v[74:77]
	ds_read_b128 v[196:199], v144 offset:19456
	v_mfma_f32_16x16x32_bf16 v[70:73], v[236:239], v[224:227], v[70:73]
	s_add_i32 s40, s44, s39
	s_mov_b32 m0, s40
	v_lshl_add_u64 v[142:143], v[132:133], 0, s[2:3]
	v_mfma_f32_16x16x32_bf16 v[66:69], v[236:239], v[228:231], v[66:69]
;     ...
;   for (int kt = 0; kt < nk; kt++) {
;     if (kt + 1 < nk) asm volatile("s_waitcnt vmcnt(6)" ::: "memory");
;     else asm volatile("s_waitcnt vmcnt(0)" ::: "memory");
;     __builtin_amdgcn_s_barrier();
;     asm volatile("" ::: "memory");
;     if (kt + 2 < nk) G2_STAGE(kt + 2);
;     const char* cS = smem + (kt % 3) * 24576;
;     bf16x8 xa[8], wb[4];
; #pragma unroll
;     for (int f = 0; f < 8; f++) xa[f] = *(const bf16x8*)(cS + aoff + f * 1024);
; #pragma unroll
;     for (int f = 0; f < 4; f++) wb[f] = *(const bf16x8*)(cS + boff + f * 1024);
; #pragma unroll
;     for (int nf = 0; nf < 4; nf++)
; #pragma unroll
;       for (int mf = 0; mf < 8; mf++)
;         acc[nf][mf] = __builtin_amdgcn_mfma_f32_16x16x32_bf16(wb[nf], xa[mf], acc[nf][mf], 0, 0, 0);
	global_load_lds_dwordx4 v[132:133], off
	s_add_i32 m0, m0, 0x1000
	v_mfma_f32_16x16x32_bf16 v[62:65], v[240:243], v[200:203], v[62:65]
	v_mfma_f32_16x16x32_bf16 v[58:61], v[240:243], v[204:207], v[58:61]
	v_mfma_f32_16x16x32_bf16 v[54:57], v[240:243], v[208:211], v[54:57]
	global_load_lds_dwordx4 v[142:143], off
	v_lshl_add_u64 v[142:143], v[142:143], 0, s[2:3]
	s_add_i32 m0, m0, 0x1000
	v_mfma_f32_16x16x32_bf16 v[50:53], v[240:243], v[212:215], v[50:53]
	v_mfma_f32_16x16x32_bf16 v[46:49], v[240:243], v[216:219], v[46:49]
	v_mfma_f32_16x16x32_bf16 v[42:45], v[240:243], v[220:223], v[42:45]
	global_load_lds_dwordx4 v[142:143], off
	v_lshl_add_u64 v[142:143], v[142:143], 0, s[2:3]
	s_add_i32 m0, m0, 0x1000
	v_mfma_f32_16x16x32_bf16 v[38:41], v[240:243], v[224:227], v[38:41]
	v_mfma_f32_16x16x32_bf16 v[34:37], v[240:243], v[228:231], v[34:37]
	s_setprio 0
	s_nop 0
	v_mfma_f32_16x16x32_bf16 v[30:33], v[244:247], v[200:203], v[30:33]
	global_load_lds_dwordx4 v[142:143], off
	s_add_i32 m0, m0, 0x1000
	v_lshl_add_u64 v[142:143], v[134:135], 0, s[2:3]
	v_mfma_f32_16x16x32_bf16 v[26:29], v[244:247], v[204:207], v[26:29]
	v_mfma_f32_16x16x32_bf16 v[22:25], v[244:247], v[208:211], v[22:25]
	v_mfma_f32_16x16x32_bf16 v[18:21], v[244:247], v[212:215], v[18:21]
	global_load_lds_dwordx4 v[134:135], off
	s_add_i32 m0, m0, 0x1000
	v_lshl_add_u64 v[132:133], v[132:133], 0, s[36:37]
	v_mfma_f32_16x16x32_bf16 v[14:17], v[244:247], v[216:219], v[14:17]
	v_mfma_f32_16x16x32_bf16 v[10:13], v[244:247], v[220:223], v[10:13]
	v_mfma_f32_16x16x32_bf16 v[6:9], v[244:247], v[224:227], v[6:9]
	global_load_lds_dwordx4 v[142:143], off
	v_lshl_add_u64 v[134:135], v[134:135], 0, s[8:9]
	v_mfma_f32_16x16x32_bf16 v[2:5], v[244:247], v[228:231], v[2:5]
	s_mov_b32 s39, s38
	s_nop 0
	s_add_i32 s38, s38, 0x6000
	s_cmp_eq_u32 s38, 0x12000
	s_cselect_b32 s38, 0, s38
	s_nop 0
	s_sub_i32 s15, s15, 1
	s_cmp_lg_u32 s15, 0
	s_cbranch_scc1 .Lt0_loop
	.p2align 3
	s_waitcnt vmcnt(6) lgkmcnt(0)
	s_barrier
	s_setprio 1
	v_add_u32_e32 v144, s38, v136
	v_mfma_f32_16x16x32_bf16 v[126:129], v[184:187], v[146:149], v[126:129]
	ds_read_b128 v[200:203], v144 offset:0
	v_mfma_f32_16x16x32_bf16 v[122:125], v[184:187], v[152:155], v[122:125]
	ds_read_b128 v[204:207], v144 offset:1024
	v_mfma_f32_16x16x32_bf16 v[118:121], v[184:187], v[156:159], v[118:121]
	ds_read_b128 v[208:211], v144 offset:2048
	v_mfma_f32_16x16x32_bf16 v[114:117], v[184:187], v[162:165], v[114:117]
	ds_read_b128 v[212:215], v144 offset:3072
	v_mfma_f32_16x16x32_bf16 v[110:113], v[184:187], v[166:169], v[110:113]
	ds_read_b128 v[216:219], v144 offset:4096
	v_mfma_f32_16x16x32_bf16 v[106:109], v[184:187], v[170:173], v[106:109]
	ds_read_b128 v[220:223], v144 offset:5120
	v_mfma_f32_16x16x32_bf16 v[102:105], v[184:187], v[176:179], v[102:105]
	ds_read_b128 v[224:227], v144 offset:6144
	v_mfma_f32_16x16x32_bf16 v[98:101], v[184:187], v[180:183], v[98:101]
	ds_read_b128 v[228:231], v144 offset:7168
	v_mfma_f32_16x16x32_bf16 v[94:97], v[188:191], v[146:149], v[94:97]
	v_add_u32_e64 v144, s38, v137
	v_mfma_f32_16x16x32_bf16 v[90:93], v[188:191], v[152:155], v[90:93]
	v_mfma_f32_16x16x32_bf16 v[86:89], v[188:191], v[156:159], v[86:89]
	ds_read_b128 v[232:235], v144 offset:16384
	v_mfma_f32_16x16x32_bf16 v[82:85], v[188:191], v[162:165], v[82:85]
	ds_read_b128 v[236:239], v144 offset:17408
	v_mfma_f32_16x16x32_bf16 v[78:81], v[188:191], v[166:169], v[78:81]
	ds_read_b128 v[240:243], v144 offset:18432
	v_mfma_f32_16x16x32_bf16 v[74:77], v[188:191], v[170:173], v[74:77]
	ds_read_b128 v[244:247], v144 offset:19456
	v_mfma_f32_16x16x32_bf16 v[70:73], v[188:191], v[176:179], v[70:73]
	s_add_i32 s40, s44, s39
	s_mov_b32 m0, s40
	v_lshl_add_u64 v[142:143], v[132:133], 0, s[2:3]
	v_mfma_f32_16x16x32_bf16 v[66:69], v[188:191], v[180:183], v[66:69]
	global_load_lds_dwordx4 v[132:133], off
	s_add_i32 m0, m0, 0x1000
	v_mfma_f32_16x16x32_bf16 v[62:65], v[192:195], v[146:149], v[62:65]
	v_mfma_f32_16x16x32_bf16 v[58:61], v[192:195], v[152:155], v[58:61]
	v_mfma_f32_16x16x32_bf16 v[54:57], v[192:195], v[156:159], v[54:57]
	global_load_lds_dwordx4 v[142:143], off
	v_lshl_add_u64 v[142:143], v[142:143], 0, s[2:3]
	s_add_i32 m0, m0, 0x1000
	v_mfma_f32_16x16x32_bf16 v[50:53], v[192:195], v[162:165], v[50:53]
	v_mfma_f32_16x16x32_bf16 v[46:49], v[192:195], v[166:169], v[46:49]
	v_mfma_f32_16x16x32_bf16 v[42:45], v[192:195], v[170:173], v[42:45]
	global_load_lds_dwordx4 v[142:143], off
	v_lshl_add_u64 v[142:143], v[142:143], 0, s[2:3]
	s_add_i32 m0, m0, 0x1000
	v_mfma_f32_16x16x32_bf16 v[38:41], v[192:195], v[176:179], v[38:41]
	v_mfma_f32_16x16x32_bf16 v[34:37], v[192:195], v[180:183], v[34:37]
	s_setprio 0
	s_nop 0
	v_mfma_f32_16x16x32_bf16 v[30:33], v[196:199], v[146:149], v[30:33]
	global_load_lds_dwordx4 v[142:143], off
	s_add_i32 m0, m0, 0x1000
	v_lshl_add_u64 v[142:143], v[134:135], 0, s[2:3]
	v_mfma_f32_16x16x32_bf16 v[26:29], v[196:199], v[152:155], v[26:29]
	v_mfma_f32_16x16x32_bf16 v[22:25], v[196:199], v[156:159], v[22:25]
	v_mfma_f32_16x16x32_bf16 v[18:21], v[196:199], v[162:165], v[18:21]
	global_load_lds_dwordx4 v[134:135], off
	s_add_i32 m0, m0, 0x1000
	v_lshl_add_u64 v[132:133], v[132:133], 0, s[36:37]
	v_mfma_f32_16x16x32_bf16 v[14:17], v[196:199], v[166:169], v[14:17]
	v_mfma_f32_16x16x32_bf16 v[10:13], v[196:199], v[170:173], v[10:13]
	v_mfma_f32_16x16x32_bf16 v[6:9], v[196:199], v[176:179], v[6:9]
	global_load_lds_dwordx4 v[142:143], off
	v_lshl_add_u64 v[134:135], v[134:135], 0, s[8:9]
	v_mfma_f32_16x16x32_bf16 v[2:5], v[196:199], v[180:183], v[2:5]
	s_mov_b32 s39, s38
	s_nop 0
	s_add_i32 s38, s38, 0x6000
	s_cmp_eq_u32 s38, 0x12000
	s_cselect_b32 s38, 0, s38
	s_nop 0
	.p2align 3
	s_waitcnt vmcnt(6) lgkmcnt(0)
	s_barrier
;     ...
;   for (int kt = 0; kt < nk; kt++) {
;     if (kt + 1 < nk) asm volatile("s_waitcnt vmcnt(6)" ::: "memory");
;     else asm volatile("s_waitcnt vmcnt(0)" ::: "memory");
;     __builtin_amdgcn_s_barrier();
;     asm volatile("" ::: "memory");
;     if (kt + 2 < nk) G2_STAGE(kt + 2);
;     const char* cS = smem + (kt % 3) * 24576;
;     bf16x8 xa[8], wb[4];
; #pragma unroll
;     for (int f = 0; f < 8; f++) xa[f] = *(const bf16x8*)(cS + aoff + f * 1024);
; #pragma unroll
;     for (int f = 0; f < 4; f++) wb[f] = *(const bf16x8*)(cS + boff + f * 1024);
; #pragma unroll
;     for (int nf = 0; nf < 4; nf++)
; #pragma unroll
;       for (int mf = 0; mf < 8; mf++)
;         acc[nf][mf] = __builtin_amdgcn_mfma_f32_16x16x32_bf16(wb[nf], xa[mf], acc[nf][mf], 0, 0, 0);
	s_setprio 1
	v_add_u32_e32 v144, s38, v136
	v_mfma_f32_16x16x32_bf16 v[126:129], v[232:235], v[200:203], v[126:129]
	ds_read_b128 v[146:149], v144 offset:0
	v_mfma_f32_16x16x32_bf16 v[122:125], v[232:235], v[204:207], v[122:125]
	ds_read_b128 v[152:155], v144 offset:1024
	v_mfma_f32_16x16x32_bf16 v[118:121], v[232:235], v[208:211], v[118:121]
	ds_read_b128 v[156:159], v144 offset:2048
	v_mfma_f32_16x16x32_bf16 v[114:117], v[232:235], v[212:215], v[114:117]
	ds_read_b128 v[162:165], v144 offset:3072
	v_mfma_f32_16x16x32_bf16 v[110:113], v[232:235], v[216:219], v[110:113]
	ds_read_b128 v[166:169], v144 offset:4096
	v_mfma_f32_16x16x32_bf16 v[106:109], v[232:235], v[220:223], v[106:109]
	ds_read_b128 v[170:173], v144 offset:5120
	v_mfma_f32_16x16x32_bf16 v[102:105], v[232:235], v[224:227], v[102:105]
	ds_read_b128 v[176:179], v144 offset:6144
	v_mfma_f32_16x16x32_bf16 v[98:101], v[232:235], v[228:231], v[98:101]
	ds_read_b128 v[180:183], v144 offset:7168
	v_mfma_f32_16x16x32_bf16 v[94:97], v[236:239], v[200:203], v[94:97]
	v_add_u32_e64 v144, s38, v137
	v_mfma_f32_16x16x32_bf16 v[90:93], v[236:239], v[204:207], v[90:93]
	v_mfma_f32_16x16x32_bf16 v[86:89], v[236:239], v[208:211], v[86:89]
	ds_read_b128 v[184:187], v144 offset:16384
	v_mfma_f32_16x16x32_bf16 v[82:85], v[236:239], v[212:215], v[82:85]
	ds_read_b128 v[188:191], v144 offset:17408
	v_mfma_f32_16x16x32_bf16 v[78:81], v[236:239], v[216:219], v[78:81]
	ds_read_b128 v[192:195], v144 offset:18432
	v_mfma_f32_16x16x32_bf16 v[74:77], v[236:239], v[220:223], v[74:77]
	ds_read_b128 v[196:199], v144 offset:19456
	v_mfma_f32_16x16x32_bf16 v[70:73], v[236:239], v[224:227], v[70:73]
	v_mfma_f32_16x16x32_bf16 v[66:69], v[236:239], v[228:231], v[66:69]
	v_mfma_f32_16x16x32_bf16 v[62:65], v[240:243], v[200:203], v[62:65]
	v_mfma_f32_16x16x32_bf16 v[58:61], v[240:243], v[204:207], v[58:61]
	v_mfma_f32_16x16x32_bf16 v[54:57], v[240:243], v[208:211], v[54:57]
	v_mfma_f32_16x16x32_bf16 v[50:53], v[240:243], v[212:215], v[50:53]
	v_mfma_f32_16x16x32_bf16 v[46:49], v[240:243], v[216:219], v[46:49]
	v_mfma_f32_16x16x32_bf16 v[42:45], v[240:243], v[220:223], v[42:45]
	v_mfma_f32_16x16x32_bf16 v[38:41], v[240:243], v[224:227], v[38:41]
	v_mfma_f32_16x16x32_bf16 v[34:37], v[240:243], v[228:231], v[34:37]
	s_setprio 0
	s_nop 0
	v_mfma_f32_16x16x32_bf16 v[30:33], v[244:247], v[200:203], v[30:33]
	v_mfma_f32_16x16x32_bf16 v[26:29], v[244:247], v[204:207], v[26:29]
	v_mfma_f32_16x16x32_bf16 v[22:25], v[244:247], v[208:211], v[22:25]
	v_mfma_f32_16x16x32_bf16 v[18:21], v[244:247], v[212:215], v[18:21]
	v_mfma_f32_16x16x32_bf16 v[14:17], v[244:247], v[216:219], v[14:17]
	v_mfma_f32_16x16x32_bf16 v[10:13], v[244:247], v[220:223], v[10:13]
	v_mfma_f32_16x16x32_bf16 v[6:9], v[244:247], v[224:227], v[6:9]
	v_mfma_f32_16x16x32_bf16 v[2:5], v[244:247], v[228:231], v[2:5]
	s_mov_b32 s39, s38
	s_nop 0
	s_add_i32 s38, s38, 0x6000
	s_cmp_eq_u32 s38, 0x12000
	s_cselect_b32 s38, 0, s38
	s_nop 0
	.p2align 3
	s_waitcnt vmcnt(0) lgkmcnt(0)
	s_barrier
	s_setprio 1
	v_add_u32_e32 v144, s38, v136
	v_mfma_f32_16x16x32_bf16 v[126:129], v[184:187], v[146:149], v[126:129]
	ds_read_b128 v[200:203], v144 offset:0
	v_mfma_f32_16x16x32_bf16 v[122:125], v[184:187], v[152:155], v[122:125]
	ds_read_b128 v[204:207], v144 offset:1024
	v_mfma_f32_16x16x32_bf16 v[118:121], v[184:187], v[156:159], v[118:121]
	ds_read_b128 v[208:211], v144 offset:2048
	v_mfma_f32_16x16x32_bf16 v[114:117], v[184:187], v[162:165], v[114:117]
	ds_read_b128 v[212:215], v144 offset:3072
	v_mfma_f32_16x16x32_bf16 v[110:113], v[184:187], v[166:169], v[110:113]
	ds_read_b128 v[216:219], v144 offset:4096
	v_mfma_f32_16x16x32_bf16 v[106:109], v[184:187], v[170:173], v[106:109]
	ds_read_b128 v[220:223], v144 offset:5120
	v_mfma_f32_16x16x32_bf16 v[102:105], v[184:187], v[176:179], v[102:105]
	ds_read_b128 v[224:227], v144 offset:6144
	v_mfma_f32_16x16x32_bf16 v[98:101], v[184:187], v[180:183], v[98:101]
	ds_read_b128 v[228:231], v144 offset:7168
	v_mfma_f32_16x16x32_bf16 v[94:97], v[188:191], v[146:149], v[94:97]
	v_add_u32_e64 v144, s38, v137
	v_mfma_f32_16x16x32_bf16 v[90:93], v[188:191], v[152:155], v[90:93]
	v_mfma_f32_16x16x32_bf16 v[86:89], v[188:191], v[156:159], v[86:89]
	ds_read_b128 v[232:235], v144 offset:16384
	v_mfma_f32_16x16x32_bf16 v[82:85], v[188:191], v[162:165], v[82:85]
	ds_read_b128 v[236:239], v144 offset:17408
	v_mfma_f32_16x16x32_bf16 v[78:81], v[188:191], v[166:169], v[78:81]
	ds_read_b128 v[240:243], v144 offset:18432
	v_mfma_f32_16x16x32_bf16 v[74:77], v[188:191], v[170:173], v[74:77]
	ds_read_b128 v[244:247], v144 offset:19456
	v_mfma_f32_16x16x32_bf16 v[70:73], v[188:191], v[176:179], v[70:73]
	v_mfma_f32_16x16x32_bf16 v[66:69], v[188:191], v[180:183], v[66:69]
	v_mfma_f32_16x16x32_bf16 v[62:65], v[192:195], v[146:149], v[62:65]
	v_mfma_f32_16x16x32_bf16 v[58:61], v[192:195], v[152:155], v[58:61]
	v_mfma_f32_16x16x32_bf16 v[54:57], v[192:195], v[156:159], v[54:57]
	v_mfma_f32_16x16x32_bf16 v[50:53], v[192:195], v[162:165], v[50:53]
	v_mfma_f32_16x16x32_bf16 v[46:49], v[192:195], v[166:169], v[46:49]
	v_mfma_f32_16x16x32_bf16 v[42:45], v[192:195], v[170:173], v[42:45]
	v_mfma_f32_16x16x32_bf16 v[38:41], v[192:195], v[176:179], v[38:41]
	v_mfma_f32_16x16x32_bf16 v[34:37], v[192:195], v[180:183], v[34:37]
	s_setprio 0
	s_nop 0
	v_mfma_f32_16x16x32_bf16 v[30:33], v[196:199], v[146:149], v[30:33]
	v_mfma_f32_16x16x32_bf16 v[26:29], v[196:199], v[152:155], v[26:29]
	v_mfma_f32_16x16x32_bf16 v[22:25], v[196:199], v[156:159], v[22:25]
	v_mfma_f32_16x16x32_bf16 v[18:21], v[196:199], v[162:165], v[18:21]
	v_mfma_f32_16x16x32_bf16 v[14:17], v[196:199], v[166:169], v[14:17]
	v_mfma_f32_16x16x32_bf16 v[10:13], v[196:199], v[170:173], v[10:13]
	v_mfma_f32_16x16x32_bf16 v[6:9], v[196:199], v[176:179], v[6:9]
	v_mfma_f32_16x16x32_bf16 v[2:5], v[196:199], v[180:183], v[2:5]
	s_mov_b32 s39, s38
	s_nop 0
	s_add_i32 s38, s38, 0x6000
	s_cmp_eq_u32 s38, 0x12000
	s_cselect_b32 s38, 0, s38
	s_nop 0
	.p2align 3
	s_waitcnt lgkmcnt(0)
; DEVI unsigned pack2(float a, float b) { return __builtin_bit_cast(unsigned, __builtin_convertvector((f32x2_t){a, b}, bf16x2_t)); }
;     ...
;     for (int nf = 0; nf < 4; nf++)
; #pragma unroll
;       for (int mf = 0; mf < 8; mf++)
;         acc[nf][mf] = __builtin_amdgcn_mfma_f32_16x16x32_bf16(wb[nf], xa[mf], acc[nf][mf], 0, 0, 0);
;     ...
;         } else {
;           u32x2 pk; pk[0] = pack2(a[0], a[1]); pk[1] = pack2(a[2], a[3]);
;           *(u32x2*)(outb + (size_t)row * ldc + col) = pk;
	s_nop 0
	v_mfma_f32_16x16x32_bf16 v[126:129], v[232:235], v[200:203], v[126:129]
	v_mfma_f32_16x16x32_bf16 v[122:125], v[232:235], v[204:207], v[122:125]
	v_mfma_f32_16x16x32_bf16 v[118:121], v[232:235], v[208:211], v[118:121]
	v_mfma_f32_16x16x32_bf16 v[114:117], v[232:235], v[212:215], v[114:117]
	v_mfma_f32_16x16x32_bf16 v[110:113], v[232:235], v[216:219], v[110:113]
	v_mfma_f32_16x16x32_bf16 v[106:109], v[232:235], v[220:223], v[106:109]
	v_mfma_f32_16x16x32_bf16 v[102:105], v[232:235], v[224:227], v[102:105]
	v_mfma_f32_16x16x32_bf16 v[98:101], v[232:235], v[228:231], v[98:101]
	v_mfma_f32_16x16x32_bf16 v[94:97], v[236:239], v[200:203], v[94:97]
	v_mfma_f32_16x16x32_bf16 v[90:93], v[236:239], v[204:207], v[90:93]
	v_mfma_f32_16x16x32_bf16 v[86:89], v[236:239], v[208:211], v[86:89]
	v_mfma_f32_16x16x32_bf16 v[82:85], v[236:239], v[212:215], v[82:85]
	v_mfma_f32_16x16x32_bf16 v[78:81], v[236:239], v[216:219], v[78:81]
	v_mfma_f32_16x16x32_bf16 v[74:77], v[236:239], v[220:223], v[74:77]
	v_mfma_f32_16x16x32_bf16 v[70:73], v[236:239], v[224:227], v[70:73]
	v_mfma_f32_16x16x32_bf16 v[66:69], v[236:239], v[228:231], v[66:69]
	v_mfma_f32_16x16x32_bf16 v[62:65], v[240:243], v[200:203], v[62:65]
	v_mfma_f32_16x16x32_bf16 v[58:61], v[240:243], v[204:207], v[58:61]
	v_mfma_f32_16x16x32_bf16 v[54:57], v[240:243], v[208:211], v[54:57]
	v_mfma_f32_16x16x32_bf16 v[50:53], v[240:243], v[212:215], v[50:53]
	v_mfma_f32_16x16x32_bf16 v[46:49], v[240:243], v[216:219], v[46:49]
	v_mfma_f32_16x16x32_bf16 v[42:45], v[240:243], v[220:223], v[42:45]
	v_mfma_f32_16x16x32_bf16 v[38:41], v[240:243], v[224:227], v[38:41]
	v_mfma_f32_16x16x32_bf16 v[34:37], v[240:243], v[228:231], v[34:37]
	v_mfma_f32_16x16x32_bf16 v[30:33], v[244:247], v[200:203], v[30:33]
	v_mfma_f32_16x16x32_bf16 v[26:29], v[244:247], v[204:207], v[26:29]
	v_mfma_f32_16x16x32_bf16 v[22:25], v[244:247], v[208:211], v[22:25]
	v_mfma_f32_16x16x32_bf16 v[18:21], v[244:247], v[212:215], v[18:21]
	v_mfma_f32_16x16x32_bf16 v[14:17], v[244:247], v[216:219], v[14:17]
	v_mfma_f32_16x16x32_bf16 v[10:13], v[244:247], v[220:223], v[10:13]
	v_mfma_f32_16x16x32_bf16 v[6:9], v[244:247], v[224:227], v[6:9]
	v_mfma_f32_16x16x32_bf16 v[2:5], v[244:247], v[228:231], v[2:5]
	s_mov_b32 m0, s41
	s_mov_b32 s8, 0x14000
	s_mov_b32 s9, 0
	s_nop 7
	v_and_b32_e32 v228, 1, v145
	v_cmp_ne_u32_e32 vcc, 0, v228
	v_mov_b32_e32 v229, 0xffffec40
	v_cndmask_b32_e32 v230, 0, v229, vcc
	v_ashrrev_i32_e32 v231, 31, v230
	v_lshl_add_u64 v[140:141], v[140:141], 0, v[230:231]
	v_add_co_u32_e32 v142, vcc, 0x1400, v140
	s_nop 0
	v_addc_co_u32_e32 v143, vcc, 0, v141, vcc
	v_cmp_ne_u32_e32 vcc, 0, v228
	v_cvt_pk_bf16_f32 v126, v126, v127
	v_cvt_pk_bf16_f32 v127, v128, v129
	v_cvt_pk_bf16_f32 v128, v94, v95
	v_cvt_pk_bf16_f32 v129, v96, v97
	v_cvt_pk_bf16_f32 v62, v62, v63
	v_cvt_pk_bf16_f32 v63, v64, v65
	v_cvt_pk_bf16_f32 v64, v30, v31
	v_cvt_pk_bf16_f32 v65, v32, v33
	v_permlane16_swap_b32_e32 v126, v128
	v_permlane16_swap_b32_e32 v127, v129
	v_permlane16_swap_b32_e32 v62, v64
	v_permlane16_swap_b32_e32 v63, v65
	v_mov_b32_dpp v224, v126 quad_perm:[1,0,3,2] row_mask:0xf bank_mask:0xf
	v_mov_b32_dpp v225, v127 quad_perm:[1,0,3,2] row_mask:0xf bank_mask:0xf
	v_mov_b32_dpp v226, v128 quad_perm:[1,0,3,2] row_mask:0xf bank_mask:0xf
	v_mov_b32_dpp v227, v129 quad_perm:[1,0,3,2] row_mask:0xf bank_mask:0xf
	v_mov_b32_dpp v220, v62 quad_perm:[1,0,3,2] row_mask:0xf bank_mask:0xf
	v_mov_b32_dpp v221, v63 quad_perm:[1,0,3,2] row_mask:0xf bank_mask:0xf
	v_mov_b32_dpp v222, v64 quad_perm:[1,0,3,2] row_mask:0xf bank_mask:0xf
	v_mov_b32_dpp v223, v65 quad_perm:[1,0,3,2] row_mask:0xf bank_mask:0xf
	v_cndmask_b32_e32 v62, v224, v62, vcc
	v_cndmask_b32_e32 v63, v225, v63, vcc
	v_cndmask_b32_e32 v64, v226, v64, vcc
	v_cndmask_b32_e32 v65, v227, v65, vcc
	v_cndmask_b32_e32 v126, v126, v220, vcc
	v_cndmask_b32_e32 v127, v127, v221, vcc
	v_cndmask_b32_e32 v128, v128, v222, vcc
	v_cndmask_b32_e32 v129, v129, v223, vcc
	global_store_dwordx4 v[140:141], v[126:129], off
	global_store_dwordx4 v[142:143], v[62:65], off
	v_lshl_add_u64 v[140:141], v[140:141], 0, s[8:9]
	v_lshl_add_u64 v[142:143], v[142:143], 0, s[8:9]
	v_cvt_pk_bf16_f32 v122, v122, v123
	v_cvt_pk_bf16_f32 v123, v124, v125
	v_cvt_pk_bf16_f32 v124, v90, v91
	v_cvt_pk_bf16_f32 v125, v92, v93
	v_cvt_pk_bf16_f32 v58, v58, v59
	v_cvt_pk_bf16_f32 v59, v60, v61
	v_cvt_pk_bf16_f32 v60, v26, v27
	v_cvt_pk_bf16_f32 v61, v28, v29
	v_permlane16_swap_b32_e32 v122, v124
	v_permlane16_swap_b32_e32 v123, v125
	v_permlane16_swap_b32_e32 v58, v60
	v_permlane16_swap_b32_e32 v59, v61
	v_mov_b32_dpp v224, v122 quad_perm:[1,0,3,2] row_mask:0xf bank_mask:0xf
	v_mov_b32_dpp v225, v123 quad_perm:[1,0,3,2] row_mask:0xf bank_mask:0xf
	v_mov_b32_dpp v226, v124 quad_perm:[1,0,3,2] row_mask:0xf bank_mask:0xf
	v_mov_b32_dpp v227, v125 quad_perm:[1,0,3,2] row_mask:0xf bank_mask:0xf
	v_mov_b32_dpp v220, v58 quad_perm:[1,0,3,2] row_mask:0xf bank_mask:0xf
	v_mov_b32_dpp v221, v59 quad_perm:[1,0,3,2] row_mask:0xf bank_mask:0xf
	v_mov_b32_dpp v222, v60 quad_perm:[1,0,3,2] row_mask:0xf bank_mask:0xf
	v_mov_b32_dpp v223, v61 quad_perm:[1,0,3,2] row_mask:0xf bank_mask:0xf
	v_cndmask_b32_e32 v58, v224, v58, vcc
	v_cndmask_b32_e32 v59, v225, v59, vcc
	v_cndmask_b32_e32 v60, v226, v60, vcc
	v_cndmask_b32_e32 v61, v227, v61, vcc
	v_cndmask_b32_e32 v122, v122, v220, vcc
	v_cndmask_b32_e32 v123, v123, v221, vcc
	v_cndmask_b32_e32 v124, v124, v222, vcc
	v_cndmask_b32_e32 v125, v125, v223, vcc
	global_store_dwordx4 v[140:141], v[122:125], off
	global_store_dwordx4 v[142:143], v[58:61], off
	v_lshl_add_u64 v[140:141], v[140:141], 0, s[8:9]
; DEVI unsigned pack2(float a, float b) { return __builtin_bit_cast(unsigned, __builtin_convertvector((f32x2_t){a, b}, bf16x2_t)); }
; DEVI float blo(unsigned u) { return __uint_as_float(u << 16); }
; DEVI float bhi(unsigned u) { return __uint_as_float(u & 0xffff0000u); }
;     ...
; #pragma unroll
;       for (int nf = 0; nf < 4; nf++) {
;         const int col = n0 + wn * 64 + nf * 16 + quad * 4;
;         f32x4 a = acc[nf][mf];
;         if (EPI == EPI_RESID || EPI == EPI_RESID_ATOMIC) {
;           f32x4 x = a;
;           if (EPI == EPI_RESID || kpart == 0) {
;             const u32x2 xr = *(const u32x2*)((const u16*)(p.ws + WS_XB) + (size_t)row * 1024 + col);
;             x[0] += ALPHA * blo(xr[0]); x[1] += ALPHA * bhi(xr[0]); x[2] += ALPHA * blo(xr[1]); x[3] += ALPHA * bhi(xr[1]);
;           }
;           if (EPI == EPI_RESID) *(f32x4*)((float*)(p.ws + WS_XF) + (size_t)row * 1024 + col) = x;
;           else *(f32x4*)((float*)(p.ws + WS_SLAB) + ((size_t)kpart * 512 + (row - T_P)) * 1024 + col) = x;
;         } else {
;           u32x2 pk; pk[0] = pack2(a[0], a[1]); pk[1] = pack2(a[2], a[3]);
;           *(u32x2*)(outb + (size_t)row * ldc + col) = pk;
;         }
	v_lshl_add_u64 v[142:143], v[142:143], 0, s[8:9]
	v_cvt_pk_bf16_f32 v118, v118, v119
	v_cvt_pk_bf16_f32 v119, v120, v121
	v_cvt_pk_bf16_f32 v120, v86, v87
	v_cvt_pk_bf16_f32 v121, v88, v89
	v_cvt_pk_bf16_f32 v54, v54, v55
	v_cvt_pk_bf16_f32 v55, v56, v57
	v_cvt_pk_bf16_f32 v56, v22, v23
	v_cvt_pk_bf16_f32 v57, v24, v25
	v_permlane16_swap_b32_e32 v118, v120
	v_permlane16_swap_b32_e32 v119, v121
	v_permlane16_swap_b32_e32 v54, v56
	v_permlane16_swap_b32_e32 v55, v57
	v_mov_b32_dpp v224, v118 quad_perm:[1,0,3,2] row_mask:0xf bank_mask:0xf
	v_mov_b32_dpp v225, v119 quad_perm:[1,0,3,2] row_mask:0xf bank_mask:0xf
	v_mov_b32_dpp v226, v120 quad_perm:[1,0,3,2] row_mask:0xf bank_mask:0xf
	v_mov_b32_dpp v227, v121 quad_perm:[1,0,3,2] row_mask:0xf bank_mask:0xf
	v_mov_b32_dpp v220, v54 quad_perm:[1,0,3,2] row_mask:0xf bank_mask:0xf
	v_mov_b32_dpp v221, v55 quad_perm:[1,0,3,2] row_mask:0xf bank_mask:0xf
	v_mov_b32_dpp v222, v56 quad_perm:[1,0,3,2] row_mask:0xf bank_mask:0xf
	v_mov_b32_dpp v223, v57 quad_perm:[1,0,3,2] row_mask:0xf bank_mask:0xf
	v_cndmask_b32_e32 v54, v224, v54, vcc
	v_cndmask_b32_e32 v55, v225, v55, vcc
	v_cndmask_b32_e32 v56, v226, v56, vcc
	v_cndmask_b32_e32 v57, v227, v57, vcc
	v_cndmask_b32_e32 v118, v118, v220, vcc
	v_cndmask_b32_e32 v119, v119, v221, vcc
	v_cndmask_b32_e32 v120, v120, v222, vcc
	v_cndmask_b32_e32 v121, v121, v223, vcc
	global_store_dwordx4 v[140:141], v[118:121], off
	global_store_dwordx4 v[142:143], v[54:57], off
	v_lshl_add_u64 v[140:141], v[140:141], 0, s[8:9]
	v_lshl_add_u64 v[142:143], v[142:143], 0, s[8:9]
	v_cvt_pk_bf16_f32 v114, v114, v115
	v_cvt_pk_bf16_f32 v115, v116, v117
	v_cvt_pk_bf16_f32 v116, v82, v83
	v_cvt_pk_bf16_f32 v117, v84, v85
	v_cvt_pk_bf16_f32 v50, v50, v51
	v_cvt_pk_bf16_f32 v51, v52, v53
	v_cvt_pk_bf16_f32 v52, v18, v19
	v_cvt_pk_bf16_f32 v53, v20, v21
	v_permlane16_swap_b32_e32 v114, v116
	v_permlane16_swap_b32_e32 v115, v117
	v_permlane16_swap_b32_e32 v50, v52
	v_permlane16_swap_b32_e32 v51, v53
	v_mov_b32_dpp v224, v114 quad_perm:[1,0,3,2] row_mask:0xf bank_mask:0xf
	v_mov_b32_dpp v225, v115 quad_perm:[1,0,3,2] row_mask:0xf bank_mask:0xf
	v_mov_b32_dpp v226, v116 quad_perm:[1,0,3,2] row_mask:0xf bank_mask:0xf
	v_mov_b32_dpp v227, v117 quad_perm:[1,0,3,2] row_mask:0xf bank_mask:0xf
	v_mov_b32_dpp v220, v50 quad_perm:[1,0,3,2] row_mask:0xf bank_mask:0xf
	v_mov_b32_dpp v221, v51 quad_perm:[1,0,3,2] row_mask:0xf bank_mask:0xf
	v_mov_b32_dpp v222, v52 quad_perm:[1,0,3,2] row_mask:0xf bank_mask:0xf
	v_mov_b32_dpp v223, v53 quad_perm:[1,0,3,2] row_mask:0xf bank_mask:0xf
	v_cndmask_b32_e32 v50, v224, v50, vcc
	v_cndmask_b32_e32 v51, v225, v51, vcc
	v_cndmask_b32_e32 v52, v226, v52, vcc
	v_cndmask_b32_e32 v53, v227, v53, vcc
	v_cndmask_b32_e32 v114, v114, v220, vcc
	v_cndmask_b32_e32 v115, v115, v221, vcc
	v_cndmask_b32_e32 v116, v116, v222, vcc
	v_cndmask_b32_e32 v117, v117, v223, vcc
	global_store_dwordx4 v[140:141], v[114:117], off
	global_store_dwordx4 v[142:143], v[50:53], off
	v_lshl_add_u64 v[140:141], v[140:141], 0, s[8:9]
	v_lshl_add_u64 v[142:143], v[142:143], 0, s[8:9]
	v_cvt_pk_bf16_f32 v110, v110, v111
	v_cvt_pk_bf16_f32 v111, v112, v113
	v_cvt_pk_bf16_f32 v112, v78, v79
	v_cvt_pk_bf16_f32 v113, v80, v81
	v_cvt_pk_bf16_f32 v46, v46, v47
	v_cvt_pk_bf16_f32 v47, v48, v49
	v_cvt_pk_bf16_f32 v48, v14, v15
	v_cvt_pk_bf16_f32 v49, v16, v17
	v_permlane16_swap_b32_e32 v110, v112
	v_permlane16_swap_b32_e32 v111, v113
	v_permlane16_swap_b32_e32 v46, v48
	v_permlane16_swap_b32_e32 v47, v49
	v_mov_b32_dpp v224, v110 quad_perm:[1,0,3,2] row_mask:0xf bank_mask:0xf
	v_mov_b32_dpp v225, v111 quad_perm:[1,0,3,2] row_mask:0xf bank_mask:0xf
	v_mov_b32_dpp v226, v112 quad_perm:[1,0,3,2] row_mask:0xf bank_mask:0xf
	v_mov_b32_dpp v227, v113 quad_perm:[1,0,3,2] row_mask:0xf bank_mask:0xf
	v_mov_b32_dpp v220, v46 quad_perm:[1,0,3,2] row_mask:0xf bank_mask:0xf
	v_mov_b32_dpp v221, v47 quad_perm:[1,0,3,2] row_mask:0xf bank_mask:0xf
	v_mov_b32_dpp v222, v48 quad_perm:[1,0,3,2] row_mask:0xf bank_mask:0xf
	v_mov_b32_dpp v223, v49 quad_perm:[1,0,3,2] row_mask:0xf bank_mask:0xf
	v_cndmask_b32_e32 v46, v224, v46, vcc
	v_cndmask_b32_e32 v47, v225, v47, vcc
	v_cndmask_b32_e32 v48, v226, v48, vcc
	v_cndmask_b32_e32 v49, v227, v49, vcc
	v_cndmask_b32_e32 v110, v110, v220, vcc
	v_cndmask_b32_e32 v111, v111, v221, vcc
	v_cndmask_b32_e32 v112, v112, v222, vcc
	v_cndmask_b32_e32 v113, v113, v223, vcc
	global_store_dwordx4 v[140:141], v[110:113], off
	global_store_dwordx4 v[142:143], v[46:49], off
; DEVI unsigned pack2(float a, float b) { return __builtin_bit_cast(unsigned, __builtin_convertvector((f32x2_t){a, b}, bf16x2_t)); }
; DEVI float blo(unsigned u) { return __uint_as_float(u << 16); }
; DEVI float bhi(unsigned u) { return __uint_as_float(u & 0xffff0000u); }
;     ...
; #pragma unroll
;       for (int nf = 0; nf < 4; nf++) {
;         const int col = n0 + wn * 64 + nf * 16 + quad * 4;
;         f32x4 a = acc[nf][mf];
;         if (EPI == EPI_RESID || EPI == EPI_RESID_ATOMIC) {
;           f32x4 x = a;
;           if (EPI == EPI_RESID || kpart == 0) {
;             const u32x2 xr = *(const u32x2*)((const u16*)(p.ws + WS_XB) + (size_t)row * 1024 + col);
;             x[0] += ALPHA * blo(xr[0]); x[1] += ALPHA * bhi(xr[0]); x[2] += ALPHA * blo(xr[1]); x[3] += ALPHA * bhi(xr[1]);
;           }
;           if (EPI == EPI_RESID) *(f32x4*)((float*)(p.ws + WS_XF) + (size_t)row * 1024 + col) = x;
;           else *(f32x4*)((float*)(p.ws + WS_SLAB) + ((size_t)kpart * 512 + (row - T_P)) * 1024 + col) = x;
;         } else {
;           u32x2 pk; pk[0] = pack2(a[0], a[1]); pk[1] = pack2(a[2], a[3]);
;           *(u32x2*)(outb + (size_t)row * ldc + col) = pk;
;         }
	v_lshl_add_u64 v[140:141], v[140:141], 0, s[8:9]
	v_lshl_add_u64 v[142:143], v[142:143], 0, s[8:9]
	v_cvt_pk_bf16_f32 v106, v106, v107
	v_cvt_pk_bf16_f32 v107, v108, v109
	v_cvt_pk_bf16_f32 v108, v74, v75
	v_cvt_pk_bf16_f32 v109, v76, v77
	v_cvt_pk_bf16_f32 v42, v42, v43
	v_cvt_pk_bf16_f32 v43, v44, v45
	v_cvt_pk_bf16_f32 v44, v10, v11
	v_cvt_pk_bf16_f32 v45, v12, v13
	v_permlane16_swap_b32_e32 v106, v108
	v_permlane16_swap_b32_e32 v107, v109
	v_permlane16_swap_b32_e32 v42, v44
	v_permlane16_swap_b32_e32 v43, v45
	v_mov_b32_dpp v224, v106 quad_perm:[1,0,3,2] row_mask:0xf bank_mask:0xf
	v_mov_b32_dpp v225, v107 quad_perm:[1,0,3,2] row_mask:0xf bank_mask:0xf
	v_mov_b32_dpp v226, v108 quad_perm:[1,0,3,2] row_mask:0xf bank_mask:0xf
	v_mov_b32_dpp v227, v109 quad_perm:[1,0,3,2] row_mask:0xf bank_mask:0xf
	v_mov_b32_dpp v220, v42 quad_perm:[1,0,3,2] row_mask:0xf bank_mask:0xf
	v_mov_b32_dpp v221, v43 quad_perm:[1,0,3,2] row_mask:0xf bank_mask:0xf
	v_mov_b32_dpp v222, v44 quad_perm:[1,0,3,2] row_mask:0xf bank_mask:0xf
	v_mov_b32_dpp v223, v45 quad_perm:[1,0,3,2] row_mask:0xf bank_mask:0xf
	v_cndmask_b32_e32 v42, v224, v42, vcc
	v_cndmask_b32_e32 v43, v225, v43, vcc
	v_cndmask_b32_e32 v44, v226, v44, vcc
	v_cndmask_b32_e32 v45, v227, v45, vcc
	v_cndmask_b32_e32 v106, v106, v220, vcc
	v_cndmask_b32_e32 v107, v107, v221, vcc
	v_cndmask_b32_e32 v108, v108, v222, vcc
	v_cndmask_b32_e32 v109, v109, v223, vcc
	global_store_dwordx4 v[140:141], v[106:109], off
	global_store_dwordx4 v[142:143], v[42:45], off
	v_lshl_add_u64 v[140:141], v[140:141], 0, s[8:9]
	v_lshl_add_u64 v[142:143], v[142:143], 0, s[8:9]
	v_cvt_pk_bf16_f32 v102, v102, v103
	v_cvt_pk_bf16_f32 v103, v104, v105
	v_cvt_pk_bf16_f32 v104, v70, v71
	v_cvt_pk_bf16_f32 v105, v72, v73
	v_cvt_pk_bf16_f32 v38, v38, v39
	v_cvt_pk_bf16_f32 v39, v40, v41
	v_cvt_pk_bf16_f32 v40, v6, v7
	v_cvt_pk_bf16_f32 v41, v8, v9
	v_permlane16_swap_b32_e32 v102, v104
	v_permlane16_swap_b32_e32 v103, v105
	v_permlane16_swap_b32_e32 v38, v40
	v_permlane16_swap_b32_e32 v39, v41
	v_mov_b32_dpp v224, v102 quad_perm:[1,0,3,2] row_mask:0xf bank_mask:0xf
	v_mov_b32_dpp v225, v103 quad_perm:[1,0,3,2] row_mask:0xf bank_mask:0xf
	v_mov_b32_dpp v226, v104 quad_perm:[1,0,3,2] row_mask:0xf bank_mask:0xf
	v_mov_b32_dpp v227, v105 quad_perm:[1,0,3,2] row_mask:0xf bank_mask:0xf
	v_mov_b32_dpp v220, v38 quad_perm:[1,0,3,2] row_mask:0xf bank_mask:0xf
	v_mov_b32_dpp v221, v39 quad_perm:[1,0,3,2] row_mask:0xf bank_mask:0xf
	v_mov_b32_dpp v222, v40 quad_perm:[1,0,3,2] row_mask:0xf bank_mask:0xf
	v_mov_b32_dpp v223, v41 quad_perm:[1,0,3,2] row_mask:0xf bank_mask:0xf
	v_cndmask_b32_e32 v38, v224, v38, vcc
	v_cndmask_b32_e32 v39, v225, v39, vcc
	v_cndmask_b32_e32 v40, v226, v40, vcc
	v_cndmask_b32_e32 v41, v227, v41, vcc
	v_cndmask_b32_e32 v102, v102, v220, vcc
	v_cndmask_b32_e32 v103, v103, v221, vcc
	v_cndmask_b32_e32 v104, v104, v222, vcc
	v_cndmask_b32_e32 v105, v105, v223, vcc
	global_store_dwordx4 v[140:141], v[102:105], off
	global_store_dwordx4 v[142:143], v[38:41], off
	v_lshl_add_u64 v[140:141], v[140:141], 0, s[8:9]
	v_lshl_add_u64 v[142:143], v[142:143], 0, s[8:9]
	v_cvt_pk_bf16_f32 v98, v98, v99
	v_cvt_pk_bf16_f32 v99, v100, v101
	v_cvt_pk_bf16_f32 v100, v66, v67
	v_cvt_pk_bf16_f32 v101, v68, v69
	v_cvt_pk_bf16_f32 v34, v34, v35
	v_cvt_pk_bf16_f32 v35, v36, v37
	v_cvt_pk_bf16_f32 v36, v2, v3
	v_cvt_pk_bf16_f32 v37, v4, v5
	v_permlane16_swap_b32_e32 v98, v100
	v_permlane16_swap_b32_e32 v99, v101
	v_permlane16_swap_b32_e32 v34, v36
	v_permlane16_swap_b32_e32 v35, v37
	v_mov_b32_dpp v224, v98 quad_perm:[1,0,3,2] row_mask:0xf bank_mask:0xf
	v_mov_b32_dpp v225, v99 quad_perm:[1,0,3,2] row_mask:0xf bank_mask:0xf
	v_mov_b32_dpp v226, v100 quad_perm:[1,0,3,2] row_mask:0xf bank_mask:0xf
	v_mov_b32_dpp v227, v101 quad_perm:[1,0,3,2] row_mask:0xf bank_mask:0xf
	v_mov_b32_dpp v220, v34 quad_perm:[1,0,3,2] row_mask:0xf bank_mask:0xf
	v_mov_b32_dpp v221, v35 quad_perm:[1,0,3,2] row_mask:0xf bank_mask:0xf
	v_mov_b32_dpp v222, v36 quad_perm:[1,0,3,2] row_mask:0xf bank_mask:0xf
	v_mov_b32_dpp v223, v37 quad_perm:[1,0,3,2] row_mask:0xf bank_mask:0xf
	v_cndmask_b32_e32 v34, v224, v34, vcc
	v_cndmask_b32_e32 v35, v225, v35, vcc
	v_cndmask_b32_e32 v36, v226, v36, vcc
	v_cndmask_b32_e32 v37, v227, v37, vcc
	v_cndmask_b32_e32 v98, v98, v220, vcc
	v_cndmask_b32_e32 v99, v99, v221, vcc
	v_cndmask_b32_e32 v100, v100, v222, vcc
	v_cndmask_b32_e32 v101, v101, v223, vcc
	global_store_dwordx4 v[140:141], v[98:101], off
	global_store_dwordx4 v[142:143], v[34:37], off
	s_branch .LBB0_886
